# attention: SADDR LDS-DMA with per-lane offsets (no per-tile address VALU), packed f32 subs split to scalar; rcp-based f32 division in GLU/SGU/attention epilogues; S5 step1 prefetch
# speedup vs baseline: 1.0435x; 1.0355x over previous
.LBB0_825:
	s_ashr_i32 s8, s65, 7
	v_mov_b32_e32 v130, v217
	s_ashr_i32 s9, s8, 31
	v_ashrrev_i32_e32 v0, 2, v130
	s_lshl_b64 s[36:37], s[8:9], 12
	s_and_b32 s7, s64, 0xf80
	v_add_u32_e32 v44, s10, v0
	s_or_b32 s36, s36, s7
	v_ashrrev_i32_e32 v45, 31, v44
	v_lshl_add_u64 v[0:1], s[36:37], 0, v[44:45]
	v_mov_b64_e32 v[2:3], s[82:83]
	v_mad_u64_u32 v[2:3], s[8:9], v0, s14, v[2:3]
	v_lshlrev_b32_e32 v0, 3, v130
	v_and_b32_e32 v45, 24, v0
	v_mad_i32_i24 v3, v1, s14, v3
	v_lshlrev_b32_e32 v194, 1, v45
	v_lshl_add_u64 v[0:1], v[2:3], 0, v[194:195]
	v_lshl_add_u64 v[2:3], v[0:1], 0, s[66:67]
	v_add_co_u32_e32 v0, vcc, s15, v0
	v_mov_b32_e32 v100, v195
	s_nop 0
	v_addc_co_u32_e32 v1, vcc, 0, v1, vcc
	global_load_dwordx4 v[46:49], v[0:1], off offset:1024
	global_load_dwordx4 v[50:53], v[2:3], off offset:64
	global_load_dwordx4 v[54:57], v[2:3], off offset:128
	global_load_dwordx4 v[60:63], v[2:3], off offset:192
	global_load_dwordx4 v[68:71], v[2:3], off offset:256
	global_load_dwordx4 v[72:75], v[2:3], off offset:320
	global_load_dwordx4 v[76:79], v[2:3], off offset:384
	global_load_dwordx4 v[80:83], v[2:3], off offset:448
	global_load_dwordx4 v[110:113], v[2:3], off offset:512
	global_load_dwordx4 v[40:43], v[2:3], off offset:576
	global_load_dwordx4 v[36:39], v[2:3], off offset:640
	global_load_dwordx4 v[32:35], v[2:3], off offset:704
	global_load_dwordx4 v[28:31], v[2:3], off offset:768
	global_load_dwordx4 v[24:27], v[2:3], off offset:832
	global_load_dwordx4 v[20:23], v[2:3], off offset:896
	global_load_dwordx4 v[16:19], v[2:3], off offset:960
	s_and_b32 s45, s65, 3
	s_lshl_b32 s60, s45, 7
	s_lshl_b32 s92, s45, 8
	s_lshl_b32 s7, s45, 9
	s_add_u32 s40, s12, s7
	s_addc_u32 s41, s16, 0
	v_lshl_add_u64 v[0:1], v[2:3], 0, s[92:93]
	s_add_u32 s46, s17, s7
	global_load_dwordx4 v[12:15], v[0:1], off
	global_load_dwordx4 v[8:11], v[0:1], off offset:64
	global_load_dwordx4 v[4:7], v[0:1], off offset:128
	s_nop 0
	global_load_dwordx4 v[0:3], v[0:1], off offset:192
	s_addc_u32 s47, s18, 0
	s_add_u32 s8, s33, s92
	v_and_b32_e32 v132, 15, v130
	s_addc_u32 s9, s34, 0
	s_lshl_b32 s7, s45, 15
	v_lshlrev_b32_e32 v194, 8, v132
	s_waitcnt vmcnt(19)
	v_lshlrev_b32_e32 v115, 16, v48
	v_lshlrev_b32_e32 v114, 16, v46
	v_and_b32_e32 v117, 0xffff0000, v48
	v_and_b32_e32 v116, 0xffff0000, v46
	v_lshlrev_b32_e32 v119, 16, v49
	v_lshlrev_b32_e32 v118, 16, v47
	v_and_b32_e32 v121, 0xffff0000, v49
	v_and_b32_e32 v120, 0xffff0000, v47
	v_pk_add_f32 v[58:59], v[114:115], v[116:117]
	v_pk_add_f32 v[46:47], v[118:119], v[120:121]
	s_waitcnt vmcnt(18)
	v_lshlrev_b32_e32 v109, 16, v51
	v_lshlrev_b32_e32 v108, 16, v50
	v_and_b32_e32 v107, 0xffff0000, v51
	v_and_b32_e32 v106, 0xffff0000, v50
	v_lshlrev_b32_e32 v105, 16, v53
	v_lshlrev_b32_e32 v104, 16, v52
	v_and_b32_e32 v103, 0xffff0000, v53
	v_and_b32_e32 v102, 0xffff0000, v52
	v_pk_add_f32 v[46:47], v[58:59], v[46:47]
	v_pk_add_f32 v[48:49], v[108:109], v[106:107]
	v_pk_add_f32 v[50:51], v[104:105], v[102:103]
	s_waitcnt vmcnt(16)
	v_lshlrev_b32_e32 v142, 16, v60
	v_lshlrev_b32_e32 v143, 16, v61
	v_and_b32_e32 v144, 0xffff0000, v61
	v_pk_add_f32 v[46:47], v[46:47], v[46:47] op_sel:[0,1] op_sel_hi:[1,0]
	v_pk_add_f32 v[48:49], v[48:49], v[48:49] op_sel:[0,1] op_sel_hi:[1,0]
	v_pk_add_f32 v[50:51], v[50:51], v[50:51] op_sel:[0,1] op_sel_hi:[1,0]
	v_lshlrev_b32_e32 v131, 16, v54
	v_and_b32_e32 v133, 0xffff0000, v54
	v_lshlrev_b32_e32 v136, 16, v55
	v_and_b32_e32 v137, 0xffff0000, v55
	v_lshlrev_b32_e32 v138, 16, v56
	v_and_b32_e32 v139, 0xffff0000, v56
	v_lshlrev_b32_e32 v140, 16, v57
	v_and_b32_e32 v141, 0xffff0000, v57
	v_and_b32_e32 v101, 0xffff0000, v60
	v_mov_b32_e32 v47, v142
	v_mov_b32_e32 v49, v143
	v_mov_b32_e32 v51, v144
	v_add_f32_e32 v54, v131, v133
	v_add_f32_e32 v58, v136, v137
	v_add_f32_e32 v64, v138, v139
	v_add_f32_e32 v66, v140, v141
	v_lshlrev_b32_e32 v55, 16, v62
	v_and_b32_e32 v59, 0xffff0000, v62
	v_lshlrev_b32_e32 v65, 16, v63
	v_and_b32_e32 v67, 0xffff0000, v63
	v_pk_add_f32 v[46:47], v[46:47], v[100:101]
	v_pk_add_f32 v[48:49], v[48:49], v[50:51]
	v_pk_add_f32 v[50:51], v[64:65], v[66:67]
	v_pk_add_f32 v[46:47], v[46:47], v[48:49]
	v_pk_add_f32 v[48:49], v[54:55], v[58:59]
	s_waitcnt vmcnt(15)
	v_lshlrev_b32_e32 v95, 16, v70
	v_pk_add_f32 v[48:49], v[48:49], v[50:51]
	v_lshlrev_b32_e32 v94, 16, v68
	v_and_b32_e32 v93, 0xffff0000, v70
	v_and_b32_e32 v92, 0xffff0000, v68
	v_lshlrev_b32_e32 v99, 16, v71
	v_lshlrev_b32_e32 v98, 16, v69
	v_and_b32_e32 v97, 0xffff0000, v71
	v_and_b32_e32 v96, 0xffff0000, v69
	v_pk_add_f32 v[56:57], v[46:47], v[48:49]
	v_pk_add_f32 v[46:47], v[94:95], v[92:93]
	v_pk_add_f32 v[48:49], v[98:99], v[96:97]
	s_waitcnt vmcnt(14)
	v_lshlrev_b32_e32 v91, 16, v73
	v_pk_add_f32 v[60:61], v[46:47], v[48:49]
	v_lshlrev_b32_e32 v90, 16, v72
	v_and_b32_e32 v89, 0xffff0000, v73
	v_and_b32_e32 v88, 0xffff0000, v72
	v_lshlrev_b32_e32 v87, 16, v75
	v_lshlrev_b32_e32 v86, 16, v74
	v_and_b32_e32 v85, 0xffff0000, v75
	v_and_b32_e32 v84, 0xffff0000, v74
	s_waitcnt vmcnt(12)
	v_lshlrev_b32_e32 v148, 16, v80
	v_and_b32_e32 v149, 0xffff0000, v80
	v_pk_add_f32 v[56:57], v[56:57], v[56:57] op_sel:[0,1] op_sel_hi:[1,0]
	v_pk_add_f32 v[60:61], v[60:61], v[60:61] op_sel:[0,1] op_sel_hi:[1,0]
	v_pk_add_f32 v[62:63], v[90:91], v[88:89]
	v_pk_add_f32 v[68:69], v[86:87], v[84:85]
	v_mov_b32_e32 v57, v148
	v_mov_b32_e32 v61, v149
	v_lshlrev_b32_e32 v150, 16, v81
	v_and_b32_e32 v151, 0xffff0000, v81
	v_pk_add_f32 v[56:57], v[56:57], v[60:61]
	v_pk_add_f32 v[60:61], v[62:63], v[62:63] op_sel:[0,1] op_sel_hi:[1,0]
	v_pk_add_f32 v[62:63], v[68:69], v[68:69] op_sel:[0,1] op_sel_hi:[1,0]
	v_lshlrev_b32_e32 v54, 16, v76
	v_and_b32_e32 v58, 0xffff0000, v76
	v_lshlrev_b32_e32 v64, 16, v77
	v_and_b32_e32 v66, 0xffff0000, v77
	v_lshlrev_b32_e32 v100, 16, v78
	v_and_b32_e32 v145, 0xffff0000, v78
	v_lshlrev_b32_e32 v146, 16, v79
	v_and_b32_e32 v147, 0xffff0000, v79
	v_mov_b32_e32 v61, v150
	v_mov_b32_e32 v63, v151
	v_add_f32_e32 v46, v54, v58
	v_add_f32_e32 v48, v64, v66
	v_add_f32_e32 v50, v100, v145
	v_add_f32_e32 v52, v146, v147
	v_lshlrev_b32_e32 v47, 16, v82
	v_and_b32_e32 v49, 0xffff0000, v82
	v_lshlrev_b32_e32 v51, 16, v83
	v_and_b32_e32 v53, 0xffff0000, v83
	v_pk_add_f32 v[60:61], v[60:61], v[62:63]
	v_pk_add_f32 v[62:63], v[50:51], v[52:53]
	v_pk_add_f32 v[56:57], v[56:57], v[60:61]
	v_pk_add_f32 v[60:61], v[46:47], v[48:49]
	s_waitcnt vmcnt(11)
	v_lshlrev_b32_e32 v79, 16, v112
	v_pk_add_f32 v[60:61], v[60:61], v[62:63]
	v_lshlrev_b32_e32 v78, 16, v110
	v_and_b32_e32 v77, 0xffff0000, v112
	v_and_b32_e32 v76, 0xffff0000, v110
	v_lshlrev_b32_e32 v83, 16, v113
	v_lshlrev_b32_e32 v82, 16, v111
	v_and_b32_e32 v81, 0xffff0000, v113
	v_and_b32_e32 v80, 0xffff0000, v111
	v_pk_add_f32 v[56:57], v[56:57], v[60:61]
	v_pk_add_f32 v[60:61], v[78:79], v[76:77]
	v_pk_add_f32 v[62:63], v[82:83], v[80:81]
	s_waitcnt vmcnt(10)
	v_lshlrev_b32_e32 v75, 16, v41
	v_pk_add_f32 v[60:61], v[60:61], v[62:63]
	v_lshlrev_b32_e32 v74, 16, v40
	v_and_b32_e32 v73, 0xffff0000, v41
	v_and_b32_e32 v72, 0xffff0000, v40
	v_lshlrev_b32_e32 v71, 16, v43
	v_lshlrev_b32_e32 v70, 16, v42
	v_and_b32_e32 v69, 0xffff0000, v43
	v_and_b32_e32 v68, 0xffff0000, v42
	s_waitcnt vmcnt(9)
	v_lshlrev_b32_e32 v50, 16, v37
	v_and_b32_e32 v52, 0xffff0000, v37
	v_lshlrev_b32_e32 v154, 16, v39
	v_and_b32_e32 v155, 0xffff0000, v39
	s_waitcnt vmcnt(8)
	v_lshlrev_b32_e32 v156, 16, v32
	v_and_b32_e32 v157, 0xffff0000, v32
	v_lshlrev_b32_e32 v158, 16, v33
	v_and_b32_e32 v159, 0xffff0000, v33
	v_lshlrev_b32_e32 v37, 16, v34
	v_and_b32_e32 v41, 0xffff0000, v34
	v_lshlrev_b32_e32 v39, 16, v35
	v_and_b32_e32 v43, 0xffff0000, v35
	v_pk_add_f32 v[32:33], v[56:57], v[56:57] op_sel:[0,1] op_sel_hi:[1,0]
	v_pk_add_f32 v[34:35], v[60:61], v[60:61] op_sel:[0,1] op_sel_hi:[1,0]
	v_pk_add_f32 v[62:63], v[74:75], v[72:73]
	v_pk_add_f32 v[110:111], v[70:71], v[68:69]
	v_mov_b32_e32 v33, v156
	v_mov_b32_e32 v35, v157
	v_pk_add_f32 v[32:33], v[32:33], v[34:35]
	v_pk_add_f32 v[34:35], v[62:63], v[62:63] op_sel:[0,1] op_sel_hi:[1,0]
	v_pk_add_f32 v[56:57], v[110:111], v[110:111] op_sel:[0,1] op_sel_hi:[1,0]
	v_lshlrev_b32_e32 v46, 16, v36
	v_and_b32_e32 v48, 0xffff0000, v36
	v_lshlrev_b32_e32 v152, 16, v38
	v_and_b32_e32 v153, 0xffff0000, v38
	v_mov_b32_e32 v35, v158
	v_mov_b32_e32 v57, v159
	v_add_f32_e32 v36, v46, v48
	v_add_f32_e32 v40, v50, v52
	v_add_f32_e32 v38, v152, v153
	v_add_f32_e32 v42, v154, v155
	v_pk_add_f32 v[34:35], v[34:35], v[56:57]
	v_pk_add_f32 v[56:57], v[38:39], v[42:43]
	v_pk_add_f32 v[32:33], v[32:33], v[34:35]
	v_pk_add_f32 v[34:35], v[36:37], v[40:41]
	s_waitcnt vmcnt(5)
	v_lshlrev_b32_e32 v40, 16, v21
	v_pk_add_f32 v[34:35], v[34:35], v[56:57]
	v_and_b32_e32 v42, 0xffff0000, v21
	v_pk_add_f32 v[32:33], v[32:33], v[34:35]
	v_and_b32_e32 v21, 64, v224
	v_pk_add_f32 v[110:111], v[32:33], v[32:33] op_sel:[0,1] op_sel_hi:[1,0]
	v_lshlrev_b32_e32 v57, 16, v30
	v_lshlrev_b32_e32 v56, 16, v28
	v_and_b32_e32 v33, 0xffff0000, v30
	v_and_b32_e32 v32, 0xffff0000, v28
	v_lshlrev_b32_e32 v63, 16, v31
	v_lshlrev_b32_e32 v62, 16, v29
	v_and_b32_e32 v61, 0xffff0000, v31
	v_and_b32_e32 v60, 0xffff0000, v29
	v_lshlrev_b32_e32 v36, 16, v20
	v_and_b32_e32 v38, 0xffff0000, v20
	v_xor_b32_e32 v20, 1, v224
	v_add_u32_e32 v21, 64, v21
	v_pk_add_f32 v[34:35], v[56:57], v[32:33]
	v_pk_add_f32 v[28:29], v[62:63], v[60:61]
	v_cmp_lt_i32_e32 vcc, v20, v21
	v_pk_add_f32 v[28:29], v[34:35], v[28:29]
	v_lshlrev_b32_e32 v35, 16, v25
	v_lshlrev_b32_e32 v34, 16, v24
	v_and_b32_e32 v31, 0xffff0000, v25
	v_and_b32_e32 v30, 0xffff0000, v24
	v_cndmask_b32_e32 v20, v224, v20, vcc
	v_pk_add_f32 v[24:25], v[34:35], v[30:31]
	v_lshlrev_b32_e32 v164, 2, v20
	v_xor_b32_e32 v20, 2, v224
	v_pk_add_f32 v[112:113], v[28:29], v[28:29] op_sel:[0,1] op_sel_hi:[1,0]
	v_pk_add_f32 v[122:123], v[24:25], v[24:25] op_sel:[0,1] op_sel_hi:[1,0]
	v_lshlrev_b32_e32 v29, 16, v27
	v_lshlrev_b32_e32 v28, 16, v26
	v_and_b32_e32 v25, 0xffff0000, v27
	v_and_b32_e32 v24, 0xffff0000, v26
	v_cmp_lt_i32_e32 vcc, v20, v21
	v_pk_add_f32 v[26:27], v[28:29], v[24:25]
	v_lshlrev_b32_e32 v160, 16, v22
	v_cndmask_b32_e32 v20, v224, v20, vcc
	v_pk_add_f32 v[26:27], v[26:27], v[26:27] op_sel:[0,1] op_sel_hi:[1,0]
	v_and_b32_e32 v161, 0xffff0000, v22
	v_lshlrev_b32_e32 v162, 16, v23
	v_and_b32_e32 v163, 0xffff0000, v23
	v_lshlrev_b32_e32 v165, 2, v20
	s_waitcnt vmcnt(4)
	v_and_b32_e32 v20, 0xffff0000, v19
	v_lshlrev_b32_e32 v21, 16, v19
	v_and_b32_e32 v22, 0xffff0000, v18
	v_lshlrev_b32_e32 v23, 16, v18
	v_and_b32_e32 v18, 0xffff0000, v17
	v_lshlrev_b32_e32 v19, 16, v17
	v_mov_b32_e32 v123, v19
	v_mov_b32_e32 v27, v18
	v_pk_add_f32 v[122:123], v[122:123], v[26:27]
	v_and_b32_e32 v26, 0xffff0000, v16
	v_lshlrev_b32_e32 v27, 16, v16
	v_add_f32_e32 v124, v36, v38
	v_add_f32_e32 v126, v40, v42
	v_add_f32_e32 v128, v160, v161
	v_add_f32_e32 v134, v162, v163
	v_mov_b32_e32 v129, v21
	v_mov_b32_e32 v135, v20
	v_mov_b32_e32 v125, v23
	v_mov_b32_e32 v127, v22
	v_mov_b32_e32 v111, v27
	v_mov_b32_e32 v113, v26
	v_pk_add_f32 v[128:129], v[128:129], v[134:135]
	v_pk_add_f32 v[124:125], v[124:125], v[126:127]
	v_pk_add_f32 v[16:17], v[110:111], v[112:113]
	v_pk_add_f32 v[124:125], v[124:125], v[128:129]
	v_pk_add_f32 v[16:17], v[16:17], v[122:123]
	s_nop 0
	v_pk_add_f32 v[16:17], v[16:17], v[124:125]
	s_nop 0
	v_add_f32_e32 v16, v16, v17
	ds_bpermute_b32 v17, v164, v16
	s_waitcnt lgkmcnt(0)
	v_add_f32_e32 v16, v16, v17
	ds_bpermute_b32 v17, v165, v16
	s_waitcnt lgkmcnt(0)
	v_add_f32_e32 v17, v16, v17
	v_fmac_f32_e32 v114, 0xbb000000, v17
	v_mul_f32_e32 v110, v114, v114
	v_fmac_f32_e32 v116, 0xbb000000, v17
	v_fmac_f32_e32 v110, v116, v116
	v_fmac_f32_e32 v118, 0xbb000000, v17
	v_fmac_f32_e32 v110, v118, v118
	v_fmac_f32_e32 v120, 0xbb000000, v17
	v_fmac_f32_e32 v110, v120, v120
	v_fmac_f32_e32 v115, 0xbb000000, v17
	v_fmac_f32_e32 v110, v115, v115
	v_fmac_f32_e32 v117, 0xbb000000, v17
	v_fmac_f32_e32 v110, v117, v117
	v_fmac_f32_e32 v119, 0xbb000000, v17
	v_fmac_f32_e32 v110, v119, v119
	v_fmac_f32_e32 v121, 0xbb000000, v17
	v_fmac_f32_e32 v110, v121, v121
	v_fmac_f32_e32 v108, 0xbb000000, v17
	v_fmac_f32_e32 v110, v108, v108
	v_fmac_f32_e32 v106, 0xbb000000, v17
	v_fmac_f32_e32 v110, v106, v106
	v_fmac_f32_e32 v109, 0xbb000000, v17
	v_fmac_f32_e32 v110, v109, v109
	v_fmac_f32_e32 v107, 0xbb000000, v17
	v_fmac_f32_e32 v110, v107, v107
	v_fmac_f32_e32 v104, 0xbb000000, v17
	v_fmac_f32_e32 v110, v104, v104
	v_fmac_f32_e32 v102, 0xbb000000, v17
	v_fmac_f32_e32 v110, v102, v102
	v_fmac_f32_e32 v105, 0xbb000000, v17
	v_fmac_f32_e32 v110, v105, v105
	v_fmac_f32_e32 v103, 0xbb000000, v17
	v_fmac_f32_e32 v110, v103, v103
	v_fmac_f32_e32 v131, 0xbb000000, v17
	v_fmac_f32_e32 v110, v131, v131
	v_fmac_f32_e32 v133, 0xbb000000, v17
	v_fmac_f32_e32 v110, v133, v133
	v_fmac_f32_e32 v136, 0xbb000000, v17
	v_fmac_f32_e32 v110, v136, v136
	v_fmac_f32_e32 v137, 0xbb000000, v17
	v_fmac_f32_e32 v110, v137, v137
	v_fmac_f32_e32 v138, 0xbb000000, v17
	v_fmac_f32_e32 v110, v138, v138
	v_fmac_f32_e32 v139, 0xbb000000, v17
	v_fmac_f32_e32 v110, v139, v139
	v_fmac_f32_e32 v140, 0xbb000000, v17
	v_fmac_f32_e32 v110, v140, v140
	v_fmac_f32_e32 v141, 0xbb000000, v17
	v_fmac_f32_e32 v110, v141, v141
	v_fmac_f32_e32 v142, 0xbb000000, v17
	v_fmac_f32_e32 v110, v142, v142
	v_fmac_f32_e32 v101, 0xbb000000, v17
	v_fmac_f32_e32 v110, v101, v101
	v_fmac_f32_e32 v143, 0xbb000000, v17
	v_fmac_f32_e32 v110, v143, v143
	v_fmac_f32_e32 v144, 0xbb000000, v17
	v_fmac_f32_e32 v110, v144, v144
	v_fmac_f32_e32 v55, 0xbb000000, v17
	v_fmac_f32_e32 v110, v55, v55
	v_fmac_f32_e32 v59, 0xbb000000, v17
	v_fmac_f32_e32 v110, v59, v59
	v_fmac_f32_e32 v65, 0xbb000000, v17
	v_fmac_f32_e32 v110, v65, v65
	v_fmac_f32_e32 v67, 0xbb000000, v17
	v_fmac_f32_e32 v110, v67, v67
	v_fmac_f32_e32 v94, 0xbb000000, v17
	v_fmac_f32_e32 v110, v94, v94
	v_fmac_f32_e32 v92, 0xbb000000, v17
	v_fmac_f32_e32 v110, v92, v92
	v_fmac_f32_e32 v98, 0xbb000000, v17
	v_fmac_f32_e32 v110, v98, v98
	v_fmac_f32_e32 v96, 0xbb000000, v17
	v_fmac_f32_e32 v110, v96, v96
	v_fmac_f32_e32 v95, 0xbb000000, v17
	v_fmac_f32_e32 v110, v95, v95
	v_fmac_f32_e32 v93, 0xbb000000, v17
	v_fmac_f32_e32 v110, v93, v93
	v_fmac_f32_e32 v99, 0xbb000000, v17
	v_fmac_f32_e32 v110, v99, v99
	v_fmac_f32_e32 v97, 0xbb000000, v17
	v_fmac_f32_e32 v110, v97, v97
	v_fmac_f32_e32 v90, 0xbb000000, v17
	v_fmac_f32_e32 v110, v90, v90
	v_fmac_f32_e32 v88, 0xbb000000, v17
	v_fmac_f32_e32 v110, v88, v88
	v_fmac_f32_e32 v91, 0xbb000000, v17
	v_fmac_f32_e32 v110, v91, v91
	v_fmac_f32_e32 v89, 0xbb000000, v17
	v_fmac_f32_e32 v110, v89, v89
	v_fmac_f32_e32 v86, 0xbb000000, v17
	v_fmac_f32_e32 v110, v86, v86
	v_fmac_f32_e32 v84, 0xbb000000, v17
	v_fmac_f32_e32 v110, v84, v84
	v_fmac_f32_e32 v87, 0xbb000000, v17
	v_fmac_f32_e32 v110, v87, v87
	v_fmac_f32_e32 v85, 0xbb000000, v17
	v_fmac_f32_e32 v110, v85, v85
	v_fmac_f32_e32 v54, 0xbb000000, v17
	v_fmac_f32_e32 v110, v54, v54
	v_fmac_f32_e32 v58, 0xbb000000, v17
	v_fmac_f32_e32 v110, v58, v58
	v_fmac_f32_e32 v64, 0xbb000000, v17
	v_fmac_f32_e32 v110, v64, v64
	v_fmac_f32_e32 v66, 0xbb000000, v17
	v_fmac_f32_e32 v110, v66, v66
	v_fmac_f32_e32 v100, 0xbb000000, v17
	v_fmac_f32_e32 v110, v100, v100
	v_fmac_f32_e32 v145, 0xbb000000, v17
	v_fmac_f32_e32 v110, v145, v145
	v_fmac_f32_e32 v146, 0xbb000000, v17
	v_fmac_f32_e32 v110, v146, v146
	v_fmac_f32_e32 v147, 0xbb000000, v17
	v_fmac_f32_e32 v110, v147, v147
	v_fmac_f32_e32 v148, 0xbb000000, v17
	v_fmac_f32_e32 v110, v148, v148
	v_fmac_f32_e32 v149, 0xbb000000, v17
	v_fmac_f32_e32 v110, v149, v149
	v_fmac_f32_e32 v150, 0xbb000000, v17
	v_fmac_f32_e32 v110, v150, v150
	v_fmac_f32_e32 v151, 0xbb000000, v17
	v_fmac_f32_e32 v110, v151, v151
	v_fmac_f32_e32 v47, 0xbb000000, v17
	v_fmac_f32_e32 v110, v47, v47
	v_fmac_f32_e32 v49, 0xbb000000, v17
	v_fmac_f32_e32 v110, v49, v49
	v_fmac_f32_e32 v51, 0xbb000000, v17
	v_fmac_f32_e32 v110, v51, v51
	v_fmac_f32_e32 v53, 0xbb000000, v17
	v_fmac_f32_e32 v110, v53, v53
	v_fmac_f32_e32 v78, 0xbb000000, v17
	v_fmac_f32_e32 v110, v78, v78
	v_fmac_f32_e32 v76, 0xbb000000, v17
	v_fmac_f32_e32 v110, v76, v76
	v_fmac_f32_e32 v82, 0xbb000000, v17
	v_fmac_f32_e32 v110, v82, v82
	v_fmac_f32_e32 v80, 0xbb000000, v17
	v_fmac_f32_e32 v110, v80, v80
	v_fmac_f32_e32 v79, 0xbb000000, v17
	v_fmac_f32_e32 v110, v79, v79
	v_fmac_f32_e32 v77, 0xbb000000, v17
	v_fmac_f32_e32 v110, v77, v77
	v_fmac_f32_e32 v83, 0xbb000000, v17
	v_fmac_f32_e32 v110, v83, v83
	v_fmac_f32_e32 v81, 0xbb000000, v17
	v_fmac_f32_e32 v110, v81, v81
	v_fmac_f32_e32 v74, 0xbb000000, v17
	v_fmac_f32_e32 v110, v74, v74
	v_fmac_f32_e32 v72, 0xbb000000, v17
	v_fmac_f32_e32 v110, v72, v72
	v_fmac_f32_e32 v75, 0xbb000000, v17
	v_fmac_f32_e32 v110, v75, v75
	v_fmac_f32_e32 v73, 0xbb000000, v17
	v_fmac_f32_e32 v110, v73, v73
	v_fmac_f32_e32 v70, 0xbb000000, v17
	v_fmac_f32_e32 v110, v70, v70
	v_fmac_f32_e32 v68, 0xbb000000, v17
	v_fmac_f32_e32 v110, v68, v68
	v_fmac_f32_e32 v71, 0xbb000000, v17
	v_fmac_f32_e32 v110, v71, v71
	v_fmac_f32_e32 v69, 0xbb000000, v17
	v_fmac_f32_e32 v110, v69, v69
	v_fmac_f32_e32 v46, 0xbb000000, v17
	v_fmac_f32_e32 v110, v46, v46
	v_fmac_f32_e32 v48, 0xbb000000, v17
	v_fmac_f32_e32 v110, v48, v48
	v_fmac_f32_e32 v50, 0xbb000000, v17
	v_fmac_f32_e32 v110, v50, v50
	v_fmac_f32_e32 v52, 0xbb000000, v17
	v_fmac_f32_e32 v110, v52, v52
	v_fmac_f32_e32 v152, 0xbb000000, v17
	v_fmac_f32_e32 v110, v152, v152
	v_fmac_f32_e32 v153, 0xbb000000, v17
	v_fmac_f32_e32 v110, v153, v153
	v_fmac_f32_e32 v154, 0xbb000000, v17
	v_fmac_f32_e32 v110, v154, v154
	v_fmac_f32_e32 v155, 0xbb000000, v17
	v_fmac_f32_e32 v110, v155, v155
	v_fmac_f32_e32 v156, 0xbb000000, v17
	v_fmac_f32_e32 v110, v156, v156
	v_fmac_f32_e32 v157, 0xbb000000, v17
	v_fmac_f32_e32 v110, v157, v157
	v_fmac_f32_e32 v158, 0xbb000000, v17
	v_fmac_f32_e32 v110, v158, v158
	v_fmac_f32_e32 v159, 0xbb000000, v17
	v_fmac_f32_e32 v110, v159, v159
	v_fmac_f32_e32 v37, 0xbb000000, v17
	v_fmac_f32_e32 v110, v37, v37
	v_fmac_f32_e32 v41, 0xbb000000, v17
	v_fmac_f32_e32 v110, v41, v41
	v_fmac_f32_e32 v39, 0xbb000000, v17
	v_fmac_f32_e32 v110, v39, v39
	v_fmac_f32_e32 v43, 0xbb000000, v17
	v_fmac_f32_e32 v110, v43, v43
	v_fmac_f32_e32 v56, 0xbb000000, v17
	v_fmac_f32_e32 v110, v56, v56
	v_fmac_f32_e32 v32, 0xbb000000, v17
	v_fmac_f32_e32 v110, v32, v32
	v_fmac_f32_e32 v62, 0xbb000000, v17
	v_fmac_f32_e32 v110, v62, v62
	v_fmac_f32_e32 v60, 0xbb000000, v17
	v_fmac_f32_e32 v110, v60, v60
	v_fmac_f32_e32 v57, 0xbb000000, v17
	v_fmac_f32_e32 v110, v57, v57
	v_fmac_f32_e32 v33, 0xbb000000, v17
	v_fmac_f32_e32 v110, v33, v33
	v_fmac_f32_e32 v63, 0xbb000000, v17
	v_fmac_f32_e32 v110, v63, v63
	v_fmac_f32_e32 v61, 0xbb000000, v17
	v_fmac_f32_e32 v110, v61, v61
	v_fmac_f32_e32 v34, 0xbb000000, v17
	v_fmac_f32_e32 v110, v34, v34
	v_fmac_f32_e32 v30, 0xbb000000, v17
	v_fmac_f32_e32 v110, v30, v30
	v_fmac_f32_e32 v35, 0xbb000000, v17
	v_fmac_f32_e32 v110, v35, v35
	v_fmac_f32_e32 v31, 0xbb000000, v17
	v_fmac_f32_e32 v110, v31, v31
	v_fmac_f32_e32 v28, 0xbb000000, v17
	v_fmac_f32_e32 v110, v28, v28
	v_fmac_f32_e32 v24, 0xbb000000, v17
	v_fmac_f32_e32 v110, v24, v24
	v_fmac_f32_e32 v29, 0xbb000000, v17
	v_fmac_f32_e32 v110, v29, v29
	v_fmac_f32_e32 v25, 0xbb000000, v17
	v_fmac_f32_e32 v110, v25, v25
	v_fmac_f32_e32 v36, 0xbb000000, v17
	v_fmac_f32_e32 v110, v36, v36
	v_fmac_f32_e32 v38, 0xbb000000, v17
	v_fmac_f32_e32 v110, v38, v38
	v_fmac_f32_e32 v40, 0xbb000000, v17
	v_fmac_f32_e32 v110, v40, v40
	v_fmac_f32_e32 v42, 0xbb000000, v17
	v_fmac_f32_e32 v110, v42, v42
	v_fmac_f32_e32 v160, 0xbb000000, v17
	v_fmac_f32_e32 v110, v160, v160
	v_fmac_f32_e32 v161, 0xbb000000, v17
	v_mul_f32_e32 v16, 0x3b000000, v17
	v_fmac_f32_e32 v110, v161, v161
	v_fmac_f32_e32 v162, 0xbb000000, v17
	v_fmac_f32_e32 v110, v162, v162
	v_fmac_f32_e32 v163, 0xbb000000, v17
	v_pk_add_f32 v[24:25], v[26:27], v[16:17] op_sel_hi:[1,0] neg_lo:[0,1] neg_hi:[0,1]
	v_fmac_f32_e32 v110, v163, v163
	v_pk_mul_f32 v[24:25], v[24:25], v[24:25]
	v_pk_add_f32 v[18:19], v[18:19], v[16:17] op_sel_hi:[1,0] neg_lo:[0,1] neg_hi:[0,1]
	v_add_f32_e32 v25, v25, v110
	v_add_f32_e32 v24, v24, v25
	v_pk_mul_f32 v[18:19], v[18:19], v[18:19]
	v_lshlrev_b32_e32 v35, 2, v45
	v_add_f32_e32 v19, v19, v24
	v_add_f32_e32 v24, v18, v19
	v_pk_add_f32 v[18:19], v[22:23], v[16:17] op_sel_hi:[1,0] neg_lo:[0,1] neg_hi:[0,1]
	s_waitcnt vmcnt(3)
	v_lshlrev_b32_e32 v36, 16, v12
	v_pk_mul_f32 v[18:19], v[18:19], v[18:19]
	v_and_b32_e32 v12, 0xffff0000, v12
	v_add_f32_e32 v19, v19, v24
	v_add_f32_e32 v22, v18, v19
	v_pk_add_f32 v[18:19], v[20:21], v[16:17] op_sel_hi:[1,0] neg_lo:[0,1] neg_hi:[0,1]
	v_fmac_f32_e32 v36, 0xbb000000, v17
	v_pk_mul_f32 v[18:19], v[18:19], v[18:19]
	v_fmac_f32_e32 v12, 0xbb000000, v17
	v_add_f32_e32 v16, v19, v22
	v_add_f32_e32 v16, v18, v16
	ds_bpermute_b32 v18, v164, v16
	v_lshlrev_b32_e32 v34, 1, v44
	v_lshlrev_b32_e32 v37, 16, v13
	v_fmac_f32_e32 v37, 0xbb000000, v17
	v_and_b32_e32 v13, 0xffff0000, v13
	s_waitcnt lgkmcnt(0)
	v_add_f32_e32 v16, v16, v18
	ds_bpermute_b32 v18, v165, v16
	v_fmac_f32_e32 v13, 0xbb000000, v17
	v_lshlrev_b32_e32 v38, 16, v14
	v_fmac_f32_e32 v38, 0xbb000000, v17
	v_and_b32_e32 v14, 0xffff0000, v14
	s_waitcnt lgkmcnt(0)
	v_add_f32_e32 v16, v16, v18
	v_fmamk_f32 v16, v16, 0x3b000000, v220
	v_cmp_gt_f32_e32 vcc, s13, v16
	v_mul_f32_e32 v18, 0x4b800000, v16
	v_fmac_f32_e32 v14, 0xbb000000, v17
	v_cndmask_b32_e32 v16, v16, v18, vcc
	v_rsq_f32_e32 v16, v16
	v_lshlrev_b32_e32 v39, 16, v15
	v_fmac_f32_e32 v39, 0xbb000000, v17
	v_and_b32_e32 v15, 0xffff0000, v15
	v_mul_f32_e32 v18, 0x45800000, v16
	v_cndmask_b32_e32 v16, v16, v18, vcc
	global_load_dwordx4 v[18:21], v35, s[40:41] offset:16
	global_load_dwordx4 v[22:25], v35, s[40:41]
	global_load_dwordx4 v[26:29], v35, s[46:47] offset:16
	global_load_dwordx4 v[30:33], v35, s[46:47]
	v_mul_f32_e32 v36, v36, v16
	v_mul_f32_e32 v12, v12, v16
	v_fmac_f32_e32 v15, 0xbb000000, v17
	v_or_b32_e32 v131, s36, v132
	v_or_b32_e32 v142, 16, v131
	v_or_b32_e32 v141, 32, v131
	v_or_b32_e32 v140, 48, v131
	v_or_b32_e32 v139, 64, v131
	v_or_b32_e32 v138, 0x50, v131
	v_or_b32_e32 v137, 0x60, v131
	v_or_b32_e32 v133, 0x70, v131
	s_waitcnt vmcnt(0)
	v_fma_f32 v22, v22, v36, v30
	v_mul_u32_u24_e32 v30, 0x110, v45
	v_fma_f32 v12, v23, v12, v31
	v_add3_u32 v30, 0, v34, v30
	v_cvt_pk_bf16_f32 v12, v12, s0
	ds_write_b16 v30, v12 offset:272
	v_mul_f32_e32 v12, v37, v16
	v_fma_f32 v12, v24, v12, v32
	v_cvt_pk_bf16_f32 v12, v12, s0
	ds_write_b16 v30, v12 offset:544
	v_mul_f32_e32 v12, v13, v16
	v_fmac_f32_e32 v33, v25, v12
	v_cvt_pk_bf16_f32 v12, v33, s0
	ds_write_b16 v30, v12 offset:816
	v_mul_f32_e32 v12, v38, v16
	v_fma_f32 v12, v18, v12, v26
	v_cvt_pk_bf16_f32 v12, v12, s0
	ds_write_b16 v30, v12 offset:1088
	v_mul_f32_e32 v12, v14, v16
	v_fma_f32 v12, v19, v12, v27
	v_cvt_pk_bf16_f32 v12, v12, s0
	ds_write_b16 v30, v12 offset:1360
	v_mul_f32_e32 v12, v39, v16
	v_fma_f32 v12, v20, v12, v28
	v_cvt_pk_bf16_f32 v12, v12, s0
	ds_write_b16 v30, v12 offset:1632
	v_mul_f32_e32 v12, v15, v16
	v_fmac_f32_e32 v29, v21, v12
	v_cvt_pk_bf16_f32 v22, v22, s0
	v_cvt_pk_bf16_f32 v12, v29, s0
	ds_write_b16 v30, v22
	ds_write_b16 v30, v12 offset:1904
	global_load_dwordx4 v[12:15], v35, s[40:41] offset:144
	global_load_dwordx4 v[18:21], v35, s[40:41] offset:128
	global_load_dwordx4 v[22:25], v35, s[46:47] offset:144
	global_load_dwordx4 v[26:29], v35, s[46:47] offset:128
	v_lshlrev_b32_e32 v31, 16, v8
	v_and_b32_e32 v8, 0xffff0000, v8
	v_fmac_f32_e32 v8, 0xbb000000, v17
	v_mul_f32_e32 v8, v8, v16
	v_lshlrev_b32_e32 v32, 16, v9
	v_fmac_f32_e32 v32, 0xbb000000, v17
	v_and_b32_e32 v9, 0xffff0000, v9
	v_fmac_f32_e32 v9, 0xbb000000, v17
	v_lshlrev_b32_e32 v33, 16, v10
	v_fmac_f32_e32 v33, 0xbb000000, v17
	v_and_b32_e32 v10, 0xffff0000, v10
	v_fmac_f32_e32 v10, 0xbb000000, v17
	v_lshlrev_b32_e32 v34, 16, v11
	v_fmac_f32_e32 v34, 0xbb000000, v17
	v_and_b32_e32 v11, 0xffff0000, v11
	v_fmac_f32_e32 v31, 0xbb000000, v17
	v_fmac_f32_e32 v11, 0xbb000000, v17
	v_mul_f32_e32 v31, v31, v16
	s_waitcnt vmcnt(0)
	v_fma_f32 v8, v19, v8, v27
	v_cvt_pk_bf16_f32 v8, v8, s0
	ds_write_b16 v30, v8 offset:8976
	v_mul_f32_e32 v8, v32, v16
	v_fma_f32 v8, v20, v8, v28
	v_cvt_pk_bf16_f32 v8, v8, s0
	ds_write_b16 v30, v8 offset:9248
	v_mul_f32_e32 v8, v9, v16
	v_fmac_f32_e32 v29, v21, v8
	v_cvt_pk_bf16_f32 v8, v29, s0
	ds_write_b16 v30, v8 offset:9520
	v_mul_f32_e32 v8, v33, v16
	v_fma_f32 v8, v12, v8, v22
	v_cvt_pk_bf16_f32 v8, v8, s0
	ds_write_b16 v30, v8 offset:9792
	v_mul_f32_e32 v8, v10, v16
	v_fma_f32 v8, v13, v8, v23
	v_cvt_pk_bf16_f32 v8, v8, s0
	ds_write_b16 v30, v8 offset:10064
	v_mul_f32_e32 v8, v34, v16
	v_fma_f32 v8, v14, v8, v24
	v_cvt_pk_bf16_f32 v8, v8, s0
	ds_write_b16 v30, v8 offset:10336
	v_mul_f32_e32 v8, v11, v16
	v_fma_f32 v18, v18, v31, v26
	v_fmac_f32_e32 v25, v15, v8
	v_cvt_pk_bf16_f32 v18, v18, s0
	v_cvt_pk_bf16_f32 v8, v25, s0
	ds_write_b16 v30, v18 offset:8704
	ds_write_b16 v30, v8 offset:10608
	global_load_dwordx4 v[8:11], v35, s[40:41] offset:272
	global_load_dwordx4 v[12:15], v35, s[40:41] offset:256
	global_load_dwordx4 v[18:21], v35, s[46:47] offset:272
	global_load_dwordx4 v[22:25], v35, s[46:47] offset:256
	v_lshlrev_b32_e32 v26, 16, v4
	v_and_b32_e32 v4, 0xffff0000, v4
	v_fmac_f32_e32 v4, 0xbb000000, v17
	v_mul_f32_e32 v4, v4, v16
	v_lshlrev_b32_e32 v27, 16, v5
	v_fmac_f32_e32 v27, 0xbb000000, v17
	v_and_b32_e32 v5, 0xffff0000, v5
	v_fmac_f32_e32 v5, 0xbb000000, v17
	v_lshlrev_b32_e32 v28, 16, v6
	v_fmac_f32_e32 v28, 0xbb000000, v17
	v_and_b32_e32 v6, 0xffff0000, v6
	v_fmac_f32_e32 v6, 0xbb000000, v17
	v_lshlrev_b32_e32 v29, 16, v7
	v_fmac_f32_e32 v29, 0xbb000000, v17
	v_and_b32_e32 v7, 0xffff0000, v7
	v_fmac_f32_e32 v26, 0xbb000000, v17
	v_fmac_f32_e32 v7, 0xbb000000, v17
	v_mul_f32_e32 v26, v26, v16
	s_waitcnt vmcnt(0)
	v_fma_f32 v4, v13, v4, v23
	v_cvt_pk_bf16_f32 v4, v4, s0
	ds_write_b16 v30, v4 offset:17680
	v_mul_f32_e32 v4, v27, v16
	v_fma_f32 v4, v14, v4, v24
	v_cvt_pk_bf16_f32 v4, v4, s0
	ds_write_b16 v30, v4 offset:17952
	v_mul_f32_e32 v4, v5, v16
	v_fmac_f32_e32 v25, v15, v4
	v_cvt_pk_bf16_f32 v4, v25, s0
	ds_write_b16 v30, v4 offset:18224
	v_mul_f32_e32 v4, v28, v16
	v_fma_f32 v4, v8, v4, v18
	v_cvt_pk_bf16_f32 v4, v4, s0
	ds_write_b16 v30, v4 offset:18496
	v_mul_f32_e32 v4, v6, v16
	v_fma_f32 v4, v9, v4, v19
	v_cvt_pk_bf16_f32 v4, v4, s0
	ds_write_b16 v30, v4 offset:18768
	v_mul_f32_e32 v4, v29, v16
	v_fma_f32 v4, v10, v4, v20
	v_cvt_pk_bf16_f32 v4, v4, s0
	ds_write_b16 v30, v4 offset:19040
	v_mul_f32_e32 v4, v7, v16
	v_fma_f32 v12, v12, v26, v22
	v_fmac_f32_e32 v21, v11, v4
	v_cvt_pk_bf16_f32 v12, v12, s0
	v_cvt_pk_bf16_f32 v4, v21, s0
	ds_write_b16 v30, v12 offset:17408
	ds_write_b16 v30, v4 offset:19312
	global_load_dwordx4 v[4:7], v35, s[40:41] offset:400
	global_load_dwordx4 v[8:11], v35, s[40:41] offset:384
	global_load_dwordx4 v[12:15], v35, s[46:47] offset:400
	global_load_dwordx4 v[18:21], v35, s[46:47] offset:384
	v_lshlrev_b32_e32 v22, 16, v0
	v_and_b32_e32 v0, 0xffff0000, v0
	v_fmac_f32_e32 v0, 0xbb000000, v17
	v_mul_f32_e32 v0, v0, v16
	v_lshlrev_b32_e32 v23, 16, v1
	v_fmac_f32_e32 v23, 0xbb000000, v17
	v_and_b32_e32 v1, 0xffff0000, v1
	v_fmac_f32_e32 v1, 0xbb000000, v17
	v_lshlrev_b32_e32 v24, 16, v2
	v_fmac_f32_e32 v24, 0xbb000000, v17
	v_and_b32_e32 v2, 0xffff0000, v2
	v_fmac_f32_e32 v2, 0xbb000000, v17
	v_lshlrev_b32_e32 v25, 16, v3
	v_fmac_f32_e32 v25, 0xbb000000, v17
	v_and_b32_e32 v3, 0xffff0000, v3
	v_fmac_f32_e32 v3, 0xbb000000, v17
	v_fmac_f32_e32 v22, 0xbb000000, v17
	v_mul_f32_e32 v22, v22, v16
	v_and_b32_e32 v17, -16, v130
	s_waitcnt vmcnt(0)
	v_fma_f32 v0, v9, v0, v19
	v_cvt_pk_bf16_f32 v0, v0, s0
	ds_write_b16 v30, v0 offset:26384
	v_mul_f32_e32 v0, v23, v16
	v_fma_f32 v0, v10, v0, v20
	v_cvt_pk_bf16_f32 v0, v0, s0
	ds_write_b16 v30, v0 offset:26656
	v_mul_f32_e32 v0, v1, v16
	v_fmac_f32_e32 v21, v11, v0
	v_cvt_pk_bf16_f32 v0, v21, s0
	ds_write_b16 v30, v0 offset:26928
	v_mul_f32_e32 v0, v24, v16
	v_fma_f32 v0, v4, v0, v12
	v_cvt_pk_bf16_f32 v0, v0, s0
	ds_write_b16 v30, v0 offset:27200
	v_mul_f32_e32 v0, v2, v16
	v_fma_f32 v0, v5, v0, v13
	v_cvt_pk_bf16_f32 v0, v0, s0
	ds_write_b16 v30, v0 offset:27472
	v_mul_f32_e32 v0, v25, v16
	v_fma_f32 v0, v6, v0, v14
	v_cvt_pk_bf16_f32 v0, v0, s0
	ds_write_b16 v30, v0 offset:27744
	v_mul_f32_e32 v0, v3, v16
	v_ashrrev_i32_e32 v4, 4, v130
	v_fmac_f32_e32 v15, v7, v0
	v_lshlrev_b32_e32 v92, 2, v4
	v_cvt_pk_bf16_f32 v0, v15, s0
	v_ashrrev_i32_e32 v93, 31, v92
	ds_write_b16 v30, v0 offset:28016
	v_lshl_add_u64 v[0:1], v[92:93], 1, s[8:9]
	v_mad_u64_u32 v[2:3], s[8:9], v131, s14, v[0:1]
	v_mad_i32_i24 v3, s37, v225, v3
	global_load_dwordx2 v[126:127], v[2:3], off offset:1024
	v_add_co_u32_e32 v2, vcc, s15, v2
	v_fma_f32 v8, v8, v22, v18
	s_nop 0
	v_addc_co_u32_e32 v3, vcc, 0, v3, vcc
	global_load_dwordx2 v[128:129], v[2:3], off offset:2048
	v_mad_u64_u32 v[2:3], s[8:9], v142, s14, v[0:1]
	v_mad_i32_i24 v3, s37, v225, v3
	global_load_dwordx2 v[122:123], v[2:3], off offset:1024
	v_add_co_u32_e32 v2, vcc, s15, v2
	v_cvt_pk_bf16_f32 v8, v8, s0
	s_nop 0
	v_addc_co_u32_e32 v3, vcc, 0, v3, vcc
	global_load_dwordx2 v[124:125], v[2:3], off offset:2048
	v_mad_u64_u32 v[2:3], s[8:9], v141, s14, v[0:1]
	v_mad_i32_i24 v3, s37, v225, v3
	global_load_dwordx2 v[118:119], v[2:3], off offset:1024
	v_add_co_u32_e32 v2, vcc, s15, v2
	ds_write_b16 v30, v8 offset:26112
	s_nop 0
	v_addc_co_u32_e32 v3, vcc, 0, v3, vcc
	global_load_dwordx2 v[120:121], v[2:3], off offset:2048
	v_mad_u64_u32 v[2:3], s[8:9], v140, s14, v[0:1]
	v_mad_i32_i24 v3, s37, v225, v3
	global_load_dwordx2 v[114:115], v[2:3], off offset:1024
	v_add_co_u32_e32 v2, vcc, s15, v2
	v_or_b32_e32 v16, s10, v132
	s_nop 0
	v_addc_co_u32_e32 v3, vcc, 0, v3, vcc
	global_load_dwordx2 v[116:117], v[2:3], off offset:2048
	v_mad_u64_u32 v[2:3], s[8:9], v139, s14, v[0:1]
	v_mad_i32_i24 v3, s37, v225, v3
	global_load_dwordx2 v[110:111], v[2:3], off offset:1024
	v_add_co_u32_e32 v2, vcc, s15, v2
	v_or_b32_e32 v132, s60, v132
	s_nop 0
	v_addc_co_u32_e32 v3, vcc, 0, v3, vcc
	global_load_dwordx2 v[112:113], v[2:3], off offset:2048
	v_mad_u64_u32 v[2:3], s[8:9], v138, s14, v[0:1]
	v_mad_i32_i24 v3, s37, v225, v3
	global_load_dwordx2 v[106:107], v[2:3], off offset:1024
	v_add_co_u32_e32 v2, vcc, s15, v2
	v_lshlrev_b32_e32 v136, 2, v132
	s_nop 0
	v_addc_co_u32_e32 v3, vcc, 0, v3, vcc
	global_load_dwordx2 v[108:109], v[2:3], off offset:2048
	v_mad_u64_u32 v[2:3], s[8:9], v137, s14, v[0:1]
	v_mad_u64_u32 v[0:1], s[8:9], v133, s14, v[0:1]
	v_mad_i32_i24 v3, s37, v225, v3
	v_mad_i32_i24 v1, s37, v225, v1
	global_load_dwordx2 v[100:101], v[2:3], off offset:1024
	global_load_dwordx2 v[96:97], v[0:1], off offset:1024
	v_add_co_u32_e32 v2, vcc, s15, v2
	s_add_u32 s8, s3, s7
	s_nop 0
	v_addc_co_u32_e32 v3, vcc, 0, v3, vcc
	v_add_co_u32_e32 v0, vcc, s15, v0
	s_addc_u32 s9, s11, 0
	s_nop 0
	v_addc_co_u32_e32 v1, vcc, 0, v1, vcc
	global_load_dwordx2 v[98:99], v[0:1], off offset:2048
	v_lshlrev_b32_e32 v0, 3, v4
	v_ashrrev_i32_e32 v1, 31, v0
	v_lshl_add_u64 v[0:1], v[0:1], 1, s[8:9]
	v_lshl_add_u64 v[0:1], v[0:1], 0, v[194:195]
	global_load_dwordx2 v[104:105], v[2:3], off offset:2048
	global_load_dwordx4 v[144:147], v[0:1], off
	v_add_co_u32_e32 v2, vcc, s4, v0
	s_movk_i32 s7, 0x4000
	s_nop 0
	v_addc_co_u32_e32 v3, vcc, 0, v1, vcc
	global_load_dwordx4 v[88:91], v[2:3], off offset:-4096
	global_load_dwordx4 v[80:83], v[2:3], off
	global_load_dwordx4 v[84:87], v[2:3], off offset:64
	v_add_co_u32_e32 v2, vcc, s35, v0
	s_waitcnt vmcnt(18)
	v_lshlrev_b32_e32 v143, 16, v128
	v_addc_co_u32_e32 v3, vcc, 0, v1, vcc
	v_add_co_u32_e32 v4, vcc, s7, v0
	s_movk_i32 s7, 0x5000
	s_nop 0
	v_addc_co_u32_e32 v5, vcc, 0, v1, vcc
	global_load_dwordx4 v[72:75], v[4:5], off offset:-4096
	global_load_dwordx4 v[76:79], v[2:3], off offset:64
	global_load_dwordx4 v[60:63], v[4:5], off
	global_load_dwordx4 v[64:67], v[4:5], off offset:64
	global_load_dwordx4 v[68:71], v[4:5], off offset:128
	v_add_co_u32_e32 v2, vcc, s7, v0
	s_movk_i32 s7, 0x7000
	s_nop 0
	v_addc_co_u32_e32 v3, vcc, 0, v1, vcc
	v_add_co_u32_e32 v4, vcc, s95, v0
	v_and_b32_e32 v128, 0xffff0000, v128
	s_nop 0
	v_addc_co_u32_e32 v5, vcc, 0, v1, vcc
	v_add_co_u32_e32 v12, vcc, s7, v0
	s_movk_i32 s7, 0x110
	v_mul_lo_u32 v16, v16, s7
	v_addc_co_u32_e32 v13, vcc, 0, v1, vcc
	v_add3_u32 v28, 0, v16, v17
	global_load_dwordx4 v[48:51], v[4:5], off offset:-4096
	global_load_dwordx4 v[52:55], v[2:3], off offset:64
	global_load_dwordx4 v[56:59], v[2:3], off offset:128
	global_load_dwordx4 v[32:35], v[4:5], off
	global_load_dwordx4 v[36:39], v[4:5], off offset:64
	global_load_dwordx4 v[40:43], v[4:5], off offset:128
	global_load_dwordx4 v[44:47], v[4:5], off offset:192
	s_nop 0
	global_load_dwordx4 v[0:3], v[12:13], off
	global_load_dwordx4 v[4:7], v[12:13], off offset:64
	global_load_dwordx4 v[8:11], v[12:13], off offset:128
	s_nop 0
	global_load_dwordx4 v[12:15], v[12:13], off offset:192
	s_waitcnt lgkmcnt(0)
	s_barrier
	ds_read_b128 v[16:19], v28
	ds_read_b128 v[20:23], v28 offset:64
	ds_read_b128 v[24:27], v28 offset:128
	ds_read_b128 v[28:31], v28 offset:192
	global_load_dword v132, v136, s[0:1]
	s_add_i32 s7, s60, s10
	v_add_u32_e32 v92, s7, v92
	v_ashrrev_i32_e32 v93, 31, v92
	v_lshl_add_u64 v[102:103], v[92:93], 1, s[82:83]
	s_waitcnt vmcnt(20) lgkmcnt(3)
	v_mfma_f32_16x16x32_bf16 v[92:95], v[16:19], v[144:147], 0
	v_mul_f32_e32 v134, 0xbfb8aa3b, v143
	v_lshlrev_b32_e32 v144, 16, v126
	v_and_b32_e32 v145, 0xffff0000, v126
	v_mul_f32_e32 v126, 0xbfb8aa3b, v128
	v_exp_f32_e32 v134, v134
	v_exp_f32_e32 v135, v126
	v_mad_u64_u32 v[130:131], s[8:9], v131, s14, v[102:103]
	v_mad_i32_i24 v131, s37, v225, v131
	v_pk_add_f32 v[134:135], v[134:135], 1.0 op_sel_hi:[1,0]
	s_waitcnt vmcnt(19)
	v_mfma_f32_16x16x32_bf16 v[88:91], v[16:19], v[88:91], 0
	s_add_i32 s65, s65, s94
	s_waitcnt vmcnt(18)
	v_mfma_f32_16x16x32_bf16 v[80:83], v[16:19], v[80:83], 0
	s_add_i32 s64, s64, s68
	s_cmpk_gt_i32 s65, 0x3ff
	s_waitcnt vmcnt(0)
	v_pk_add_f32 v[92:93], v[92:93], v[132:133] op_sel_hi:[1,0]
	s_nop 0
	v_pk_mul_f32 v[92:93], v[92:93], v[144:145]
	v_rcp_f32_e32 v144, v135
	v_pk_add_f32 v[94:95], v[94:95], v[132:133] op_sel_hi:[1,0]
	s_waitcnt lgkmcnt(2)
	v_mfma_f32_16x16x32_bf16 v[80:83], v[20:23], v[84:87], v[80:83]
	v_lshlrev_b32_e32 v87, 16, v120
	v_mul_f32_e32 v126, v128, v144
	v_mov_b32_e32 v135, v126
	v_rcp_f32_e32 v128, v134
	v_mfma_f32_16x16x32_bf16 v[72:75], v[16:19], v[72:75], 0
	v_mad_u64_u32 v[84:85], s[8:9], v141, s14, v[102:103]
	v_mul_f32_e32 v126, v143, v128
	v_mov_b32_e32 v134, v126
	v_pk_mul_f32 v[92:93], v[134:135], v[92:93]
	v_lshlrev_b32_e32 v134, 16, v129
	v_and_b32_e32 v135, 0xffff0000, v129
	v_mul_f32_e32 v126, 0xbfb8aa3b, v134
	v_lshlrev_b32_e32 v128, 16, v127
	v_and_b32_e32 v129, 0xffff0000, v127
	v_mul_f32_e32 v127, 0xbfb8aa3b, v135
	v_exp_f32_e32 v126, v126
	v_exp_f32_e32 v127, v127
	v_pk_mul_f32 v[94:95], v[94:95], v[128:129]
	v_cvt_pk_bf16_f32 v92, v92, v93
	v_mad_i32_i24 v85, s37, v225, v85
	v_pk_add_f32 v[126:127], v[126:127], 1.0 op_sel_hi:[1,0]
	v_mfma_f32_16x16x32_bf16 v[72:75], v[20:23], v[76:79], v[72:75]
	v_rcp_f32_e32 v129, v127
	v_lshlrev_b32_e32 v79, 16, v116
	v_mfma_f32_16x16x32_bf16 v[60:63], v[16:19], v[60:63], 0
	v_mad_u64_u32 v[76:77], s[8:9], v140, s14, v[102:103]
	v_mul_f32_e32 v128, v135, v129
	v_mov_b32_e32 v127, v128
	v_rcp_f32_e32 v129, v126
	v_mad_i32_i24 v77, s37, v225, v77
	v_mfma_f32_16x16x32_bf16 v[60:63], v[20:23], v[64:67], v[60:63]
	v_lshlrev_b32_e32 v67, 16, v112
	v_mul_f32_e32 v128, v134, v129
	v_mov_b32_e32 v126, v128
	v_pk_mul_f32 v[94:95], v[126:127], v[94:95]
	v_lshlrev_b32_e32 v128, 16, v122
	v_cvt_pk_bf16_f32 v93, v94, v95
	global_store_dwordx2 v[130:131], v[92:93], off offset:1024
	global_load_dword v94, v136, s[0:1] offset:64
	v_lshlrev_b32_e32 v95, 16, v124
	v_and_b32_e32 v124, 0xffff0000, v124
	v_mul_f32_e32 v126, 0xbfb8aa3b, v95
	v_and_b32_e32 v129, 0xffff0000, v122
	v_mul_f32_e32 v122, 0xbfb8aa3b, v124
	v_exp_f32_e32 v126, v126
	v_exp_f32_e32 v127, v122
	v_mad_u64_u32 v[92:93], s[8:9], v142, s14, v[102:103]
	v_mad_i32_i24 v93, s37, v225, v93
	v_pk_add_f32 v[126:127], v[126:127], 1.0 op_sel_hi:[1,0]
	s_waitcnt lgkmcnt(1)
	v_mfma_f32_16x16x32_bf16 v[60:63], v[24:27], v[68:71], v[60:63]
	v_mul_f32_e32 v68, 0xbfb8aa3b, v67
	v_exp_f32_e32 v68, v68
	v_lshlrev_b32_e32 v70, 16, v110
	v_and_b32_e32 v71, 0xffff0000, v110
	v_mfma_f32_16x16x32_bf16 v[48:51], v[16:19], v[48:51], 0
	v_mad_u64_u32 v[64:65], s[8:9], v139, s14, v[102:103]
	v_mad_i32_i24 v65, s37, v225, v65
	v_mfma_f32_16x16x32_bf16 v[48:51], v[20:23], v[52:55], v[48:51]
	v_lshlrev_b32_e32 v55, 16, v108
	v_mad_u64_u32 v[52:53], s[8:9], v138, s14, v[102:103]
	v_mfma_f32_16x16x32_bf16 v[48:51], v[24:27], v[56:59], v[48:51]
	v_mul_f32_e32 v56, 0xbfb8aa3b, v55
	v_exp_f32_e32 v56, v56
	v_lshlrev_b32_e32 v58, 16, v106
	v_and_b32_e32 v59, 0xffff0000, v106
	v_mfma_f32_16x16x32_bf16 v[32:35], v[16:19], v[32:35], 0
	v_mad_i32_i24 v53, s37, v225, v53
	s_waitcnt vmcnt(0)
	v_pk_add_f32 v[88:89], v[88:89], v[94:95] op_sel_hi:[1,0]
	s_nop 0
	v_pk_mul_f32 v[88:89], v[88:89], v[128:129]
	v_rcp_f32_e32 v128, v127
	v_mfma_f32_16x16x32_bf16 v[32:35], v[20:23], v[36:39], v[32:35]
	v_lshlrev_b32_e32 v39, 16, v104
	v_mad_u64_u32 v[36:37], s[8:9], v137, s14, v[102:103]
	v_mul_f32_e32 v122, v124, v128
	v_mov_b32_e32 v127, v122
	v_rcp_f32_e32 v124, v126
	v_mfma_f32_16x16x32_bf16 v[32:35], v[24:27], v[40:43], v[32:35]
	v_mul_f32_e32 v40, 0xbfb8aa3b, v39
	v_exp_f32_e32 v40, v40
	v_mul_f32_e32 v122, v95, v124
	v_mov_b32_e32 v126, v122
	v_pk_mul_f32 v[88:89], v[126:127], v[88:89]
	v_lshlrev_b32_e32 v126, 16, v125
	v_and_b32_e32 v127, 0xffff0000, v125
	v_mul_f32_e32 v95, 0xbfb8aa3b, v126
	v_pk_add_f32 v[90:91], v[90:91], v[94:95] op_sel_hi:[1,0]
	v_mul_f32_e32 v94, 0xbfb8aa3b, v127
	v_exp_f32_e32 v122, v95
	v_lshlrev_b32_e32 v124, 16, v123
	v_and_b32_e32 v125, 0xffff0000, v123
	v_exp_f32_e32 v123, v94
	v_pk_mul_f32 v[90:91], v[90:91], v[124:125]
	v_cvt_pk_bf16_f32 v88, v88, v89
	s_waitcnt lgkmcnt(0)
	v_mfma_f32_16x16x32_bf16 v[32:35], v[28:31], v[44:47], v[32:35]
	v_add_f32_e64 v94, v122, 1.0
	v_add_f32_e64 v95, v123, 1.0
	v_and_b32_e32 v44, 0xffff0000, v104
	v_rcp_f32_e32 v123, v95
	v_mul_f32_e32 v41, 0xbfb8aa3b, v44
	v_exp_f32_e32 v41, v41
	v_lshlrev_b32_e32 v42, 16, v100
	v_mul_f32_e32 v122, v127, v123
	v_mov_b32_e32 v95, v122
	v_rcp_f32_e32 v123, v94
	v_and_b32_e32 v43, 0xffff0000, v100
	v_pk_add_f32 v[40:41], v[40:41], 1.0 op_sel_hi:[1,0]
	v_mfma_f32_16x16x32_bf16 v[0:3], v[16:19], v[0:3], 0
	v_mul_f32_e32 v122, v126, v123
	v_mov_b32_e32 v94, v122
	v_pk_mul_f32 v[90:91], v[94:95], v[90:91]
	v_mad_i32_i24 v37, s37, v225, v37
	v_cvt_pk_bf16_f32 v89, v90, v91
	global_store_dwordx2 v[92:93], v[88:89], off offset:1024
	global_load_dword v86, v136, s[0:1] offset:128
	v_and_b32_e32 v92, 0xffff0000, v120
	v_mul_f32_e32 v88, 0xbfb8aa3b, v87
	v_mul_f32_e32 v89, 0xbfb8aa3b, v92
	v_exp_f32_e32 v88, v88
	v_exp_f32_e32 v89, v89
	v_lshlrev_b32_e32 v90, 16, v118
	v_and_b32_e32 v91, 0xffff0000, v118
	v_mfma_f32_16x16x32_bf16 v[0:3], v[20:23], v[4:7], v[0:3]
	v_add_f32_e64 v88, v88, 1.0
	v_add_f32_e64 v89, v89, 1.0
	v_lshlrev_b32_e32 v7, 16, v98
	v_mad_u64_u32 v[4:5], s[8:9], v133, s14, v[102:103]
	v_mfma_f32_16x16x32_bf16 v[0:3], v[24:27], v[8:11], v[0:3]
	v_mul_f32_e32 v8, 0xbfb8aa3b, v7
	v_exp_f32_e32 v8, v8
	v_lshlrev_b32_e32 v10, 16, v96
	v_mfma_f32_16x16x32_bf16 v[0:3], v[28:31], v[12:15], v[0:3]
	v_and_b32_e32 v12, 0xffff0000, v98
	v_mul_f32_e32 v9, 0xbfb8aa3b, v12
	v_exp_f32_e32 v9, v9
	v_and_b32_e32 v11, 0xffff0000, v96
	v_mad_i32_i24 v5, s37, v225, v5
	v_pk_add_f32 v[8:9], v[8:9], 1.0 op_sel_hi:[1,0]
	s_waitcnt vmcnt(0)
	v_pk_add_f32 v[80:81], v[80:81], v[86:87] op_sel_hi:[1,0]
	s_nop 0
	v_pk_mul_f32 v[80:81], v[80:81], v[90:91]
	v_rcp_f32_e32 v91, v89
	s_nop 0
	v_mul_f32_e32 v90, v92, v91
	v_mov_b32_e32 v89, v90
	v_rcp_f32_e32 v91, v88
	s_nop 0
	v_mul_f32_e32 v90, v87, v91
	v_lshlrev_b32_e32 v92, 16, v121
	v_mov_b32_e32 v88, v90
	v_and_b32_e32 v93, 0xffff0000, v121
	v_mul_f32_e32 v87, 0xbfb8aa3b, v92
	v_pk_add_f32 v[82:83], v[82:83], v[86:87] op_sel_hi:[1,0]
	v_mul_f32_e32 v86, 0xbfb8aa3b, v93
	v_pk_mul_f32 v[80:81], v[88:89], v[80:81]
	v_exp_f32_e32 v88, v87
	v_exp_f32_e32 v89, v86
	v_lshlrev_b32_e32 v90, 16, v119
	v_and_b32_e32 v91, 0xffff0000, v119
	v_pk_mul_f32 v[82:83], v[82:83], v[90:91]
	v_pk_add_f32 v[86:87], v[88:89], 1.0 op_sel_hi:[1,0]
	v_cvt_pk_bf16_f32 v80, v80, v81
	v_rcp_f32_e32 v89, v87
	s_nop 0
	v_mul_f32_e32 v88, v93, v89
	v_mov_b32_e32 v87, v88
	v_rcp_f32_e32 v89, v86
	s_nop 0
	v_mul_f32_e32 v88, v92, v89
	v_mov_b32_e32 v86, v88
	v_pk_mul_f32 v[82:83], v[86:87], v[82:83]
	s_nop 0
	v_cvt_pk_bf16_f32 v81, v82, v83
	global_store_dwordx2 v[84:85], v[80:81], off offset:1024
	global_load_dword v78, v136, s[0:1] offset:192
	v_and_b32_e32 v84, 0xffff0000, v116
	v_mul_f32_e32 v80, 0xbfb8aa3b, v79
	v_mul_f32_e32 v81, 0xbfb8aa3b, v84
	v_exp_f32_e32 v80, v80
	v_exp_f32_e32 v81, v81
	v_lshlrev_b32_e32 v82, 16, v114
	v_and_b32_e32 v83, 0xffff0000, v114
	v_pk_add_f32 v[80:81], v[80:81], 1.0 op_sel_hi:[1,0]
	s_waitcnt vmcnt(0)
	v_pk_add_f32 v[72:73], v[72:73], v[78:79] op_sel_hi:[1,0]
	s_nop 0
	v_pk_mul_f32 v[72:73], v[72:73], v[82:83]
	v_rcp_f32_e32 v83, v81
	s_nop 0
	v_mul_f32_e32 v82, v84, v83
	v_mov_b32_e32 v81, v82
	v_rcp_f32_e32 v83, v80
	s_nop 0
	v_mul_f32_e32 v82, v79, v83
	v_lshlrev_b32_e32 v84, 16, v117
	v_mov_b32_e32 v80, v82
	v_and_b32_e32 v85, 0xffff0000, v117
	v_mul_f32_e32 v79, 0xbfb8aa3b, v84
	v_pk_add_f32 v[74:75], v[74:75], v[78:79] op_sel_hi:[1,0]
	v_mul_f32_e32 v78, 0xbfb8aa3b, v85
	v_pk_mul_f32 v[72:73], v[80:81], v[72:73]
	v_exp_f32_e32 v80, v79
	v_exp_f32_e32 v81, v78
	v_lshlrev_b32_e32 v82, 16, v115
	v_and_b32_e32 v83, 0xffff0000, v115
	v_pk_mul_f32 v[74:75], v[74:75], v[82:83]
	v_pk_add_f32 v[78:79], v[80:81], 1.0 op_sel_hi:[1,0]
	v_cvt_pk_bf16_f32 v72, v72, v73
	v_rcp_f32_e32 v81, v79
	s_nop 0
	v_mul_f32_e32 v80, v85, v81
	v_mov_b32_e32 v79, v80
	v_rcp_f32_e32 v81, v78
	s_nop 0
	v_mul_f32_e32 v80, v84, v81
	v_mov_b32_e32 v78, v80
	v_pk_mul_f32 v[74:75], v[78:79], v[74:75]
	s_nop 0
	v_cvt_pk_bf16_f32 v73, v74, v75
	global_store_dwordx2 v[76:77], v[72:73], off offset:1024
	global_load_dword v66, v136, s[0:1] offset:256
	v_and_b32_e32 v72, 0xffff0000, v112
	v_mul_f32_e32 v69, 0xbfb8aa3b, v72
	v_exp_f32_e32 v69, v69
	s_waitcnt vmcnt(0)
	v_pk_add_f32 v[60:61], v[60:61], v[66:67] op_sel_hi:[1,0]
	v_pk_add_f32 v[68:69], v[68:69], 1.0 op_sel_hi:[1,0]
	v_pk_mul_f32 v[60:61], v[60:61], v[70:71]
	v_rcp_f32_e32 v71, v69
	s_nop 0
	v_mul_f32_e32 v70, v72, v71
	v_mov_b32_e32 v69, v70
	v_rcp_f32_e32 v71, v68
	s_nop 0
	v_mul_f32_e32 v70, v67, v71
	v_lshlrev_b32_e32 v72, 16, v113
	v_mov_b32_e32 v68, v70
	v_and_b32_e32 v73, 0xffff0000, v113
	v_mul_f32_e32 v67, 0xbfb8aa3b, v72
	v_pk_add_f32 v[62:63], v[62:63], v[66:67] op_sel_hi:[1,0]
	v_mul_f32_e32 v66, 0xbfb8aa3b, v73
	v_pk_mul_f32 v[60:61], v[68:69], v[60:61]
	v_exp_f32_e32 v68, v67
	v_exp_f32_e32 v69, v66
	v_lshlrev_b32_e32 v70, 16, v111
	v_and_b32_e32 v71, 0xffff0000, v111
	v_pk_mul_f32 v[62:63], v[62:63], v[70:71]
	v_pk_add_f32 v[66:67], v[68:69], 1.0 op_sel_hi:[1,0]
	v_cvt_pk_bf16_f32 v60, v60, v61
	v_rcp_f32_e32 v69, v67
	s_nop 0
	v_mul_f32_e32 v68, v73, v69
	v_mov_b32_e32 v67, v68
	v_rcp_f32_e32 v69, v66
	s_nop 0
	v_mul_f32_e32 v68, v72, v69
	v_mov_b32_e32 v66, v68
	v_pk_mul_f32 v[62:63], v[66:67], v[62:63]
	s_nop 0
	v_cvt_pk_bf16_f32 v61, v62, v63
	global_store_dwordx2 v[64:65], v[60:61], off offset:1024
	global_load_dword v54, v136, s[0:1] offset:320
	v_and_b32_e32 v60, 0xffff0000, v108
	v_mul_f32_e32 v57, 0xbfb8aa3b, v60
	v_exp_f32_e32 v57, v57
	s_waitcnt vmcnt(0)
	v_pk_add_f32 v[48:49], v[48:49], v[54:55] op_sel_hi:[1,0]
	v_pk_add_f32 v[56:57], v[56:57], 1.0 op_sel_hi:[1,0]
	v_pk_mul_f32 v[48:49], v[48:49], v[58:59]
	v_rcp_f32_e32 v59, v57
	s_nop 0
	v_mul_f32_e32 v58, v60, v59
	v_mov_b32_e32 v57, v58
	v_rcp_f32_e32 v59, v56
	s_nop 0
	v_mul_f32_e32 v58, v55, v59
	v_lshlrev_b32_e32 v60, 16, v109
	v_mov_b32_e32 v56, v58
	v_and_b32_e32 v61, 0xffff0000, v109
	v_mul_f32_e32 v55, 0xbfb8aa3b, v60
	v_pk_add_f32 v[50:51], v[50:51], v[54:55] op_sel_hi:[1,0]
	v_mul_f32_e32 v54, 0xbfb8aa3b, v61
	v_pk_mul_f32 v[48:49], v[56:57], v[48:49]
	v_exp_f32_e32 v56, v55
	v_exp_f32_e32 v57, v54
	v_lshlrev_b32_e32 v58, 16, v107
	v_and_b32_e32 v59, 0xffff0000, v107
	v_pk_mul_f32 v[50:51], v[50:51], v[58:59]
	v_pk_add_f32 v[54:55], v[56:57], 1.0 op_sel_hi:[1,0]
	v_cvt_pk_bf16_f32 v48, v48, v49
	v_rcp_f32_e32 v57, v55
	s_nop 0
	v_mul_f32_e32 v56, v61, v57
	v_mov_b32_e32 v55, v56
	v_rcp_f32_e32 v57, v54
	s_nop 0
	v_mul_f32_e32 v56, v60, v57
	v_mov_b32_e32 v54, v56
	v_pk_mul_f32 v[50:51], v[54:55], v[50:51]
	s_nop 0
	v_cvt_pk_bf16_f32 v49, v50, v51
	global_store_dwordx2 v[52:53], v[48:49], off offset:1024
	global_load_dword v38, v136, s[0:1] offset:384
	s_waitcnt vmcnt(0)
	v_pk_add_f32 v[32:33], v[32:33], v[38:39] op_sel_hi:[1,0]
	s_nop 0
	v_pk_mul_f32 v[32:33], v[32:33], v[42:43]
	v_rcp_f32_e32 v43, v41
	s_nop 0
	v_mul_f32_e32 v42, v44, v43
	v_mov_b32_e32 v41, v42
	v_rcp_f32_e32 v43, v40
	s_nop 0
	v_mul_f32_e32 v42, v39, v43
	v_lshlrev_b32_e32 v44, 16, v105
	v_mov_b32_e32 v40, v42
	v_and_b32_e32 v45, 0xffff0000, v105
	v_mul_f32_e32 v39, 0xbfb8aa3b, v44
	v_pk_add_f32 v[34:35], v[34:35], v[38:39] op_sel_hi:[1,0]
	v_mul_f32_e32 v38, 0xbfb8aa3b, v45
	v_pk_mul_f32 v[32:33], v[40:41], v[32:33]
	v_exp_f32_e32 v40, v39
	v_exp_f32_e32 v41, v38
	v_lshlrev_b32_e32 v42, 16, v101
	v_and_b32_e32 v43, 0xffff0000, v101
	v_pk_mul_f32 v[34:35], v[34:35], v[42:43]
	v_pk_add_f32 v[38:39], v[40:41], 1.0 op_sel_hi:[1,0]
	v_cvt_pk_bf16_f32 v32, v32, v33
	v_rcp_f32_e32 v41, v39
	s_nop 0
	v_mul_f32_e32 v40, v45, v41
	v_mov_b32_e32 v39, v40
	v_rcp_f32_e32 v41, v38
	s_nop 0
	v_mul_f32_e32 v40, v44, v41
	v_mov_b32_e32 v38, v40
	v_pk_mul_f32 v[34:35], v[38:39], v[34:35]
	s_nop 0
	v_cvt_pk_bf16_f32 v33, v34, v35
	global_store_dwordx2 v[36:37], v[32:33], off offset:1024
	global_load_dword v6, v136, s[0:1] offset:448
	s_waitcnt vmcnt(0)
	v_pk_add_f32 v[0:1], v[0:1], v[6:7] op_sel_hi:[1,0]
	s_nop 0
	v_pk_mul_f32 v[0:1], v[0:1], v[10:11]
	v_rcp_f32_e32 v11, v9
	s_nop 0
	v_mul_f32_e32 v10, v12, v11
	v_mov_b32_e32 v9, v10
	v_rcp_f32_e32 v11, v8
	s_nop 0
	v_mul_f32_e32 v10, v7, v11
	v_lshlrev_b32_e32 v12, 16, v99
	v_mov_b32_e32 v8, v10
	v_and_b32_e32 v13, 0xffff0000, v99
	v_mul_f32_e32 v7, 0xbfb8aa3b, v12
	v_pk_add_f32 v[2:3], v[2:3], v[6:7] op_sel_hi:[1,0]
	v_mul_f32_e32 v6, 0xbfb8aa3b, v13
	v_pk_mul_f32 v[0:1], v[8:9], v[0:1]
	v_exp_f32_e32 v8, v7
	v_exp_f32_e32 v9, v6
	v_lshlrev_b32_e32 v10, 16, v97
	v_and_b32_e32 v11, 0xffff0000, v97
	v_pk_mul_f32 v[2:3], v[2:3], v[10:11]
	v_pk_add_f32 v[6:7], v[8:9], 1.0 op_sel_hi:[1,0]
	v_cvt_pk_bf16_f32 v0, v0, v1
	v_rcp_f32_e32 v9, v7
	s_nop 0
	v_mul_f32_e32 v8, v13, v9
	v_mov_b32_e32 v7, v8
	v_rcp_f32_e32 v9, v6
	s_nop 0
	v_mul_f32_e32 v8, v12, v9
	v_mov_b32_e32 v6, v8
	v_pk_mul_f32 v[2:3], v[6:7], v[2:3]
	s_nop 0
	v_cvt_pk_bf16_f32 v1, v2, v3
	global_store_dwordx2 v[4:5], v[0:1], off offset:1024
	s_barrier
	s_cbranch_scc0 .LBB0_825
.LBB0_826:
	s_and_b64 vcc, exec, s[38:39]
	s_cbranch_vccnz .LBB0_883
	v_lshrrev_b32_e32 v246, 3, v216
	v_lshrrev_b32_e32 v245, 4, v216
	v_xor_b32_e32 v245, v245, v216
	v_and_b32_e32 v245, 7, v245
	v_lshlrev_b32_e32 v245, 4, v245
	v_mul_u32_u24_e32 v244, 0x2c00, v246
	v_add_u32_e32 v244, v244, v245
	v_lshl_or_b32 v245, v246, 13, v245
	s_mov_b64 s[10:11], s[86:87]
	s_lshl_b32 s92, s10, 1
	s_lshl_b64 s[0:1], s[92:93], 2
	v_readlane_b32 s8, v252, 50
	v_readlane_b32 s9, v252, 51
	s_add_u32 s0, s8, s0
	s_addc_u32 s1, s9, s1
	global_load_dwordx2 v[208:209], v195, s[0:1]
	v_readlane_b32 s0, v252, 0
	v_readlane_b32 s1, v252, 1
	s_lshl_b32 s92, s10, 7
	s_mov_b32 s7, s70
	v_readlane_b32 s64, v252, 52
	s_mov_b32 s8, s0
	s_mov_b32 s3, s0
	s_lshl_b64 s[0:1], s[92:93], 2
	v_readlane_b32 s66, v252, 54
	v_readlane_b32 s67, v252, 55
	v_readlane_b32 s74, v252, 62
	v_readlane_b32 s68, v252, 56
	v_readlane_b32 s69, v252, 57
	v_readlane_b32 s70, v252, 58
	v_readlane_b32 s75, v252, 63
	v_readlane_b32 s66, v253, 8
	s_add_u32 s36, s74, s0
	v_readlane_b32 s11, v252, 22
	v_readlane_b32 s69, v255, 54
	v_readlane_b32 s67, v253, 9
	v_readlane_b32 s68, v255, 53
	s_mov_b32 s70, s7
	s_addc_u32 s37, s75, s1
	s_mov_b32 s12, s8
	v_readlane_b32 s65, v252, 53
	v_readlane_b32 s71, v252, 59
	v_readlane_b32 s72, v252, 60
	v_readlane_b32 s73, v252, 61
	v_readlane_b32 s76, v253, 0
	v_readlane_b32 s77, v253, 1
	v_readlane_b32 s78, v253, 2
	v_readlane_b32 s79, v253, 3
	s_waitcnt vmcnt(0)
	v_mov_b32_e32 v210, v208
	v_mov_b32_e32 v211, v208
	s_branch .LBB0_829

.LBB0_829:
	s_and_b32 s16, s12, 15
	s_ashr_i32 s8, s12, 7
	s_xor_b32 s34, s16, 31
	s_lshl_b32 s0, s34, 7
	s_ashr_i32 s9, s8, 31
	v_mov_b32_e32 v233, v216
	s_lshl_b64 s[74:75], s[8:9], 12
	s_or_b32 s1, s0, s6
	s_or_b32 s7, s74, s1
	v_and_b32_e32 v214, 31, v233
	v_or_b32_e32 v0, s7, v214
	v_mov_b64_e32 v[38:39], s[82:83]
	s_lshl_b32 s1, s12, 3
	v_mad_u64_u32 v[0:1], s[38:39], v0, s14, v[38:39]
	s_and_b32 s46, s1, 0x380
	v_mad_i32_i24 v1, s75, v225, v1
	s_lshl_b32 s92, s46, 1
	v_readlane_b32 s1, v254, 36
	v_bfe_u32 v215, v233, 5, 1
	v_lshl_add_u64 v[0:1], v[0:1], 0, s[92:93]
	s_lshl_b32 s64, s1, 1
	s_mov_b32 s65, s93
	v_lshl_add_u64 v[0:1], v[0:1], 0, s[64:65]
	v_lshlrev_b32_e32 v194, 4, v215
	v_lshl_add_u64 v[0:1], v[0:1], 0, v[194:195]
	global_load_dwordx4 v[160:163], v[0:1], off offset:2048
	global_load_dwordx4 v[164:167], v[0:1], off offset:2080
	global_load_dwordx4 v[168:171], v[0:1], off offset:2112
	global_load_dwordx4 v[172:175], v[0:1], off offset:2144
	v_lshrrev_b32_e32 v0, 1, v233
	v_bitop3_b32 v0, v215, v0, 7 bitop3:0x78
	v_mov_b32_e32 v1, v233
	v_lshlrev_b32_e32 v228, 4, v0
	v_lshlrev_b32_e32 v227, 7, v214
	v_ashrrev_i32_e32 v0, 3, v1
	v_lshrrev_b32_e32 v2, 4, v1
	v_xor_b32_e32 v6, v2, v1
	v_ashrrev_i32_e32 v1, 31, v0
	v_readlane_b32 s1, v254, 37
	v_lshl_add_u64 v[2:3], s[74:75], 0, v[0:1]
	v_mad_u64_u32 v[4:5], s[38:39], v2, s14, v[38:39]
	v_or_b32_e32 v8, s1, v227
	s_lshl_b32 s1, s8, 10
	v_mad_i32_i24 v5, v3, s14, v5
	v_lshlrev_b32_e32 v1, 4, v6
	s_or_b32 s18, s46, s1
	v_lshl_add_u64 v[2:3], v[4:5], 0, s[92:93]
	v_and_b32_e32 v194, 0x70, v1
	v_add_u32_e32 v0, s18, v0
	v_lshl_add_u64 v[2:3], v[2:3], 0, v[194:195]
	v_ashrrev_i32_e32 v1, 31, v0
	s_mov_b32 m0, s5
	v_lshl_add_u64 v[4:5], v[2:3], 0, s[30:31]
	v_lshlrev_b64 v[0:1], 13, v[0:1]
	s_add_i32 s47, s5, 0x2000
	v_lshl_add_u64 v[0:1], s[66:67], 0, v[0:1]
	global_load_lds_dwordx4 v[4:5], off
	v_lshl_add_u64 v[2:3], v[2:3], 0, s[42:43]
	s_mov_b32 m0, s47
	s_add_i32 s71, s5, 0x4000
	v_lshl_add_u64 v[0:1], v[0:1], 0, v[194:195]
	global_load_lds_dwordx4 v[2:3], off
	s_mov_b32 m0, s71
	s_mov_b64 s[8:9], 0x80000
	s_add_i32 s90, s5, 0x6000
	global_load_lds_dwordx4 v[0:1], off
	v_lshl_add_u64 v[0:1], v[0:1], 0, s[8:9]
	s_mov_b32 m0, s90
	s_add_i32 s91, s5, 0x8000
	global_load_lds_dwordx4 v[0:1], off
	v_mov_b32_e32 v1, v233
	s_mov_b32 s84, s94
	v_ashrrev_i32_e32 v0, 3, v1
	v_lshrrev_b32_e32 v2, 4, v1
	v_xor_b32_e32 v6, v2, v1
	v_ashrrev_i32_e32 v1, 31, v0
	v_lshl_add_u64 v[2:3], s[74:75], 0, v[0:1]
	v_mad_u64_u32 v[4:5], s[8:9], v2, s14, v[38:39]
	v_mad_i32_i24 v5, v3, s14, v5
	v_lshlrev_b32_e32 v1, 4, v6
	v_add_u32_e32 v0, s18, v0
	v_lshl_add_u64 v[2:3], v[4:5], 0, s[92:93]
	v_and_b32_e32 v194, 0x70, v1
	v_ashrrev_i32_e32 v1, 31, v0
	v_lshl_add_u64 v[2:3], v[2:3], 0, v[194:195]
	s_mov_b64 s[8:9], 0xb1c00
	v_lshlrev_b64 v[0:1], 13, v[0:1]
	v_lshl_add_u64 v[4:5], v[2:3], 0, s[8:9]
	v_lshl_add_u64 v[0:1], s[66:67], 0, v[0:1]
	s_mov_b32 m0, s91
	s_mov_b64 s[8:9], 0xb1c80
	s_add_i32 s94, s5, 0xa000
	v_lshl_add_u64 v[0:1], v[0:1], 0, v[194:195]
	global_load_lds_dwordx4 v[4:5], off
	v_lshl_add_u64 v[2:3], v[2:3], 0, s[8:9]
	s_mov_b32 m0, s94
	s_add_i32 s95, s5, 0xc000
	v_lshl_add_u64 v[6:7], v[0:1], 0, s[48:49]
	global_load_lds_dwordx4 v[2:3], off
	s_mov_b32 m0, s95
	s_add_i32 s72, s5, 0xe000
	v_add_u32_e32 v235, 0, v8
	global_load_lds_dwordx4 v[6:7], off
	v_lshl_add_u64 v[0:1], v[0:1], 0, s[96:97]
	s_mov_b32 m0, s72
	v_add_u32_e32 v40, v235, v228
	global_load_lds_dwordx4 v[0:1], off
	s_waitcnt vmcnt(0)
	s_waitcnt lgkmcnt(0)
	s_barrier
	ds_read_b128 v[0:3], v40
	ds_read_b128 v[18:21], v40 offset:4096
	s_waitcnt lgkmcnt(1)
	v_mfma_f32_32x32x16_bf16 v[2:17], v[0:3], v[160:163], 0
	v_bfe_u32 v0, v233, 1, 3
	v_bitop3_b32 v1, v215, v0, 2 bitop3:0x36
	v_lshlrev_b32_e32 v231, 4, v1
	v_add_u32_e32 v41, v235, v231
	ds_read_b128 v[34:37], v41
	v_bitop3_b32 v1, v215, v0, 4 bitop3:0x36
	v_lshlrev_b32_e32 v230, 4, v1
	s_waitcnt lgkmcnt(0)
	v_mfma_f32_32x32x16_bf16 v[2:17], v[34:37], v[164:167], v[2:17]
	ds_read_b128 v[34:37], v41 offset:4096
	v_add_u32_e32 v42, v235, v230
	v_bitop3_b32 v0, v215, v0, 6 bitop3:0x36
	v_lshlrev_b32_e32 v229, 4, v0
	v_add_u32_e32 v62, v235, v229
	v_mov_b32_e32 v1, v233
	s_add_i32 s45, s5, 0x10000
	v_mfma_f32_32x32x16_bf16 v[18:33], v[18:21], v[160:163], 0
	s_mov_b32 m0, s45
	s_add_i32 s73, s5, 0x12000
	s_add_i32 s89, s5, 0x14000
	s_add_i32 s60, s5, 0x16000
	s_lshl_b32 s35, s34, 1
	s_mov_b32 s17, 0xf149f2ca
	v_and_b32_e32 v234, 63, v233
	s_waitcnt lgkmcnt(0)
	v_mfma_f32_32x32x16_bf16 v[18:33], v[34:37], v[164:167], v[18:33]
	ds_read_b128 v[34:37], v42
	s_mov_b32 s65, s75
	s_mov_b32 s10, 2
	v_or_b32_e32 v236, s6, v214
	s_mov_b32 s78, 0x10000
	s_mov_b64 s[38:39], 0
	s_waitcnt lgkmcnt(0)
	v_mfma_f32_32x32x16_bf16 v[2:17], v[34:37], v[168:171], v[2:17]
	ds_read_b128 v[34:37], v42 offset:4096
	s_waitcnt lgkmcnt(0)
	v_mfma_f32_32x32x16_bf16 v[18:33], v[34:37], v[168:171], v[18:33]
	ds_read_b128 v[34:37], v62
	s_waitcnt lgkmcnt(0)
	v_mfma_f32_32x32x16_bf16 v[2:17], v[34:37], v[172:175], v[2:17]
	ds_read_b128 v[34:37], v62 offset:4096
	s_waitcnt lgkmcnt(0)
	v_mfma_f32_32x32x16_bf16 v[18:33], v[34:37], v[172:175], v[18:33]
	s_nop 15
	s_nop 7
	s_nop 0
	v_ashrrev_i32_e32 v0, 3, v1
	v_lshrrev_b32_e32 v34, 4, v1
	v_xor_b32_e32 v43, v34, v1
	v_ashrrev_i32_e32 v1, 31, v0
	v_lshl_add_u64 v[34:35], s[74:75], 0, v[0:1]
	v_mad_u64_u32 v[36:37], s[8:9], v34, s14, v[38:39]
	v_lshlrev_b32_e32 v1, 4, v43
	v_add_u32_e32 v0, s18, v0
	v_mad_i32_i24 v37, v35, s14, v37
	v_and_b32_e32 v194, 0x70, v1
	v_ashrrev_i32_e32 v1, 31, v0
	v_lshl_add_u64 v[34:35], v[36:37], 0, s[92:93]
	v_lshlrev_b64 v[0:1], 13, v[0:1]
	v_lshl_add_u64 v[34:35], v[34:35], 0, v[194:195]
	s_mov_b64 s[8:9], 0x161c00
	v_lshl_add_u64 v[0:1], s[66:67], 0, v[0:1]
	v_lshl_add_u64 v[36:37], v[34:35], 0, s[8:9]
	v_lshl_add_u64 v[0:1], v[0:1], 0, v[194:195]
	s_mov_b64 s[8:9], 0x100
	v_lshl_add_u64 v[38:39], v[0:1], 0, s[8:9]
	s_mov_b64 s[8:9], 0x161c80
	global_load_lds_dwordx4 v[36:37], off
	v_lshl_add_u64 v[34:35], v[34:35], 0, s[8:9]
	s_mov_b32 m0, s73
	s_mov_b64 s[8:9], 0x80100
	global_load_lds_dwordx4 v[34:35], off
	s_mov_b32 m0, s89
	v_lshl_add_u64 v[0:1], v[0:1], 0, s[8:9]
	global_load_lds_dwordx4 v[38:39], off
	s_mov_b32 m0, s60
	v_max3_f32 v34, v18, v19, v20
	v_max3_f32 v35, v26, v27, v28
	s_and_b32 s9, s11, 0x380
	global_load_lds_dwordx4 v[0:1], off
	v_max3_f32 v0, v2, v3, v4
	v_max3_f32 v1, v10, v11, v12
	v_max3_f32 v34, v34, v21, v22
	v_max3_f32 v35, v35, v29, v30
	s_add_i32 s8, s35, 2
	v_max3_f32 v0, v0, v5, v6
	v_max3_f32 v1, v1, v13, v14
	v_max3_f32 v34, v34, v23, v24
	v_max3_f32 v35, v35, v31, v32
	s_nop 0
	v_max3_f32 v0, v0, v7, v8
	v_max3_f32 v1, v1, v15, v16
	s_nop 0
	v_max3_f32 v0, v0, v9, v1
	v_max3_f32 v1, v34, v25, v35
	s_nop 0
	v_max3_f32 v0, v0, v17, v33
	s_nop 0
	v_max3_f32 v0, v0, v1, v1
	s_nop 0
	v_mov_b32_e32 v1, v0
	s_nop 1
	v_permlane32_swap_b32_e32 v0, v1
	v_max3_f32 v0, v0, v1, v1
	s_nop 0
	v_max_f32_e32 v1, v0, v0
	v_max_f32_e32 v1, 0xf149f2ca, v1
	v_sub_f32_e32 v34, 0xf149f2ca, v1
	v_exp_f32_e32 v34, v34
	v_cmp_lt_f32_e32 vcc, s17, v0
	s_cmp_eq_u64 vcc, 0
	s_cselect_b64 vcc, -1, 0
	v_mul_f32_e32 v0, 0, v34
	v_cndmask_b32_e64 v0, v0, 0, vcc
	ds_read_b128 v[54:57], v40 offset:32768
	ds_read_b128 v[58:61], v40 offset:36864
	ds_read_b128 v[80:83], v41 offset:32768
	ds_read_b128 v[50:53], v41 offset:36864
	ds_read_b128 v[46:49], v42 offset:32768
	ds_read_b128 v[42:45], v42 offset:36864
	ds_read_b128 v[38:41], v62 offset:32768
	ds_read_b128 v[34:37], v62 offset:36864
	s_waitcnt lgkmcnt(0)
	v_mfma_f32_32x32x16_bf16 v[64:79], v[54:57], v[160:163], 0
	v_cndmask_b32_e32 v212, v1, v226, vcc
	v_mov_b32_e32 v213, v212
	v_sub_f32_e32 v2, v2, v212
	v_sub_f32_e32 v3, v3, v213
	v_sub_f32_e32 v18, v18, v212
	v_sub_f32_e32 v19, v19, v213
	v_sub_f32_e32 v4, v4, v212
	v_sub_f32_e32 v5, v5, v213
	v_sub_f32_e32 v20, v20, v212
	v_sub_f32_e32 v21, v21, v213
	v_sub_f32_e32 v6, v6, v212
	v_sub_f32_e32 v7, v7, v213
	v_mfma_f32_32x32x16_bf16 v[64:79], v[80:83], v[164:167], v[64:79]
	v_sub_f32_e32 v22, v22, v212
	v_sub_f32_e32 v23, v23, v213
	v_sub_f32_e32 v8, v8, v212
	v_sub_f32_e32 v9, v9, v213
	v_sub_f32_e32 v24, v24, v212
	v_sub_f32_e32 v25, v25, v213
	v_sub_f32_e32 v10, v10, v212
	v_sub_f32_e32 v11, v11, v213
	v_sub_f32_e32 v26, v26, v212
	v_sub_f32_e32 v27, v27, v213
	v_sub_f32_e32 v12, v12, v212
	v_sub_f32_e32 v13, v13, v213
	v_sub_f32_e32 v28, v28, v212
	v_sub_f32_e32 v29, v29, v213
	v_mfma_f32_32x32x16_bf16 v[80:95], v[58:61], v[160:163], 0
	v_sub_f32_e32 v14, v14, v212
	v_sub_f32_e32 v15, v15, v213
	v_sub_f32_e32 v30, v30, v212
	v_sub_f32_e32 v31, v31, v213
	v_sub_f32_e32 v16, v16, v212
	v_sub_f32_e32 v17, v17, v213
	v_sub_f32_e32 v32, v32, v212
	v_sub_f32_e32 v33, v33, v213
	v_exp_f32_e32 v2, v2
	v_exp_f32_e32 v18, v18
	v_exp_f32_e32 v3, v3
	v_mfma_f32_32x32x16_bf16 v[80:95], v[50:53], v[164:167], v[80:95]
	v_exp_f32_e32 v19, v19
	v_exp_f32_e32 v4, v4
	v_exp_f32_e32 v20, v20
	v_exp_f32_e32 v5, v5
	v_exp_f32_e32 v21, v21
	v_exp_f32_e32 v6, v6
	v_exp_f32_e32 v22, v22
	v_mfma_f32_32x32x16_bf16 v[64:79], v[46:49], v[168:171], v[64:79]
	v_exp_f32_e32 v7, v7
	v_exp_f32_e32 v23, v23
	v_exp_f32_e32 v8, v8
	v_exp_f32_e32 v24, v24
	v_exp_f32_e32 v9, v9
	v_exp_f32_e32 v25, v25
	v_exp_f32_e32 v10, v10
	v_mfma_f32_32x32x16_bf16 v[80:95], v[42:45], v[168:171], v[80:95]
	v_exp_f32_e32 v26, v26
	v_exp_f32_e32 v11, v11
	v_exp_f32_e32 v27, v27
	v_exp_f32_e32 v12, v12
	v_exp_f32_e32 v28, v28
	v_exp_f32_e32 v13, v13
	v_exp_f32_e32 v29, v29
	v_exp_f32_e32 v14, v14
	v_exp_f32_e32 v30, v30
	v_exp_f32_e32 v15, v15
	v_exp_f32_e32 v31, v31
	v_exp_f32_e32 v16, v16
	v_exp_f32_e32 v32, v32
	v_exp_f32_e32 v17, v17
	v_exp_f32_e32 v33, v33
	v_mfma_f32_32x32x16_bf16 v[64:79], v[38:41], v[172:175], v[64:79]
	v_add_f32_e64 v54, v12, v28
	v_add_f32_e64 v55, v13, v29
	v_add_f32_e64 v56, v4, v20
	v_add_f32_e64 v57, v5, v21
	v_add_f32_e64 v58, v16, v32
	v_add_f32_e64 v59, v17, v33
	v_add_f32_e32 v60, v8, v24
	v_add_f32_e32 v61, v9, v25
	v_add_f32_e32 v62, v10, v26
	v_add_f32_e32 v63, v11, v27
	v_add_f32_e32 v96, v2, v18
	v_add_f32_e32 v97, v3, v19
	v_add_f32_e32 v98, v14, v30
	v_add_f32_e32 v99, v15, v31
	v_mfma_f32_32x32x16_bf16 v[80:95], v[34:37], v[172:175], v[80:95]
	v_add_f32_e64 v100, v6, v22
	v_add_f32_e64 v101, v7, v23
	v_add_f32_e64 v62, v96, v62
	v_add_f32_e64 v63, v97, v63
	v_add_f32_e64 v98, v100, v98
	v_add_f32_e64 v99, v101, v99
	v_add_f32_e32 v58, v60, v58
	v_add_f32_e32 v59, v61, v59
	v_add_f32_e32 v54, v56, v54
	v_add_f32_e32 v55, v57, v55
	v_add_f32_e32 v56, v62, v98
	v_add_f32_e32 v57, v63, v99
	v_add_f32_e32 v54, v54, v58
	v_add_f32_e32 v55, v55, v59
	v_cvt_pk_bf16_f32 v96, v2, v3
	v_pk_mov_b32 v[58:59], v[56:57], v[54:55] op_sel:[1,0]
	v_mov_b32_e32 v57, v55
	v_add_f32_e32 v54, v58, v56
	v_add_f32_e32 v55, v59, v57
	v_cvt_pk_bf16_f32 v97, v4, v5
	v_add_f32_e32 v1, v54, v55
	v_cvt_pk_bf16_f32 v98, v6, v7
	v_cvt_pk_bf16_f32 v99, v8, v9
	v_cvt_pk_bf16_f32 v180, v18, v19
	v_cvt_pk_bf16_f32 v181, v20, v21
	v_cvt_pk_bf16_f32 v182, v22, v23
	v_cvt_pk_bf16_f32 v183, v24, v25
	v_cvt_pk_bf16_f32 v184, v10, v11
	v_cvt_pk_bf16_f32 v185, v12, v13
	v_cvt_pk_bf16_f32 v186, v14, v15
	v_cvt_pk_bf16_f32 v187, v16, v17
	v_cvt_pk_bf16_f32 v176, v26, v27
	v_cvt_pk_bf16_f32 v177, v28, v29
	v_cvt_pk_bf16_f32 v178, v30, v31
	v_cvt_pk_bf16_f32 v179, v32, v33
	v_add_f32_e32 v100, v0, v1
	v_mov_b32_e32 v14, v0
	v_mov_b32_e32 v15, v0
	v_mov_b32_e32 v1, v0
	v_mov_b32_e32 v2, v0
	v_mov_b32_e32 v3, v0
	v_mov_b32_e32 v4, v0
	v_mov_b32_e32 v5, v0
	v_mov_b32_e32 v6, v0
	v_mov_b32_e32 v7, v0
	v_mov_b32_e32 v8, v0
	v_mov_b32_e32 v9, v0
	v_mov_b32_e32 v10, v0
	v_mov_b32_e32 v11, v0
	v_mov_b32_e32 v12, v0
	v_mov_b32_e32 v13, v0
	v_lshlrev_b32_e32 v232, 2, v215
	v_readlane_b32 s40, v255, 45
	v_mov_b64_e32 v[62:63], v[14:15]
	v_mov_b64_e32 v[46:47], v[14:15]
	v_mov_b64_e32 v[30:31], v[14:15]
	v_add_u32_e32 v237, 0, v227
	v_subrev_u32_e32 v208, s0, v232
	s_or_b32 s17, s1, s9
	v_readlane_b32 s41, v255, 46
	v_mov_b64_e32 v[60:61], v[12:13]
	v_mov_b64_e32 v[58:59], v[10:11]
	v_mov_b64_e32 v[56:57], v[8:9]
	v_mov_b64_e32 v[54:55], v[6:7]
	v_mov_b64_e32 v[52:53], v[4:5]
	v_mov_b64_e32 v[50:51], v[2:3]
	v_mov_b64_e32 v[48:49], v[0:1]
	v_mov_b64_e32 v[44:45], v[12:13]
	v_mov_b64_e32 v[42:43], v[10:11]
	v_mov_b64_e32 v[40:41], v[8:9]
	v_mov_b64_e32 v[38:39], v[6:7]
	v_mov_b64_e32 v[36:37], v[4:5]
	v_mov_b64_e32 v[34:35], v[2:3]
	v_mov_b64_e32 v[32:33], v[0:1]
	v_mov_b64_e32 v[28:29], v[12:13]
	v_mov_b64_e32 v[26:27], v[10:11]
	v_mov_b64_e32 v[24:25], v[8:9]
	v_mov_b64_e32 v[22:23], v[6:7]
	v_mov_b64_e32 v[20:21], v[4:5]
	v_mov_b64_e32 v[18:19], v[2:3]
	v_mov_b64_e32 v[16:17], v[0:1]
	s_waitcnt vmcnt(2)
	s_barrier

.LBB0_832:
	s_andn2_b64 vcc, exec, s[0:1]
	s_cbranch_vccnz .LBB0_834
	s_add_i32 s0, s74, s38
	s_addk_i32 s0, 0xc0
	s_mul_i32 s0, s0, s14
	s_lshl_b32 s92, s46, 1
	s_add_i32 s0, s0, s92
	s_addk_i32 s0, 0x1c00
	s_add_u32 s98, s82, s0
	s_addc_u32 s99, s83, 0
	s_lshl_b32 s1, s17, 13
	s_add_u32 s76, s40, s1
	s_addc_u32 s77, s41, 0
	s_add_i32 s0, s78, 0x8000
	s_and_b32 s0, s0, 0x18000
	s_add_i32 s0, s5, s0
	s_mov_b32 m0, s0
	s_nop 0
	global_load_lds_dwordx4 v244, s[98:99]
	s_add_i32 m0, s0, 0x2000
	s_add_u32 s98, s98, 0x80
	s_addc_u32 s99, s99, 0
	global_load_lds_dwordx4 v244, s[98:99]
	s_add_i32 m0, s0, 0x4000
	s_nop 0
	global_load_lds_dwordx4 v245, s[76:77]
	s_add_i32 m0, s0, 0x6000
	s_add_u32 s76, s76, 0x80000
	s_addc_u32 s77, s77, 0
	global_load_lds_dwordx4 v245, s[76:77]
	v_mov_b64_e32 v[142:143], v[94:95]
	v_mov_b64_e32 v[158:159], v[78:79]
	v_mov_b64_e32 v[140:141], v[92:93]
	v_mov_b64_e32 v[138:139], v[90:91]
	v_mov_b64_e32 v[136:137], v[88:89]
	v_mov_b64_e32 v[134:135], v[86:87]
	v_mov_b64_e32 v[132:133], v[84:85]
	v_mov_b64_e32 v[130:131], v[82:83]
	v_mov_b64_e32 v[128:129], v[80:81]
	v_mov_b64_e32 v[156:157], v[76:77]
	v_mov_b64_e32 v[154:155], v[74:75]
	v_mov_b64_e32 v[152:153], v[72:73]
	v_mov_b64_e32 v[150:151], v[70:71]
	v_mov_b64_e32 v[148:149], v[68:69]
	v_mov_b64_e32 v[146:147], v[66:67]
	v_mov_b64_e32 v[144:145], v[64:65]
.LBB0_834:
	v_max3_f32 v64, v144, v145, v146
	v_max3_f32 v65, v152, v153, v154
	v_max3_f32 v66, v128, v129, v130
	v_max3_f32 v67, v136, v137, v138
	s_add_i32 s9, s78, 0x10000
	v_max3_f32 v64, v64, v147, v148
	v_max3_f32 v65, v65, v155, v156
	v_max3_f32 v66, v66, v131, v132
	v_max3_f32 v67, v67, v139, v140
	s_and_b32 s33, s9, 0x18000
	v_max3_f32 v64, v64, v149, v150
	v_max3_f32 v65, v65, v157, v158
	v_max3_f32 v66, v66, v133, v134
	v_max3_f32 v67, v67, v141, v142
	s_and_b32 s76, s78, 0x18000
	v_max3_f32 v64, v64, v151, v65
	v_max3_f32 v65, v66, v135, v67
	v_max_f32_e32 v66, v212, v212
	v_max3_f32 v64, v64, v159, v143
	s_nop 0
	v_max3_f32 v64, v64, v65, v65
	s_nop 0
	v_mov_b32_e32 v65, v64
	s_nop 1
	v_permlane32_swap_b32_e32 v64, v65
	v_max3_f32 v64, v64, v65, v65
	s_nop 0
	v_max_f32_e32 v65, v64, v64
	v_max_f32_e32 v69, v66, v65
	v_sub_f32_e32 v65, v212, v69
	v_exp_f32_e32 v68, v65
	v_add_f32_e32 v65, 0x41000000, v212
	v_cmp_gt_f32_e32 vcc, v64, v65
	s_cmp_eq_u64 vcc, 0
	v_mul_f32_e32 v64, v100, v68
	s_cselect_b64 s[0:1], -1, 0
	v_cndmask_b32_e64 v194, v64, v100, s[0:1]
	v_add_u32_e32 v239, s33, v237
	v_add_u32_e32 v74, v239, v228
	ds_read_b128 v[64:67], v74 offset:16384
	ds_read_b128 v[70:73], v74 offset:20480
	v_add_u32_e32 v86, s76, v235
	v_add_u32_e32 v78, v239, v231
	v_add_u32_e32 v82, v86, v230
	s_waitcnt lgkmcnt(0)
	v_mfma_f32_32x32x16_bf16 v[0:15], v[64:67], v[96:99], v[0:15]
	v_cndmask_b32_e64 v212, v69, v212, s[0:1]
	v_add_u32_e32 v69, v239, v230
	v_mov_b32_e32 v213, v212
	v_sub_f32_e32 v92, v128, v212
	v_sub_f32_e32 v93, v129, v213
	v_sub_f32_e32 v128, v130, v212
	v_sub_f32_e32 v129, v131, v213
	v_sub_f32_e32 v130, v148, v212
	v_sub_f32_e32 v131, v149, v213
	v_sub_f32_e32 v90, v144, v212
	v_sub_f32_e32 v91, v145, v213
	v_mfma_f32_32x32x16_bf16 v[48:63], v[70:73], v[96:99], v[48:63]
	ds_read_b128 v[64:67], v74 offset:24576
	ds_read_b128 v[70:73], v74 offset:28672
	v_add_u32_e32 v74, v86, v228
	v_sub_f32_e32 v132, v132, v212
	v_sub_f32_e32 v133, v133, v213
	v_sub_f32_e32 v144, v150, v212
	v_sub_f32_e32 v145, v151, v213
	v_sub_f32_e32 v148, v154, v212
	v_sub_f32_e32 v149, v155, v213
	v_sub_f32_e32 v150, v156, v212
	v_sub_f32_e32 v151, v157, v213
	v_sub_f32_e32 v140, v140, v212
	v_sub_f32_e32 v141, v141, v213
	s_waitcnt lgkmcnt(0)
	v_mfma_f32_32x32x16_bf16 v[32:47], v[64:67], v[96:99], v[32:47]
	v_exp_f32_e32 v130, v130
	v_exp_f32_e32 v154, v132
	v_exp_f32_e32 v131, v131
	v_exp_f32_e32 v155, v133
	v_sub_f32_e32 v138, v138, v212
	v_sub_f32_e32 v139, v139, v213
	v_sub_f32_e32 v94, v146, v212
	v_sub_f32_e32 v95, v147, v213
	v_sub_f32_e32 v146, v152, v212
	v_sub_f32_e32 v147, v153, v213
	v_mfma_f32_32x32x16_bf16 v[16:31], v[70:73], v[96:99], v[16:31]
	ds_read_b128 v[64:67], v74
	ds_read_b128 v[70:73], v74 offset:4096
	v_add_u32_e32 v74, v86, v231
	v_add_u32_e32 v86, v86, v229
	v_sub_f32_e32 v152, v158, v212
	v_sub_f32_e32 v153, v159, v213
	v_exp_f32_e32 v158, v138
	v_exp_f32_e32 v159, v139
	v_sub_f32_e32 v142, v142, v212
	v_sub_f32_e32 v143, v143, v213
	s_waitcnt lgkmcnt(0)
	v_mfma_f32_32x32x16_bf16 v[96:111], v[64:67], v[160:163], 0
	ds_read_b128 v[64:67], v74
	ds_read_b128 v[74:77], v74 offset:4096
	v_sub_f32_e32 v134, v134, v212
	v_sub_f32_e32 v135, v135, v213
	v_exp_f32_e32 v94, v94
	v_exp_f32_e32 v128, v128
	v_exp_f32_e32 v95, v95
	v_exp_f32_e32 v129, v129
	v_exp_f32_e32 v132, v144
	v_mfma_f32_32x32x16_bf16 v[112:127], v[70:73], v[160:163], 0
	v_exp_f32_e32 v144, v134
	v_exp_f32_e32 v133, v145
	v_exp_f32_e32 v145, v135
	v_exp_f32_e32 v148, v148
	v_exp_f32_e32 v149, v149
	v_exp_f32_e32 v142, v142
	v_exp_f32_e32 v143, v143
	s_waitcnt lgkmcnt(0)
	v_mfma_f32_32x32x16_bf16 v[96:111], v[64:67], v[164:167], v[96:111]
	ds_read_b128 v[64:67], v78 offset:16384
	ds_read_b128 v[70:73], v78 offset:20480
	v_sub_f32_e32 v136, v136, v212
	v_sub_f32_e32 v137, v137, v213
	v_exp_f32_e32 v90, v90
	v_exp_f32_e32 v92, v92
	v_exp_f32_e32 v91, v91
	v_exp_f32_e32 v93, v93
	v_exp_f32_e32 v146, v146
	v_mfma_f32_32x32x16_bf16 v[112:127], v[74:77], v[164:167], v[112:127]
	v_exp_f32_e32 v156, v136
	v_exp_f32_e32 v147, v147
	v_exp_f32_e32 v157, v137
	v_add_f32_e32 v136, v90, v92
	v_add_f32_e32 v137, v91, v93
	s_waitcnt lgkmcnt(0)
	v_mfma_f32_32x32x16_bf16 v[0:15], v[64:67], v[184:187], v[0:15]
	ds_read_b128 v[64:67], v78 offset:24576
	ds_read_b128 v[74:77], v78 offset:28672
	ds_read_b128 v[78:81], v82
	ds_read_b128 v[82:85], v82 offset:4096
	v_mfma_f32_32x32x16_bf16 v[48:63], v[70:73], v[184:187], v[48:63]
	ds_read_b128 v[70:73], v86
	ds_read_b128 v[86:89], v86 offset:4096
	s_waitcnt lgkmcnt(0)
	v_mfma_f32_32x32x16_bf16 v[32:47], v[64:67], v[184:187], v[32:47]
	ds_read_b128 v[64:67], v69 offset:16384
	v_mfma_f32_32x32x16_bf16 v[16:31], v[74:77], v[184:187], v[16:31]
	ds_read_b128 v[74:77], v69 offset:20480
	s_waitcnt lgkmcnt(0)
	v_mfma_f32_32x32x16_bf16 v[0:15], v[64:67], v[180:183], v[0:15]
	ds_read_b128 v[64:67], v69 offset:24576
	v_mfma_f32_32x32x16_bf16 v[96:111], v[78:81], v[168:171], v[96:111]
	v_exp_f32_e32 v78, v150
	v_exp_f32_e32 v80, v140
	v_exp_f32_e32 v79, v151
	v_exp_f32_e32 v81, v141
	v_exp_f32_e32 v150, v152
	v_exp_f32_e32 v151, v153
	v_mfma_f32_32x32x16_bf16 v[48:63], v[74:77], v[180:183], v[48:63]
	ds_read_b128 v[74:77], v69 offset:28672
	v_add_u32_e32 v69, v239, v229
	v_add_f32_e64 v134, v150, v142
	v_add_f32_e64 v135, v151, v143
	s_waitcnt lgkmcnt(0)
	v_mfma_f32_32x32x16_bf16 v[32:47], v[64:67], v[180:183], v[32:47]
	ds_read_b128 v[64:67], v69 offset:16384
	v_mfma_f32_32x32x16_bf16 v[96:111], v[70:73], v[172:175], v[96:111]
	v_add_f32_e64 v70, v78, v80
	v_add_f32_e64 v71, v79, v81
	v_add_f32_e64 v72, v130, v154
	v_add_f32_e64 v73, v131, v155
	v_add_f32_e64 v138, v72, v70
	v_add_f32_e64 v139, v73, v71
	ds_read_b128 v[70:73], v69 offset:20480
	v_mfma_f32_32x32x16_bf16 v[16:31], v[74:77], v[180:183], v[16:31]
	v_add_f32_e64 v74, v148, v158
	v_add_f32_e64 v75, v149, v159
	v_add_f32_e64 v76, v94, v128
	v_add_f32_e64 v77, v95, v129
	v_add_f32_e64 v74, v76, v74
	v_add_f32_e64 v75, v77, v75
	v_mfma_f32_32x32x16_bf16 v[112:127], v[82:85], v[168:171], v[112:127]
	v_add_f32_e64 v82, v132, v144
	v_add_f32_e64 v83, v133, v145
	v_add_f32_e64 v84, v146, v156
	v_add_f32_e64 v85, v147, v157
	s_waitcnt lgkmcnt(0)
	v_mfma_f32_32x32x16_bf16 v[0:15], v[64:67], v[176:179], v[0:15]
	v_add_f32_e64 v66, v82, v134
	v_add_f32_e64 v67, v83, v135
	v_add_f32_e64 v64, v136, v84
	v_add_f32_e64 v65, v137, v85
	v_add_f32_e64 v66, v74, v66
	v_add_f32_e64 v67, v75, v67
	ds_read_b128 v[74:77], v69 offset:24576
	v_add_f32_e32 v64, v64, v138
	v_add_f32_e32 v65, v65, v139
	v_cvt_pk_bf16_f32 v134, v154, v155
	v_add_f32_e32 v64, v64, v65
	v_mfma_f32_32x32x16_bf16 v[48:63], v[70:73], v[176:179], v[48:63]
	ds_read_b128 v[70:73], v69 offset:28672
	v_add_f32_e32 v65, v66, v67
	v_add_f32_e32 v82, v64, v65
	v_cvt_pk_bf16_f32 v64, v90, v91
	v_cvt_pk_bf16_f32 v65, v94, v95
	v_cvt_pk_bf16_f32 v66, v130, v131
	v_cvt_pk_bf16_f32 v67, v132, v133
	s_waitcnt lgkmcnt(0)
	v_mfma_f32_32x32x16_bf16 v[32:47], v[74:77], v[176:179], v[32:47]
	v_cvt_pk_bf16_f32 v132, v92, v93
	v_cvt_pk_bf16_f32 v133, v128, v129
	v_cvt_pk_bf16_f32 v135, v144, v145
	v_cvt_pk_bf16_f32 v136, v146, v147
	v_cvt_pk_bf16_f32 v137, v148, v149
	v_cvt_pk_bf16_f32 v138, v78, v79
	v_cvt_pk_bf16_f32 v139, v150, v151
	v_mfma_f32_32x32x16_bf16 v[16:31], v[70:73], v[176:179], v[16:31]
	v_cvt_pk_bf16_f32 v128, v156, v157
	v_cvt_pk_bf16_f32 v129, v158, v159
	v_cvt_pk_bf16_f32 v130, v80, v81
	v_cvt_pk_bf16_f32 v131, v142, v143
	v_add_f32_e32 v69, v194, v82
	v_mfma_f32_32x32x16_bf16 v[112:127], v[86:89], v[172:175], v[112:127]
	s_cbranch_vccz .LBB0_836
	v_pk_mul_f32 v[14:15], v[68:69], v[14:15] op_sel_hi:[0,1]
	v_pk_mul_f32 v[12:13], v[68:69], v[12:13] op_sel_hi:[0,1]
	v_pk_mul_f32 v[10:11], v[68:69], v[10:11] op_sel_hi:[0,1]
	v_pk_mul_f32 v[8:9], v[68:69], v[8:9] op_sel_hi:[0,1]
	v_pk_mul_f32 v[6:7], v[68:69], v[6:7] op_sel_hi:[0,1]
	v_pk_mul_f32 v[4:5], v[68:69], v[4:5] op_sel_hi:[0,1]
	v_pk_mul_f32 v[2:3], v[68:69], v[2:3] op_sel_hi:[0,1]
	v_pk_mul_f32 v[0:1], v[68:69], v[0:1] op_sel_hi:[0,1]
	v_pk_mul_f32 v[62:63], v[68:69], v[62:63] op_sel_hi:[0,1]
	v_pk_mul_f32 v[60:61], v[68:69], v[60:61] op_sel_hi:[0,1]
	v_pk_mul_f32 v[58:59], v[68:69], v[58:59] op_sel_hi:[0,1]
	v_pk_mul_f32 v[56:57], v[68:69], v[56:57] op_sel_hi:[0,1]
	v_pk_mul_f32 v[54:55], v[68:69], v[54:55] op_sel_hi:[0,1]
	v_pk_mul_f32 v[52:53], v[68:69], v[52:53] op_sel_hi:[0,1]
	v_pk_mul_f32 v[50:51], v[68:69], v[50:51] op_sel_hi:[0,1]
	v_pk_mul_f32 v[48:49], v[68:69], v[48:49] op_sel_hi:[0,1]
	v_pk_mul_f32 v[46:47], v[68:69], v[46:47] op_sel_hi:[0,1]
	v_pk_mul_f32 v[44:45], v[68:69], v[44:45] op_sel_hi:[0,1]
	v_pk_mul_f32 v[42:43], v[68:69], v[42:43] op_sel_hi:[0,1]
	v_pk_mul_f32 v[40:41], v[68:69], v[40:41] op_sel_hi:[0,1]
	v_pk_mul_f32 v[38:39], v[68:69], v[38:39] op_sel_hi:[0,1]
	v_pk_mul_f32 v[36:37], v[68:69], v[36:37] op_sel_hi:[0,1]
	v_pk_mul_f32 v[34:35], v[68:69], v[34:35] op_sel_hi:[0,1]
	v_pk_mul_f32 v[32:33], v[68:69], v[32:33] op_sel_hi:[0,1]
	v_pk_mul_f32 v[30:31], v[68:69], v[30:31] op_sel_hi:[0,1]
	v_pk_mul_f32 v[28:29], v[68:69], v[28:29] op_sel_hi:[0,1]
	v_pk_mul_f32 v[26:27], v[68:69], v[26:27] op_sel_hi:[0,1]
	v_pk_mul_f32 v[24:25], v[68:69], v[24:25] op_sel_hi:[0,1]
	v_pk_mul_f32 v[22:23], v[68:69], v[22:23] op_sel_hi:[0,1]
	v_pk_mul_f32 v[20:21], v[68:69], v[20:21] op_sel_hi:[0,1]
	v_pk_mul_f32 v[18:19], v[68:69], v[18:19] op_sel_hi:[0,1]
	v_pk_mul_f32 v[16:17], v[68:69], v[16:17] op_sel_hi:[0,1]
.LBB0_836:
	s_add_i32 s79, s10, 2
	s_cmp_ge_u32 s79, s8
	s_cselect_b64 s[76:77], -1, 0
	s_and_b64 vcc, exec, s[76:77]
	s_waitcnt vmcnt(2)
	s_barrier
	s_cbranch_vccnz .LBB0_838
	s_add_i32 s0, s74, s38
	s_addk_i32 s0, 0x100
	s_mul_i32 s0, s0, s14
	s_lshl_b32 s92, s46, 1
	s_add_i32 s0, s0, s92
	s_addk_i32 s0, 0x1c00
	s_add_u32 s98, s82, s0
	s_addc_u32 s99, s83, 0
	s_lshl_b32 s1, s17, 13
	s_add_u32 s0, s40, s1
	s_addc_u32 s1, s41, 0
	s_add_u32 s0, s0, 0x80
	s_addc_u32 s1, s1, 0
	s_add_i32 s32, s5, s33
	s_mov_b32 m0, s32
	s_nop 0
	global_load_lds_dwordx4 v244, s[98:99]
	s_add_i32 m0, s32, 0x2000
	s_add_u32 s98, s98, 0x80
	s_addc_u32 s99, s99, 0
	global_load_lds_dwordx4 v244, s[98:99]
	s_add_i32 m0, s32, 0x4000
	s_nop 0
	global_load_lds_dwordx4 v245, s[0:1]
	s_add_i32 m0, s32, 0x6000
	s_add_u32 s0, s0, 0x80000
	s_addc_u32 s1, s1, 0
	global_load_lds_dwordx4 v245, s[0:1]

.LBB0_840:
	v_max3_f32 v68, v96, v97, v98
	v_max3_f32 v70, v104, v105, v106
	v_max3_f32 v71, v112, v113, v114
	v_max3_f32 v72, v120, v121, v122
	s_add_i32 s0, s78, 0xffff8000
	v_max3_f32 v68, v68, v99, v100
	v_max3_f32 v70, v70, v107, v108
	v_max3_f32 v71, v71, v115, v116
	v_max3_f32 v72, v72, v123, v124
	s_and_b32 s10, s0, 0x18000
	v_max3_f32 v68, v68, v101, v102
	v_max3_f32 v70, v70, v109, v110
	v_max3_f32 v71, v71, v117, v118
	v_max3_f32 v72, v72, v125, v126
	s_xor_b32 s33, s10, 0x10000
	v_max3_f32 v68, v68, v103, v70
	v_max3_f32 v70, v71, v119, v72
	v_max_f32_e32 v71, v212, v212
	v_max3_f32 v68, v68, v111, v127
	s_nop 0
	v_max3_f32 v68, v68, v70, v70
	s_nop 0
	v_mov_b32_e32 v70, v68
	s_nop 1
	v_permlane32_swap_b32_e32 v68, v70
	v_max3_f32 v68, v68, v70, v70
	s_nop 0
	v_max_f32_e32 v70, v68, v68
	v_max_f32_e32 v141, v71, v70
	v_sub_f32_e32 v70, v212, v141
	v_exp_f32_e32 v140, v70
	v_add_f32_e32 v70, 0x41000000, v212
	v_cmp_gt_f32_e32 vcc, v68, v70
	s_cmp_eq_u64 vcc, 0
	v_mul_f32_e32 v68, v69, v140
	s_cselect_b64 s[0:1], -1, 0
	v_cndmask_b32_e64 v194, v68, v69, s[0:1]
	v_add_u32_e32 v182, s10, v237
	v_add_u32_e32 v76, v182, v228
	ds_read_b128 v[68:71], v76 offset:16384
	ds_read_b128 v[72:75], v76 offset:20480
	v_add_u32_e32 v158, s33, v235
	v_add_u32_e32 v88, v158, v231
	v_add_u32_e32 v150, v182, v231
	s_waitcnt lgkmcnt(0)
	v_mfma_f32_32x32x16_bf16 v[0:15], v[68:71], v[64:67], v[0:15]
	v_add_u32_e32 v159, v158, v230
	v_cndmask_b32_e64 v212, v141, v212, s[0:1]
	v_add_u32_e32 v141, v182, v230
	v_mov_b32_e32 v213, v212
	v_sub_f32_e32 v180, v102, v212
	v_sub_f32_e32 v181, v103, v213
	v_sub_f32_e32 v116, v116, v212
	v_sub_f32_e32 v117, v117, v213
	v_sub_f32_e32 v108, v108, v212
	v_sub_f32_e32 v109, v109, v213
	v_mfma_f32_32x32x16_bf16 v[48:63], v[72:75], v[64:67], v[48:63]
	ds_read_b128 v[68:71], v76 offset:24576
	ds_read_b128 v[72:75], v76 offset:28672
	v_sub_f32_e32 v124, v124, v212
	v_sub_f32_e32 v125, v125, v213
	v_exp_f32_e32 v116, v116
	v_exp_f32_e32 v117, v117
	v_exp_f32_e32 v108, v108
	v_exp_f32_e32 v124, v124
	v_exp_f32_e32 v109, v109
	s_waitcnt lgkmcnt(0)
	v_mfma_f32_32x32x16_bf16 v[32:47], v[68:71], v[64:67], v[32:47]
	v_add_u32_e32 v68, v158, v228
	v_add_u32_e32 v158, v158, v229
	v_exp_f32_e32 v125, v125
	v_sub_f32_e32 v114, v114, v212
	v_sub_f32_e32 v115, v115, v213
	v_sub_f32_e32 v118, v118, v212
	v_sub_f32_e32 v119, v119, v213
	v_sub_f32_e32 v122, v122, v212
	v_sub_f32_e32 v123, v123, v213
	v_sub_f32_e32 v110, v110, v212
	v_sub_f32_e32 v111, v111, v213
	v_mfma_f32_32x32x16_bf16 v[16:31], v[72:75], v[64:67], v[16:31]
	ds_read_b128 v[64:67], v68
	ds_read_b128 v[80:83], v68 offset:4096
	ds_read_b128 v[84:87], v88
	ds_read_b128 v[142:145], v88 offset:4096
	v_sub_f32_e32 v126, v126, v212
	v_sub_f32_e32 v127, v127, v213
	v_sub_f32_e32 v106, v106, v212
	v_sub_f32_e32 v107, v107, v213
	v_exp_f32_e32 v114, v114
	v_exp_f32_e32 v115, v115
	v_exp_f32_e32 v118, v118
	s_waitcnt lgkmcnt(0)
	v_mfma_f32_32x32x16_bf16 v[64:79], v[64:67], v[160:163], 0
	v_exp_f32_e32 v119, v119
	v_exp_f32_e32 v122, v122
	v_exp_f32_e32 v123, v123
	v_exp_f32_e32 v110, v110
	v_exp_f32_e32 v126, v126
	v_exp_f32_e32 v111, v111
	v_exp_f32_e32 v127, v127
	v_mfma_f32_32x32x16_bf16 v[64:79], v[84:87], v[164:167], v[64:79]
	v_sub_f32_e32 v104, v104, v212
	v_sub_f32_e32 v105, v105, v213
	v_sub_f32_e32 v112, v112, v212
	v_sub_f32_e32 v113, v113, v213
	v_sub_f32_e32 v120, v120, v212
	v_sub_f32_e32 v121, v121, v213
	v_cvt_pk_bf16_f32 v183, v118, v119
	v_exp_f32_e32 v112, v112
	v_exp_f32_e32 v113, v113
	v_exp_f32_e32 v120, v120
	v_mfma_f32_32x32x16_bf16 v[80:95], v[80:83], v[160:163], 0
	v_exp_f32_e32 v121, v121
	v_cvt_pk_bf16_f32 v186, v108, v109
	v_cvt_pk_bf16_f32 v187, v110, v111
	v_mfma_f32_32x32x16_bf16 v[80:95], v[142:145], v[164:167], v[80:95]
	ds_read_b128 v[142:145], v150 offset:16384
	ds_read_b128 v[146:149], v150 offset:20480
	s_waitcnt lgkmcnt(0)
	v_mfma_f32_32x32x16_bf16 v[0:15], v[142:145], v[136:139], v[0:15]
	ds_read_b128 v[142:145], v150 offset:24576
	ds_read_b128 v[150:153], v150 offset:28672
	ds_read_b128 v[154:157], v159
	ds_read_b128 v[176:179], v159 offset:4096
	v_mfma_f32_32x32x16_bf16 v[48:63], v[146:149], v[136:139], v[48:63]
	ds_read_b128 v[146:149], v158
	ds_read_b128 v[238:241], v158 offset:4096
	v_sub_f32_e32 v158, v96, v212
	v_sub_f32_e32 v159, v97, v213
	s_waitcnt lgkmcnt(0)
	v_mfma_f32_32x32x16_bf16 v[32:47], v[142:145], v[136:139], v[32:47]
	v_sub_f32_e32 v142, v98, v212
	v_sub_f32_e32 v143, v99, v213
	v_sub_f32_e32 v144, v100, v212
	v_sub_f32_e32 v145, v101, v213
	ds_read_b128 v[96:99], v141 offset:16384
	ds_read_b128 v[100:103], v141 offset:20480
	s_waitcnt lgkmcnt(0)
	v_mfma_f32_32x32x16_bf16 v[0:15], v[96:99], v[132:135], v[0:15]
	ds_read_b128 v[96:99], v141 offset:24576
	v_mfma_f32_32x32x16_bf16 v[48:63], v[100:103], v[132:135], v[48:63]
	ds_read_b128 v[100:103], v141 offset:28672
	v_add_u32_e32 v141, v182, v229
	v_cvt_pk_bf16_f32 v182, v116, v117
	v_mfma_f32_32x32x16_bf16 v[16:31], v[150:153], v[136:139], v[16:31]
	v_exp_f32_e32 v138, v142
	v_exp_f32_e32 v139, v143
	v_exp_f32_e32 v142, v144
	v_exp_f32_e32 v143, v145
	v_exp_f32_e32 v144, v180
	v_exp_f32_e32 v145, v181
	v_exp_f32_e32 v136, v158
	s_waitcnt lgkmcnt(0)
	v_mfma_f32_32x32x16_bf16 v[32:47], v[96:99], v[132:135], v[32:47]
	ds_read_b128 v[96:99], v141 offset:16384
	v_exp_f32_e32 v137, v159
	v_cvt_pk_bf16_f32 v180, v112, v113
	v_cvt_pk_bf16_f32 v181, v114, v115
	v_add_f32_e32 v152, v136, v112
	v_add_f32_e32 v153, v137, v113
	v_mfma_f32_32x32x16_bf16 v[16:31], v[100:103], v[132:135], v[16:31]
	v_add_f32_e64 v100, v108, v124
	v_add_f32_e64 v101, v109, v125
	v_add_f32_e64 v102, v142, v116
	v_add_f32_e64 v103, v143, v117
	v_exp_f32_e32 v134, v106
	v_exp_f32_e32 v135, v107
	v_exp_f32_e32 v132, v104
	v_exp_f32_e32 v133, v105
	v_add_f32_e32 v106, v138, v114
	v_add_f32_e32 v107, v139, v115
	v_mfma_f32_32x32x16_bf16 v[64:79], v[154:157], v[168:171], v[64:79]
	v_add_f32_e64 v154, v102, v100
	v_add_f32_e64 v155, v103, v101
	ds_read_b128 v[100:103], v141 offset:20480
	v_add_f32_e64 v104, v134, v122
	v_add_f32_e64 v105, v135, v123
	v_add_f32_e32 v150, v132, v120
	v_add_f32_e32 v151, v133, v121
	v_add_f32_e32 v104, v106, v104
	v_add_f32_e32 v105, v107, v105
	v_cvt_pk_bf16_f32 v184, v132, v133
	v_cvt_pk_bf16_f32 v185, v134, v135
	v_mfma_f32_32x32x16_bf16 v[64:79], v[146:149], v[172:175], v[64:79]
	v_add_f32_e64 v146, v110, v126
	v_add_f32_e64 v147, v111, v127
	v_add_f32_e64 v148, v144, v118
	v_add_f32_e64 v149, v145, v119
	s_waitcnt lgkmcnt(0)
	v_mfma_f32_32x32x16_bf16 v[0:15], v[96:99], v[128:131], v[0:15]
	v_add_f32_e64 v98, v148, v146
	v_add_f32_e64 v99, v149, v147
	v_add_f32_e64 v96, v152, v150
	v_add_f32_e64 v97, v153, v151
	v_add_f32_e64 v98, v104, v98
	v_add_f32_e64 v99, v105, v99
	ds_read_b128 v[104:107], v141 offset:24576
	v_add_f32_e32 v96, v96, v154
	v_add_f32_e32 v97, v97, v155
	s_nop 0
	v_add_f32_e32 v96, v96, v97
	v_mfma_f32_32x32x16_bf16 v[48:63], v[100:103], v[128:131], v[48:63]
	ds_read_b128 v[100:103], v141 offset:28672
	v_add_f32_e32 v97, v98, v99
	v_add_f32_e32 v146, v96, v97
	v_cvt_pk_bf16_f32 v96, v136, v137
	v_cvt_pk_bf16_f32 v97, v138, v139
	v_cvt_pk_bf16_f32 v98, v142, v143
	v_cvt_pk_bf16_f32 v99, v144, v145
	v_mfma_f32_32x32x16_bf16 v[80:95], v[176:179], v[168:171], v[80:95]
	v_cvt_pk_bf16_f32 v176, v120, v121
	v_cvt_pk_bf16_f32 v177, v122, v123
	v_cvt_pk_bf16_f32 v178, v124, v125
	v_cvt_pk_bf16_f32 v179, v126, v127
	s_waitcnt lgkmcnt(0)
	v_mfma_f32_32x32x16_bf16 v[32:47], v[104:107], v[128:131], v[32:47]
	v_mfma_f32_32x32x16_bf16 v[16:31], v[100:103], v[128:131], v[16:31]
	v_add_f32_e32 v100, v194, v146
	v_mfma_f32_32x32x16_bf16 v[80:95], v[238:241], v[172:175], v[80:95]
	s_cbranch_vccz .LBB0_842
	v_pk_mul_f32 v[14:15], v[140:141], v[14:15] op_sel_hi:[0,1]
	v_pk_mul_f32 v[12:13], v[140:141], v[12:13] op_sel_hi:[0,1]
	v_pk_mul_f32 v[10:11], v[140:141], v[10:11] op_sel_hi:[0,1]
	v_pk_mul_f32 v[8:9], v[140:141], v[8:9] op_sel_hi:[0,1]
	v_pk_mul_f32 v[6:7], v[140:141], v[6:7] op_sel_hi:[0,1]
	v_pk_mul_f32 v[4:5], v[140:141], v[4:5] op_sel_hi:[0,1]
	v_pk_mul_f32 v[2:3], v[140:141], v[2:3] op_sel_hi:[0,1]
	v_pk_mul_f32 v[0:1], v[140:141], v[0:1] op_sel_hi:[0,1]
	v_pk_mul_f32 v[62:63], v[140:141], v[62:63] op_sel_hi:[0,1]
	v_pk_mul_f32 v[60:61], v[140:141], v[60:61] op_sel_hi:[0,1]
	v_pk_mul_f32 v[58:59], v[140:141], v[58:59] op_sel_hi:[0,1]
	v_pk_mul_f32 v[56:57], v[140:141], v[56:57] op_sel_hi:[0,1]
	v_pk_mul_f32 v[54:55], v[140:141], v[54:55] op_sel_hi:[0,1]
	v_pk_mul_f32 v[52:53], v[140:141], v[52:53] op_sel_hi:[0,1]
	v_pk_mul_f32 v[50:51], v[140:141], v[50:51] op_sel_hi:[0,1]
	v_pk_mul_f32 v[48:49], v[140:141], v[48:49] op_sel_hi:[0,1]
	v_pk_mul_f32 v[46:47], v[140:141], v[46:47] op_sel_hi:[0,1]
	v_pk_mul_f32 v[44:45], v[140:141], v[44:45] op_sel_hi:[0,1]
	v_pk_mul_f32 v[42:43], v[140:141], v[42:43] op_sel_hi:[0,1]
	v_pk_mul_f32 v[40:41], v[140:141], v[40:41] op_sel_hi:[0,1]
	v_pk_mul_f32 v[38:39], v[140:141], v[38:39] op_sel_hi:[0,1]
	v_pk_mul_f32 v[36:37], v[140:141], v[36:37] op_sel_hi:[0,1]
	v_pk_mul_f32 v[34:35], v[140:141], v[34:35] op_sel_hi:[0,1]
	v_pk_mul_f32 v[32:33], v[140:141], v[32:33] op_sel_hi:[0,1]
	v_pk_mul_f32 v[30:31], v[140:141], v[30:31] op_sel_hi:[0,1]
	v_pk_mul_f32 v[28:29], v[140:141], v[28:29] op_sel_hi:[0,1]
	v_pk_mul_f32 v[26:27], v[140:141], v[26:27] op_sel_hi:[0,1]
	v_pk_mul_f32 v[24:25], v[140:141], v[24:25] op_sel_hi:[0,1]
	v_pk_mul_f32 v[22:23], v[140:141], v[22:23] op_sel_hi:[0,1]
	v_pk_mul_f32 v[20:21], v[140:141], v[20:21] op_sel_hi:[0,1]
	v_pk_mul_f32 v[18:19], v[140:141], v[18:19] op_sel_hi:[0,1]
	v_pk_mul_f32 v[16:17], v[140:141], v[16:17] op_sel_hi:[0,1]

.LBB0_844:
	s_or_b32 s8, s35, 1
	s_sub_i32 s1, s8, s35
	v_lshl_or_b32 v101, s1, 6, v232
	v_or_b32_e32 v102, 32, v101
	v_cmp_le_i32_e32 vcc, v102, v236
	s_lshl_b32 s0, s34, 16
	s_and_b32 s0, s0, 0x10000
	v_cndmask_b32_e32 v102, v226, v80, vcc
	v_cmp_le_i32_e32 vcc, v101, v236
	s_add_i32 s9, s0, 0
	s_nop 0
	v_cndmask_b32_e32 v104, v226, v64, vcc
	v_cmp_lt_i32_e32 vcc, v101, v236
	v_or_b32_e32 v64, 33, v101
	s_nop 0
	v_cndmask_b32_e32 v105, v226, v65, vcc
	v_cmp_le_i32_e32 vcc, v64, v236
	v_or_b32_e32 v64, 2, v101
	s_nop 0
	v_cndmask_b32_e32 v103, v226, v81, vcc
	v_cmp_le_i32_e32 vcc, v64, v236
	v_or_b32_e32 v64, 34, v101
	s_nop 0
	v_cndmask_b32_e32 v106, v226, v66, vcc
	v_cmp_le_i32_e32 vcc, v64, v236
	v_or_b32_e32 v64, 3, v101
	s_nop 0
	v_cndmask_b32_e32 v108, v226, v82, vcc
	v_cmp_le_i32_e32 vcc, v64, v236
	v_or_b32_e32 v64, 35, v101
	v_max3_f32 v66, v102, v103, v108
	s_nop 0
	v_cndmask_b32_e32 v107, v226, v67, vcc
	v_cmp_le_i32_e32 vcc, v64, v236
	v_or_b32_e32 v64, 8, v101
	s_nop 0
	v_cndmask_b32_e32 v109, v226, v83, vcc
	v_cmp_le_i32_e32 vcc, v64, v236
	v_or_b32_e32 v64, 40, v101
	s_nop 0
	v_cndmask_b32_e32 v110, v226, v68, vcc
	v_cmp_le_i32_e32 vcc, v64, v236
	v_or_b32_e32 v64, 9, v101
	s_nop 0
	v_cndmask_b32_e32 v112, v226, v84, vcc
	v_cmp_le_i32_e32 vcc, v64, v236
	v_or_b32_e32 v64, 41, v101
	v_max3_f32 v66, v66, v109, v112
	s_nop 0
	v_cndmask_b32_e32 v111, v226, v69, vcc
	v_cmp_le_i32_e32 vcc, v64, v236
	v_or_b32_e32 v64, 10, v101
	s_nop 0
	v_cndmask_b32_e32 v113, v226, v85, vcc
	v_cmp_le_i32_e32 vcc, v64, v236
	v_or_b32_e32 v64, 42, v101
	s_nop 0
	v_cndmask_b32_e32 v114, v226, v70, vcc
	v_cmp_le_i32_e32 vcc, v64, v236
	v_or_b32_e32 v64, 11, v101
	s_nop 0
	v_cndmask_b32_e32 v116, v226, v86, vcc
	v_cmp_le_i32_e32 vcc, v64, v236
	v_or_b32_e32 v64, 43, v101
	v_max3_f32 v66, v66, v113, v116
	s_nop 0
	v_cndmask_b32_e32 v115, v226, v71, vcc
	v_cmp_le_i32_e32 vcc, v64, v236
	v_or_b32_e32 v64, 16, v101
	s_nop 0
	v_cndmask_b32_e32 v117, v226, v87, vcc
	v_cmp_le_i32_e32 vcc, v64, v236
	v_or_b32_e32 v64, 48, v101
	s_nop 0
	v_cndmask_b32_e32 v118, v226, v72, vcc
	v_cmp_le_i32_e32 vcc, v64, v236
	v_or_b32_e32 v64, 17, v101
	s_nop 0
	v_cndmask_b32_e32 v120, v226, v88, vcc
	v_cmp_le_i32_e32 vcc, v64, v236
	v_or_b32_e32 v64, 49, v101
	s_nop 0
	v_cndmask_b32_e32 v119, v226, v73, vcc
	v_cmp_le_i32_e32 vcc, v64, v236
	v_or_b32_e32 v64, 18, v101
	s_nop 0
	v_cndmask_b32_e32 v121, v226, v89, vcc
	v_cmp_le_i32_e32 vcc, v64, v236
	v_or_b32_e32 v64, 50, v101
	s_nop 0
	v_cndmask_b32_e32 v122, v226, v74, vcc
	v_cmp_le_i32_e32 vcc, v64, v236
	v_or_b32_e32 v64, 19, v101
	v_max3_f32 v65, v118, v119, v122
	s_nop 0
	v_cndmask_b32_e32 v90, v226, v90, vcc
	v_cmp_le_i32_e32 vcc, v64, v236
	v_or_b32_e32 v64, 51, v101
	v_max3_f32 v67, v120, v121, v90
	s_nop 0
	v_cndmask_b32_e32 v123, v226, v75, vcc
	v_cmp_le_i32_e32 vcc, v64, v236
	v_or_b32_e32 v64, 24, v101
	s_nop 0
	v_cndmask_b32_e32 v91, v226, v91, vcc
	v_cmp_le_i32_e32 vcc, v64, v236
	v_or_b32_e32 v64, 56, v101
	s_nop 0
	v_cndmask_b32_e32 v124, v226, v76, vcc
	v_cmp_le_i32_e32 vcc, v64, v236
	v_or_b32_e32 v64, 25, v101
	v_max3_f32 v65, v65, v123, v124
	s_nop 0
	v_cndmask_b32_e32 v92, v226, v92, vcc
	v_cmp_le_i32_e32 vcc, v64, v236
	v_or_b32_e32 v64, 57, v101
	v_max3_f32 v67, v67, v91, v92
	s_nop 0
	v_cndmask_b32_e32 v125, v226, v77, vcc
	v_cmp_le_i32_e32 vcc, v64, v236
	v_or_b32_e32 v64, 26, v101
	s_nop 0
	v_cndmask_b32_e32 v93, v226, v93, vcc
	v_cmp_le_i32_e32 vcc, v64, v236
	v_or_b32_e32 v64, 58, v101
	s_nop 0
	v_cndmask_b32_e32 v126, v226, v78, vcc
	v_cmp_le_i32_e32 vcc, v64, v236
	v_or_b32_e32 v64, 27, v101
	v_max3_f32 v65, v65, v125, v126
	s_nop 0
	v_cndmask_b32_e32 v94, v226, v94, vcc
	v_cmp_le_i32_e32 vcc, v64, v236
	v_or_b32_e32 v64, 59, v101
	v_max3_f32 v67, v67, v93, v94
	s_nop 0
	v_cndmask_b32_e32 v127, v226, v79, vcc
	v_cmp_le_i32_e32 vcc, v64, v236
	v_max3_f32 v64, v104, v105, v106
	s_nop 0
	v_max3_f32 v64, v64, v107, v110
	s_nop 0
	v_max3_f32 v64, v64, v111, v114
	v_cndmask_b32_e32 v95, v226, v95, vcc
	v_max3_f32 v64, v64, v115, v65
	v_max3_f32 v65, v66, v117, v67
	v_max_f32_e32 v66, v212, v212
	v_max3_f32 v64, v64, v127, v95
	s_nop 0
	v_max3_f32 v64, v64, v65, v65
	s_nop 0
	v_mov_b32_e32 v65, v64
	s_nop 1
	v_permlane32_swap_b32_e32 v64, v65
	v_max3_f32 v65, v64, v65, v65
	s_nop 0
	v_max_f32_e32 v64, v65, v65
	v_max_f32_e32 v101, v66, v64
	v_sub_f32_e32 v64, v212, v101
	v_exp_f32_e32 v64, v64
	v_add_f32_e32 v66, 0x41000000, v212
	v_cmp_gt_f32_e32 vcc, v65, v66
	s_cmp_eq_u64 vcc, 0
	v_mul_f32_e32 v65, v100, v64
	s_cselect_b64 s[0:1], -1, 0
	v_cndmask_b32_e64 v65, v65, v100, s[0:1]
	v_add_u32_e32 v128, s9, v227
	v_add_u32_e32 v74, v128, v228
	ds_read_b128 v[66:69], v74 offset:16384
	ds_read_b128 v[70:73], v74 offset:20480
	v_add_u32_e32 v86, v128, v231
	v_cndmask_b32_e64 v100, v101, v212, s[0:1]
	v_mov_b32_e32 v101, v100
	s_waitcnt lgkmcnt(1)
	v_mfma_f32_32x32x16_bf16 v[0:15], v[66:69], v[96:99], v[0:15]
	ds_read_b128 v[66:69], v74 offset:24576
	ds_read_b128 v[74:77], v74 offset:28672
	v_sub_f32_e32 v104, v104, v100
	v_sub_f32_e32 v105, v105, v101
	v_sub_f32_e32 v90, v90, v100
	v_sub_f32_e32 v91, v91, v101
	v_sub_f32_e32 v92, v92, v100
	v_sub_f32_e32 v93, v93, v101
	v_sub_f32_e32 v94, v94, v100
	v_sub_f32_e32 v95, v95, v101
	s_nop 0
	v_exp_f32_e32 v94, v94
	s_waitcnt lgkmcnt(2)
	v_mfma_f32_32x32x16_bf16 v[48:63], v[70:73], v[96:99], v[48:63]
	ds_read_b128 v[70:73], v86 offset:16384
	ds_read_b128 v[78:81], v86 offset:20480
	ds_read_b128 v[82:85], v86 offset:24576
	ds_read_b128 v[86:89], v86 offset:28672
	v_exp_f32_e32 v95, v95
	s_waitcnt lgkmcnt(5)
	v_mfma_f32_32x32x16_bf16 v[32:47], v[66:69], v[96:99], v[32:47]
	v_sub_f32_e32 v66, v102, v100
	v_sub_f32_e32 v67, v103, v101
	v_sub_f32_e32 v68, v106, v100
	v_sub_f32_e32 v69, v107, v101
	v_sub_f32_e32 v102, v108, v100
	v_sub_f32_e32 v103, v109, v101
	v_sub_f32_e32 v106, v110, v100
	v_sub_f32_e32 v107, v111, v101
	v_sub_f32_e32 v108, v112, v100
	v_sub_f32_e32 v109, v113, v101
	v_sub_f32_e32 v110, v114, v100
	v_sub_f32_e32 v111, v115, v101
	v_sub_f32_e32 v112, v116, v100
	v_sub_f32_e32 v113, v117, v101
	s_waitcnt lgkmcnt(4)
	v_mfma_f32_32x32x16_bf16 v[16:31], v[74:77], v[96:99], v[16:31]
	v_sub_f32_e32 v74, v118, v100
	v_sub_f32_e32 v75, v119, v101
	v_add_u32_e32 v118, v128, v230
	v_sub_f32_e32 v76, v120, v100
	v_sub_f32_e32 v77, v121, v101
	v_sub_f32_e32 v96, v122, v100
	v_sub_f32_e32 v97, v123, v101
	v_sub_f32_e32 v98, v124, v100
	v_sub_f32_e32 v99, v125, v101
	v_sub_f32_e32 v114, v126, v100
	v_sub_f32_e32 v115, v127, v101
	v_exp_f32_e32 v100, v104
	v_exp_f32_e32 v104, v66
	v_exp_f32_e32 v101, v105
	v_exp_f32_e32 v105, v67
	v_exp_f32_e32 v116, v68
	v_exp_f32_e32 v117, v69
	ds_read_b128 v[66:69], v118 offset:16384
	s_waitcnt lgkmcnt(4)
	v_mfma_f32_32x32x16_bf16 v[0:15], v[70:73], v[184:187], v[0:15]
	ds_read_b128 v[70:73], v118 offset:20480
	v_exp_f32_e32 v102, v102
	v_exp_f32_e32 v103, v103
	v_exp_f32_e32 v112, v112
	v_exp_f32_e32 v113, v113
	v_exp_f32_e32 v74, v74
	v_exp_f32_e32 v76, v76
	s_waitcnt lgkmcnt(4)
	v_mfma_f32_32x32x16_bf16 v[48:63], v[78:81], v[184:187], v[48:63]
	v_exp_f32_e32 v78, v106
	v_exp_f32_e32 v80, v108
	v_exp_f32_e32 v79, v107
	v_exp_f32_e32 v81, v109
	v_exp_f32_e32 v106, v110
	v_exp_f32_e32 v107, v111
	v_exp_f32_e32 v75, v75
	s_waitcnt lgkmcnt(1)
	v_mfma_f32_32x32x16_bf16 v[0:15], v[66:69], v[180:183], v[0:15]
	ds_read_b128 v[66:69], v118 offset:24576
	v_exp_f32_e32 v77, v77
	v_add_f32_e32 v108, v106, v112
	v_add_f32_e32 v109, v107, v113
	v_add_f32_e32 v110, v74, v76
	v_add_f32_e32 v111, v75, v77
	v_mfma_f32_32x32x16_bf16 v[32:47], v[82:85], v[184:187], v[32:47]
	v_exp_f32_e32 v82, v96
	v_exp_f32_e32 v84, v90
	v_exp_f32_e32 v83, v97
	v_exp_f32_e32 v85, v91
	v_exp_f32_e32 v90, v114
	v_exp_f32_e32 v91, v115
	v_add_f32_e32 v96, v116, v102
	v_add_f32_e32 v97, v117, v103
	s_waitcnt lgkmcnt(1)
	v_mfma_f32_32x32x16_bf16 v[48:63], v[70:73], v[180:183], v[48:63]
	ds_read_b128 v[70:73], v118 offset:28672
	v_add_f32_e64 v114, v78, v80
	v_add_f32_e64 v115, v79, v81
	v_add_u32_e32 v118, v128, v229
	v_mfma_f32_32x32x16_bf16 v[16:31], v[86:89], v[184:187], v[16:31]
	v_exp_f32_e32 v86, v98
	v_exp_f32_e32 v88, v92
	v_exp_f32_e32 v87, v99
	v_exp_f32_e32 v89, v93
	v_add_f32_e32 v92, v82, v84
	v_add_f32_e32 v93, v83, v85
	v_add_f32_e32 v98, v90, v94
	v_add_f32_e32 v99, v91, v95
	s_waitcnt lgkmcnt(1)
	v_mfma_f32_32x32x16_bf16 v[32:47], v[66:69], v[180:183], v[32:47]
	v_add_f32_e64 v66, v100, v104
	v_add_f32_e64 v67, v101, v105
	v_add_f32_e64 v68, v86, v88
	v_add_f32_e64 v69, v87, v89
	v_add_f32_e64 v110, v66, v110
	v_add_f32_e64 v111, v67, v111
	v_add_f32_e32 v114, v114, v68
	v_add_f32_e32 v115, v115, v69
	ds_read_b128 v[66:69], v118 offset:16384
	s_waitcnt lgkmcnt(1)
	v_mfma_f32_32x32x16_bf16 v[16:31], v[70:73], v[180:183], v[16:31]
	v_add_f32_e64 v70, v108, v98
	v_add_f32_e64 v71, v109, v99
	v_add_f32_e64 v72, v96, v92
	v_add_f32_e64 v73, v97, v93
	v_cvt_pk_bf16_f32 v108, v100, v101
	v_add_f32_e32 v70, v72, v70
	v_add_f32_e32 v71, v73, v71
	v_add_f32_e32 v72, v110, v114
	v_add_f32_e32 v73, v111, v115
	v_add_f32_e32 v93, v70, v71
	v_add_f32_e32 v92, v72, v73
	ds_read_b128 v[70:73], v118 offset:20480
	s_waitcnt lgkmcnt(1)
	v_mfma_f32_32x32x16_bf16 v[0:15], v[66:69], v[176:179], v[0:15]
	ds_read_b128 v[66:69], v118 offset:24576
	v_add_f32_e32 v92, v92, v93
	v_cvt_pk_bf16_f32 v109, v116, v117
	v_cvt_pk_bf16_f32 v110, v78, v79
	v_cvt_pk_bf16_f32 v111, v106, v107
	v_cvt_pk_bf16_f32 v100, v104, v105
	v_cvt_pk_bf16_f32 v101, v102, v103
	s_waitcnt lgkmcnt(1)
	v_mfma_f32_32x32x16_bf16 v[48:63], v[70:73], v[176:179], v[48:63]
	ds_read_b128 v[70:73], v118 offset:28672
	v_cvt_pk_bf16_f32 v102, v80, v81
	v_cvt_pk_bf16_f32 v103, v112, v113
	v_cvt_pk_bf16_f32 v104, v74, v75
	v_cvt_pk_bf16_f32 v105, v82, v83
	v_cvt_pk_bf16_f32 v106, v86, v87
	v_cvt_pk_bf16_f32 v107, v90, v91
	s_waitcnt lgkmcnt(1)
	v_mfma_f32_32x32x16_bf16 v[32:47], v[66:69], v[176:179], v[32:47]
	v_cvt_pk_bf16_f32 v96, v76, v77
	v_cvt_pk_bf16_f32 v97, v84, v85
	v_cvt_pk_bf16_f32 v98, v88, v89
	v_cvt_pk_bf16_f32 v99, v94, v95
	v_add_f32_e32 v112, v65, v92
	s_waitcnt lgkmcnt(0)
	v_mfma_f32_32x32x16_bf16 v[16:31], v[70:73], v[176:179], v[16:31]
	s_cbranch_vccz .LBB0_846
	v_pk_mul_f32 v[14:15], v[64:65], v[14:15] op_sel_hi:[0,1]
	v_pk_mul_f32 v[12:13], v[64:65], v[12:13] op_sel_hi:[0,1]
	v_pk_mul_f32 v[10:11], v[64:65], v[10:11] op_sel_hi:[0,1]
	v_pk_mul_f32 v[8:9], v[64:65], v[8:9] op_sel_hi:[0,1]
	v_pk_mul_f32 v[6:7], v[64:65], v[6:7] op_sel_hi:[0,1]
	v_pk_mul_f32 v[4:5], v[64:65], v[4:5] op_sel_hi:[0,1]
	v_pk_mul_f32 v[2:3], v[64:65], v[2:3] op_sel_hi:[0,1]
	v_pk_mul_f32 v[0:1], v[64:65], v[0:1] op_sel_hi:[0,1]
	v_pk_mul_f32 v[62:63], v[64:65], v[62:63] op_sel_hi:[0,1]
	v_pk_mul_f32 v[60:61], v[64:65], v[60:61] op_sel_hi:[0,1]
	v_pk_mul_f32 v[58:59], v[64:65], v[58:59] op_sel_hi:[0,1]
	v_pk_mul_f32 v[56:57], v[64:65], v[56:57] op_sel_hi:[0,1]
	v_pk_mul_f32 v[54:55], v[64:65], v[54:55] op_sel_hi:[0,1]
	v_pk_mul_f32 v[52:53], v[64:65], v[52:53] op_sel_hi:[0,1]
	v_pk_mul_f32 v[50:51], v[64:65], v[50:51] op_sel_hi:[0,1]
	v_pk_mul_f32 v[48:49], v[64:65], v[48:49] op_sel_hi:[0,1]
	v_pk_mul_f32 v[46:47], v[64:65], v[46:47] op_sel_hi:[0,1]
	v_pk_mul_f32 v[44:45], v[64:65], v[44:45] op_sel_hi:[0,1]
	v_pk_mul_f32 v[42:43], v[64:65], v[42:43] op_sel_hi:[0,1]
	v_pk_mul_f32 v[40:41], v[64:65], v[40:41] op_sel_hi:[0,1]
	v_pk_mul_f32 v[38:39], v[64:65], v[38:39] op_sel_hi:[0,1]
	v_pk_mul_f32 v[36:37], v[64:65], v[36:37] op_sel_hi:[0,1]
	v_pk_mul_f32 v[34:35], v[64:65], v[34:35] op_sel_hi:[0,1]
	v_pk_mul_f32 v[32:33], v[64:65], v[32:33] op_sel_hi:[0,1]
	v_pk_mul_f32 v[30:31], v[64:65], v[30:31] op_sel_hi:[0,1]
	v_pk_mul_f32 v[28:29], v[64:65], v[28:29] op_sel_hi:[0,1]
	v_pk_mul_f32 v[26:27], v[64:65], v[26:27] op_sel_hi:[0,1]
	v_pk_mul_f32 v[24:25], v[64:65], v[24:25] op_sel_hi:[0,1]
	v_pk_mul_f32 v[22:23], v[64:65], v[22:23] op_sel_hi:[0,1]
	v_pk_mul_f32 v[20:21], v[64:65], v[20:21] op_sel_hi:[0,1]
	v_pk_mul_f32 v[18:19], v[64:65], v[18:19] op_sel_hi:[0,1]
	v_pk_mul_f32 v[16:17], v[64:65], v[16:17] op_sel_hi:[0,1]

.LBB0_848:
	s_lshl_b32 s1, s8, 15
	s_and_b32 s1, s1, 0x18000
	s_add_i32 s1, s1, 0
	v_add_u32_e32 v118, s1, v227
	v_add_u32_e32 v119, v118, v228
	ds_read_b128 v[114:117], v119 offset:16384
	v_readlane_b32 s1, v254, 40
	s_waitcnt lgkmcnt(0)
	v_mfma_f32_32x32x16_bf16 v[0:15], v[114:117], v[108:111], v[0:15]
	ds_read_b128 v[114:117], v119 offset:20480
	s_waitcnt lgkmcnt(0)
	v_mfma_f32_32x32x16_bf16 v[48:63], v[114:117], v[108:111], v[48:63]
	ds_read_b128 v[114:117], v119 offset:24576
	s_waitcnt lgkmcnt(0)
	v_mfma_f32_32x32x16_bf16 v[32:47], v[114:117], v[108:111], v[32:47]
	ds_read_b128 v[114:117], v119 offset:28672
	v_add_u32_e32 v119, v118, v231
	s_waitcnt lgkmcnt(0)
	v_mfma_f32_32x32x16_bf16 v[16:31], v[114:117], v[108:111], v[16:31]
	ds_read_b128 v[108:111], v119 offset:16384
	v_and_b32_e32 v116, 64, v224
	v_add_u32_e32 v114, v118, v229
	v_xor_b32_e32 v115, 32, v224
	v_add_u32_e32 v116, 64, v116
	v_cmp_lt_i32_e32 vcc, v115, v116
	s_waitcnt lgkmcnt(0)
	v_mfma_f32_32x32x16_bf16 v[0:15], v[108:111], v[104:107], v[0:15]
	ds_read_b128 v[108:111], v119 offset:20480
	v_cndmask_b32_e32 v115, v224, v115, vcc
	v_lshlrev_b32_e32 v227, 2, v115
	s_waitcnt lgkmcnt(0)
	v_mfma_f32_32x32x16_bf16 v[48:63], v[108:111], v[104:107], v[48:63]
	ds_read_b128 v[108:111], v119 offset:24576
	s_waitcnt lgkmcnt(0)
	v_mfma_f32_32x32x16_bf16 v[32:47], v[108:111], v[104:107], v[32:47]
	ds_read_b128 v[108:111], v119 offset:28672
	s_waitcnt lgkmcnt(0)
	v_mfma_f32_32x32x16_bf16 v[16:31], v[108:111], v[104:107], v[16:31]
	v_add_u32_e32 v108, v118, v230
	ds_read_b128 v[104:107], v108 offset:16384
	ds_bpermute_b32 v118, v227, v112
	s_waitcnt lgkmcnt(0)
	v_add_f32_e32 v112, v112, v118
	v_mfma_f32_32x32x16_bf16 v[0:15], v[104:107], v[100:103], v[0:15]
	ds_read_b128 v[104:107], v108 offset:20480
	s_waitcnt lgkmcnt(0)
	v_mfma_f32_32x32x16_bf16 v[48:63], v[104:107], v[100:103], v[48:63]
	ds_read_b128 v[104:107], v108 offset:24576
	ds_read_b128 v[108:111], v108 offset:28672
	s_waitcnt lgkmcnt(1)
	v_mfma_f32_32x32x16_bf16 v[32:47], v[104:107], v[100:103], v[32:47]
	ds_read_b128 v[104:107], v114 offset:16384
	s_waitcnt lgkmcnt(1)
	v_mfma_f32_32x32x16_bf16 v[16:31], v[108:111], v[100:103], v[16:31]
	ds_read_b128 v[100:103], v114 offset:20480
	ds_read_b128 v[108:111], v114 offset:24576
	ds_read_b128 v[114:117], v114 offset:28672
	s_waitcnt lgkmcnt(0)
	s_barrier
	v_mfma_f32_32x32x16_bf16 v[0:15], v[104:107], v[96:99], v[0:15]
	v_rcp_f32_e32 v105, v112
	v_readlane_b32 s8, v254, 41
	v_readlane_b32 s9, v254, 42
	v_mfma_f32_32x32x16_bf16 v[48:63], v[100:103], v[96:99], v[48:63]
	v_mfma_f32_32x32x16_bf16 v[32:47], v[108:111], v[96:99], v[32:47]
	v_mul_f32_e32 v100, 1.0, v105
	v_mov_b32_e32 v112, v100
	v_cndmask_b32_e64 v100, 0, 1, s[8:9]
	v_cmp_ne_u32_e64 s[40:41], 1, v100
	v_lshlrev_b32_e32 v100, 9, v215
	v_lshlrev_b32_e32 v101, 2, v214
	s_andn2_b64 vcc, exec, s[8:9]
	v_mfma_f32_32x32x16_bf16 v[16:31], v[114:117], v[96:99], v[16:31]
	v_add3_u32 v100, s1, v100, v101
	s_cbranch_vccnz .LBB0_850
	v_mul_f32_e32 v96, v0, v112
	v_mul_f32_e32 v97, v1, v112
	ds_write2_b32 v100, v96, v97 offset1:32
	v_mul_f32_e32 v96, v2, v112
	v_mul_f32_e32 v97, v3, v112
	ds_write2_b32 v100, v96, v97 offset0:64 offset1:96
	v_mul_f32_e32 v96, v4, v112
	v_mul_f32_e32 v97, v5, v112
	v_add_u32_e32 v98, 0x400, v100
	ds_write2_b32 v98, v96, v97 offset1:32
	v_mul_f32_e32 v96, v6, v112
	v_mul_f32_e32 v97, v7, v112
	ds_write2_b32 v98, v96, v97 offset0:64 offset1:96
	v_mul_f32_e32 v96, v8, v112
	v_mul_f32_e32 v97, v9, v112
	v_add_u32_e32 v98, 0x800, v100
	ds_write2_b32 v98, v96, v97 offset1:32
	v_mul_f32_e32 v96, v10, v112
	v_mul_f32_e32 v97, v11, v112
	ds_write2_b32 v98, v96, v97 offset0:64 offset1:96
	v_mul_f32_e32 v96, v12, v112
	v_mul_f32_e32 v97, v13, v112
	v_add_u32_e32 v98, 0xc00, v100
	ds_write2_b32 v98, v96, v97 offset1:32
	v_mul_f32_e32 v96, v14, v112
	v_mul_f32_e32 v97, v15, v112
	ds_write2_b32 v98, v96, v97 offset0:64 offset1:96
	v_mul_f32_e32 v96, v48, v112
	v_mul_f32_e32 v97, v49, v112
	v_add_u32_e32 v98, 0x1000, v100
	ds_write2_b32 v98, v96, v97 offset1:32
	v_mul_f32_e32 v96, v50, v112
	v_mul_f32_e32 v97, v51, v112
	ds_write2_b32 v98, v96, v97 offset0:64 offset1:96
	v_mul_f32_e32 v96, v52, v112
	v_mul_f32_e32 v97, v53, v112
	v_add_u32_e32 v98, 0x1400, v100
	ds_write2_b32 v98, v96, v97 offset1:32
	v_mul_f32_e32 v96, v54, v112
	v_mul_f32_e32 v97, v55, v112
	ds_write2_b32 v98, v96, v97 offset0:64 offset1:96
	v_mul_f32_e32 v96, v56, v112
	v_mul_f32_e32 v97, v57, v112
	v_add_u32_e32 v98, 0x1800, v100
	ds_write2_b32 v98, v96, v97 offset1:32
	v_mul_f32_e32 v96, v58, v112
	v_mul_f32_e32 v97, v59, v112
	ds_write2_b32 v98, v96, v97 offset0:64 offset1:96
	v_mul_f32_e32 v96, v60, v112
	v_mul_f32_e32 v97, v61, v112
	v_add_u32_e32 v98, 0x1c00, v100
	ds_write2_b32 v98, v96, v97 offset1:32
	v_mul_f32_e32 v96, v62, v112
	v_mul_f32_e32 v97, v63, v112
	ds_write2_b32 v98, v96, v97 offset0:64 offset1:96
	v_mul_f32_e32 v96, v32, v112
	v_mul_f32_e32 v97, v33, v112
	v_add_u32_e32 v98, 0x2000, v100
	ds_write2_b32 v98, v96, v97 offset1:32
	v_mul_f32_e32 v96, v34, v112
	v_mul_f32_e32 v97, v35, v112
	ds_write2_b32 v98, v96, v97 offset0:64 offset1:96
	v_mul_f32_e32 v96, v36, v112
	v_mul_f32_e32 v97, v37, v112
	v_add_u32_e32 v98, 0x2400, v100
	ds_write2_b32 v98, v96, v97 offset1:32
	v_mul_f32_e32 v96, v38, v112
	v_mul_f32_e32 v97, v39, v112
	ds_write2_b32 v98, v96, v97 offset0:64 offset1:96
	v_mul_f32_e32 v96, v40, v112
	v_mul_f32_e32 v97, v41, v112
	v_add_u32_e32 v98, 0x2800, v100
	ds_write2_b32 v98, v96, v97 offset1:32
	v_mul_f32_e32 v96, v42, v112
	v_mul_f32_e32 v97, v43, v112
	ds_write2_b32 v98, v96, v97 offset0:64 offset1:96
	v_mul_f32_e32 v96, v44, v112
	v_mul_f32_e32 v97, v45, v112
	v_add_u32_e32 v98, 0x2c00, v100
	ds_write2_b32 v98, v96, v97 offset1:32
	v_mul_f32_e32 v96, v46, v112
	v_mul_f32_e32 v97, v47, v112
	ds_write2_b32 v98, v96, v97 offset0:64 offset1:96
	v_mul_f32_e32 v96, v16, v112
	v_mul_f32_e32 v97, v17, v112
	v_add_u32_e32 v98, 0x3000, v100
	ds_write2_b32 v98, v96, v97 offset1:32
	v_mul_f32_e32 v96, v18, v112
	v_mul_f32_e32 v97, v19, v112
	ds_write2_b32 v98, v96, v97 offset0:64 offset1:96
	v_mul_f32_e32 v96, v20, v112
	v_mul_f32_e32 v97, v21, v112
	v_add_u32_e32 v98, 0x3400, v100
	ds_write2_b32 v98, v96, v97 offset1:32
	v_mul_f32_e32 v96, v22, v112
	v_mul_f32_e32 v97, v23, v112
	ds_write2_b32 v98, v96, v97 offset0:64 offset1:96
	v_mul_f32_e32 v96, v24, v112
	v_mul_f32_e32 v97, v25, v112
	v_add_u32_e32 v98, 0x3800, v100
	ds_write2_b32 v98, v96, v97 offset1:32
	v_mul_f32_e32 v96, v26, v112
	v_mul_f32_e32 v97, v27, v112
	ds_write2_b32 v98, v96, v97 offset0:64 offset1:96
	v_mul_f32_e32 v96, v28, v112
	v_mul_f32_e32 v97, v29, v112
	v_add_u32_e32 v98, 0x3c00, v100
	ds_write2_b32 v98, v96, v97 offset1:32
	v_mul_f32_e32 v96, v30, v112
	v_mul_f32_e32 v97, v31, v112
	ds_write2_b32 v98, v96, v97 offset0:64 offset1:96
.LBB0_850:
	s_and_b64 vcc, exec, s[38:39]
	s_waitcnt lgkmcnt(0)
	s_barrier
	s_cbranch_vccnz .LBB0_852
	v_add_u32_e32 v101, 0x400, v100
	ds_read2_b32 v[96:97], v100 offset1:32
	ds_read2_b32 v[98:99], v100 offset0:64 offset1:96
	ds_read2_b32 v[104:105], v101 offset1:32
	ds_read2_b32 v[106:107], v101 offset0:64 offset1:96
	v_add_u32_e32 v101, 0x800, v100
	ds_read2_b32 v[114:115], v101 offset1:32
	ds_read2_b32 v[116:117], v101 offset0:64 offset1:96
	v_add_u32_e32 v101, 0xc00, v100
	ds_read2_b32 v[118:119], v101 offset1:32
	ds_read2_b32 v[120:121], v101 offset0:64 offset1:96
	v_add_u32_e32 v101, 0x1000, v100
	ds_read2_b32 v[122:123], v101 offset1:32
	ds_read2_b32 v[124:125], v101 offset0:64 offset1:96
	v_add_u32_e32 v101, 0x1400, v100
	ds_read2_b32 v[158:159], v101 offset1:32
	ds_read2_b32 v[160:161], v101 offset0:64 offset1:96
	v_add_u32_e32 v101, 0x1800, v100
	ds_read2_b32 v[162:163], v101 offset1:32
	ds_read2_b32 v[164:165], v101 offset0:64 offset1:96
	v_add_u32_e32 v101, 0x1c00, v100
	ds_read2_b32 v[166:167], v101 offset1:32
	ds_read2_b32 v[168:169], v101 offset0:64 offset1:96
	v_add_u32_e32 v101, 0x2000, v100
	ds_read2_b32 v[170:171], v101 offset1:32
	ds_read2_b32 v[172:173], v101 offset0:64 offset1:96
	v_add_u32_e32 v101, 0x2400, v100
	ds_read2_b32 v[174:175], v101 offset1:32
	ds_read2_b32 v[176:177], v101 offset0:64 offset1:96
	v_add_u32_e32 v101, 0x2800, v100
	ds_read2_b32 v[178:179], v101 offset1:32
	ds_read2_b32 v[180:181], v101 offset0:64 offset1:96
	v_add_u32_e32 v101, 0x2c00, v100
	ds_read2_b32 v[154:155], v101 offset1:32
	ds_read2_b32 v[182:183], v101 offset0:64 offset1:96
	v_add_u32_e32 v101, 0x3000, v100
	ds_read2_b32 v[148:149], v101 offset1:32
	ds_read2_b32 v[152:153], v101 offset0:64 offset1:96
	v_add_u32_e32 v101, 0x3400, v100
	ds_read2_b32 v[144:145], v101 offset1:32
	ds_read2_b32 v[146:147], v101 offset0:64 offset1:96
	v_add_u32_e32 v101, 0x3c00, v100
	ds_read2_b32 v[102:103], v101 offset1:32
	v_add_u32_e32 v108, 0x3800, v100
	ds_read2_b32 v[142:143], v108 offset1:32
	ds_read2_b32 v[100:101], v101 offset0:64 offset1:96
	ds_read2_b32 v[150:151], v108 offset0:64 offset1:96
	s_waitcnt lgkmcnt(12)
	v_pk_mul_f32 v[176:177], v[210:211], v[176:177]
	v_pk_mul_f32 v[174:175], v[210:211], v[174:175]
	s_waitcnt lgkmcnt(3)
	v_pk_mul_f32 v[102:103], v[210:211], v[102:103]
	v_pk_mul_f32 v[180:181], v[210:211], v[180:181]
	v_pk_fma_f32 v[108:109], v[28:29], v[112:113], v[102:103] op_sel_hi:[1,0,1] neg_lo:[0,0,1] neg_hi:[0,0,1]
	s_waitcnt lgkmcnt(1)
	v_pk_mul_f32 v[28:29], v[210:211], v[100:101]
	v_pk_mul_f32 v[178:179], v[210:211], v[178:179]
	v_pk_fma_f32 v[110:111], v[30:31], v[112:113], v[28:29] op_sel_hi:[1,0,1] neg_lo:[0,0,1] neg_hi:[0,0,1]
	v_pk_mul_f32 v[28:29], v[210:211], v[98:99]
	v_pk_mul_f32 v[182:183], v[210:211], v[182:183]
	v_pk_fma_f32 v[126:127], v[2:3], v[112:113], v[28:29] op_sel_hi:[1,0,1] neg_lo:[0,0,1] neg_hi:[0,0,1]
	v_pk_mul_f32 v[2:3], v[210:211], v[96:97]
	v_pk_mul_f32 v[154:155], v[210:211], v[154:155]
	v_pk_fma_f32 v[130:131], v[0:1], v[112:113], v[2:3] op_sel_hi:[1,0,1] neg_lo:[0,0,1] neg_hi:[0,0,1]
	v_pk_mul_f32 v[0:1], v[210:211], v[106:107]
	v_pk_mul_f32 v[186:187], v[130:131], v[130:131]
	v_pk_fma_f32 v[132:133], v[6:7], v[112:113], v[0:1] op_sel_hi:[1,0,1] neg_lo:[0,0,1] neg_hi:[0,0,1]
	v_pk_mul_f32 v[0:1], v[210:211], v[104:105]
	v_pk_mul_f32 v[152:153], v[210:211], v[152:153]
	v_pk_fma_f32 v[138:139], v[4:5], v[112:113], v[0:1] op_sel_hi:[1,0,1] neg_lo:[0,0,1] neg_hi:[0,0,1]
	v_pk_mul_f32 v[0:1], v[210:211], v[116:117]
	v_pk_mul_f32 v[4:5], v[210:211], v[120:121]
	v_pk_fma_f32 v[136:137], v[10:11], v[112:113], v[0:1] op_sel_hi:[1,0,1] neg_lo:[0,0,1] neg_hi:[0,0,1]
	v_pk_mul_f32 v[0:1], v[210:211], v[114:115]
	v_pk_fma_f32 v[114:115], v[14:15], v[112:113], v[4:5] op_sel_hi:[1,0,1] neg_lo:[0,0,1] neg_hi:[0,0,1]
	v_pk_mul_f32 v[4:5], v[210:211], v[118:119]
	v_pk_mul_f32 v[148:149], v[210:211], v[148:149]
	v_pk_fma_f32 v[116:117], v[12:13], v[112:113], v[4:5] op_sel_hi:[1,0,1] neg_lo:[0,0,1] neg_hi:[0,0,1]
	v_pk_mul_f32 v[4:5], v[210:211], v[124:125]
	v_pk_mul_f32 v[12:13], v[210:211], v[160:161]
	v_pk_fma_f32 v[118:119], v[50:51], v[112:113], v[4:5] op_sel_hi:[1,0,1] neg_lo:[0,0,1] neg_hi:[0,0,1]
	v_pk_mul_f32 v[4:5], v[210:211], v[122:123]
	v_pk_fma_f32 v[54:55], v[54:55], v[112:113], v[12:13] op_sel_hi:[1,0,1] neg_lo:[0,0,1] neg_hi:[0,0,1]
	v_pk_fma_f32 v[120:121], v[48:49], v[112:113], v[4:5] op_sel_hi:[1,0,1] neg_lo:[0,0,1] neg_hi:[0,0,1]
	v_pk_mul_f32 v[48:49], v[210:211], v[168:169]
	v_pk_mul_f32 v[12:13], v[210:211], v[158:159]
	v_pk_fma_f32 v[62:63], v[62:63], v[112:113], v[48:49] op_sel_hi:[1,0,1] neg_lo:[0,0,1] neg_hi:[0,0,1]
	v_pk_mul_f32 v[48:49], v[210:211], v[166:167]
	v_pk_fma_f32 v[52:53], v[52:53], v[112:113], v[12:13] op_sel_hi:[1,0,1] neg_lo:[0,0,1] neg_hi:[0,0,1]
	v_pk_mul_f32 v[12:13], v[210:211], v[164:165]
	v_pk_fma_f32 v[60:61], v[60:61], v[112:113], v[48:49] op_sel_hi:[1,0,1] neg_lo:[0,0,1] neg_hi:[0,0,1]
	v_pk_mul_f32 v[48:49], v[210:211], v[172:173]
	v_pk_fma_f32 v[58:59], v[58:59], v[112:113], v[12:13] op_sel_hi:[1,0,1] neg_lo:[0,0,1] neg_hi:[0,0,1]
	v_pk_mul_f32 v[12:13], v[210:211], v[162:163]
	v_pk_fma_f32 v[122:123], v[34:35], v[112:113], v[48:49] op_sel_hi:[1,0,1] neg_lo:[0,0,1] neg_hi:[0,0,1]
	v_pk_mul_f32 v[34:35], v[210:211], v[170:171]
	v_pk_mul_f32 v[146:147], v[210:211], v[146:147]
	v_pk_mul_f32 v[144:145], v[210:211], v[144:145]
	s_waitcnt lgkmcnt(0)
	v_pk_mul_f32 v[150:151], v[210:211], v[150:151]
	v_pk_mul_f32 v[142:143], v[210:211], v[142:143]
	v_lshlrev_b32_e32 v208, 2, v232
	v_pk_mul_f32 v[184:185], v[126:127], v[126:127]
	v_pk_fma_f32 v[140:141], v[8:9], v[112:113], v[0:1] op_sel_hi:[1,0,1] neg_lo:[0,0,1] neg_hi:[0,0,1]
	v_pk_fma_f32 v[56:57], v[56:57], v[112:113], v[12:13] op_sel_hi:[1,0,1] neg_lo:[0,0,1] neg_hi:[0,0,1]
	v_pk_fma_f32 v[124:125], v[32:33], v[112:113], v[34:35] op_sel_hi:[1,0,1] neg_lo:[0,0,1] neg_hi:[0,0,1]
	v_pk_fma_f32 v[38:39], v[38:39], v[112:113], v[176:177] op_sel_hi:[1,0,1] neg_lo:[0,0,1] neg_hi:[0,0,1]
	v_pk_fma_f32 v[36:37], v[36:37], v[112:113], v[174:175] op_sel_hi:[1,0,1] neg_lo:[0,0,1] neg_hi:[0,0,1]
	v_pk_fma_f32 v[42:43], v[42:43], v[112:113], v[180:181] op_sel_hi:[1,0,1] neg_lo:[0,0,1] neg_hi:[0,0,1]
	v_pk_fma_f32 v[40:41], v[40:41], v[112:113], v[178:179] op_sel_hi:[1,0,1] neg_lo:[0,0,1] neg_hi:[0,0,1]
	v_pk_fma_f32 v[46:47], v[46:47], v[112:113], v[182:183] op_sel_hi:[1,0,1] neg_lo:[0,0,1] neg_hi:[0,0,1]
	v_pk_fma_f32 v[44:45], v[44:45], v[112:113], v[154:155] op_sel_hi:[1,0,1] neg_lo:[0,0,1] neg_hi:[0,0,1]
	v_pk_fma_f32 v[18:19], v[18:19], v[112:113], v[152:153] op_sel_hi:[1,0,1] neg_lo:[0,0,1] neg_hi:[0,0,1]
	v_pk_fma_f32 v[16:17], v[16:17], v[112:113], v[148:149] op_sel_hi:[1,0,1] neg_lo:[0,0,1] neg_hi:[0,0,1]
	v_pk_fma_f32 v[22:23], v[22:23], v[112:113], v[146:147] op_sel_hi:[1,0,1] neg_lo:[0,0,1] neg_hi:[0,0,1]
	v_pk_fma_f32 v[20:21], v[20:21], v[112:113], v[144:145] op_sel_hi:[1,0,1] neg_lo:[0,0,1] neg_hi:[0,0,1]
	v_pk_fma_f32 v[26:27], v[26:27], v[112:113], v[150:151] op_sel_hi:[1,0,1] neg_lo:[0,0,1] neg_hi:[0,0,1]
	v_pk_fma_f32 v[24:25], v[24:25], v[112:113], v[142:143] op_sel_hi:[1,0,1] neg_lo:[0,0,1] neg_hi:[0,0,1]
	v_add_f32_e32 v112, v186, v187
	global_load_dwordx4 v[100:103], v208, s[36:37]
	global_load_dwordx4 v[96:99], v208, s[36:37] offset:32
	v_add_f32_e32 v112, v112, v184
	v_mul_u32_u24_e32 v157, 0x110, v214
	v_pk_mul_f32 v[214:215], v[138:139], v[138:139]
	v_add_f32_e32 v112, v112, v185
	v_add_f32_e32 v112, v112, v214
	v_pk_mul_f32 v[212:213], v[132:133], v[132:133]
	v_add_f32_e32 v112, v112, v215
	v_add_f32_e32 v112, v112, v212
	v_pk_mul_f32 v[230:231], v[140:141], v[140:141]
	v_add_f32_e32 v112, v112, v213
	global_load_dwordx4 v[104:107], v208, s[36:37] offset:64
	global_load_dwordx4 v[0:3], v208, s[36:37] offset:96
	v_add_f32_e32 v112, v112, v230
	v_pk_mul_f32 v[228:229], v[136:137], v[136:137]
	v_add_f32_e32 v112, v112, v231
	v_add_f32_e32 v112, v112, v228
	v_pk_mul_f32 v[236:237], v[116:117], v[116:117]
	v_add_f32_e32 v112, v112, v229
	v_add_f32_e32 v112, v112, v236
	v_pk_mul_f32 v[234:235], v[114:115], v[114:115]
	v_add_f32_e32 v112, v112, v237
	v_add_f32_e32 v112, v112, v234
	v_pk_mul_f32 v[240:241], v[120:121], v[120:121]
	v_add_f32_e32 v112, v112, v235
	v_add_f32_e32 v112, v112, v240
	v_pk_mul_f32 v[238:239], v[118:119], v[118:119]
	v_add_f32_e32 v112, v112, v241
	v_add_f32_e32 v112, v112, v238
	v_pk_mul_f32 v[158:159], v[52:53], v[52:53]
	v_add_f32_e32 v112, v112, v239
	v_add_f32_e32 v112, v112, v158
	v_pk_mul_f32 v[160:161], v[54:55], v[54:55]
	v_add_f32_e32 v112, v112, v159
	v_add_f32_e32 v112, v112, v160
	v_pk_mul_f32 v[162:163], v[56:57], v[56:57]
	v_add_f32_e32 v112, v112, v161
	v_add_f32_e32 v112, v112, v162
	v_pk_mul_f32 v[164:165], v[58:59], v[58:59]
	v_add_f32_e32 v112, v112, v163
	v_add_f32_e32 v112, v112, v164
	v_pk_mul_f32 v[166:167], v[60:61], v[60:61]
	v_add_f32_e32 v112, v112, v165
	v_add_f32_e32 v112, v112, v166
	v_pk_mul_f32 v[168:169], v[62:63], v[62:63]
	v_add_f32_e32 v112, v112, v167
	v_add_f32_e32 v112, v112, v168
	v_pk_mul_f32 v[170:171], v[124:125], v[124:125]
	v_add_f32_e32 v112, v112, v169
	v_add_f32_e32 v112, v112, v170
	v_pk_mul_f32 v[172:173], v[122:123], v[122:123]
	v_add_f32_e32 v112, v112, v171
	v_add_f32_e32 v112, v112, v172
	v_pk_mul_f32 v[174:175], v[36:37], v[36:37]
	v_add_f32_e32 v112, v112, v173
	v_add_f32_e32 v112, v112, v174
	v_pk_mul_f32 v[176:177], v[38:39], v[38:39]
	v_add_f32_e32 v112, v112, v175
	v_add_f32_e32 v112, v112, v176
	v_pk_mul_f32 v[178:179], v[40:41], v[40:41]
	v_add_f32_e32 v112, v112, v177
	v_add_f32_e32 v112, v112, v178
	v_pk_mul_f32 v[180:181], v[42:43], v[42:43]
	v_add_f32_e32 v112, v112, v179
	v_add_f32_e32 v112, v112, v180
	v_pk_mul_f32 v[154:155], v[44:45], v[44:45]
	v_add_f32_e32 v112, v112, v181
	v_add_f32_e32 v112, v112, v154
	v_pk_mul_f32 v[182:183], v[46:47], v[46:47]
	v_add_f32_e32 v112, v112, v155
	v_add_f32_e32 v112, v112, v182
	v_pk_mul_f32 v[148:149], v[16:17], v[16:17]
	v_add_f32_e32 v112, v112, v183
	v_add_f32_e32 v112, v112, v148
	v_pk_mul_f32 v[152:153], v[18:19], v[18:19]
	v_add_f32_e32 v112, v112, v149
	v_add_f32_e32 v112, v112, v152
	v_pk_mul_f32 v[144:145], v[20:21], v[20:21]
	v_add_f32_e32 v112, v112, v153
	v_add_f32_e32 v112, v112, v144
	v_pk_mul_f32 v[146:147], v[22:23], v[22:23]
	v_add_f32_e32 v112, v112, v145
	v_add_f32_e32 v112, v112, v146
	v_pk_mul_f32 v[142:143], v[24:25], v[24:25]
	v_add_f32_e32 v112, v112, v147
	v_add_f32_e32 v112, v112, v142
	v_pk_mul_f32 v[150:151], v[26:27], v[26:27]
	v_add_f32_e32 v112, v112, v143
	v_add_f32_e32 v112, v112, v150
	v_pk_mul_f32 v[128:129], v[108:109], v[108:109]
	v_add_f32_e32 v112, v112, v151
	v_add_f32_e32 v112, v112, v128
	v_pk_mul_f32 v[134:135], v[110:111], v[110:111]
	v_add_f32_e32 v112, v112, v129
	v_add_f32_e32 v112, v112, v134
	global_load_dwordx4 v[8:11], v208, s[36:37] offset:128
	global_load_dwordx4 v[4:7], v208, s[36:37] offset:160
	v_add_f32_e32 v112, v112, v135
	ds_bpermute_b32 v128, v227, v112
	global_load_dwordx4 v[28:31], v208, s[36:37] offset:192
	global_load_dwordx4 v[12:15], v208, s[36:37] offset:224
	global_load_dwordx4 v[48:51], v208, s[36:37] offset:256
	global_load_dwordx4 v[32:35], v208, s[36:37] offset:288
	v_lshlrev_b32_e32 v129, 1, v232
	v_readlane_b32 s7, v254, 43
	s_waitcnt lgkmcnt(0)
	v_add_f32_e32 v112, v112, v128
	v_fmamk_f32 v112, v112, 0x3c000000, v189
	v_mul_f32_e32 v128, 0x4b800000, v112
	v_cmp_gt_f32_e32 vcc, s13, v112
	global_load_dwordx4 v[142:145], v208, s[36:37] offset:320
	global_load_dwordx4 v[146:149], v208, s[36:37] offset:352
	v_cndmask_b32_e32 v112, v112, v128, vcc
	v_rsq_f32_e32 v112, v112
	v_add3_u32 v134, s7, v157, v129
	global_load_dwordx4 v[150:153], v208, s[36:37] offset:384
	global_load_dwordx4 v[158:161], v208, s[36:37] offset:416
	global_load_dwordx4 v[162:165], v208, s[36:37] offset:448
	s_lshl_b32 s1, s46, 1
	v_mul_f32_e32 v128, 0x45800000, v112
	v_cndmask_b32_e32 v112, v112, v128, vcc
	v_mul_f32_e32 v112, v209, v112
	v_pk_mul_f32 v[128:129], v[130:131], v[112:113] op_sel_hi:[1,0]
	v_pk_mul_f32 v[126:127], v[126:127], v[112:113] op_sel_hi:[1,0]
	s_waitcnt vmcnt(14)
	v_pk_mul_f32 v[100:101], v[100:101], v[128:129]
	v_pk_mul_f32 v[102:103], v[102:103], v[126:127]
	v_cvt_pk_bf16_f32 v100, v100, v101
	v_cvt_pk_bf16_f32 v101, v102, v103
	v_pk_mul_f32 v[102:103], v[138:139], v[112:113] op_sel_hi:[1,0]
	s_add_u32 s8, s82, s1
	s_waitcnt vmcnt(13)
	v_pk_mul_f32 v[96:97], v[96:97], v[102:103]
	v_pk_mul_f32 v[102:103], v[132:133], v[112:113] op_sel_hi:[1,0]
	v_cvt_pk_bf16_f32 v96, v96, v97
	v_pk_mul_f32 v[98:99], v[98:99], v[102:103]
	v_pk_mul_f32 v[102:103], v[116:117], v[112:113] op_sel_hi:[1,0]
	v_cvt_pk_bf16_f32 v97, v98, v99
	ds_write2_b64 v134, v[100:101], v[96:97] offset1:2
	v_pk_mul_f32 v[96:97], v[140:141], v[112:113] op_sel_hi:[1,0]
	s_waitcnt vmcnt(11)
	v_pk_mul_f32 v[0:1], v[0:1], v[102:103]
	v_pk_mul_f32 v[96:97], v[104:105], v[96:97]
	v_pk_mul_f32 v[102:103], v[114:115], v[112:113] op_sel_hi:[1,0]
	v_cvt_pk_bf16_f32 v100, v96, v97
	v_pk_mul_f32 v[96:97], v[136:137], v[112:113] op_sel_hi:[1,0]
	v_pk_mul_f32 v[2:3], v[2:3], v[102:103]
	v_pk_mul_f32 v[96:97], v[106:107], v[96:97]
	v_cvt_pk_bf16_f32 v0, v0, v1
	v_cvt_pk_bf16_f32 v101, v96, v97
	global_load_dwordx4 v[96:99], v208, s[36:37] offset:480
	v_cvt_pk_bf16_f32 v1, v2, v3
	ds_write2_b64 v134, v[100:101], v[0:1] offset0:4 offset1:6
	v_pk_mul_f32 v[0:1], v[120:121], v[112:113] op_sel_hi:[1,0]
	v_pk_mul_f32 v[2:3], v[118:119], v[112:113] op_sel_hi:[1,0]
	s_addc_u32 s9, s83, 0
	s_waitcnt vmcnt(11)
	v_pk_mul_f32 v[0:1], v[8:9], v[0:1]
	v_pk_mul_f32 v[2:3], v[10:11], v[2:3]
	v_cvt_pk_bf16_f32 v0, v0, v1
	v_cvt_pk_bf16_f32 v1, v2, v3
	v_pk_mul_f32 v[2:3], v[52:53], v[112:113] op_sel_hi:[1,0]
	v_lshl_add_u64 v[8:9], s[8:9], 0, v[194:195]
	s_waitcnt vmcnt(10)
	v_pk_mul_f32 v[2:3], v[4:5], v[2:3]
	v_pk_mul_f32 v[4:5], v[54:55], v[112:113] op_sel_hi:[1,0]
	v_cvt_pk_bf16_f32 v2, v2, v3
	v_pk_mul_f32 v[4:5], v[6:7], v[4:5]
	v_mad_u64_u32 v[10:11], s[8:9], v113, s14, v[8:9]
	v_cvt_pk_bf16_f32 v3, v4, v5
	ds_write2_b64 v134, v[0:1], v[2:3] offset0:8 offset1:10
	v_pk_mul_f32 v[0:1], v[56:57], v[112:113] op_sel_hi:[1,0]
	v_pk_mul_f32 v[2:3], v[58:59], v[112:113] op_sel_hi:[1,0]
	s_waitcnt vmcnt(9)
	v_pk_mul_f32 v[0:1], v[28:29], v[0:1]
	v_pk_mul_f32 v[2:3], v[30:31], v[2:3]
	v_cvt_pk_bf16_f32 v0, v0, v1
	v_cvt_pk_bf16_f32 v1, v2, v3
	v_pk_mul_f32 v[2:3], v[60:61], v[112:113] op_sel_hi:[1,0]
	v_pk_mul_f32 v[4:5], v[62:63], v[112:113] op_sel_hi:[1,0]
	s_waitcnt vmcnt(8)
	v_pk_mul_f32 v[2:3], v[2:3], v[12:13]
	v_pk_mul_f32 v[4:5], v[4:5], v[14:15]
	v_cvt_pk_bf16_f32 v2, v2, v3
	v_cvt_pk_bf16_f32 v3, v4, v5
	ds_write2_b64 v134, v[0:1], v[2:3] offset0:12 offset1:14
	v_pk_mul_f32 v[0:1], v[124:125], v[112:113] op_sel_hi:[1,0]
	v_pk_mul_f32 v[2:3], v[122:123], v[112:113] op_sel_hi:[1,0]
	s_waitcnt vmcnt(7)
	v_pk_mul_f32 v[0:1], v[0:1], v[48:49]
	v_pk_mul_f32 v[2:3], v[2:3], v[50:51]
	v_cvt_pk_bf16_f32 v0, v0, v1
	v_cvt_pk_bf16_f32 v1, v2, v3
	v_pk_mul_f32 v[2:3], v[36:37], v[112:113] op_sel_hi:[1,0]
	v_pk_mul_f32 v[4:5], v[38:39], v[112:113] op_sel_hi:[1,0]
	s_waitcnt vmcnt(6)
	v_pk_mul_f32 v[2:3], v[2:3], v[32:33]
	v_pk_mul_f32 v[4:5], v[4:5], v[34:35]
	v_cvt_pk_bf16_f32 v2, v2, v3
	v_cvt_pk_bf16_f32 v3, v4, v5
	ds_write2_b64 v134, v[0:1], v[2:3] offset0:16 offset1:18
	v_pk_mul_f32 v[0:1], v[40:41], v[112:113] op_sel_hi:[1,0]
	v_pk_mul_f32 v[2:3], v[42:43], v[112:113] op_sel_hi:[1,0]
	s_waitcnt vmcnt(5)
	v_pk_mul_f32 v[0:1], v[0:1], v[142:143]
	v_pk_mul_f32 v[2:3], v[2:3], v[144:145]
	v_cvt_pk_bf16_f32 v0, v0, v1
	v_cvt_pk_bf16_f32 v1, v2, v3
	v_pk_mul_f32 v[2:3], v[44:45], v[112:113] op_sel_hi:[1,0]
	v_pk_mul_f32 v[4:5], v[46:47], v[112:113] op_sel_hi:[1,0]
	s_waitcnt vmcnt(4)
	v_pk_mul_f32 v[2:3], v[2:3], v[146:147]
	v_pk_mul_f32 v[4:5], v[4:5], v[148:149]
	v_cvt_pk_bf16_f32 v2, v2, v3
	v_cvt_pk_bf16_f32 v3, v4, v5
	ds_write2_b64 v134, v[0:1], v[2:3] offset0:20 offset1:22
	v_pk_mul_f32 v[0:1], v[16:17], v[112:113] op_sel_hi:[1,0]
	v_pk_mul_f32 v[2:3], v[18:19], v[112:113] op_sel_hi:[1,0]
	s_waitcnt vmcnt(3)
	v_pk_mul_f32 v[0:1], v[0:1], v[150:151]
	v_pk_mul_f32 v[2:3], v[2:3], v[152:153]
	v_cvt_pk_bf16_f32 v0, v0, v1
	v_cvt_pk_bf16_f32 v1, v2, v3
	v_pk_mul_f32 v[2:3], v[20:21], v[112:113] op_sel_hi:[1,0]
	v_pk_mul_f32 v[4:5], v[22:23], v[112:113] op_sel_hi:[1,0]
	s_waitcnt vmcnt(2)
	v_pk_mul_f32 v[2:3], v[2:3], v[158:159]
	v_pk_mul_f32 v[4:5], v[4:5], v[160:161]
	v_cvt_pk_bf16_f32 v2, v2, v3
	v_cvt_pk_bf16_f32 v3, v4, v5
	ds_write2_b64 v134, v[0:1], v[2:3] offset0:24 offset1:26
	v_pk_mul_f32 v[0:1], v[24:25], v[112:113] op_sel_hi:[1,0]
	v_pk_mul_f32 v[2:3], v[26:27], v[112:113] op_sel_hi:[1,0]
	s_waitcnt vmcnt(1)
	v_pk_mul_f32 v[0:1], v[0:1], v[162:163]
	v_pk_mul_f32 v[2:3], v[2:3], v[164:165]
	v_cvt_pk_bf16_f32 v0, v0, v1
	v_cvt_pk_bf16_f32 v1, v2, v3
	v_pk_mul_f32 v[2:3], v[108:109], v[112:113] op_sel_hi:[1,0]
	v_pk_mul_f32 v[4:5], v[110:111], v[112:113] op_sel_hi:[1,0]
	s_waitcnt vmcnt(0)
	v_pk_mul_f32 v[2:3], v[2:3], v[96:97]
	v_pk_mul_f32 v[4:5], v[4:5], v[98:99]
	v_cvt_pk_bf16_f32 v2, v2, v3
	v_cvt_pk_bf16_f32 v3, v4, v5
	ds_write2_b64 v134, v[0:1], v[2:3] offset0:28 offset1:30
	v_mul_u32_u24_e32 v0, 0x110, v156
	v_lshlrev_b32_e32 v13, 16, v92
	v_and_b32_e32 v18, 0xffff0000, v92
	v_add3_u32 v12, s7, v194, v0
	v_mul_f32_e32 v0, 0xbfb8aa3b, v13
	v_mul_f32_e32 v1, 0xbfb8aa3b, v18
	v_exp_f32_e32 v0, v0
	v_exp_f32_e32 v1, v1
	s_waitcnt lgkmcnt(0)
	ds_read_b128 v[4:7], v12
	v_and_b32_e32 v23, 0xffff0000, v93
	v_pk_add_f32 v[14:15], v[0:1], 1.0 op_sel_hi:[1,0]
	ds_read_b128 v[0:3], v12 offset:1088
	v_rcp_f32_e32 v20, v15
	s_waitcnt lgkmcnt(1)
	v_lshlrev_b32_e32 v16, 16, v4
	v_and_b32_e32 v17, 0xffff0000, v4
	v_add_u32_e32 v11, s0, v11
	v_rcp_f32_e32 v22, v14
	v_mul_f32_e32 v4, v18, v20
	v_mov_b32_e32 v15, v4
	v_lshlrev_b32_e32 v21, 16, v93
	v_mul_f32_e32 v18, 0xbfb8aa3b, v21
	v_mul_f32_e32 v19, 0xbfb8aa3b, v23
	v_exp_f32_e32 v18, v18
	v_exp_f32_e32 v19, v19
	v_mul_f32_e32 v4, v13, v22
	v_mov_b32_e32 v14, v4
	v_pk_mul_f32 v[14:15], v[14:15], v[16:17]
	v_pk_add_f32 v[16:17], v[18:19], 1.0 op_sel_hi:[1,0]
	v_cvt_pk_bf16_f32 v4, v14, v15
	v_rcp_f32_e32 v18, v17
	v_lshlrev_b32_e32 v14, 16, v5
	v_and_b32_e32 v15, 0xffff0000, v5
	v_rcp_f32_e32 v20, v16
	v_mul_f32_e32 v5, v23, v18
	v_mov_b32_e32 v17, v5
	v_and_b32_e32 v23, 0xffff0000, v94
	v_lshlrev_b32_e32 v13, 16, v94
	v_mul_f32_e32 v18, 0xbfb8aa3b, v13
	v_mul_f32_e32 v19, 0xbfb8aa3b, v23
	v_exp_f32_e32 v18, v18
	v_exp_f32_e32 v19, v19
	v_mul_f32_e32 v5, v21, v20
	v_mov_b32_e32 v16, v5
	v_pk_mul_f32 v[14:15], v[16:17], v[14:15]
	v_pk_add_f32 v[16:17], v[18:19], 1.0 op_sel_hi:[1,0]
	v_cvt_pk_bf16_f32 v5, v14, v15
	v_rcp_f32_e32 v19, v17
	v_lshlrev_b32_e32 v14, 16, v6
	v_and_b32_e32 v15, 0xffff0000, v6
	v_lshlrev_b32_e32 v22, 16, v95
	v_rcp_f32_e32 v21, v16
	v_mul_f32_e32 v6, v23, v19
	v_mov_b32_e32 v17, v6
	v_and_b32_e32 v23, 0xffff0000, v95
	v_mul_f32_e32 v18, 0xbfb8aa3b, v22
	v_mul_f32_e32 v19, 0xbfb8aa3b, v23
	v_exp_f32_e32 v18, v18
	v_exp_f32_e32 v19, v19
	v_mul_f32_e32 v6, v13, v21
	v_mov_b32_e32 v16, v6
	v_pk_mul_f32 v[14:15], v[16:17], v[14:15]
	v_pk_add_f32 v[16:17], v[18:19], 1.0 op_sel_hi:[1,0]
	v_cvt_pk_bf16_f32 v6, v14, v15
	v_rcp_f32_e32 v18, v17
	v_lshlrev_b32_e32 v14, 16, v7
	v_and_b32_e32 v15, 0xffff0000, v7
	v_rcp_f32_e32 v20, v16
	v_mul_f32_e32 v7, v23, v18
	v_mov_b32_e32 v17, v7
	v_and_b32_e32 v23, 0xffff0000, v85
	v_mul_f32_e32 v7, v22, v20
	v_mov_b32_e32 v16, v7
	v_pk_mul_f32 v[14:15], v[16:17], v[14:15]
	v_lshlrev_b32_e32 v13, 16, v88
	v_cvt_pk_bf16_f32 v7, v14, v15
	v_and_b32_e32 v14, 0xffff0000, v88
	global_store_dwordx4 v[10:11], v[4:7], off offset:2048
	s_waitcnt lgkmcnt(0)
	v_lshlrev_b32_e32 v10, 16, v0
	v_and_b32_e32 v11, 0xffff0000, v0
	v_mul_f32_e32 v4, 0xbfb8aa3b, v13
	v_mul_f32_e32 v5, 0xbfb8aa3b, v14
	v_exp_f32_e32 v4, v4
	v_exp_f32_e32 v5, v5
	v_and_b32_e32 v19, 0xffff0000, v89
	v_or_b32_e32 v6, 4, v113
	v_mad_u64_u32 v[6:7], s[8:9], v6, s14, v[8:9]
	v_pk_add_f32 v[4:5], v[4:5], 1.0 op_sel_hi:[1,0]
	v_add_u32_e32 v7, s0, v7
	v_rcp_f32_e32 v16, v5
	s_nop 0
	v_rcp_f32_e32 v18, v4
	v_mul_f32_e32 v0, v14, v16
	v_mov_b32_e32 v5, v0
	v_lshlrev_b32_e32 v17, 16, v89
	v_mul_f32_e32 v14, 0xbfb8aa3b, v17
	v_mul_f32_e32 v15, 0xbfb8aa3b, v19
	v_exp_f32_e32 v14, v14
	v_exp_f32_e32 v15, v15
	v_mul_f32_e32 v0, v13, v18
	v_mov_b32_e32 v4, v0
	v_pk_mul_f32 v[4:5], v[4:5], v[10:11]
	v_pk_add_f32 v[10:11], v[14:15], 1.0 op_sel_hi:[1,0]
	v_cvt_pk_bf16_f32 v0, v4, v5
	v_rcp_f32_e32 v14, v11
	v_lshlrev_b32_e32 v4, 16, v1
	v_and_b32_e32 v5, 0xffff0000, v1
	v_rcp_f32_e32 v16, v10
	v_mul_f32_e32 v1, v19, v14
	v_mov_b32_e32 v11, v1
	v_and_b32_e32 v19, 0xffff0000, v90
	v_lshlrev_b32_e32 v13, 16, v90
	v_mul_f32_e32 v14, 0xbfb8aa3b, v13
	v_mul_f32_e32 v15, 0xbfb8aa3b, v19
	v_exp_f32_e32 v14, v14
	v_exp_f32_e32 v15, v15
	v_mul_f32_e32 v1, v17, v16
	v_mov_b32_e32 v10, v1
	v_pk_mul_f32 v[4:5], v[10:11], v[4:5]
	v_pk_add_f32 v[10:11], v[14:15], 1.0 op_sel_hi:[1,0]
	v_cvt_pk_bf16_f32 v1, v4, v5
	v_rcp_f32_e32 v15, v11
	v_lshlrev_b32_e32 v4, 16, v2
	v_and_b32_e32 v5, 0xffff0000, v2
	v_lshlrev_b32_e32 v18, 16, v91
	v_rcp_f32_e32 v17, v10
	v_mul_f32_e32 v2, v19, v15
	v_mov_b32_e32 v11, v2
	v_and_b32_e32 v19, 0xffff0000, v91
	v_mul_f32_e32 v14, 0xbfb8aa3b, v18
	v_mul_f32_e32 v15, 0xbfb8aa3b, v19
	v_exp_f32_e32 v14, v14
	v_exp_f32_e32 v15, v15
	v_mul_f32_e32 v2, v13, v17
	v_mov_b32_e32 v10, v2
	v_pk_mul_f32 v[4:5], v[10:11], v[4:5]
	v_pk_add_f32 v[10:11], v[14:15], 1.0 op_sel_hi:[1,0]
	v_cvt_pk_bf16_f32 v2, v4, v5
	v_rcp_f32_e32 v14, v11
	v_lshlrev_b32_e32 v4, 16, v3
	v_and_b32_e32 v5, 0xffff0000, v3
	v_rcp_f32_e32 v16, v10
	v_mul_f32_e32 v3, v19, v14
	v_mov_b32_e32 v11, v3
	v_mul_f32_e32 v3, v18, v16
	v_mov_b32_e32 v10, v3
	v_pk_mul_f32 v[4:5], v[10:11], v[4:5]
	v_lshlrev_b32_e32 v13, 16, v84
	v_cvt_pk_bf16_f32 v3, v4, v5
	v_and_b32_e32 v18, 0xffff0000, v84
	global_store_dwordx4 v[6:7], v[0:3], off offset:2048
	ds_read_b128 v[4:7], v12 offset:2176
	s_nop 0
	v_mul_f32_e32 v0, 0xbfb8aa3b, v13
	v_mul_f32_e32 v1, 0xbfb8aa3b, v18
	v_exp_f32_e32 v0, v0
	v_exp_f32_e32 v1, v1
	v_or_b32_e32 v2, 8, v113
	v_mad_u64_u32 v[10:11], s[8:9], v2, s14, v[8:9]
	v_pk_add_f32 v[14:15], v[0:1], 1.0 op_sel_hi:[1,0]
	ds_read_b128 v[0:3], v12 offset:3264
	v_rcp_f32_e32 v20, v15
	s_waitcnt lgkmcnt(1)
	v_lshlrev_b32_e32 v16, 16, v4
	v_and_b32_e32 v17, 0xffff0000, v4
	v_add_u32_e32 v11, s0, v11
	v_rcp_f32_e32 v22, v14
	v_mul_f32_e32 v4, v18, v20
	v_mov_b32_e32 v15, v4
	v_lshlrev_b32_e32 v21, 16, v85
	v_mul_f32_e32 v18, 0xbfb8aa3b, v21
	v_mul_f32_e32 v19, 0xbfb8aa3b, v23
	v_exp_f32_e32 v18, v18
	v_exp_f32_e32 v19, v19
	v_mul_f32_e32 v4, v13, v22
	v_mov_b32_e32 v14, v4
	v_pk_mul_f32 v[14:15], v[14:15], v[16:17]
	v_pk_add_f32 v[16:17], v[18:19], 1.0 op_sel_hi:[1,0]
	v_cvt_pk_bf16_f32 v4, v14, v15
	v_rcp_f32_e32 v18, v17
	v_lshlrev_b32_e32 v14, 16, v5
	v_and_b32_e32 v15, 0xffff0000, v5
	v_rcp_f32_e32 v20, v16
	v_mul_f32_e32 v5, v23, v18
	v_mov_b32_e32 v17, v5
	v_and_b32_e32 v23, 0xffff0000, v86
	v_lshlrev_b32_e32 v13, 16, v86
	v_mul_f32_e32 v18, 0xbfb8aa3b, v13
	v_mul_f32_e32 v19, 0xbfb8aa3b, v23
	v_exp_f32_e32 v18, v18
	v_exp_f32_e32 v19, v19
	v_mul_f32_e32 v5, v21, v20
	v_mov_b32_e32 v16, v5
	v_pk_mul_f32 v[14:15], v[16:17], v[14:15]
	v_pk_add_f32 v[16:17], v[18:19], 1.0 op_sel_hi:[1,0]
	v_cvt_pk_bf16_f32 v5, v14, v15
	v_rcp_f32_e32 v19, v17
	v_lshlrev_b32_e32 v14, 16, v6
	v_and_b32_e32 v15, 0xffff0000, v6
	v_lshlrev_b32_e32 v22, 16, v87
	v_rcp_f32_e32 v21, v16
	v_mul_f32_e32 v6, v23, v19
	v_mov_b32_e32 v17, v6
	v_and_b32_e32 v23, 0xffff0000, v87
	v_mul_f32_e32 v18, 0xbfb8aa3b, v22
	v_mul_f32_e32 v19, 0xbfb8aa3b, v23
	v_exp_f32_e32 v18, v18
	v_exp_f32_e32 v19, v19
	v_mul_f32_e32 v6, v13, v21
	v_mov_b32_e32 v16, v6
	v_pk_mul_f32 v[14:15], v[16:17], v[14:15]
	v_pk_add_f32 v[16:17], v[18:19], 1.0 op_sel_hi:[1,0]
	v_cvt_pk_bf16_f32 v6, v14, v15
	v_rcp_f32_e32 v18, v17
	v_lshlrev_b32_e32 v14, 16, v7
	v_and_b32_e32 v15, 0xffff0000, v7
	v_rcp_f32_e32 v20, v16
	v_mul_f32_e32 v7, v23, v18
	v_mov_b32_e32 v17, v7
	v_and_b32_e32 v23, 0xffff0000, v77
	v_mul_f32_e32 v7, v22, v20
	v_mov_b32_e32 v16, v7
	v_pk_mul_f32 v[14:15], v[16:17], v[14:15]
	v_lshlrev_b32_e32 v13, 16, v80
	v_cvt_pk_bf16_f32 v7, v14, v15
	v_and_b32_e32 v14, 0xffff0000, v80
	global_store_dwordx4 v[10:11], v[4:7], off offset:2048
	s_waitcnt lgkmcnt(0)
	v_lshlrev_b32_e32 v10, 16, v0
	v_and_b32_e32 v11, 0xffff0000, v0
	v_mul_f32_e32 v4, 0xbfb8aa3b, v13
	v_mul_f32_e32 v5, 0xbfb8aa3b, v14
	v_exp_f32_e32 v4, v4
	v_exp_f32_e32 v5, v5
	v_and_b32_e32 v19, 0xffff0000, v81
	v_or_b32_e32 v6, 12, v113
	v_mad_u64_u32 v[6:7], s[8:9], v6, s14, v[8:9]
	v_pk_add_f32 v[4:5], v[4:5], 1.0 op_sel_hi:[1,0]
	v_add_u32_e32 v7, s0, v7
	v_rcp_f32_e32 v16, v5
	s_nop 0
	v_rcp_f32_e32 v18, v4
	v_mul_f32_e32 v0, v14, v16
	v_mov_b32_e32 v5, v0
	v_lshlrev_b32_e32 v17, 16, v81
	v_mul_f32_e32 v14, 0xbfb8aa3b, v17
	v_mul_f32_e32 v15, 0xbfb8aa3b, v19
	v_exp_f32_e32 v14, v14
	v_exp_f32_e32 v15, v15
	v_mul_f32_e32 v0, v13, v18
	v_mov_b32_e32 v4, v0
	v_pk_mul_f32 v[4:5], v[4:5], v[10:11]
	v_pk_add_f32 v[10:11], v[14:15], 1.0 op_sel_hi:[1,0]
	v_cvt_pk_bf16_f32 v0, v4, v5
	v_rcp_f32_e32 v14, v11
	v_lshlrev_b32_e32 v4, 16, v1
	v_and_b32_e32 v5, 0xffff0000, v1
	v_rcp_f32_e32 v16, v10
	v_mul_f32_e32 v1, v19, v14
	v_mov_b32_e32 v11, v1
	v_and_b32_e32 v19, 0xffff0000, v82
	v_lshlrev_b32_e32 v13, 16, v82
	v_mul_f32_e32 v14, 0xbfb8aa3b, v13
	v_mul_f32_e32 v15, 0xbfb8aa3b, v19
	v_exp_f32_e32 v14, v14
	v_exp_f32_e32 v15, v15
	v_mul_f32_e32 v1, v17, v16
	v_mov_b32_e32 v10, v1
	v_pk_mul_f32 v[4:5], v[10:11], v[4:5]
	v_pk_add_f32 v[10:11], v[14:15], 1.0 op_sel_hi:[1,0]
	v_cvt_pk_bf16_f32 v1, v4, v5
	v_rcp_f32_e32 v15, v11
	v_lshlrev_b32_e32 v4, 16, v2
	v_and_b32_e32 v5, 0xffff0000, v2
	v_lshlrev_b32_e32 v18, 16, v83
	v_rcp_f32_e32 v17, v10
	v_mul_f32_e32 v2, v19, v15
	v_mov_b32_e32 v11, v2
	v_and_b32_e32 v19, 0xffff0000, v83
	v_mul_f32_e32 v14, 0xbfb8aa3b, v18
	v_mul_f32_e32 v15, 0xbfb8aa3b, v19
	v_exp_f32_e32 v14, v14
	v_exp_f32_e32 v15, v15
	v_mul_f32_e32 v2, v13, v17
	v_mov_b32_e32 v10, v2
	v_pk_mul_f32 v[4:5], v[10:11], v[4:5]
	v_pk_add_f32 v[10:11], v[14:15], 1.0 op_sel_hi:[1,0]
	v_cvt_pk_bf16_f32 v2, v4, v5
	v_rcp_f32_e32 v14, v11
	v_lshlrev_b32_e32 v4, 16, v3
	v_and_b32_e32 v5, 0xffff0000, v3
	v_rcp_f32_e32 v16, v10
	v_mul_f32_e32 v3, v19, v14
	v_mov_b32_e32 v11, v3
	v_mul_f32_e32 v3, v18, v16
	v_mov_b32_e32 v10, v3
	v_pk_mul_f32 v[4:5], v[10:11], v[4:5]
	v_lshlrev_b32_e32 v13, 16, v76
	v_cvt_pk_bf16_f32 v3, v4, v5
	v_and_b32_e32 v18, 0xffff0000, v76
	global_store_dwordx4 v[6:7], v[0:3], off offset:2048
	ds_read_b128 v[4:7], v12 offset:4352
	s_nop 0
	v_mul_f32_e32 v0, 0xbfb8aa3b, v13
	v_mul_f32_e32 v1, 0xbfb8aa3b, v18
	v_exp_f32_e32 v0, v0
	v_exp_f32_e32 v1, v1
	v_or_b32_e32 v2, 16, v113
	v_mad_u64_u32 v[10:11], s[8:9], v2, s14, v[8:9]
	v_pk_add_f32 v[14:15], v[0:1], 1.0 op_sel_hi:[1,0]
	ds_read_b128 v[0:3], v12 offset:5440
	v_rcp_f32_e32 v20, v15
	s_waitcnt lgkmcnt(1)
	v_lshlrev_b32_e32 v16, 16, v4
	v_and_b32_e32 v17, 0xffff0000, v4
	v_add_u32_e32 v11, s0, v11
	v_rcp_f32_e32 v22, v14
	v_mul_f32_e32 v4, v18, v20
	v_mov_b32_e32 v15, v4
	v_lshlrev_b32_e32 v21, 16, v77
	v_mul_f32_e32 v18, 0xbfb8aa3b, v21
	v_mul_f32_e32 v19, 0xbfb8aa3b, v23
	v_exp_f32_e32 v18, v18
	v_exp_f32_e32 v19, v19
	v_mul_f32_e32 v4, v13, v22
	v_mov_b32_e32 v14, v4
	v_pk_mul_f32 v[14:15], v[14:15], v[16:17]
	v_pk_add_f32 v[16:17], v[18:19], 1.0 op_sel_hi:[1,0]
	v_cvt_pk_bf16_f32 v4, v14, v15
	v_rcp_f32_e32 v18, v17
	v_lshlrev_b32_e32 v14, 16, v5
	v_and_b32_e32 v15, 0xffff0000, v5
	v_rcp_f32_e32 v20, v16
	v_mul_f32_e32 v5, v23, v18
	v_mov_b32_e32 v17, v5
	v_and_b32_e32 v23, 0xffff0000, v78
	v_lshlrev_b32_e32 v13, 16, v78
	v_mul_f32_e32 v18, 0xbfb8aa3b, v13
	v_mul_f32_e32 v19, 0xbfb8aa3b, v23
	v_exp_f32_e32 v18, v18
	v_exp_f32_e32 v19, v19
	v_mul_f32_e32 v5, v21, v20
	v_mov_b32_e32 v16, v5
	v_pk_mul_f32 v[14:15], v[16:17], v[14:15]
	v_pk_add_f32 v[16:17], v[18:19], 1.0 op_sel_hi:[1,0]
	v_cvt_pk_bf16_f32 v5, v14, v15
	v_rcp_f32_e32 v19, v17
	v_lshlrev_b32_e32 v14, 16, v6
	v_and_b32_e32 v15, 0xffff0000, v6
	v_lshlrev_b32_e32 v22, 16, v79
	v_rcp_f32_e32 v21, v16
	v_mul_f32_e32 v6, v23, v19
	v_mov_b32_e32 v17, v6
	v_and_b32_e32 v23, 0xffff0000, v79
	v_mul_f32_e32 v18, 0xbfb8aa3b, v22
	v_mul_f32_e32 v19, 0xbfb8aa3b, v23
	v_exp_f32_e32 v18, v18
	v_exp_f32_e32 v19, v19
	v_mul_f32_e32 v6, v13, v21
	v_mov_b32_e32 v16, v6
	v_pk_mul_f32 v[14:15], v[16:17], v[14:15]
	v_pk_add_f32 v[16:17], v[18:19], 1.0 op_sel_hi:[1,0]
	v_cvt_pk_bf16_f32 v6, v14, v15
	v_rcp_f32_e32 v18, v17
	v_lshlrev_b32_e32 v14, 16, v7
	v_and_b32_e32 v15, 0xffff0000, v7
	v_rcp_f32_e32 v20, v16
	v_mul_f32_e32 v7, v23, v18
	v_mov_b32_e32 v17, v7
	v_mul_f32_e32 v7, v22, v20
	v_mov_b32_e32 v16, v7
	v_pk_mul_f32 v[14:15], v[16:17], v[14:15]
	v_lshlrev_b32_e32 v13, 16, v72
	v_cvt_pk_bf16_f32 v7, v14, v15
	v_and_b32_e32 v14, 0xffff0000, v72
	global_store_dwordx4 v[10:11], v[4:7], off offset:2048
	s_waitcnt lgkmcnt(0)
	v_lshlrev_b32_e32 v10, 16, v0
	v_and_b32_e32 v11, 0xffff0000, v0
	v_mul_f32_e32 v4, 0xbfb8aa3b, v13
	v_mul_f32_e32 v5, 0xbfb8aa3b, v14
	v_exp_f32_e32 v4, v4
	v_exp_f32_e32 v5, v5
	v_and_b32_e32 v19, 0xffff0000, v73
	v_or_b32_e32 v6, 20, v113
	v_mad_u64_u32 v[6:7], s[8:9], v6, s14, v[8:9]
	v_pk_add_f32 v[4:5], v[4:5], 1.0 op_sel_hi:[1,0]
	v_add_u32_e32 v7, s0, v7
	v_rcp_f32_e32 v16, v5
	v_and_b32_e32 v22, 0xffff0000, v69
	v_rcp_f32_e32 v18, v4
	v_mul_f32_e32 v0, v14, v16
	v_mov_b32_e32 v5, v0
	v_lshlrev_b32_e32 v17, 16, v73
	v_mul_f32_e32 v14, 0xbfb8aa3b, v17
	v_mul_f32_e32 v15, 0xbfb8aa3b, v19
	v_exp_f32_e32 v14, v14
	v_exp_f32_e32 v15, v15
	v_mul_f32_e32 v0, v13, v18
	v_mov_b32_e32 v4, v0
	v_pk_mul_f32 v[4:5], v[4:5], v[10:11]
	v_pk_add_f32 v[10:11], v[14:15], 1.0 op_sel_hi:[1,0]
	v_cvt_pk_bf16_f32 v0, v4, v5
	v_rcp_f32_e32 v14, v11
	v_lshlrev_b32_e32 v4, 16, v1
	v_and_b32_e32 v5, 0xffff0000, v1
	v_rcp_f32_e32 v16, v10
	v_mul_f32_e32 v1, v19, v14
	v_mov_b32_e32 v11, v1
	v_and_b32_e32 v19, 0xffff0000, v74
	v_lshlrev_b32_e32 v13, 16, v74
	v_mul_f32_e32 v14, 0xbfb8aa3b, v13
	v_mul_f32_e32 v15, 0xbfb8aa3b, v19
	v_exp_f32_e32 v14, v14
	v_exp_f32_e32 v15, v15
	v_mul_f32_e32 v1, v17, v16
	v_mov_b32_e32 v10, v1
	v_pk_mul_f32 v[4:5], v[10:11], v[4:5]
	v_pk_add_f32 v[10:11], v[14:15], 1.0 op_sel_hi:[1,0]
	v_cvt_pk_bf16_f32 v1, v4, v5
	v_rcp_f32_e32 v15, v11
	v_lshlrev_b32_e32 v4, 16, v2
	v_and_b32_e32 v5, 0xffff0000, v2
	v_lshlrev_b32_e32 v18, 16, v75
	v_rcp_f32_e32 v17, v10
	v_mul_f32_e32 v2, v19, v15
	v_mov_b32_e32 v11, v2
	v_and_b32_e32 v19, 0xffff0000, v75
	v_mul_f32_e32 v14, 0xbfb8aa3b, v18
	v_mul_f32_e32 v15, 0xbfb8aa3b, v19
	v_exp_f32_e32 v14, v14
	v_exp_f32_e32 v15, v15
	v_mul_f32_e32 v2, v13, v17
	v_mov_b32_e32 v10, v2
	v_pk_mul_f32 v[4:5], v[10:11], v[4:5]
	v_pk_add_f32 v[10:11], v[14:15], 1.0 op_sel_hi:[1,0]
	v_cvt_pk_bf16_f32 v2, v4, v5
	v_rcp_f32_e32 v14, v11
	v_lshlrev_b32_e32 v4, 16, v3
	v_and_b32_e32 v5, 0xffff0000, v3
	v_rcp_f32_e32 v16, v10
	v_mul_f32_e32 v3, v19, v14
	v_mov_b32_e32 v11, v3
	v_mul_f32_e32 v3, v18, v16
	v_mov_b32_e32 v10, v3
	v_pk_mul_f32 v[4:5], v[10:11], v[4:5]
	v_lshlrev_b32_e32 v18, 16, v68
	v_cvt_pk_bf16_f32 v3, v4, v5
	v_and_b32_e32 v16, 0xffff0000, v68
	global_store_dwordx4 v[6:7], v[0:3], off offset:2048
	ds_read_b128 v[4:7], v12 offset:6528
	s_nop 0
	v_mul_f32_e32 v0, 0xbfb8aa3b, v18
	v_mul_f32_e32 v1, 0xbfb8aa3b, v16
	v_exp_f32_e32 v0, v0
	v_exp_f32_e32 v1, v1
	v_or_b32_e32 v2, 24, v113
	v_mad_u64_u32 v[10:11], s[8:9], v2, s14, v[8:9]
	v_pk_add_f32 v[14:15], v[0:1], 1.0 op_sel_hi:[1,0]
	ds_read_b128 v[0:3], v12 offset:7616
	v_rcp_f32_e32 v19, v15
	s_waitcnt lgkmcnt(1)
	v_lshlrev_b32_e32 v12, 16, v4
	v_and_b32_e32 v13, 0xffff0000, v4
	v_add_u32_e32 v11, s0, v11
	v_rcp_f32_e32 v21, v14
	v_mul_f32_e32 v4, v16, v19
	v_mov_b32_e32 v15, v4
	v_lshlrev_b32_e32 v20, 16, v69
	v_mul_f32_e32 v16, 0xbfb8aa3b, v20
	v_mul_f32_e32 v17, 0xbfb8aa3b, v22
	v_exp_f32_e32 v16, v16
	v_exp_f32_e32 v17, v17
	v_mul_f32_e32 v4, v18, v21
	v_mov_b32_e32 v14, v4
	v_pk_mul_f32 v[12:13], v[14:15], v[12:13]
	v_pk_add_f32 v[14:15], v[16:17], 1.0 op_sel_hi:[1,0]
	v_cvt_pk_bf16_f32 v4, v12, v13
	v_rcp_f32_e32 v17, v15
	v_lshlrev_b32_e32 v12, 16, v5
	v_and_b32_e32 v13, 0xffff0000, v5
	v_lshlrev_b32_e32 v21, 16, v70
	v_rcp_f32_e32 v19, v14
	v_mul_f32_e32 v5, v22, v17
	v_mov_b32_e32 v15, v5
	v_and_b32_e32 v22, 0xffff0000, v70
	v_mul_f32_e32 v16, 0xbfb8aa3b, v21
	v_mul_f32_e32 v17, 0xbfb8aa3b, v22
	v_exp_f32_e32 v16, v16
	v_exp_f32_e32 v17, v17
	v_mul_f32_e32 v5, v20, v19
	v_mov_b32_e32 v14, v5
	v_pk_mul_f32 v[12:13], v[14:15], v[12:13]
	v_pk_add_f32 v[14:15], v[16:17], 1.0 op_sel_hi:[1,0]
	v_cvt_pk_bf16_f32 v5, v12, v13
	v_rcp_f32_e32 v17, v15
	v_lshlrev_b32_e32 v12, 16, v6
	v_and_b32_e32 v13, 0xffff0000, v6
	v_lshlrev_b32_e32 v20, 16, v71
	v_rcp_f32_e32 v19, v14
	v_mul_f32_e32 v6, v22, v17
	v_mov_b32_e32 v15, v6
	v_and_b32_e32 v22, 0xffff0000, v71
	v_mul_f32_e32 v16, 0xbfb8aa3b, v20
	v_mul_f32_e32 v17, 0xbfb8aa3b, v22
	v_exp_f32_e32 v16, v16
	v_exp_f32_e32 v17, v17
	v_mul_f32_e32 v6, v21, v19
	v_mov_b32_e32 v14, v6
	v_pk_mul_f32 v[12:13], v[14:15], v[12:13]
	v_pk_add_f32 v[14:15], v[16:17], 1.0 op_sel_hi:[1,0]
	v_cvt_pk_bf16_f32 v6, v12, v13
	v_rcp_f32_e32 v17, v15
	v_lshlrev_b32_e32 v12, 16, v7
	v_and_b32_e32 v13, 0xffff0000, v7
	v_rcp_f32_e32 v19, v14
	v_mul_f32_e32 v7, v22, v17
	v_mov_b32_e32 v15, v7
	v_mul_f32_e32 v7, v20, v19
	v_mov_b32_e32 v14, v7
	v_pk_mul_f32 v[12:13], v[14:15], v[12:13]
	v_and_b32_e32 v16, 0xffff0000, v65
	v_cvt_pk_bf16_f32 v7, v12, v13
	global_store_dwordx4 v[10:11], v[4:7], off offset:2048
	v_lshlrev_b32_e32 v12, 16, v64
	v_and_b32_e32 v10, 0xffff0000, v64
	v_mul_f32_e32 v4, 0xbfb8aa3b, v12
	v_mul_f32_e32 v5, 0xbfb8aa3b, v10
	v_exp_f32_e32 v4, v4
	v_exp_f32_e32 v5, v5
	v_or_b32_e32 v6, 28, v113
	v_mad_u64_u32 v[6:7], s[8:9], v6, s14, v[8:9]
	v_pk_add_f32 v[4:5], v[4:5], 1.0 op_sel_hi:[1,0]
	s_waitcnt lgkmcnt(0)
	v_lshlrev_b32_e32 v8, 16, v0
	v_rcp_f32_e32 v13, v5
	v_and_b32_e32 v9, 0xffff0000, v0
	v_add_u32_e32 v7, s0, v7
	v_rcp_f32_e32 v15, v4
	v_mul_f32_e32 v0, v10, v13
	v_mov_b32_e32 v5, v0
	v_lshlrev_b32_e32 v14, 16, v65
	v_mul_f32_e32 v10, 0xbfb8aa3b, v14
	v_mul_f32_e32 v11, 0xbfb8aa3b, v16
	v_exp_f32_e32 v10, v10
	v_exp_f32_e32 v11, v11
	v_mul_f32_e32 v0, v12, v15
	v_mov_b32_e32 v4, v0
	v_pk_mul_f32 v[4:5], v[4:5], v[8:9]
	v_pk_add_f32 v[8:9], v[10:11], 1.0 op_sel_hi:[1,0]
	v_cvt_pk_bf16_f32 v0, v4, v5
	v_rcp_f32_e32 v11, v9
	v_lshlrev_b32_e32 v4, 16, v1
	v_and_b32_e32 v5, 0xffff0000, v1
	v_lshlrev_b32_e32 v15, 16, v66
	v_rcp_f32_e32 v13, v8
	v_mul_f32_e32 v1, v16, v11
	v_mov_b32_e32 v9, v1
	v_and_b32_e32 v16, 0xffff0000, v66
	v_mul_f32_e32 v10, 0xbfb8aa3b, v15
	v_mul_f32_e32 v11, 0xbfb8aa3b, v16
	v_exp_f32_e32 v10, v10
	v_exp_f32_e32 v11, v11
	v_mul_f32_e32 v1, v14, v13
	v_mov_b32_e32 v8, v1
	v_pk_mul_f32 v[4:5], v[8:9], v[4:5]
	v_pk_add_f32 v[8:9], v[10:11], 1.0 op_sel_hi:[1,0]
	v_cvt_pk_bf16_f32 v1, v4, v5
	v_rcp_f32_e32 v11, v9
	v_lshlrev_b32_e32 v4, 16, v2
	v_and_b32_e32 v5, 0xffff0000, v2
	v_lshlrev_b32_e32 v14, 16, v67
	v_rcp_f32_e32 v13, v8
	v_mul_f32_e32 v2, v16, v11
	v_mov_b32_e32 v9, v2
	v_and_b32_e32 v16, 0xffff0000, v67
	v_mul_f32_e32 v10, 0xbfb8aa3b, v14
	v_mul_f32_e32 v11, 0xbfb8aa3b, v16
	v_exp_f32_e32 v10, v10
	v_exp_f32_e32 v11, v11
	v_mul_f32_e32 v2, v15, v13
	v_mov_b32_e32 v8, v2
	v_pk_mul_f32 v[4:5], v[8:9], v[4:5]
	v_pk_add_f32 v[8:9], v[10:11], 1.0 op_sel_hi:[1,0]
	v_cvt_pk_bf16_f32 v2, v4, v5
	v_rcp_f32_e32 v11, v9
	v_lshlrev_b32_e32 v4, 16, v3
	v_and_b32_e32 v5, 0xffff0000, v3
	v_rcp_f32_e32 v13, v8
	v_mul_f32_e32 v3, v16, v11
	v_mov_b32_e32 v9, v3
	v_mul_f32_e32 v3, v14, v13
	v_mov_b32_e32 v8, v3
	v_pk_mul_f32 v[4:5], v[8:9], v[4:5]
	s_nop 0
	v_cvt_pk_bf16_f32 v3, v4, v5
	global_store_dwordx4 v[6:7], v[0:3], off offset:2048

.LBB0_858:
	v_max3_f32 v0, v2, v3, v4
	v_max3_f32 v37, v10, v11, v12
	v_max3_f32 v38, v18, v19, v20
	v_max3_f32 v39, v26, v27, v28
	s_mov_b32 s9, 0xf149f2ca
	v_max3_f32 v0, v0, v5, v6
	v_max3_f32 v37, v37, v13, v14
	v_max3_f32 v38, v38, v21, v22
	v_max3_f32 v39, v39, v29, v30
	s_lshl_b32 s8, s16, 1
	v_max3_f32 v0, v0, v7, v8
	v_max3_f32 v37, v37, v15, v16
	v_max3_f32 v38, v38, v23, v24
	v_max3_f32 v39, v39, v31, v32
	s_nop 0
	v_max3_f32 v0, v0, v9, v37
	v_max3_f32 v37, v38, v25, v39
	s_nop 0
	v_max3_f32 v0, v0, v17, v33
	s_nop 0
	v_max3_f32 v0, v0, v37, v37
	s_nop 0
	v_mov_b32_e32 v37, v0
	s_nop 1
	v_permlane32_swap_b32_e32 v0, v37
	v_max3_f32 v0, v0, v37, v37
	s_nop 0
	v_max_f32_e32 v37, v0, v0
	v_max_f32_e32 v62, 0xf149f2ca, v37
	v_sub_f32_e32 v37, 0xf149f2ca, v62
	v_exp_f32_e32 v37, v37
	v_cmp_lt_f32_e32 vcc, s9, v0
	s_cmp_eq_u64 vcc, 0
	s_cselect_b64 vcc, -1, 0
	v_mul_f32_e32 v0, 0, v37
	v_cndmask_b32_e64 v0, v0, 0, vcc
	ds_read_b128 v[54:57], v1 offset:32768
	ds_read_b128 v[58:61], v1 offset:36864
	ds_read_b128 v[80:83], v34 offset:32768
	ds_read_b128 v[50:53], v34 offset:36864
	ds_read_b128 v[46:49], v35 offset:32768
	ds_read_b128 v[42:45], v35 offset:36864
	ds_read_b128 v[38:41], v36 offset:32768
	ds_read_b128 v[34:37], v36 offset:36864
	s_waitcnt lgkmcnt(0)
	v_mfma_f32_32x32x16_bf16 v[64:79], v[54:57], v[160:163], 0
	v_cndmask_b32_e32 v214, v62, v226, vcc
	v_mov_b32_e32 v215, v214
	v_sub_f32_e32 v2, v2, v214
	v_sub_f32_e32 v3, v3, v215
	v_sub_f32_e32 v18, v18, v214
	v_sub_f32_e32 v19, v19, v215
	v_sub_f32_e32 v4, v4, v214
	v_sub_f32_e32 v5, v5, v215
	v_sub_f32_e32 v20, v20, v214
	v_sub_f32_e32 v21, v21, v215
	v_sub_f32_e32 v6, v6, v214
	v_sub_f32_e32 v7, v7, v215
	v_mfma_f32_32x32x16_bf16 v[64:79], v[80:83], v[164:167], v[64:79]
	v_sub_f32_e32 v22, v22, v214
	v_sub_f32_e32 v23, v23, v215
	v_sub_f32_e32 v8, v8, v214
	v_sub_f32_e32 v9, v9, v215
	v_sub_f32_e32 v24, v24, v214
	v_sub_f32_e32 v25, v25, v215
	v_sub_f32_e32 v10, v10, v214
	v_sub_f32_e32 v11, v11, v215
	v_sub_f32_e32 v26, v26, v214
	v_sub_f32_e32 v27, v27, v215
	v_sub_f32_e32 v12, v12, v214
	v_sub_f32_e32 v13, v13, v215
	v_sub_f32_e32 v28, v28, v214
	v_sub_f32_e32 v29, v29, v215
	v_mfma_f32_32x32x16_bf16 v[80:95], v[58:61], v[160:163], 0
	v_sub_f32_e32 v14, v14, v214
	v_sub_f32_e32 v15, v15, v215
	v_sub_f32_e32 v30, v30, v214
	v_sub_f32_e32 v31, v31, v215
	v_sub_f32_e32 v16, v16, v214
	v_sub_f32_e32 v17, v17, v215
	v_sub_f32_e32 v32, v32, v214
	v_sub_f32_e32 v33, v33, v215
	v_exp_f32_e32 v2, v2
	v_exp_f32_e32 v18, v18
	v_exp_f32_e32 v3, v3
	v_mfma_f32_32x32x16_bf16 v[80:95], v[50:53], v[164:167], v[80:95]
	v_exp_f32_e32 v19, v19
	v_exp_f32_e32 v4, v4
	v_exp_f32_e32 v20, v20
	v_exp_f32_e32 v5, v5
	v_exp_f32_e32 v21, v21
	v_exp_f32_e32 v6, v6
	v_exp_f32_e32 v22, v22
	v_mfma_f32_32x32x16_bf16 v[64:79], v[46:49], v[168:171], v[64:79]
	v_exp_f32_e32 v7, v7
	v_exp_f32_e32 v23, v23
	v_exp_f32_e32 v8, v8
	v_exp_f32_e32 v24, v24
	v_exp_f32_e32 v9, v9
	v_exp_f32_e32 v25, v25
	v_exp_f32_e32 v10, v10
	v_mfma_f32_32x32x16_bf16 v[80:95], v[42:45], v[168:171], v[80:95]
	v_exp_f32_e32 v26, v26
	v_exp_f32_e32 v11, v11
	v_exp_f32_e32 v27, v27
	v_exp_f32_e32 v12, v12
	v_exp_f32_e32 v28, v28
	v_exp_f32_e32 v13, v13
	v_exp_f32_e32 v29, v29
	v_exp_f32_e32 v14, v14
	v_exp_f32_e32 v30, v30
	v_exp_f32_e32 v15, v15
	v_exp_f32_e32 v31, v31
	v_exp_f32_e32 v16, v16
	v_exp_f32_e32 v32, v32
	v_exp_f32_e32 v17, v17
	v_exp_f32_e32 v33, v33
	v_mfma_f32_32x32x16_bf16 v[64:79], v[38:41], v[172:175], v[64:79]
	v_add_f32_e64 v54, v12, v28
	v_add_f32_e64 v55, v13, v29
	v_add_f32_e64 v56, v4, v20
	v_add_f32_e64 v57, v5, v21
	v_add_f32_e64 v58, v16, v32
	v_add_f32_e64 v59, v17, v33
	v_add_f32_e32 v60, v8, v24
	v_add_f32_e32 v61, v9, v25
	v_add_f32_e32 v62, v10, v26
	v_add_f32_e32 v63, v11, v27
	v_add_f32_e32 v96, v2, v18
	v_add_f32_e32 v97, v3, v19
	v_add_f32_e32 v98, v14, v30
	v_add_f32_e32 v99, v15, v31
	v_mfma_f32_32x32x16_bf16 v[80:95], v[34:37], v[172:175], v[80:95]
	v_add_f32_e64 v100, v6, v22
	v_add_f32_e64 v101, v7, v23
	v_add_f32_e64 v62, v96, v62
	v_add_f32_e64 v63, v97, v63
	v_add_f32_e64 v98, v100, v98
	v_add_f32_e64 v99, v101, v99
	v_add_f32_e32 v58, v60, v58
	v_add_f32_e32 v59, v61, v59
	v_add_f32_e32 v54, v56, v54
	v_add_f32_e32 v55, v57, v55
	v_add_f32_e32 v56, v62, v98
	v_add_f32_e32 v57, v63, v99
	v_add_f32_e32 v54, v54, v58
	v_add_f32_e32 v55, v55, v59
	v_cvt_pk_bf16_f32 v96, v2, v3
	v_pk_mov_b32 v[58:59], v[56:57], v[54:55] op_sel:[1,0]
	v_mov_b32_e32 v57, v55
	v_add_f32_e32 v54, v58, v56
	v_add_f32_e32 v55, v59, v57
	v_cvt_pk_bf16_f32 v97, v4, v5
	v_add_f32_e32 v1, v54, v55
	v_cvt_pk_bf16_f32 v98, v6, v7
	v_cvt_pk_bf16_f32 v99, v8, v9
	v_cvt_pk_bf16_f32 v180, v18, v19
	v_cvt_pk_bf16_f32 v181, v20, v21
	v_cvt_pk_bf16_f32 v182, v22, v23
	v_cvt_pk_bf16_f32 v183, v24, v25
	v_cvt_pk_bf16_f32 v184, v10, v11
	v_cvt_pk_bf16_f32 v185, v12, v13
	v_cvt_pk_bf16_f32 v186, v14, v15
	v_cvt_pk_bf16_f32 v187, v16, v17
	v_cvt_pk_bf16_f32 v176, v26, v27
	v_cvt_pk_bf16_f32 v177, v28, v29
	v_cvt_pk_bf16_f32 v178, v30, v31
	v_cvt_pk_bf16_f32 v179, v32, v33
	v_add_f32_e32 v100, v0, v1
	v_mov_b32_e32 v1, v0
	v_mov_b32_e32 v2, v0
	v_mov_b32_e32 v3, v0
	v_mov_b32_e32 v4, v0
	v_mov_b32_e32 v5, v0
	v_mov_b32_e32 v6, v0
	v_mov_b32_e32 v7, v0
	v_mov_b32_e32 v8, v0
	v_mov_b32_e32 v9, v0
	v_mov_b32_e32 v10, v0
	v_mov_b32_e32 v11, v0
	v_mov_b32_e32 v12, v0
	v_mov_b32_e32 v13, v0
	v_mov_b32_e32 v14, v0
	v_mov_b32_e32 v15, v0
	s_andn2_b64 vcc, exec, s[0:1]
	s_waitcnt vmcnt(2)
	s_barrier
	s_cbranch_vccnz .LBB0_874
	s_and_b32 s0, s3, 15
	s_lshl_b32 s0, s0, 7
	v_readlane_b32 s76, v255, 45
	v_mov_b64_e32 v[62:63], v[14:15]
	v_mov_b64_e32 v[46:47], v[14:15]
	v_mov_b64_e32 v[30:31], v[14:15]
	s_mov_b32 s35, 2
	s_add_i32 s18, s8, 2
	v_add_u32_e32 v237, 0, v229
	v_subrev_u32_e32 v208, s0, v212
	s_mov_b64 s[64:65], 0
	s_mov_b32 s34, 0x10000
	v_readlane_b32 s77, v255, 46
	v_mov_b64_e32 v[60:61], v[12:13]
	v_mov_b64_e32 v[58:59], v[10:11]
	v_mov_b64_e32 v[56:57], v[8:9]
	v_mov_b64_e32 v[54:55], v[6:7]
	v_mov_b64_e32 v[52:53], v[4:5]
	v_mov_b64_e32 v[50:51], v[2:3]
	v_mov_b64_e32 v[48:49], v[0:1]
	v_mov_b64_e32 v[44:45], v[12:13]
	v_mov_b64_e32 v[42:43], v[10:11]
	v_mov_b64_e32 v[40:41], v[8:9]
	v_mov_b64_e32 v[38:39], v[6:7]
	v_mov_b64_e32 v[36:37], v[4:5]
	v_mov_b64_e32 v[34:35], v[2:3]
	v_mov_b64_e32 v[32:33], v[0:1]
	v_mov_b64_e32 v[28:29], v[12:13]
	v_mov_b64_e32 v[26:27], v[10:11]
	v_mov_b64_e32 v[24:25], v[8:9]
	v_mov_b64_e32 v[22:23], v[6:7]
	v_mov_b64_e32 v[20:21], v[4:5]
	v_mov_b64_e32 v[18:19], v[2:3]
	v_mov_b64_e32 v[16:17], v[0:1]

.LBB0_862:
	s_andn2_b64 vcc, exec, s[0:1]
	s_cbranch_vccnz .LBB0_864
	s_add_i32 s0, s74, s64
	s_addk_i32 s0, 0xc0
	s_mul_i32 s0, s0, s14
	s_add_i32 s0, s0, s92
	s_addk_i32 s0, 0x1c00
	s_add_u32 s98, s82, s0
	s_addc_u32 s99, s83, 0
	s_lshl_b32 s1, s17, 13
	s_add_u32 s46, s76, s1
	s_addc_u32 s47, s77, 0
	s_add_i32 s0, s34, 0x8000
	s_and_b32 s0, s0, 0x18000
	s_add_i32 s0, s5, s0
	s_mov_b32 m0, s0
	s_nop 0
	global_load_lds_dwordx4 v244, s[98:99]
	s_add_i32 m0, s0, 0x2000
	s_add_u32 s98, s98, 0x80
	s_addc_u32 s99, s99, 0
	global_load_lds_dwordx4 v244, s[98:99]
	s_add_i32 m0, s0, 0x4000
	s_nop 0
	global_load_lds_dwordx4 v245, s[46:47]
	s_add_i32 m0, s0, 0x6000
	s_add_u32 s46, s46, 0x80000
	s_addc_u32 s47, s47, 0
	global_load_lds_dwordx4 v245, s[46:47]
	v_mov_b64_e32 v[142:143], v[94:95]
	v_mov_b64_e32 v[158:159], v[78:79]
	v_mov_b64_e32 v[140:141], v[92:93]
	v_mov_b64_e32 v[138:139], v[90:91]
	v_mov_b64_e32 v[136:137], v[88:89]
	v_mov_b64_e32 v[134:135], v[86:87]
	v_mov_b64_e32 v[132:133], v[84:85]
	v_mov_b64_e32 v[130:131], v[82:83]
	v_mov_b64_e32 v[128:129], v[80:81]
	v_mov_b64_e32 v[156:157], v[76:77]
	v_mov_b64_e32 v[154:155], v[74:75]
	v_mov_b64_e32 v[152:153], v[72:73]
	v_mov_b64_e32 v[150:151], v[70:71]
	v_mov_b64_e32 v[148:149], v[68:69]
	v_mov_b64_e32 v[146:147], v[66:67]
	v_mov_b64_e32 v[144:145], v[64:65]
.LBB0_864:
	v_max3_f32 v64, v144, v145, v146
	v_max3_f32 v65, v152, v153, v154
	v_max3_f32 v66, v128, v129, v130
	v_max3_f32 v67, v136, v137, v138
	s_add_i32 s9, s34, 0x10000
	v_max3_f32 v64, v64, v147, v148
	v_max3_f32 v65, v65, v155, v156
	v_max3_f32 v66, v66, v131, v132
	v_max3_f32 v67, v67, v139, v140
	s_and_b32 s33, s9, 0x18000
	v_max3_f32 v64, v64, v149, v150
	v_max3_f32 v65, v65, v157, v158
	v_max3_f32 v66, v66, v133, v134
	v_max3_f32 v67, v67, v141, v142
	s_and_b32 s10, s34, 0x18000
	v_max3_f32 v64, v64, v151, v65
	v_max3_f32 v65, v66, v135, v67
	v_max_f32_e32 v66, v214, v214
	v_max3_f32 v64, v64, v159, v143
	s_nop 0
	v_max3_f32 v64, v64, v65, v65
	s_nop 0
	v_mov_b32_e32 v65, v64
	s_nop 1
	v_permlane32_swap_b32_e32 v64, v65
	v_max3_f32 v64, v64, v65, v65
	s_nop 0
	v_max_f32_e32 v65, v64, v64
	v_max_f32_e32 v69, v66, v65
	v_sub_f32_e32 v65, v214, v69
	v_exp_f32_e32 v68, v65
	v_add_f32_e32 v65, 0x41000000, v214
	v_cmp_gt_f32_e32 vcc, v64, v65
	s_cmp_eq_u64 vcc, 0
	v_mul_f32_e32 v64, v100, v68
	s_cselect_b64 s[0:1], -1, 0
	v_cndmask_b32_e64 v194, v64, v100, s[0:1]
	v_add_u32_e32 v239, s33, v237
	v_add_u32_e32 v74, v239, v230
	ds_read_b128 v[64:67], v74 offset:16384
	ds_read_b128 v[70:73], v74 offset:20480
	v_add_u32_e32 v86, s10, v236
	v_add_u32_e32 v78, v239, v233
	v_add_u32_e32 v82, v86, v232
	s_waitcnt lgkmcnt(0)
	v_mfma_f32_32x32x16_bf16 v[0:15], v[64:67], v[96:99], v[0:15]
	v_cndmask_b32_e64 v214, v69, v214, s[0:1]
	v_add_u32_e32 v69, v239, v232
	v_mov_b32_e32 v215, v214
	v_sub_f32_e32 v92, v128, v214
	v_sub_f32_e32 v93, v129, v215
	v_sub_f32_e32 v128, v130, v214
	v_sub_f32_e32 v129, v131, v215
	v_sub_f32_e32 v130, v148, v214
	v_sub_f32_e32 v131, v149, v215
	v_sub_f32_e32 v90, v144, v214
	v_sub_f32_e32 v91, v145, v215
	v_mfma_f32_32x32x16_bf16 v[48:63], v[70:73], v[96:99], v[48:63]
	ds_read_b128 v[64:67], v74 offset:24576
	ds_read_b128 v[70:73], v74 offset:28672
	v_add_u32_e32 v74, v86, v230
	v_sub_f32_e32 v132, v132, v214
	v_sub_f32_e32 v133, v133, v215
	v_sub_f32_e32 v144, v150, v214
	v_sub_f32_e32 v145, v151, v215
	v_sub_f32_e32 v148, v154, v214
	v_sub_f32_e32 v149, v155, v215
	v_sub_f32_e32 v150, v156, v214
	v_sub_f32_e32 v151, v157, v215
	v_sub_f32_e32 v140, v140, v214
	v_sub_f32_e32 v141, v141, v215
	s_waitcnt lgkmcnt(0)
	v_mfma_f32_32x32x16_bf16 v[32:47], v[64:67], v[96:99], v[32:47]
	v_exp_f32_e32 v130, v130
	v_exp_f32_e32 v154, v132
	v_exp_f32_e32 v131, v131
	v_exp_f32_e32 v155, v133
	v_sub_f32_e32 v138, v138, v214
	v_sub_f32_e32 v139, v139, v215
	v_sub_f32_e32 v94, v146, v214
	v_sub_f32_e32 v95, v147, v215
	v_sub_f32_e32 v146, v152, v214
	v_sub_f32_e32 v147, v153, v215
	v_mfma_f32_32x32x16_bf16 v[16:31], v[70:73], v[96:99], v[16:31]
	ds_read_b128 v[64:67], v74
	ds_read_b128 v[70:73], v74 offset:4096
	v_add_u32_e32 v74, v86, v233
	v_add_u32_e32 v86, v86, v231
	v_sub_f32_e32 v152, v158, v214
	v_sub_f32_e32 v153, v159, v215
	v_exp_f32_e32 v158, v138
	v_exp_f32_e32 v159, v139
	v_sub_f32_e32 v142, v142, v214
	v_sub_f32_e32 v143, v143, v215
	s_waitcnt lgkmcnt(0)
	v_mfma_f32_32x32x16_bf16 v[96:111], v[64:67], v[160:163], 0
	ds_read_b128 v[64:67], v74
	ds_read_b128 v[74:77], v74 offset:4096
	v_sub_f32_e32 v134, v134, v214
	v_sub_f32_e32 v135, v135, v215
	v_exp_f32_e32 v94, v94
	v_exp_f32_e32 v128, v128
	v_exp_f32_e32 v95, v95
	v_exp_f32_e32 v129, v129
	v_exp_f32_e32 v132, v144
	v_mfma_f32_32x32x16_bf16 v[112:127], v[70:73], v[160:163], 0
	v_exp_f32_e32 v144, v134
	v_exp_f32_e32 v133, v145
	v_exp_f32_e32 v145, v135
	v_exp_f32_e32 v148, v148
	v_exp_f32_e32 v149, v149
	v_exp_f32_e32 v142, v142
	v_exp_f32_e32 v143, v143
	s_waitcnt lgkmcnt(0)
	v_mfma_f32_32x32x16_bf16 v[96:111], v[64:67], v[164:167], v[96:111]
	ds_read_b128 v[64:67], v78 offset:16384
	ds_read_b128 v[70:73], v78 offset:20480
	v_sub_f32_e32 v136, v136, v214
	v_sub_f32_e32 v137, v137, v215
	v_exp_f32_e32 v90, v90
	v_exp_f32_e32 v92, v92
	v_exp_f32_e32 v91, v91
	v_exp_f32_e32 v93, v93
	v_exp_f32_e32 v146, v146
	v_mfma_f32_32x32x16_bf16 v[112:127], v[74:77], v[164:167], v[112:127]
	v_exp_f32_e32 v156, v136
	v_exp_f32_e32 v147, v147
	v_exp_f32_e32 v157, v137
	v_add_f32_e32 v136, v90, v92
	v_add_f32_e32 v137, v91, v93
	s_waitcnt lgkmcnt(0)
	v_mfma_f32_32x32x16_bf16 v[0:15], v[64:67], v[184:187], v[0:15]
	ds_read_b128 v[64:67], v78 offset:24576
	ds_read_b128 v[74:77], v78 offset:28672
	ds_read_b128 v[78:81], v82
	ds_read_b128 v[82:85], v82 offset:4096
	v_mfma_f32_32x32x16_bf16 v[48:63], v[70:73], v[184:187], v[48:63]
	ds_read_b128 v[70:73], v86
	ds_read_b128 v[86:89], v86 offset:4096
	s_waitcnt lgkmcnt(0)
	v_mfma_f32_32x32x16_bf16 v[32:47], v[64:67], v[184:187], v[32:47]
	ds_read_b128 v[64:67], v69 offset:16384
	v_mfma_f32_32x32x16_bf16 v[16:31], v[74:77], v[184:187], v[16:31]
	ds_read_b128 v[74:77], v69 offset:20480
	s_waitcnt lgkmcnt(0)
	v_mfma_f32_32x32x16_bf16 v[0:15], v[64:67], v[180:183], v[0:15]
	ds_read_b128 v[64:67], v69 offset:24576
	v_mfma_f32_32x32x16_bf16 v[96:111], v[78:81], v[168:171], v[96:111]
	v_exp_f32_e32 v78, v150
	v_exp_f32_e32 v80, v140
	v_exp_f32_e32 v79, v151
	v_exp_f32_e32 v81, v141
	v_exp_f32_e32 v150, v152
	v_exp_f32_e32 v151, v153
	v_mfma_f32_32x32x16_bf16 v[48:63], v[74:77], v[180:183], v[48:63]
	ds_read_b128 v[74:77], v69 offset:28672
	v_add_u32_e32 v69, v239, v231
	v_add_f32_e64 v134, v150, v142
	v_add_f32_e64 v135, v151, v143
	s_waitcnt lgkmcnt(0)
	v_mfma_f32_32x32x16_bf16 v[32:47], v[64:67], v[180:183], v[32:47]
	ds_read_b128 v[64:67], v69 offset:16384
	v_mfma_f32_32x32x16_bf16 v[96:111], v[70:73], v[172:175], v[96:111]
	v_add_f32_e64 v70, v78, v80
	v_add_f32_e64 v71, v79, v81
	v_add_f32_e64 v72, v130, v154
	v_add_f32_e64 v73, v131, v155
	v_add_f32_e64 v138, v72, v70
	v_add_f32_e64 v139, v73, v71
	ds_read_b128 v[70:73], v69 offset:20480
	v_mfma_f32_32x32x16_bf16 v[16:31], v[74:77], v[180:183], v[16:31]
	v_add_f32_e64 v74, v148, v158
	v_add_f32_e64 v75, v149, v159
	v_add_f32_e64 v76, v94, v128
	v_add_f32_e64 v77, v95, v129
	v_add_f32_e64 v74, v76, v74
	v_add_f32_e64 v75, v77, v75
	v_mfma_f32_32x32x16_bf16 v[112:127], v[82:85], v[168:171], v[112:127]
	v_add_f32_e64 v82, v132, v144
	v_add_f32_e64 v83, v133, v145
	v_add_f32_e64 v84, v146, v156
	v_add_f32_e64 v85, v147, v157
	s_waitcnt lgkmcnt(0)
	v_mfma_f32_32x32x16_bf16 v[0:15], v[64:67], v[176:179], v[0:15]
	v_add_f32_e64 v66, v82, v134
	v_add_f32_e64 v67, v83, v135
	v_add_f32_e64 v64, v136, v84
	v_add_f32_e64 v65, v137, v85
	v_add_f32_e64 v66, v74, v66
	v_add_f32_e64 v67, v75, v67
	ds_read_b128 v[74:77], v69 offset:24576
	v_add_f32_e32 v64, v64, v138
	v_add_f32_e32 v65, v65, v139
	v_cvt_pk_bf16_f32 v134, v154, v155
	v_add_f32_e32 v64, v64, v65
	v_mfma_f32_32x32x16_bf16 v[48:63], v[70:73], v[176:179], v[48:63]
	ds_read_b128 v[70:73], v69 offset:28672
	v_add_f32_e32 v65, v66, v67
	v_add_f32_e32 v82, v64, v65
	v_cvt_pk_bf16_f32 v64, v90, v91
	v_cvt_pk_bf16_f32 v65, v94, v95
	v_cvt_pk_bf16_f32 v66, v130, v131
	v_cvt_pk_bf16_f32 v67, v132, v133
	s_waitcnt lgkmcnt(0)
	v_mfma_f32_32x32x16_bf16 v[32:47], v[74:77], v[176:179], v[32:47]
	v_cvt_pk_bf16_f32 v132, v92, v93
	v_cvt_pk_bf16_f32 v133, v128, v129
	v_cvt_pk_bf16_f32 v135, v144, v145
	v_cvt_pk_bf16_f32 v136, v146, v147
	v_cvt_pk_bf16_f32 v137, v148, v149
	v_cvt_pk_bf16_f32 v138, v78, v79
	v_cvt_pk_bf16_f32 v139, v150, v151
	v_mfma_f32_32x32x16_bf16 v[16:31], v[70:73], v[176:179], v[16:31]
	v_cvt_pk_bf16_f32 v128, v156, v157
	v_cvt_pk_bf16_f32 v129, v158, v159
	v_cvt_pk_bf16_f32 v130, v80, v81
	v_cvt_pk_bf16_f32 v131, v142, v143
	v_add_f32_e32 v69, v194, v82
	v_mfma_f32_32x32x16_bf16 v[112:127], v[86:89], v[172:175], v[112:127]
	s_cbranch_vccz .LBB0_866
	v_pk_mul_f32 v[14:15], v[68:69], v[14:15] op_sel_hi:[0,1]
	v_pk_mul_f32 v[12:13], v[68:69], v[12:13] op_sel_hi:[0,1]
	v_pk_mul_f32 v[10:11], v[68:69], v[10:11] op_sel_hi:[0,1]
	v_pk_mul_f32 v[8:9], v[68:69], v[8:9] op_sel_hi:[0,1]
	v_pk_mul_f32 v[6:7], v[68:69], v[6:7] op_sel_hi:[0,1]
	v_pk_mul_f32 v[4:5], v[68:69], v[4:5] op_sel_hi:[0,1]
	v_pk_mul_f32 v[2:3], v[68:69], v[2:3] op_sel_hi:[0,1]
	v_pk_mul_f32 v[0:1], v[68:69], v[0:1] op_sel_hi:[0,1]
	v_pk_mul_f32 v[62:63], v[68:69], v[62:63] op_sel_hi:[0,1]
	v_pk_mul_f32 v[60:61], v[68:69], v[60:61] op_sel_hi:[0,1]
	v_pk_mul_f32 v[58:59], v[68:69], v[58:59] op_sel_hi:[0,1]
	v_pk_mul_f32 v[56:57], v[68:69], v[56:57] op_sel_hi:[0,1]
	v_pk_mul_f32 v[54:55], v[68:69], v[54:55] op_sel_hi:[0,1]
	v_pk_mul_f32 v[52:53], v[68:69], v[52:53] op_sel_hi:[0,1]
	v_pk_mul_f32 v[50:51], v[68:69], v[50:51] op_sel_hi:[0,1]
	v_pk_mul_f32 v[48:49], v[68:69], v[48:49] op_sel_hi:[0,1]
	v_pk_mul_f32 v[46:47], v[68:69], v[46:47] op_sel_hi:[0,1]
	v_pk_mul_f32 v[44:45], v[68:69], v[44:45] op_sel_hi:[0,1]
	v_pk_mul_f32 v[42:43], v[68:69], v[42:43] op_sel_hi:[0,1]
	v_pk_mul_f32 v[40:41], v[68:69], v[40:41] op_sel_hi:[0,1]
	v_pk_mul_f32 v[38:39], v[68:69], v[38:39] op_sel_hi:[0,1]
	v_pk_mul_f32 v[36:37], v[68:69], v[36:37] op_sel_hi:[0,1]
	v_pk_mul_f32 v[34:35], v[68:69], v[34:35] op_sel_hi:[0,1]
	v_pk_mul_f32 v[32:33], v[68:69], v[32:33] op_sel_hi:[0,1]
	v_pk_mul_f32 v[30:31], v[68:69], v[30:31] op_sel_hi:[0,1]
	v_pk_mul_f32 v[28:29], v[68:69], v[28:29] op_sel_hi:[0,1]
	v_pk_mul_f32 v[26:27], v[68:69], v[26:27] op_sel_hi:[0,1]
	v_pk_mul_f32 v[24:25], v[68:69], v[24:25] op_sel_hi:[0,1]
	v_pk_mul_f32 v[22:23], v[68:69], v[22:23] op_sel_hi:[0,1]
	v_pk_mul_f32 v[20:21], v[68:69], v[20:21] op_sel_hi:[0,1]
	v_pk_mul_f32 v[18:19], v[68:69], v[18:19] op_sel_hi:[0,1]
	v_pk_mul_f32 v[16:17], v[68:69], v[16:17] op_sel_hi:[0,1]
.LBB0_866:
	s_add_i32 s10, s35, 2
	s_cmp_ge_u32 s10, s18
	s_cselect_b64 s[90:91], -1, 0
	s_and_b64 vcc, exec, s[90:91]
	s_waitcnt vmcnt(2)
	s_barrier
	s_cbranch_vccnz .LBB0_868
	s_add_i32 s0, s74, s64
	s_addk_i32 s0, 0x100
	s_mul_i32 s0, s0, s14
	s_add_i32 s0, s0, s92
	s_addk_i32 s0, 0x1c00
	s_add_u32 s98, s82, s0
	s_addc_u32 s99, s83, 0
	s_lshl_b32 s1, s17, 13
	s_add_u32 s0, s76, s1
	s_addc_u32 s1, s77, 0
	s_add_u32 s0, s0, 0x80
	s_addc_u32 s1, s1, 0
	s_add_i32 s32, s5, s33
	s_mov_b32 m0, s32
	s_nop 0
	global_load_lds_dwordx4 v244, s[98:99]
	s_add_i32 m0, s32, 0x2000
	s_add_u32 s98, s98, 0x80
	s_addc_u32 s99, s99, 0
	global_load_lds_dwordx4 v244, s[98:99]
	s_add_i32 m0, s32, 0x4000
	s_nop 0
	global_load_lds_dwordx4 v245, s[0:1]
	s_add_i32 m0, s32, 0x6000
	s_add_u32 s0, s0, 0x80000
	s_addc_u32 s1, s1, 0
	global_load_lds_dwordx4 v245, s[0:1]

.LBB0_870:
	v_max3_f32 v68, v96, v97, v98
	v_max3_f32 v70, v104, v105, v106
	v_max3_f32 v71, v112, v113, v114
	v_max3_f32 v72, v120, v121, v122
	s_add_i32 s0, s34, 0xffff8000
	v_max3_f32 v68, v68, v99, v100
	v_max3_f32 v70, v70, v107, v108
	v_max3_f32 v71, v71, v115, v116
	v_max3_f32 v72, v72, v123, v124
	s_and_b32 s33, s0, 0x18000
	v_max3_f32 v68, v68, v101, v102
	v_max3_f32 v70, v70, v109, v110
	v_max3_f32 v71, v71, v117, v118
	v_max3_f32 v72, v72, v125, v126
	s_xor_b32 s34, s33, 0x10000
	v_max3_f32 v68, v68, v103, v70
	v_max3_f32 v70, v71, v119, v72
	v_max_f32_e32 v71, v214, v214
	v_max3_f32 v68, v68, v111, v127
	s_nop 0
	v_max3_f32 v68, v68, v70, v70
	s_nop 0
	v_mov_b32_e32 v70, v68
	s_nop 1
	v_permlane32_swap_b32_e32 v68, v70
	v_max3_f32 v68, v68, v70, v70
	s_nop 0
	v_max_f32_e32 v70, v68, v68
	v_max_f32_e32 v141, v71, v70
	v_sub_f32_e32 v70, v214, v141
	v_exp_f32_e32 v140, v70
	v_add_f32_e32 v70, 0x41000000, v214
	v_cmp_gt_f32_e32 vcc, v68, v70
	s_cmp_eq_u64 vcc, 0
	v_mul_f32_e32 v68, v69, v140
	s_cselect_b64 s[0:1], -1, 0
	v_cndmask_b32_e64 v194, v68, v69, s[0:1]
	v_add_u32_e32 v182, s33, v237
	v_add_u32_e32 v76, v182, v230
	ds_read_b128 v[68:71], v76 offset:16384
	ds_read_b128 v[72:75], v76 offset:20480
	v_add_u32_e32 v158, s34, v236
	v_add_u32_e32 v88, v158, v233
	v_add_u32_e32 v150, v182, v233
	s_waitcnt lgkmcnt(0)
	v_mfma_f32_32x32x16_bf16 v[0:15], v[68:71], v[64:67], v[0:15]
	v_add_u32_e32 v159, v158, v232
	v_cndmask_b32_e64 v214, v141, v214, s[0:1]
	v_add_u32_e32 v141, v182, v232
	v_mov_b32_e32 v215, v214
	v_sub_f32_e32 v180, v102, v214
	v_sub_f32_e32 v181, v103, v215
	v_sub_f32_e32 v116, v116, v214
	v_sub_f32_e32 v117, v117, v215
	v_sub_f32_e32 v108, v108, v214
	v_sub_f32_e32 v109, v109, v215
	v_mfma_f32_32x32x16_bf16 v[48:63], v[72:75], v[64:67], v[48:63]
	ds_read_b128 v[68:71], v76 offset:24576
	ds_read_b128 v[72:75], v76 offset:28672
	v_sub_f32_e32 v124, v124, v214
	v_sub_f32_e32 v125, v125, v215
	v_exp_f32_e32 v116, v116
	v_exp_f32_e32 v117, v117
	v_exp_f32_e32 v108, v108
	v_exp_f32_e32 v124, v124
	v_exp_f32_e32 v109, v109
	s_waitcnt lgkmcnt(0)
	v_mfma_f32_32x32x16_bf16 v[32:47], v[68:71], v[64:67], v[32:47]
	v_add_u32_e32 v68, v158, v230
	v_add_u32_e32 v158, v158, v231
	v_exp_f32_e32 v125, v125
	v_sub_f32_e32 v114, v114, v214
	v_sub_f32_e32 v115, v115, v215
	v_sub_f32_e32 v118, v118, v214
	v_sub_f32_e32 v119, v119, v215
	v_sub_f32_e32 v122, v122, v214
	v_sub_f32_e32 v123, v123, v215
	v_sub_f32_e32 v110, v110, v214
	v_sub_f32_e32 v111, v111, v215
	v_mfma_f32_32x32x16_bf16 v[16:31], v[72:75], v[64:67], v[16:31]
	ds_read_b128 v[64:67], v68
	ds_read_b128 v[80:83], v68 offset:4096
	ds_read_b128 v[84:87], v88
	ds_read_b128 v[142:145], v88 offset:4096
	v_sub_f32_e32 v126, v126, v214
	v_sub_f32_e32 v127, v127, v215
	v_sub_f32_e32 v106, v106, v214
	v_sub_f32_e32 v107, v107, v215
	v_exp_f32_e32 v114, v114
	v_exp_f32_e32 v115, v115
	v_exp_f32_e32 v118, v118
	s_waitcnt lgkmcnt(0)
	v_mfma_f32_32x32x16_bf16 v[64:79], v[64:67], v[160:163], 0
	v_exp_f32_e32 v119, v119
	v_exp_f32_e32 v122, v122
	v_exp_f32_e32 v123, v123
	v_exp_f32_e32 v110, v110
	v_exp_f32_e32 v126, v126
	v_exp_f32_e32 v111, v111
	v_exp_f32_e32 v127, v127
	v_mfma_f32_32x32x16_bf16 v[64:79], v[84:87], v[164:167], v[64:79]
	v_sub_f32_e32 v104, v104, v214
	v_sub_f32_e32 v105, v105, v215
	v_sub_f32_e32 v112, v112, v214
	v_sub_f32_e32 v113, v113, v215
	v_sub_f32_e32 v120, v120, v214
	v_sub_f32_e32 v121, v121, v215
	v_cvt_pk_bf16_f32 v183, v118, v119
	v_exp_f32_e32 v112, v112
	v_exp_f32_e32 v113, v113
	v_exp_f32_e32 v120, v120
	v_mfma_f32_32x32x16_bf16 v[80:95], v[80:83], v[160:163], 0
	v_exp_f32_e32 v121, v121
	v_cvt_pk_bf16_f32 v186, v108, v109
	v_cvt_pk_bf16_f32 v187, v110, v111
	v_mfma_f32_32x32x16_bf16 v[80:95], v[142:145], v[164:167], v[80:95]
	ds_read_b128 v[142:145], v150 offset:16384
	ds_read_b128 v[146:149], v150 offset:20480
	s_waitcnt lgkmcnt(0)
	v_mfma_f32_32x32x16_bf16 v[0:15], v[142:145], v[136:139], v[0:15]
	ds_read_b128 v[142:145], v150 offset:24576
	ds_read_b128 v[150:153], v150 offset:28672
	ds_read_b128 v[154:157], v159
	ds_read_b128 v[176:179], v159 offset:4096
	v_mfma_f32_32x32x16_bf16 v[48:63], v[146:149], v[136:139], v[48:63]
	ds_read_b128 v[146:149], v158
	ds_read_b128 v[238:241], v158 offset:4096
	v_sub_f32_e32 v158, v96, v214
	v_sub_f32_e32 v159, v97, v215
	s_waitcnt lgkmcnt(0)
	v_mfma_f32_32x32x16_bf16 v[32:47], v[142:145], v[136:139], v[32:47]
	v_sub_f32_e32 v142, v98, v214
	v_sub_f32_e32 v143, v99, v215
	v_sub_f32_e32 v144, v100, v214
	v_sub_f32_e32 v145, v101, v215
	ds_read_b128 v[96:99], v141 offset:16384
	ds_read_b128 v[100:103], v141 offset:20480
	s_waitcnt lgkmcnt(0)
	v_mfma_f32_32x32x16_bf16 v[0:15], v[96:99], v[132:135], v[0:15]
	ds_read_b128 v[96:99], v141 offset:24576
	v_mfma_f32_32x32x16_bf16 v[48:63], v[100:103], v[132:135], v[48:63]
	ds_read_b128 v[100:103], v141 offset:28672
	v_add_u32_e32 v141, v182, v231
	v_cvt_pk_bf16_f32 v182, v116, v117
	v_mfma_f32_32x32x16_bf16 v[16:31], v[150:153], v[136:139], v[16:31]
	v_exp_f32_e32 v138, v142
	v_exp_f32_e32 v139, v143
	v_exp_f32_e32 v142, v144
	v_exp_f32_e32 v143, v145
	v_exp_f32_e32 v144, v180
	v_exp_f32_e32 v145, v181
	v_exp_f32_e32 v136, v158
	s_waitcnt lgkmcnt(0)
	v_mfma_f32_32x32x16_bf16 v[32:47], v[96:99], v[132:135], v[32:47]
	ds_read_b128 v[96:99], v141 offset:16384
	v_exp_f32_e32 v137, v159
	v_cvt_pk_bf16_f32 v180, v112, v113
	v_cvt_pk_bf16_f32 v181, v114, v115
	v_add_f32_e32 v152, v136, v112
	v_add_f32_e32 v153, v137, v113
	v_mfma_f32_32x32x16_bf16 v[16:31], v[100:103], v[132:135], v[16:31]
	v_add_f32_e64 v100, v108, v124
	v_add_f32_e64 v101, v109, v125
	v_add_f32_e64 v102, v142, v116
	v_add_f32_e64 v103, v143, v117
	v_exp_f32_e32 v134, v106
	v_exp_f32_e32 v135, v107
	v_exp_f32_e32 v132, v104
	v_exp_f32_e32 v133, v105
	v_add_f32_e32 v106, v138, v114
	v_add_f32_e32 v107, v139, v115
	v_mfma_f32_32x32x16_bf16 v[64:79], v[154:157], v[168:171], v[64:79]
	v_add_f32_e64 v154, v102, v100
	v_add_f32_e64 v155, v103, v101
	ds_read_b128 v[100:103], v141 offset:20480
	v_add_f32_e64 v104, v134, v122
	v_add_f32_e64 v105, v135, v123
	v_add_f32_e32 v150, v132, v120
	v_add_f32_e32 v151, v133, v121
	v_add_f32_e32 v104, v106, v104
	v_add_f32_e32 v105, v107, v105
	v_cvt_pk_bf16_f32 v184, v132, v133
	v_cvt_pk_bf16_f32 v185, v134, v135
	v_mfma_f32_32x32x16_bf16 v[64:79], v[146:149], v[172:175], v[64:79]
	v_add_f32_e64 v146, v110, v126
	v_add_f32_e64 v147, v111, v127
	v_add_f32_e64 v148, v144, v118
	v_add_f32_e64 v149, v145, v119
	s_waitcnt lgkmcnt(0)
	v_mfma_f32_32x32x16_bf16 v[0:15], v[96:99], v[128:131], v[0:15]
	v_add_f32_e64 v98, v148, v146
	v_add_f32_e64 v99, v149, v147
	v_add_f32_e64 v96, v152, v150
	v_add_f32_e64 v97, v153, v151
	v_add_f32_e64 v98, v104, v98
	v_add_f32_e64 v99, v105, v99
	ds_read_b128 v[104:107], v141 offset:24576
	v_add_f32_e32 v96, v96, v154
	v_add_f32_e32 v97, v97, v155
	s_nop 0
	v_add_f32_e32 v96, v96, v97
	v_mfma_f32_32x32x16_bf16 v[48:63], v[100:103], v[128:131], v[48:63]
	ds_read_b128 v[100:103], v141 offset:28672
	v_add_f32_e32 v97, v98, v99
	v_add_f32_e32 v146, v96, v97
	v_cvt_pk_bf16_f32 v96, v136, v137
	v_cvt_pk_bf16_f32 v97, v138, v139
	v_cvt_pk_bf16_f32 v98, v142, v143
	v_cvt_pk_bf16_f32 v99, v144, v145
	v_mfma_f32_32x32x16_bf16 v[80:95], v[176:179], v[168:171], v[80:95]
	v_cvt_pk_bf16_f32 v176, v120, v121
	v_cvt_pk_bf16_f32 v177, v122, v123
	v_cvt_pk_bf16_f32 v178, v124, v125
	v_cvt_pk_bf16_f32 v179, v126, v127
	s_waitcnt lgkmcnt(0)
	v_mfma_f32_32x32x16_bf16 v[32:47], v[104:107], v[128:131], v[32:47]
	v_mfma_f32_32x32x16_bf16 v[16:31], v[100:103], v[128:131], v[16:31]
	v_add_f32_e32 v100, v194, v146
	v_mfma_f32_32x32x16_bf16 v[80:95], v[238:241], v[172:175], v[80:95]
	s_cbranch_vccz .LBB0_872
	v_pk_mul_f32 v[14:15], v[140:141], v[14:15] op_sel_hi:[0,1]
	v_pk_mul_f32 v[12:13], v[140:141], v[12:13] op_sel_hi:[0,1]
	v_pk_mul_f32 v[10:11], v[140:141], v[10:11] op_sel_hi:[0,1]
	v_pk_mul_f32 v[8:9], v[140:141], v[8:9] op_sel_hi:[0,1]
	v_pk_mul_f32 v[6:7], v[140:141], v[6:7] op_sel_hi:[0,1]
	v_pk_mul_f32 v[4:5], v[140:141], v[4:5] op_sel_hi:[0,1]
	v_pk_mul_f32 v[2:3], v[140:141], v[2:3] op_sel_hi:[0,1]
	v_pk_mul_f32 v[0:1], v[140:141], v[0:1] op_sel_hi:[0,1]
	v_pk_mul_f32 v[62:63], v[140:141], v[62:63] op_sel_hi:[0,1]
	v_pk_mul_f32 v[60:61], v[140:141], v[60:61] op_sel_hi:[0,1]
	v_pk_mul_f32 v[58:59], v[140:141], v[58:59] op_sel_hi:[0,1]
	v_pk_mul_f32 v[56:57], v[140:141], v[56:57] op_sel_hi:[0,1]
	v_pk_mul_f32 v[54:55], v[140:141], v[54:55] op_sel_hi:[0,1]
	v_pk_mul_f32 v[52:53], v[140:141], v[52:53] op_sel_hi:[0,1]
	v_pk_mul_f32 v[50:51], v[140:141], v[50:51] op_sel_hi:[0,1]
	v_pk_mul_f32 v[48:49], v[140:141], v[48:49] op_sel_hi:[0,1]
	v_pk_mul_f32 v[46:47], v[140:141], v[46:47] op_sel_hi:[0,1]
	v_pk_mul_f32 v[44:45], v[140:141], v[44:45] op_sel_hi:[0,1]
	v_pk_mul_f32 v[42:43], v[140:141], v[42:43] op_sel_hi:[0,1]
	v_pk_mul_f32 v[40:41], v[140:141], v[40:41] op_sel_hi:[0,1]
	v_pk_mul_f32 v[38:39], v[140:141], v[38:39] op_sel_hi:[0,1]
	v_pk_mul_f32 v[36:37], v[140:141], v[36:37] op_sel_hi:[0,1]
	v_pk_mul_f32 v[34:35], v[140:141], v[34:35] op_sel_hi:[0,1]
	v_pk_mul_f32 v[32:33], v[140:141], v[32:33] op_sel_hi:[0,1]
	v_pk_mul_f32 v[30:31], v[140:141], v[30:31] op_sel_hi:[0,1]
	v_pk_mul_f32 v[28:29], v[140:141], v[28:29] op_sel_hi:[0,1]
	v_pk_mul_f32 v[26:27], v[140:141], v[26:27] op_sel_hi:[0,1]
	v_pk_mul_f32 v[24:25], v[140:141], v[24:25] op_sel_hi:[0,1]
	v_pk_mul_f32 v[22:23], v[140:141], v[22:23] op_sel_hi:[0,1]
	v_pk_mul_f32 v[20:21], v[140:141], v[20:21] op_sel_hi:[0,1]
	v_pk_mul_f32 v[18:19], v[140:141], v[18:19] op_sel_hi:[0,1]
	v_pk_mul_f32 v[16:17], v[140:141], v[16:17] op_sel_hi:[0,1]

.LBB0_875:
	s_or_b32 s9, s8, 1
	s_sub_i32 s1, s9, s8
	v_lshl_or_b32 v101, s1, 6, v212
	v_or_b32_e32 v102, 32, v101
	v_cmp_le_i32_e32 vcc, v102, v235
	s_lshl_b32 s0, s16, 16
	s_and_b32 s0, s0, 0x10000
	v_cndmask_b32_e32 v102, v226, v80, vcc
	v_cmp_le_i32_e32 vcc, v101, v235
	s_add_i32 s8, s0, 0
	v_and_b32_e32 v112, 63, v234
	v_cndmask_b32_e32 v104, v226, v64, vcc
	v_cmp_lt_i32_e32 vcc, v101, v235
	v_or_b32_e32 v64, 33, v101
	s_nop 0
	v_cndmask_b32_e32 v105, v226, v65, vcc
	v_cmp_le_i32_e32 vcc, v64, v235
	v_or_b32_e32 v64, 2, v101
	s_nop 0
	v_cndmask_b32_e32 v103, v226, v81, vcc
	v_cmp_le_i32_e32 vcc, v64, v235
	v_or_b32_e32 v64, 34, v101
	s_nop 0
	v_cndmask_b32_e32 v106, v226, v66, vcc
	v_cmp_le_i32_e32 vcc, v64, v235
	v_or_b32_e32 v64, 3, v101
	s_nop 0
	v_cndmask_b32_e32 v108, v226, v82, vcc
	v_cmp_le_i32_e32 vcc, v64, v235
	v_or_b32_e32 v64, 35, v101
	v_max3_f32 v66, v102, v103, v108
	s_nop 0
	v_cndmask_b32_e32 v107, v226, v67, vcc
	v_cmp_le_i32_e32 vcc, v64, v235
	v_or_b32_e32 v64, 8, v101
	s_nop 0
	v_cndmask_b32_e32 v109, v226, v83, vcc
	v_cmp_le_i32_e32 vcc, v64, v235
	v_or_b32_e32 v64, 40, v101
	s_nop 0
	v_cndmask_b32_e32 v110, v226, v68, vcc
	v_cmp_le_i32_e32 vcc, v64, v235
	v_or_b32_e32 v64, 9, v101
	s_nop 0
	v_cndmask_b32_e32 v114, v226, v84, vcc
	v_cmp_le_i32_e32 vcc, v64, v235
	v_or_b32_e32 v64, 41, v101
	v_max3_f32 v66, v66, v109, v114
	s_nop 0
	v_cndmask_b32_e32 v111, v226, v69, vcc
	v_cmp_le_i32_e32 vcc, v64, v235
	v_or_b32_e32 v64, 10, v101
	s_nop 0
	v_cndmask_b32_e32 v115, v226, v85, vcc
	v_cmp_le_i32_e32 vcc, v64, v235
	v_or_b32_e32 v64, 42, v101
	s_nop 0
	v_cndmask_b32_e32 v116, v226, v70, vcc
	v_cmp_le_i32_e32 vcc, v64, v235
	v_or_b32_e32 v64, 11, v101
	s_nop 0
	v_cndmask_b32_e32 v118, v226, v86, vcc
	v_cmp_le_i32_e32 vcc, v64, v235
	v_or_b32_e32 v64, 43, v101
	v_max3_f32 v66, v66, v115, v118
	s_nop 0
	v_cndmask_b32_e32 v117, v226, v71, vcc
	v_cmp_le_i32_e32 vcc, v64, v235
	v_or_b32_e32 v64, 16, v101
	s_nop 0
	v_cndmask_b32_e32 v119, v226, v87, vcc
	v_cmp_le_i32_e32 vcc, v64, v235
	v_or_b32_e32 v64, 48, v101
	s_nop 0
	v_cndmask_b32_e32 v120, v226, v72, vcc
	v_cmp_le_i32_e32 vcc, v64, v235
	v_or_b32_e32 v64, 17, v101
	s_nop 0
	v_cndmask_b32_e32 v122, v226, v88, vcc
	v_cmp_le_i32_e32 vcc, v64, v235
	v_or_b32_e32 v64, 49, v101
	s_nop 0
	v_cndmask_b32_e32 v121, v226, v73, vcc
	v_cmp_le_i32_e32 vcc, v64, v235
	v_or_b32_e32 v64, 18, v101
	s_nop 0
	v_cndmask_b32_e32 v123, v226, v89, vcc
	v_cmp_le_i32_e32 vcc, v64, v235
	v_or_b32_e32 v64, 50, v101
	s_nop 0
	v_cndmask_b32_e32 v124, v226, v74, vcc
	v_cmp_le_i32_e32 vcc, v64, v235
	v_or_b32_e32 v64, 19, v101
	v_max3_f32 v65, v120, v121, v124
	s_nop 0
	v_cndmask_b32_e32 v90, v226, v90, vcc
	v_cmp_le_i32_e32 vcc, v64, v235
	v_or_b32_e32 v64, 51, v101
	v_max3_f32 v67, v122, v123, v90
	s_nop 0
	v_cndmask_b32_e32 v125, v226, v75, vcc
	v_cmp_le_i32_e32 vcc, v64, v235
	v_or_b32_e32 v64, 24, v101
	s_nop 0
	v_cndmask_b32_e32 v91, v226, v91, vcc
	v_cmp_le_i32_e32 vcc, v64, v235
	v_or_b32_e32 v64, 56, v101
	s_nop 0
	v_cndmask_b32_e32 v126, v226, v76, vcc
	v_cmp_le_i32_e32 vcc, v64, v235
	v_or_b32_e32 v64, 25, v101
	v_max3_f32 v65, v65, v125, v126
	s_nop 0
	v_cndmask_b32_e32 v92, v226, v92, vcc
	v_cmp_le_i32_e32 vcc, v64, v235
	v_or_b32_e32 v64, 57, v101
	v_max3_f32 v67, v67, v91, v92
	s_nop 0
	v_cndmask_b32_e32 v127, v226, v77, vcc
	v_cmp_le_i32_e32 vcc, v64, v235
	v_or_b32_e32 v64, 26, v101
	s_nop 0
	v_cndmask_b32_e32 v93, v226, v93, vcc
	v_cmp_le_i32_e32 vcc, v64, v235
	v_or_b32_e32 v64, 58, v101
	s_nop 0
	v_cndmask_b32_e32 v128, v226, v78, vcc
	v_cmp_le_i32_e32 vcc, v64, v235
	v_or_b32_e32 v64, 27, v101
	v_max3_f32 v65, v65, v127, v128
	s_nop 0
	v_cndmask_b32_e32 v94, v226, v94, vcc
	v_cmp_le_i32_e32 vcc, v64, v235
	v_or_b32_e32 v64, 59, v101
	v_max3_f32 v67, v67, v93, v94
	s_nop 0
	v_cndmask_b32_e32 v129, v226, v79, vcc
	v_cmp_le_i32_e32 vcc, v64, v235
	v_max3_f32 v64, v104, v105, v106
	s_nop 0
	v_max3_f32 v64, v64, v107, v110
	s_nop 0
	v_max3_f32 v64, v64, v111, v116
	v_cndmask_b32_e32 v95, v226, v95, vcc
	v_max3_f32 v64, v64, v117, v65
	v_max3_f32 v65, v66, v119, v67
	v_max_f32_e32 v66, v214, v214
	v_max3_f32 v64, v64, v129, v95
	s_nop 0
	v_max3_f32 v64, v64, v65, v65
	s_nop 0
	v_mov_b32_e32 v65, v64
	s_nop 1
	v_permlane32_swap_b32_e32 v64, v65
	v_max3_f32 v65, v64, v65, v65
	s_nop 0
	v_max_f32_e32 v64, v65, v65
	v_max_f32_e32 v101, v66, v64
	v_sub_f32_e32 v64, v214, v101
	v_exp_f32_e32 v64, v64
	v_add_f32_e32 v66, 0x41000000, v214
	v_cmp_gt_f32_e32 vcc, v65, v66
	s_cmp_eq_u64 vcc, 0
	v_mul_f32_e32 v65, v100, v64
	s_cselect_b64 s[0:1], -1, 0
	v_cndmask_b32_e64 v65, v65, v100, s[0:1]
	v_add_u32_e32 v113, s8, v229
	v_add_u32_e32 v74, v113, v230
	ds_read_b128 v[66:69], v74 offset:16384
	ds_read_b128 v[70:73], v74 offset:20480
	v_add_u32_e32 v86, v113, v233
	v_cndmask_b32_e64 v100, v101, v214, s[0:1]
	v_mov_b32_e32 v101, v100
	s_waitcnt lgkmcnt(1)
	v_mfma_f32_32x32x16_bf16 v[0:15], v[66:69], v[96:99], v[0:15]
	ds_read_b128 v[66:69], v74 offset:24576
	ds_read_b128 v[74:77], v74 offset:28672
	v_sub_f32_e32 v104, v104, v100
	v_sub_f32_e32 v105, v105, v101
	v_sub_f32_e32 v90, v90, v100
	v_sub_f32_e32 v91, v91, v101
	v_sub_f32_e32 v92, v92, v100
	v_sub_f32_e32 v93, v93, v101
	v_sub_f32_e32 v94, v94, v100
	v_sub_f32_e32 v95, v95, v101
	s_nop 0
	v_exp_f32_e32 v94, v94
	s_waitcnt lgkmcnt(2)
	v_mfma_f32_32x32x16_bf16 v[48:63], v[70:73], v[96:99], v[48:63]
	ds_read_b128 v[70:73], v86 offset:16384
	ds_read_b128 v[78:81], v86 offset:20480
	ds_read_b128 v[82:85], v86 offset:24576
	ds_read_b128 v[86:89], v86 offset:28672
	v_exp_f32_e32 v95, v95
	s_waitcnt lgkmcnt(5)
	v_mfma_f32_32x32x16_bf16 v[32:47], v[66:69], v[96:99], v[32:47]
	v_sub_f32_e32 v66, v102, v100
	v_sub_f32_e32 v67, v103, v101
	v_sub_f32_e32 v68, v106, v100
	v_sub_f32_e32 v69, v107, v101
	v_sub_f32_e32 v102, v108, v100
	v_sub_f32_e32 v103, v109, v101
	v_sub_f32_e32 v106, v110, v100
	v_sub_f32_e32 v107, v111, v101
	v_sub_f32_e32 v108, v114, v100
	v_sub_f32_e32 v109, v115, v101
	v_sub_f32_e32 v110, v116, v100
	v_sub_f32_e32 v111, v117, v101
	v_sub_f32_e32 v114, v118, v100
	v_sub_f32_e32 v115, v119, v101
	s_waitcnt lgkmcnt(4)
	v_mfma_f32_32x32x16_bf16 v[16:31], v[74:77], v[96:99], v[16:31]
	v_sub_f32_e32 v74, v120, v100
	v_sub_f32_e32 v75, v121, v101
	v_add_u32_e32 v120, v113, v232
	v_sub_f32_e32 v76, v122, v100
	v_sub_f32_e32 v77, v123, v101
	v_sub_f32_e32 v96, v124, v100
	v_sub_f32_e32 v97, v125, v101
	v_sub_f32_e32 v98, v126, v100
	v_sub_f32_e32 v99, v127, v101
	v_sub_f32_e32 v116, v128, v100
	v_sub_f32_e32 v117, v129, v101
	v_exp_f32_e32 v100, v104
	v_exp_f32_e32 v104, v66
	v_exp_f32_e32 v101, v105
	v_exp_f32_e32 v105, v67
	v_exp_f32_e32 v118, v68
	v_exp_f32_e32 v119, v69
	ds_read_b128 v[66:69], v120 offset:16384
	s_waitcnt lgkmcnt(4)
	v_mfma_f32_32x32x16_bf16 v[0:15], v[70:73], v[184:187], v[0:15]
	ds_read_b128 v[70:73], v120 offset:20480
	v_exp_f32_e32 v102, v102
	v_exp_f32_e32 v103, v103
	v_exp_f32_e32 v114, v114
	v_exp_f32_e32 v115, v115
	v_exp_f32_e32 v74, v74
	v_exp_f32_e32 v76, v76
	s_waitcnt lgkmcnt(4)
	v_mfma_f32_32x32x16_bf16 v[48:63], v[78:81], v[184:187], v[48:63]
	v_exp_f32_e32 v78, v106
	v_exp_f32_e32 v80, v108
	v_exp_f32_e32 v79, v107
	v_exp_f32_e32 v81, v109
	v_exp_f32_e32 v106, v110
	v_exp_f32_e32 v107, v111
	v_exp_f32_e32 v75, v75
	s_waitcnt lgkmcnt(1)
	v_mfma_f32_32x32x16_bf16 v[0:15], v[66:69], v[180:183], v[0:15]
	ds_read_b128 v[66:69], v120 offset:24576
	v_exp_f32_e32 v77, v77
	v_add_f32_e32 v108, v106, v114
	v_add_f32_e32 v109, v107, v115
	v_add_u32_e32 v113, v113, v231
	v_add_f32_e32 v110, v74, v76
	v_add_f32_e32 v111, v75, v77
	v_mfma_f32_32x32x16_bf16 v[32:47], v[82:85], v[184:187], v[32:47]
	v_exp_f32_e32 v82, v96
	v_exp_f32_e32 v84, v90
	v_exp_f32_e32 v83, v97
	v_exp_f32_e32 v85, v91
	v_exp_f32_e32 v90, v116
	v_exp_f32_e32 v91, v117
	v_add_f32_e32 v96, v118, v102
	v_add_f32_e32 v97, v119, v103
	s_waitcnt lgkmcnt(1)
	v_mfma_f32_32x32x16_bf16 v[48:63], v[70:73], v[180:183], v[48:63]
	ds_read_b128 v[70:73], v120 offset:28672
	v_add_f32_e64 v116, v78, v80
	v_add_f32_e64 v117, v79, v81
	v_mfma_f32_32x32x16_bf16 v[16:31], v[86:89], v[184:187], v[16:31]
	v_exp_f32_e32 v86, v98
	v_exp_f32_e32 v88, v92
	v_exp_f32_e32 v87, v99
	v_exp_f32_e32 v89, v93
	v_add_f32_e32 v92, v82, v84
	v_add_f32_e32 v93, v83, v85
	v_add_f32_e32 v98, v90, v94
	v_add_f32_e32 v99, v91, v95
	s_waitcnt lgkmcnt(1)
	v_mfma_f32_32x32x16_bf16 v[32:47], v[66:69], v[180:183], v[32:47]
	v_add_f32_e64 v66, v100, v104
	v_add_f32_e64 v67, v101, v105
	v_add_f32_e64 v68, v86, v88
	v_add_f32_e64 v69, v87, v89
	v_add_f32_e64 v110, v66, v110
	v_add_f32_e64 v111, v67, v111
	v_add_f32_e32 v116, v116, v68
	v_add_f32_e32 v117, v117, v69
	ds_read_b128 v[66:69], v113 offset:16384
	s_waitcnt lgkmcnt(1)
	v_mfma_f32_32x32x16_bf16 v[16:31], v[70:73], v[180:183], v[16:31]
	v_add_f32_e64 v70, v108, v98
	v_add_f32_e64 v71, v109, v99
	v_add_f32_e64 v72, v96, v92
	v_add_f32_e64 v73, v97, v93
	v_cvt_pk_bf16_f32 v108, v100, v101
	v_add_f32_e32 v70, v72, v70
	v_add_f32_e32 v71, v73, v71
	v_add_f32_e32 v72, v110, v116
	v_add_f32_e32 v73, v111, v117
	v_add_f32_e32 v93, v70, v71
	v_add_f32_e32 v92, v72, v73
	ds_read_b128 v[70:73], v113 offset:20480
	s_waitcnt lgkmcnt(1)
	v_mfma_f32_32x32x16_bf16 v[0:15], v[66:69], v[176:179], v[0:15]
	ds_read_b128 v[66:69], v113 offset:24576
	v_add_f32_e32 v92, v92, v93
	v_cvt_pk_bf16_f32 v109, v118, v119
	v_cvt_pk_bf16_f32 v110, v78, v79
	v_cvt_pk_bf16_f32 v111, v106, v107
	v_cvt_pk_bf16_f32 v100, v104, v105
	v_cvt_pk_bf16_f32 v101, v102, v103
	s_waitcnt lgkmcnt(1)
	v_mfma_f32_32x32x16_bf16 v[48:63], v[70:73], v[176:179], v[48:63]
	ds_read_b128 v[70:73], v113 offset:28672
	v_cvt_pk_bf16_f32 v102, v80, v81
	v_cvt_pk_bf16_f32 v103, v114, v115
	v_cvt_pk_bf16_f32 v104, v74, v75
	v_cvt_pk_bf16_f32 v105, v82, v83
	v_cvt_pk_bf16_f32 v106, v86, v87
	v_cvt_pk_bf16_f32 v107, v90, v91
	s_waitcnt lgkmcnt(1)
	v_mfma_f32_32x32x16_bf16 v[32:47], v[66:69], v[176:179], v[32:47]
	v_cvt_pk_bf16_f32 v96, v76, v77
	v_cvt_pk_bf16_f32 v97, v84, v85
	v_cvt_pk_bf16_f32 v98, v88, v89
	v_cvt_pk_bf16_f32 v99, v94, v95
	v_add_f32_e32 v114, v65, v92
	s_waitcnt lgkmcnt(0)
	v_mfma_f32_32x32x16_bf16 v[16:31], v[70:73], v[176:179], v[16:31]
	s_cbranch_vccz .LBB0_877
	v_pk_mul_f32 v[14:15], v[64:65], v[14:15] op_sel_hi:[0,1]
	v_pk_mul_f32 v[12:13], v[64:65], v[12:13] op_sel_hi:[0,1]
	v_pk_mul_f32 v[10:11], v[64:65], v[10:11] op_sel_hi:[0,1]
	v_pk_mul_f32 v[8:9], v[64:65], v[8:9] op_sel_hi:[0,1]
	v_pk_mul_f32 v[6:7], v[64:65], v[6:7] op_sel_hi:[0,1]
	v_pk_mul_f32 v[4:5], v[64:65], v[4:5] op_sel_hi:[0,1]
	v_pk_mul_f32 v[2:3], v[64:65], v[2:3] op_sel_hi:[0,1]
	v_pk_mul_f32 v[0:1], v[64:65], v[0:1] op_sel_hi:[0,1]
	v_pk_mul_f32 v[62:63], v[64:65], v[62:63] op_sel_hi:[0,1]
	v_pk_mul_f32 v[60:61], v[64:65], v[60:61] op_sel_hi:[0,1]
	v_pk_mul_f32 v[58:59], v[64:65], v[58:59] op_sel_hi:[0,1]
	v_pk_mul_f32 v[56:57], v[64:65], v[56:57] op_sel_hi:[0,1]
	v_pk_mul_f32 v[54:55], v[64:65], v[54:55] op_sel_hi:[0,1]
	v_pk_mul_f32 v[52:53], v[64:65], v[52:53] op_sel_hi:[0,1]
	v_pk_mul_f32 v[50:51], v[64:65], v[50:51] op_sel_hi:[0,1]
	v_pk_mul_f32 v[48:49], v[64:65], v[48:49] op_sel_hi:[0,1]
	v_pk_mul_f32 v[46:47], v[64:65], v[46:47] op_sel_hi:[0,1]
	v_pk_mul_f32 v[44:45], v[64:65], v[44:45] op_sel_hi:[0,1]
	v_pk_mul_f32 v[42:43], v[64:65], v[42:43] op_sel_hi:[0,1]
	v_pk_mul_f32 v[40:41], v[64:65], v[40:41] op_sel_hi:[0,1]
	v_pk_mul_f32 v[38:39], v[64:65], v[38:39] op_sel_hi:[0,1]
	v_pk_mul_f32 v[36:37], v[64:65], v[36:37] op_sel_hi:[0,1]
	v_pk_mul_f32 v[34:35], v[64:65], v[34:35] op_sel_hi:[0,1]
	v_pk_mul_f32 v[32:33], v[64:65], v[32:33] op_sel_hi:[0,1]
	v_pk_mul_f32 v[30:31], v[64:65], v[30:31] op_sel_hi:[0,1]
	v_pk_mul_f32 v[28:29], v[64:65], v[28:29] op_sel_hi:[0,1]
	v_pk_mul_f32 v[26:27], v[64:65], v[26:27] op_sel_hi:[0,1]
	v_pk_mul_f32 v[24:25], v[64:65], v[24:25] op_sel_hi:[0,1]
	v_pk_mul_f32 v[22:23], v[64:65], v[22:23] op_sel_hi:[0,1]
	v_pk_mul_f32 v[20:21], v[64:65], v[20:21] op_sel_hi:[0,1]
	v_pk_mul_f32 v[18:19], v[64:65], v[18:19] op_sel_hi:[0,1]
	v_pk_mul_f32 v[16:17], v[64:65], v[16:17] op_sel_hi:[0,1]

.LBB0_879:
	s_lshl_b32 s1, s9, 15
	s_and_b32 s1, s1, 0x18000
	s_add_i32 s1, s1, 0
	v_add_u32_e32 v112, s1, v229
	v_add_u32_e32 v115, v112, v230
	ds_read_b128 v[116:119], v115 offset:16384
	v_readlane_b32 s1, v254, 40
	s_waitcnt lgkmcnt(0)
	v_mfma_f32_32x32x16_bf16 v[0:15], v[116:119], v[108:111], v[0:15]
	ds_read_b128 v[116:119], v115 offset:20480
	s_waitcnt lgkmcnt(0)
	v_mfma_f32_32x32x16_bf16 v[48:63], v[116:119], v[108:111], v[48:63]
	ds_read_b128 v[116:119], v115 offset:24576
	s_waitcnt lgkmcnt(0)
	v_mfma_f32_32x32x16_bf16 v[32:47], v[116:119], v[108:111], v[32:47]
	ds_read_b128 v[116:119], v115 offset:28672
	v_add_u32_e32 v115, v112, v233
	s_waitcnt lgkmcnt(0)
	v_mfma_f32_32x32x16_bf16 v[16:31], v[116:119], v[108:111], v[16:31]
	ds_read_b128 v[108:111], v115 offset:16384
	s_waitcnt lgkmcnt(0)
	v_mfma_f32_32x32x16_bf16 v[0:15], v[108:111], v[104:107], v[0:15]
	ds_read_b128 v[108:111], v115 offset:20480
	s_waitcnt lgkmcnt(0)
	v_mfma_f32_32x32x16_bf16 v[48:63], v[108:111], v[104:107], v[48:63]
	ds_read_b128 v[108:111], v115 offset:24576
	s_waitcnt lgkmcnt(0)
	v_mfma_f32_32x32x16_bf16 v[32:47], v[108:111], v[104:107], v[32:47]
	ds_read_b128 v[108:111], v115 offset:28672
	ds_bpermute_b32 v115, v227, v114
	s_waitcnt lgkmcnt(1)
	v_mfma_f32_32x32x16_bf16 v[16:31], v[108:111], v[104:107], v[16:31]
	v_add_u32_e32 v108, v112, v232
	ds_read_b128 v[104:107], v108 offset:16384
	v_add_u32_e32 v112, v112, v231
	s_waitcnt lgkmcnt(0)
	v_mfma_f32_32x32x16_bf16 v[0:15], v[104:107], v[100:103], v[0:15]
	ds_read_b128 v[104:107], v108 offset:20480
	s_waitcnt lgkmcnt(0)
	v_mfma_f32_32x32x16_bf16 v[48:63], v[104:107], v[100:103], v[48:63]
	ds_read_b128 v[104:107], v108 offset:24576
	s_waitcnt lgkmcnt(0)
	v_mfma_f32_32x32x16_bf16 v[32:47], v[104:107], v[100:103], v[32:47]
	ds_read_b128 v[104:107], v108 offset:28672
	s_waitcnt lgkmcnt(0)
	v_mfma_f32_32x32x16_bf16 v[16:31], v[104:107], v[100:103], v[16:31]
	ds_read_b128 v[100:103], v112 offset:16384
	ds_read_b128 v[104:107], v112 offset:20480
	ds_read_b128 v[108:111], v112 offset:24576
	ds_read_b128 v[116:119], v112 offset:28672
	s_waitcnt lgkmcnt(0)
	s_barrier
	v_mfma_f32_32x32x16_bf16 v[0:15], v[100:103], v[96:99], v[0:15]
	v_add_f32_e32 v100, v114, v115
	v_rcp_f32_e32 v102, v100
	s_nop 0
	v_mfma_f32_32x32x16_bf16 v[48:63], v[104:107], v[96:99], v[48:63]
	v_mfma_f32_32x32x16_bf16 v[32:47], v[108:111], v[96:99], v[32:47]
	v_mul_f32_e32 v101, 1.0, v102
	v_mov_b32_e32 v112, v101
	v_lshlrev_b32_e32 v100, 9, v228
	v_lshlrev_b32_e32 v101, 2, v213
	s_and_b64 vcc, exec, s[40:41]
	v_add3_u32 v100, s1, v100, v101
	v_mfma_f32_32x32x16_bf16 v[16:31], v[116:119], v[96:99], v[16:31]
	s_cbranch_vccnz .LBB0_881
	v_mul_f32_e32 v96, v0, v112
	v_mul_f32_e32 v97, v1, v112
	ds_write2_b32 v100, v96, v97 offset1:32
	v_mul_f32_e32 v96, v2, v112
	v_mul_f32_e32 v97, v3, v112
	ds_write2_b32 v100, v96, v97 offset0:64 offset1:96
	v_mul_f32_e32 v96, v4, v112
	v_mul_f32_e32 v97, v5, v112
	v_add_u32_e32 v98, 0x400, v100
	ds_write2_b32 v98, v96, v97 offset1:32
	v_mul_f32_e32 v96, v6, v112
	v_mul_f32_e32 v97, v7, v112
	ds_write2_b32 v98, v96, v97 offset0:64 offset1:96
	v_mul_f32_e32 v96, v8, v112
	v_mul_f32_e32 v97, v9, v112
	v_add_u32_e32 v98, 0x800, v100
	ds_write2_b32 v98, v96, v97 offset1:32
	v_mul_f32_e32 v96, v10, v112
	v_mul_f32_e32 v97, v11, v112
	ds_write2_b32 v98, v96, v97 offset0:64 offset1:96
	v_mul_f32_e32 v96, v12, v112
	v_mul_f32_e32 v97, v13, v112
	v_add_u32_e32 v98, 0xc00, v100
	ds_write2_b32 v98, v96, v97 offset1:32
	v_mul_f32_e32 v96, v14, v112
	v_mul_f32_e32 v97, v15, v112
	ds_write2_b32 v98, v96, v97 offset0:64 offset1:96
	v_mul_f32_e32 v96, v48, v112
	v_mul_f32_e32 v97, v49, v112
	v_add_u32_e32 v98, 0x1000, v100
	ds_write2_b32 v98, v96, v97 offset1:32
	v_mul_f32_e32 v96, v50, v112
	v_mul_f32_e32 v97, v51, v112
	ds_write2_b32 v98, v96, v97 offset0:64 offset1:96
	v_mul_f32_e32 v96, v52, v112
	v_mul_f32_e32 v97, v53, v112
	v_add_u32_e32 v98, 0x1400, v100
	ds_write2_b32 v98, v96, v97 offset1:32
	v_mul_f32_e32 v96, v54, v112
	v_mul_f32_e32 v97, v55, v112
	ds_write2_b32 v98, v96, v97 offset0:64 offset1:96
	v_mul_f32_e32 v96, v56, v112
	v_mul_f32_e32 v97, v57, v112
	v_add_u32_e32 v98, 0x1800, v100
	ds_write2_b32 v98, v96, v97 offset1:32
	v_mul_f32_e32 v96, v58, v112
	v_mul_f32_e32 v97, v59, v112
	ds_write2_b32 v98, v96, v97 offset0:64 offset1:96
	v_mul_f32_e32 v96, v60, v112
	v_mul_f32_e32 v97, v61, v112
	v_add_u32_e32 v98, 0x1c00, v100
	ds_write2_b32 v98, v96, v97 offset1:32
	v_mul_f32_e32 v96, v62, v112
	v_mul_f32_e32 v97, v63, v112
	ds_write2_b32 v98, v96, v97 offset0:64 offset1:96
	v_mul_f32_e32 v96, v32, v112
	v_mul_f32_e32 v97, v33, v112
	v_add_u32_e32 v98, 0x2000, v100
	ds_write2_b32 v98, v96, v97 offset1:32
	v_mul_f32_e32 v96, v34, v112
	v_mul_f32_e32 v97, v35, v112
	ds_write2_b32 v98, v96, v97 offset0:64 offset1:96
	v_mul_f32_e32 v96, v36, v112
	v_mul_f32_e32 v97, v37, v112
	v_add_u32_e32 v98, 0x2400, v100
	ds_write2_b32 v98, v96, v97 offset1:32
	v_mul_f32_e32 v96, v38, v112
	v_mul_f32_e32 v97, v39, v112
	ds_write2_b32 v98, v96, v97 offset0:64 offset1:96
	v_mul_f32_e32 v96, v40, v112
	v_mul_f32_e32 v97, v41, v112
	v_add_u32_e32 v98, 0x2800, v100
	ds_write2_b32 v98, v96, v97 offset1:32
	v_mul_f32_e32 v96, v42, v112
	v_mul_f32_e32 v97, v43, v112
	ds_write2_b32 v98, v96, v97 offset0:64 offset1:96
	v_mul_f32_e32 v96, v44, v112
	v_mul_f32_e32 v97, v45, v112
	v_add_u32_e32 v98, 0x2c00, v100
	ds_write2_b32 v98, v96, v97 offset1:32
	v_mul_f32_e32 v96, v46, v112
	v_mul_f32_e32 v97, v47, v112
	ds_write2_b32 v98, v96, v97 offset0:64 offset1:96
	v_mul_f32_e32 v96, v16, v112
	v_mul_f32_e32 v97, v17, v112
	v_add_u32_e32 v98, 0x3000, v100
	ds_write2_b32 v98, v96, v97 offset1:32
	v_mul_f32_e32 v96, v18, v112
	v_mul_f32_e32 v97, v19, v112
	ds_write2_b32 v98, v96, v97 offset0:64 offset1:96
	v_mul_f32_e32 v96, v20, v112
	v_mul_f32_e32 v97, v21, v112
	v_add_u32_e32 v98, 0x3400, v100
	ds_write2_b32 v98, v96, v97 offset1:32
	v_mul_f32_e32 v96, v22, v112
	v_mul_f32_e32 v97, v23, v112
	ds_write2_b32 v98, v96, v97 offset0:64 offset1:96
	v_mul_f32_e32 v96, v24, v112
	v_mul_f32_e32 v97, v25, v112
	v_add_u32_e32 v98, 0x3800, v100
	ds_write2_b32 v98, v96, v97 offset1:32
	v_mul_f32_e32 v96, v26, v112
	v_mul_f32_e32 v97, v27, v112
	ds_write2_b32 v98, v96, v97 offset0:64 offset1:96
	v_mul_f32_e32 v96, v28, v112
	v_mul_f32_e32 v97, v29, v112
	v_add_u32_e32 v98, 0x3c00, v100
	ds_write2_b32 v98, v96, v97 offset1:32
	v_mul_f32_e32 v96, v30, v112
	v_mul_f32_e32 v97, v31, v112
	ds_write2_b32 v98, v96, v97 offset0:64 offset1:96
.LBB0_881:
	s_and_b64 vcc, exec, s[38:39]
	s_waitcnt lgkmcnt(0)
	s_barrier
	s_cbranch_vccnz .LBB0_828
	v_add_u32_e32 v101, 0x400, v100
	ds_read2_b32 v[96:97], v100 offset1:32
	ds_read2_b32 v[98:99], v100 offset0:64 offset1:96
	ds_read2_b32 v[104:105], v101 offset1:32
	ds_read2_b32 v[106:107], v101 offset0:64 offset1:96
	v_add_u32_e32 v101, 0x800, v100
	ds_read2_b32 v[116:117], v101 offset1:32
	ds_read2_b32 v[118:119], v101 offset0:64 offset1:96
	v_add_u32_e32 v101, 0xc00, v100
	ds_read2_b32 v[120:121], v101 offset1:32
	ds_read2_b32 v[122:123], v101 offset0:64 offset1:96
	v_add_u32_e32 v101, 0x1000, v100
	ds_read2_b32 v[124:125], v101 offset1:32
	ds_read2_b32 v[126:127], v101 offset0:64 offset1:96
	v_add_u32_e32 v101, 0x1400, v100
	ds_read2_b32 v[160:161], v101 offset1:32
	ds_read2_b32 v[162:163], v101 offset0:64 offset1:96
	v_add_u32_e32 v101, 0x1800, v100
	ds_read2_b32 v[164:165], v101 offset1:32
	ds_read2_b32 v[166:167], v101 offset0:64 offset1:96
	v_add_u32_e32 v101, 0x1c00, v100
	ds_read2_b32 v[168:169], v101 offset1:32
	ds_read2_b32 v[170:171], v101 offset0:64 offset1:96
	v_add_u32_e32 v101, 0x2000, v100
	ds_read2_b32 v[172:173], v101 offset1:32
	ds_read2_b32 v[174:175], v101 offset0:64 offset1:96
	v_add_u32_e32 v101, 0x2400, v100
	ds_read2_b32 v[176:177], v101 offset1:32
	ds_read2_b32 v[178:179], v101 offset0:64 offset1:96
	v_add_u32_e32 v101, 0x2800, v100
	ds_read2_b32 v[180:181], v101 offset1:32
	ds_read2_b32 v[182:183], v101 offset0:64 offset1:96
	v_add_u32_e32 v101, 0x2c00, v100
	ds_read2_b32 v[156:157], v101 offset1:32
	ds_read2_b32 v[184:185], v101 offset0:64 offset1:96
	v_add_u32_e32 v101, 0x3000, v100
	ds_read2_b32 v[150:151], v101 offset1:32
	ds_read2_b32 v[154:155], v101 offset0:64 offset1:96
	v_add_u32_e32 v101, 0x3400, v100
	ds_read2_b32 v[146:147], v101 offset1:32
	ds_read2_b32 v[148:149], v101 offset0:64 offset1:96
	v_add_u32_e32 v101, 0x3c00, v100
	ds_read2_b32 v[102:103], v101 offset1:32
	v_add_u32_e32 v108, 0x3800, v100
	ds_read2_b32 v[144:145], v108 offset1:32
	ds_read2_b32 v[100:101], v101 offset0:64 offset1:96
	ds_read2_b32 v[152:153], v108 offset0:64 offset1:96
	v_mul_u32_u24_e32 v159, 0x110, v213
	v_mov_b32_e32 v213, v195
	s_waitcnt lgkmcnt(3)
	v_pk_mul_f32 v[102:103], v[210:211], v[102:103]
	v_pk_mul_f32 v[178:179], v[210:211], v[178:179]
	v_pk_fma_f32 v[108:109], v[28:29], v[112:113], v[102:103] op_sel_hi:[1,0,1] neg_lo:[0,0,1] neg_hi:[0,0,1]
	s_waitcnt lgkmcnt(1)
	v_pk_mul_f32 v[28:29], v[210:211], v[100:101]
	v_pk_mul_f32 v[176:177], v[210:211], v[176:177]
	v_pk_fma_f32 v[110:111], v[30:31], v[112:113], v[28:29] op_sel_hi:[1,0,1] neg_lo:[0,0,1] neg_hi:[0,0,1]
	v_pk_mul_f32 v[28:29], v[210:211], v[98:99]
	v_pk_mul_f32 v[182:183], v[210:211], v[182:183]
	v_pk_fma_f32 v[128:129], v[2:3], v[112:113], v[28:29] op_sel_hi:[1,0,1] neg_lo:[0,0,1] neg_hi:[0,0,1]
	v_pk_mul_f32 v[2:3], v[210:211], v[96:97]
	v_pk_mul_f32 v[180:181], v[210:211], v[180:181]
	v_pk_fma_f32 v[132:133], v[0:1], v[112:113], v[2:3] op_sel_hi:[1,0,1] neg_lo:[0,0,1] neg_hi:[0,0,1]
	v_pk_mul_f32 v[0:1], v[210:211], v[106:107]
	v_pk_mul_f32 v[214:215], v[132:133], v[132:133]
	v_pk_fma_f32 v[134:135], v[6:7], v[112:113], v[0:1] op_sel_hi:[1,0,1] neg_lo:[0,0,1] neg_hi:[0,0,1]
	v_pk_mul_f32 v[0:1], v[210:211], v[104:105]
	v_pk_mul_f32 v[184:185], v[210:211], v[184:185]
	v_pk_fma_f32 v[140:141], v[4:5], v[112:113], v[0:1] op_sel_hi:[1,0,1] neg_lo:[0,0,1] neg_hi:[0,0,1]
	v_pk_mul_f32 v[0:1], v[210:211], v[118:119]
	v_pk_mul_f32 v[4:5], v[210:211], v[122:123]
	v_pk_fma_f32 v[138:139], v[10:11], v[112:113], v[0:1] op_sel_hi:[1,0,1] neg_lo:[0,0,1] neg_hi:[0,0,1]
	v_pk_mul_f32 v[0:1], v[210:211], v[116:117]
	v_pk_fma_f32 v[116:117], v[14:15], v[112:113], v[4:5] op_sel_hi:[1,0,1] neg_lo:[0,0,1] neg_hi:[0,0,1]
	v_pk_mul_f32 v[4:5], v[210:211], v[120:121]
	v_pk_mul_f32 v[156:157], v[210:211], v[156:157]
	v_pk_fma_f32 v[118:119], v[12:13], v[112:113], v[4:5] op_sel_hi:[1,0,1] neg_lo:[0,0,1] neg_hi:[0,0,1]
	v_pk_mul_f32 v[4:5], v[210:211], v[126:127]
	v_pk_mul_f32 v[12:13], v[210:211], v[162:163]
	v_pk_fma_f32 v[120:121], v[50:51], v[112:113], v[4:5] op_sel_hi:[1,0,1] neg_lo:[0,0,1] neg_hi:[0,0,1]
	v_pk_mul_f32 v[4:5], v[210:211], v[124:125]
	v_pk_fma_f32 v[54:55], v[54:55], v[112:113], v[12:13] op_sel_hi:[1,0,1] neg_lo:[0,0,1] neg_hi:[0,0,1]
	v_pk_fma_f32 v[122:123], v[48:49], v[112:113], v[4:5] op_sel_hi:[1,0,1] neg_lo:[0,0,1] neg_hi:[0,0,1]
	v_pk_mul_f32 v[48:49], v[210:211], v[170:171]
	v_pk_mul_f32 v[12:13], v[210:211], v[160:161]
	v_pk_fma_f32 v[62:63], v[62:63], v[112:113], v[48:49] op_sel_hi:[1,0,1] neg_lo:[0,0,1] neg_hi:[0,0,1]
	v_pk_mul_f32 v[48:49], v[210:211], v[168:169]
	v_pk_fma_f32 v[52:53], v[52:53], v[112:113], v[12:13] op_sel_hi:[1,0,1] neg_lo:[0,0,1] neg_hi:[0,0,1]
	v_pk_mul_f32 v[12:13], v[210:211], v[166:167]
	v_pk_fma_f32 v[60:61], v[60:61], v[112:113], v[48:49] op_sel_hi:[1,0,1] neg_lo:[0,0,1] neg_hi:[0,0,1]
	v_pk_mul_f32 v[48:49], v[210:211], v[174:175]
	v_pk_fma_f32 v[58:59], v[58:59], v[112:113], v[12:13] op_sel_hi:[1,0,1] neg_lo:[0,0,1] neg_hi:[0,0,1]
	v_pk_mul_f32 v[12:13], v[210:211], v[164:165]
	v_pk_fma_f32 v[124:125], v[34:35], v[112:113], v[48:49] op_sel_hi:[1,0,1] neg_lo:[0,0,1] neg_hi:[0,0,1]
	v_pk_mul_f32 v[34:35], v[210:211], v[172:173]
	v_pk_mul_f32 v[154:155], v[210:211], v[154:155]
	v_pk_mul_f32 v[150:151], v[210:211], v[150:151]
	v_pk_mul_f32 v[148:149], v[210:211], v[148:149]
	v_pk_mul_f32 v[146:147], v[210:211], v[146:147]
	s_waitcnt lgkmcnt(0)
	v_pk_mul_f32 v[152:153], v[210:211], v[152:153]
	v_pk_mul_f32 v[144:145], v[210:211], v[144:145]
	v_lshl_add_u64 v[114:115], v[212:213], 2, s[36:37]
	v_pk_mul_f32 v[186:187], v[128:129], v[128:129]
	v_pk_fma_f32 v[142:143], v[8:9], v[112:113], v[0:1] op_sel_hi:[1,0,1] neg_lo:[0,0,1] neg_hi:[0,0,1]
	v_pk_fma_f32 v[56:57], v[56:57], v[112:113], v[12:13] op_sel_hi:[1,0,1] neg_lo:[0,0,1] neg_hi:[0,0,1]
	v_pk_fma_f32 v[126:127], v[32:33], v[112:113], v[34:35] op_sel_hi:[1,0,1] neg_lo:[0,0,1] neg_hi:[0,0,1]
	v_pk_fma_f32 v[38:39], v[38:39], v[112:113], v[178:179] op_sel_hi:[1,0,1] neg_lo:[0,0,1] neg_hi:[0,0,1]
	v_pk_fma_f32 v[36:37], v[36:37], v[112:113], v[176:177] op_sel_hi:[1,0,1] neg_lo:[0,0,1] neg_hi:[0,0,1]
	v_pk_fma_f32 v[42:43], v[42:43], v[112:113], v[182:183] op_sel_hi:[1,0,1] neg_lo:[0,0,1] neg_hi:[0,0,1]
	v_pk_fma_f32 v[40:41], v[40:41], v[112:113], v[180:181] op_sel_hi:[1,0,1] neg_lo:[0,0,1] neg_hi:[0,0,1]
	v_pk_fma_f32 v[46:47], v[46:47], v[112:113], v[184:185] op_sel_hi:[1,0,1] neg_lo:[0,0,1] neg_hi:[0,0,1]
	v_pk_fma_f32 v[44:45], v[44:45], v[112:113], v[156:157] op_sel_hi:[1,0,1] neg_lo:[0,0,1] neg_hi:[0,0,1]
	v_pk_fma_f32 v[18:19], v[18:19], v[112:113], v[154:155] op_sel_hi:[1,0,1] neg_lo:[0,0,1] neg_hi:[0,0,1]
	v_pk_fma_f32 v[16:17], v[16:17], v[112:113], v[150:151] op_sel_hi:[1,0,1] neg_lo:[0,0,1] neg_hi:[0,0,1]
	v_pk_fma_f32 v[22:23], v[22:23], v[112:113], v[148:149] op_sel_hi:[1,0,1] neg_lo:[0,0,1] neg_hi:[0,0,1]
	v_pk_fma_f32 v[20:21], v[20:21], v[112:113], v[146:147] op_sel_hi:[1,0,1] neg_lo:[0,0,1] neg_hi:[0,0,1]
	v_pk_fma_f32 v[26:27], v[26:27], v[112:113], v[152:153] op_sel_hi:[1,0,1] neg_lo:[0,0,1] neg_hi:[0,0,1]
	v_pk_fma_f32 v[24:25], v[24:25], v[112:113], v[144:145] op_sel_hi:[1,0,1] neg_lo:[0,0,1] neg_hi:[0,0,1]
	v_add_f32_e32 v112, v214, v215
	global_load_dwordx4 v[100:103], v[114:115], off
	global_load_dwordx4 v[96:99], v[114:115], off offset:32
	v_add_f32_e32 v112, v112, v186
	v_pk_mul_f32 v[230:231], v[140:141], v[140:141]
	v_add_f32_e32 v112, v112, v187
	v_add_f32_e32 v112, v112, v230
	v_pk_mul_f32 v[228:229], v[134:135], v[134:135]
	v_add_f32_e32 v112, v112, v231
	v_add_f32_e32 v112, v112, v228
	v_pk_mul_f32 v[234:235], v[142:143], v[142:143]
	v_add_f32_e32 v112, v112, v229
	global_load_dwordx4 v[104:107], v[114:115], off offset:64
	global_load_dwordx4 v[0:3], v[114:115], off offset:96
	v_add_f32_e32 v112, v112, v234
	v_pk_mul_f32 v[232:233], v[138:139], v[138:139]
	v_add_f32_e32 v112, v112, v235
	v_add_f32_e32 v112, v112, v232
	v_pk_mul_f32 v[238:239], v[118:119], v[118:119]
	v_add_f32_e32 v112, v112, v233
	v_add_f32_e32 v112, v112, v238
	v_pk_mul_f32 v[236:237], v[116:117], v[116:117]
	v_add_f32_e32 v112, v112, v239
	v_add_f32_e32 v112, v112, v236
	v_pk_mul_f32 v[242:243], v[122:123], v[122:123]
	v_add_f32_e32 v112, v112, v237
	v_add_f32_e32 v112, v112, v242
	v_pk_mul_f32 v[240:241], v[120:121], v[120:121]
	v_add_f32_e32 v112, v112, v243
	v_add_f32_e32 v112, v112, v240
	v_pk_mul_f32 v[160:161], v[52:53], v[52:53]
	v_add_f32_e32 v112, v112, v241
	v_add_f32_e32 v112, v112, v160
	v_pk_mul_f32 v[162:163], v[54:55], v[54:55]
	v_add_f32_e32 v112, v112, v161
	v_add_f32_e32 v112, v112, v162
	v_pk_mul_f32 v[164:165], v[56:57], v[56:57]
	v_add_f32_e32 v112, v112, v163
	v_add_f32_e32 v112, v112, v164
	v_pk_mul_f32 v[166:167], v[58:59], v[58:59]
	v_add_f32_e32 v112, v112, v165
	v_add_f32_e32 v112, v112, v166
	v_pk_mul_f32 v[168:169], v[60:61], v[60:61]
	v_add_f32_e32 v112, v112, v167
	v_add_f32_e32 v112, v112, v168
	v_pk_mul_f32 v[170:171], v[62:63], v[62:63]
	v_add_f32_e32 v112, v112, v169
	v_add_f32_e32 v112, v112, v170
	v_pk_mul_f32 v[172:173], v[126:127], v[126:127]
	v_add_f32_e32 v112, v112, v171
	v_add_f32_e32 v112, v112, v172
	v_pk_mul_f32 v[174:175], v[124:125], v[124:125]
	v_add_f32_e32 v112, v112, v173
	v_add_f32_e32 v112, v112, v174
	v_pk_mul_f32 v[176:177], v[36:37], v[36:37]
	v_add_f32_e32 v112, v112, v175
	v_add_f32_e32 v112, v112, v176
	v_pk_mul_f32 v[178:179], v[38:39], v[38:39]
	v_add_f32_e32 v112, v112, v177
	v_add_f32_e32 v112, v112, v178
	v_pk_mul_f32 v[180:181], v[40:41], v[40:41]
	v_add_f32_e32 v112, v112, v179
	v_add_f32_e32 v112, v112, v180
	v_pk_mul_f32 v[182:183], v[42:43], v[42:43]
	v_add_f32_e32 v112, v112, v181
	v_add_f32_e32 v112, v112, v182
	v_pk_mul_f32 v[156:157], v[44:45], v[44:45]
	v_add_f32_e32 v112, v112, v183
	v_add_f32_e32 v112, v112, v156
	v_pk_mul_f32 v[184:185], v[46:47], v[46:47]
	v_add_f32_e32 v112, v112, v157
	v_add_f32_e32 v112, v112, v184
	v_pk_mul_f32 v[150:151], v[16:17], v[16:17]
	v_add_f32_e32 v112, v112, v185
	v_add_f32_e32 v112, v112, v150
	v_pk_mul_f32 v[154:155], v[18:19], v[18:19]
	v_add_f32_e32 v112, v112, v151
	v_add_f32_e32 v112, v112, v154
	v_pk_mul_f32 v[146:147], v[20:21], v[20:21]
	v_add_f32_e32 v112, v112, v155
	v_add_f32_e32 v112, v112, v146
	v_pk_mul_f32 v[148:149], v[22:23], v[22:23]
	v_add_f32_e32 v112, v112, v147
	v_add_f32_e32 v112, v112, v148
	v_pk_mul_f32 v[144:145], v[24:25], v[24:25]
	v_add_f32_e32 v112, v112, v149
	v_add_f32_e32 v112, v112, v144
	v_pk_mul_f32 v[152:153], v[26:27], v[26:27]
	v_add_f32_e32 v112, v112, v145
	v_add_f32_e32 v112, v112, v152
	v_pk_mul_f32 v[130:131], v[108:109], v[108:109]
	v_add_f32_e32 v112, v112, v153
	v_add_f32_e32 v112, v112, v130
	v_pk_mul_f32 v[136:137], v[110:111], v[110:111]
	v_add_f32_e32 v112, v112, v131
	v_add_f32_e32 v112, v112, v136
	global_load_dwordx4 v[8:11], v[114:115], off offset:128
	global_load_dwordx4 v[4:7], v[114:115], off offset:160
	v_add_f32_e32 v112, v112, v137
	ds_bpermute_b32 v130, v227, v112
	global_load_dwordx4 v[28:31], v[114:115], off offset:192
	global_load_dwordx4 v[12:15], v[114:115], off offset:224
	global_load_dwordx4 v[48:51], v[114:115], off offset:256
	global_load_dwordx4 v[32:35], v[114:115], off offset:288
	v_lshlrev_b32_e32 v131, 1, v212
	v_readlane_b32 s1, v254, 43
	s_waitcnt lgkmcnt(0)
	v_add_f32_e32 v112, v112, v130
	v_fmamk_f32 v112, v112, 0x3c000000, v189
	v_mul_f32_e32 v130, 0x4b800000, v112
	v_cmp_gt_f32_e32 vcc, s13, v112
	global_load_dwordx4 v[144:147], v[114:115], off offset:320
	global_load_dwordx4 v[148:151], v[114:115], off offset:352
	v_cndmask_b32_e32 v112, v112, v130, vcc
	v_rsq_f32_e32 v112, v112
	v_add3_u32 v136, s1, v159, v131
	global_load_dwordx4 v[152:155], v[114:115], off offset:384
	global_load_dwordx4 v[160:163], v[114:115], off offset:416
	global_load_dwordx4 v[164:167], v[114:115], off offset:448
	s_add_u32 s8, s82, s92
	v_mul_f32_e32 v130, 0x45800000, v112
	v_cndmask_b32_e32 v112, v112, v130, vcc
	v_mul_f32_e32 v112, v209, v112
	v_pk_mul_f32 v[130:131], v[132:133], v[112:113] op_sel_hi:[1,0]
	v_pk_mul_f32 v[128:129], v[128:129], v[112:113] op_sel_hi:[1,0]
	s_waitcnt vmcnt(14)
	v_pk_mul_f32 v[100:101], v[100:101], v[130:131]
	v_pk_mul_f32 v[102:103], v[102:103], v[128:129]
	v_cvt_pk_bf16_f32 v100, v100, v101
	v_cvt_pk_bf16_f32 v101, v102, v103
	v_pk_mul_f32 v[102:103], v[140:141], v[112:113] op_sel_hi:[1,0]
	s_addc_u32 s9, s83, 0
	s_waitcnt vmcnt(13)
	v_pk_mul_f32 v[96:97], v[96:97], v[102:103]
	v_pk_mul_f32 v[102:103], v[134:135], v[112:113] op_sel_hi:[1,0]
	v_cvt_pk_bf16_f32 v96, v96, v97
	v_pk_mul_f32 v[98:99], v[98:99], v[102:103]
	v_pk_mul_f32 v[102:103], v[118:119], v[112:113] op_sel_hi:[1,0]
	v_cvt_pk_bf16_f32 v97, v98, v99
	ds_write2_b64 v136, v[100:101], v[96:97] offset1:2
	v_pk_mul_f32 v[96:97], v[142:143], v[112:113] op_sel_hi:[1,0]
	s_waitcnt vmcnt(11)
	v_pk_mul_f32 v[0:1], v[0:1], v[102:103]
	v_pk_mul_f32 v[96:97], v[104:105], v[96:97]
	v_pk_mul_f32 v[102:103], v[116:117], v[112:113] op_sel_hi:[1,0]
	v_cvt_pk_bf16_f32 v100, v96, v97
	v_pk_mul_f32 v[96:97], v[138:139], v[112:113] op_sel_hi:[1,0]
	v_pk_mul_f32 v[2:3], v[2:3], v[102:103]
	v_pk_mul_f32 v[96:97], v[106:107], v[96:97]
	v_cvt_pk_bf16_f32 v0, v0, v1
	v_cvt_pk_bf16_f32 v101, v96, v97
	global_load_dwordx4 v[96:99], v[114:115], off offset:480
	v_cvt_pk_bf16_f32 v1, v2, v3
	ds_write2_b64 v136, v[100:101], v[0:1] offset0:4 offset1:6
	v_pk_mul_f32 v[0:1], v[122:123], v[112:113] op_sel_hi:[1,0]
	v_pk_mul_f32 v[2:3], v[120:121], v[112:113] op_sel_hi:[1,0]
	s_waitcnt vmcnt(11)
	v_pk_mul_f32 v[0:1], v[8:9], v[0:1]
	v_pk_mul_f32 v[2:3], v[10:11], v[2:3]
	v_cvt_pk_bf16_f32 v0, v0, v1
	v_cvt_pk_bf16_f32 v1, v2, v3
	v_pk_mul_f32 v[2:3], v[52:53], v[112:113] op_sel_hi:[1,0]
	v_lshl_add_u64 v[8:9], s[8:9], 0, v[194:195]
	s_waitcnt vmcnt(10)
	v_pk_mul_f32 v[2:3], v[4:5], v[2:3]
	v_pk_mul_f32 v[4:5], v[54:55], v[112:113] op_sel_hi:[1,0]
	v_cvt_pk_bf16_f32 v2, v2, v3
	v_pk_mul_f32 v[4:5], v[6:7], v[4:5]
	v_mad_u64_u32 v[10:11], s[8:9], v113, s14, v[8:9]
	v_cvt_pk_bf16_f32 v3, v4, v5
	ds_write2_b64 v136, v[0:1], v[2:3] offset0:8 offset1:10
	v_pk_mul_f32 v[0:1], v[56:57], v[112:113] op_sel_hi:[1,0]
	v_pk_mul_f32 v[2:3], v[58:59], v[112:113] op_sel_hi:[1,0]
	s_waitcnt vmcnt(9)
	v_pk_mul_f32 v[0:1], v[28:29], v[0:1]
	v_pk_mul_f32 v[2:3], v[30:31], v[2:3]
	v_cvt_pk_bf16_f32 v0, v0, v1
	v_cvt_pk_bf16_f32 v1, v2, v3
	v_pk_mul_f32 v[2:3], v[60:61], v[112:113] op_sel_hi:[1,0]
	v_pk_mul_f32 v[4:5], v[62:63], v[112:113] op_sel_hi:[1,0]
	s_waitcnt vmcnt(8)
	v_pk_mul_f32 v[2:3], v[2:3], v[12:13]
	v_pk_mul_f32 v[4:5], v[4:5], v[14:15]
	v_cvt_pk_bf16_f32 v2, v2, v3
	v_cvt_pk_bf16_f32 v3, v4, v5
	ds_write2_b64 v136, v[0:1], v[2:3] offset0:12 offset1:14
	v_pk_mul_f32 v[0:1], v[126:127], v[112:113] op_sel_hi:[1,0]
	v_pk_mul_f32 v[2:3], v[124:125], v[112:113] op_sel_hi:[1,0]
	s_waitcnt vmcnt(7)
	v_pk_mul_f32 v[0:1], v[0:1], v[48:49]
	v_pk_mul_f32 v[2:3], v[2:3], v[50:51]
	v_cvt_pk_bf16_f32 v0, v0, v1
	v_cvt_pk_bf16_f32 v1, v2, v3
	v_pk_mul_f32 v[2:3], v[36:37], v[112:113] op_sel_hi:[1,0]
	v_pk_mul_f32 v[4:5], v[38:39], v[112:113] op_sel_hi:[1,0]
	s_waitcnt vmcnt(6)
	v_pk_mul_f32 v[2:3], v[2:3], v[32:33]
	v_pk_mul_f32 v[4:5], v[4:5], v[34:35]
	v_cvt_pk_bf16_f32 v2, v2, v3
	v_cvt_pk_bf16_f32 v3, v4, v5
	ds_write2_b64 v136, v[0:1], v[2:3] offset0:16 offset1:18
	v_pk_mul_f32 v[0:1], v[40:41], v[112:113] op_sel_hi:[1,0]
	v_pk_mul_f32 v[2:3], v[42:43], v[112:113] op_sel_hi:[1,0]
	s_waitcnt vmcnt(5)
	v_pk_mul_f32 v[0:1], v[0:1], v[144:145]
	v_pk_mul_f32 v[2:3], v[2:3], v[146:147]
	v_cvt_pk_bf16_f32 v0, v0, v1
	v_cvt_pk_bf16_f32 v1, v2, v3
	v_pk_mul_f32 v[2:3], v[44:45], v[112:113] op_sel_hi:[1,0]
	v_pk_mul_f32 v[4:5], v[46:47], v[112:113] op_sel_hi:[1,0]
	s_waitcnt vmcnt(4)
	v_pk_mul_f32 v[2:3], v[2:3], v[148:149]
	v_pk_mul_f32 v[4:5], v[4:5], v[150:151]
	v_cvt_pk_bf16_f32 v2, v2, v3
	v_cvt_pk_bf16_f32 v3, v4, v5
	ds_write2_b64 v136, v[0:1], v[2:3] offset0:20 offset1:22
	v_pk_mul_f32 v[0:1], v[16:17], v[112:113] op_sel_hi:[1,0]
	v_pk_mul_f32 v[2:3], v[18:19], v[112:113] op_sel_hi:[1,0]
	s_waitcnt vmcnt(3)
	v_pk_mul_f32 v[0:1], v[0:1], v[152:153]
	v_pk_mul_f32 v[2:3], v[2:3], v[154:155]
	v_cvt_pk_bf16_f32 v0, v0, v1
	v_cvt_pk_bf16_f32 v1, v2, v3
	v_pk_mul_f32 v[2:3], v[20:21], v[112:113] op_sel_hi:[1,0]
	v_pk_mul_f32 v[4:5], v[22:23], v[112:113] op_sel_hi:[1,0]
	s_waitcnt vmcnt(2)
	v_pk_mul_f32 v[2:3], v[2:3], v[160:161]
	v_pk_mul_f32 v[4:5], v[4:5], v[162:163]
	v_cvt_pk_bf16_f32 v2, v2, v3
	v_cvt_pk_bf16_f32 v3, v4, v5
	ds_write2_b64 v136, v[0:1], v[2:3] offset0:24 offset1:26
	v_pk_mul_f32 v[0:1], v[24:25], v[112:113] op_sel_hi:[1,0]
	v_pk_mul_f32 v[2:3], v[26:27], v[112:113] op_sel_hi:[1,0]
	s_waitcnt vmcnt(1)
	v_pk_mul_f32 v[0:1], v[0:1], v[164:165]
	v_pk_mul_f32 v[2:3], v[2:3], v[166:167]
	v_cvt_pk_bf16_f32 v0, v0, v1
	v_cvt_pk_bf16_f32 v1, v2, v3
	v_pk_mul_f32 v[2:3], v[108:109], v[112:113] op_sel_hi:[1,0]
	v_pk_mul_f32 v[4:5], v[110:111], v[112:113] op_sel_hi:[1,0]
	s_waitcnt vmcnt(0)
	v_pk_mul_f32 v[2:3], v[2:3], v[96:97]
	v_pk_mul_f32 v[4:5], v[4:5], v[98:99]
	v_cvt_pk_bf16_f32 v2, v2, v3
	v_cvt_pk_bf16_f32 v3, v4, v5
	ds_write2_b64 v136, v[0:1], v[2:3] offset0:28 offset1:30
	v_mul_u32_u24_e32 v0, 0x110, v158
	v_lshlrev_b32_e32 v13, 16, v92
	v_and_b32_e32 v18, 0xffff0000, v92
	v_add3_u32 v12, s1, v194, v0
	v_mul_f32_e32 v0, 0xbfb8aa3b, v13
	v_mul_f32_e32 v1, 0xbfb8aa3b, v18
	v_exp_f32_e32 v0, v0
	v_exp_f32_e32 v1, v1
	s_waitcnt lgkmcnt(0)
	ds_read_b128 v[4:7], v12
	v_and_b32_e32 v23, 0xffff0000, v93
	v_pk_add_f32 v[14:15], v[0:1], 1.0 op_sel_hi:[1,0]
	ds_read_b128 v[0:3], v12 offset:1088
	v_rcp_f32_e32 v20, v15
	s_waitcnt lgkmcnt(1)
	v_lshlrev_b32_e32 v16, 16, v4
	v_and_b32_e32 v17, 0xffff0000, v4
	v_add_u32_e32 v11, s0, v11
	v_rcp_f32_e32 v22, v14
	v_mul_f32_e32 v4, v18, v20
	v_mov_b32_e32 v15, v4
	v_lshlrev_b32_e32 v21, 16, v93
	v_mul_f32_e32 v18, 0xbfb8aa3b, v21
	v_mul_f32_e32 v19, 0xbfb8aa3b, v23
	v_exp_f32_e32 v18, v18
	v_exp_f32_e32 v19, v19
	v_mul_f32_e32 v4, v13, v22
	v_mov_b32_e32 v14, v4
	v_pk_mul_f32 v[14:15], v[14:15], v[16:17]
	v_pk_add_f32 v[16:17], v[18:19], 1.0 op_sel_hi:[1,0]
	v_cvt_pk_bf16_f32 v4, v14, v15
	v_rcp_f32_e32 v18, v17
	v_lshlrev_b32_e32 v14, 16, v5
	v_and_b32_e32 v15, 0xffff0000, v5
	v_rcp_f32_e32 v20, v16
	v_mul_f32_e32 v5, v23, v18
	v_mov_b32_e32 v17, v5
	v_and_b32_e32 v23, 0xffff0000, v94
	v_lshlrev_b32_e32 v13, 16, v94
	v_mul_f32_e32 v18, 0xbfb8aa3b, v13
	v_mul_f32_e32 v19, 0xbfb8aa3b, v23
	v_exp_f32_e32 v18, v18
	v_exp_f32_e32 v19, v19
	v_mul_f32_e32 v5, v21, v20
	v_mov_b32_e32 v16, v5
	v_pk_mul_f32 v[14:15], v[16:17], v[14:15]
	v_pk_add_f32 v[16:17], v[18:19], 1.0 op_sel_hi:[1,0]
	v_cvt_pk_bf16_f32 v5, v14, v15
	v_rcp_f32_e32 v19, v17
	v_lshlrev_b32_e32 v14, 16, v6
	v_and_b32_e32 v15, 0xffff0000, v6
	v_lshlrev_b32_e32 v22, 16, v95
	v_rcp_f32_e32 v21, v16
	v_mul_f32_e32 v6, v23, v19
	v_mov_b32_e32 v17, v6
	v_and_b32_e32 v23, 0xffff0000, v95
	v_mul_f32_e32 v18, 0xbfb8aa3b, v22
	v_mul_f32_e32 v19, 0xbfb8aa3b, v23
	v_exp_f32_e32 v18, v18
	v_exp_f32_e32 v19, v19
	v_mul_f32_e32 v6, v13, v21
	v_mov_b32_e32 v16, v6
	v_pk_mul_f32 v[14:15], v[16:17], v[14:15]
	v_pk_add_f32 v[16:17], v[18:19], 1.0 op_sel_hi:[1,0]
	v_cvt_pk_bf16_f32 v6, v14, v15
	v_rcp_f32_e32 v18, v17
	v_lshlrev_b32_e32 v14, 16, v7
	v_and_b32_e32 v15, 0xffff0000, v7
	v_rcp_f32_e32 v20, v16
	v_mul_f32_e32 v7, v23, v18
	v_mov_b32_e32 v17, v7
	v_and_b32_e32 v23, 0xffff0000, v85
	v_mul_f32_e32 v7, v22, v20
	v_mov_b32_e32 v16, v7
	v_pk_mul_f32 v[14:15], v[16:17], v[14:15]
	v_lshlrev_b32_e32 v13, 16, v88
	v_cvt_pk_bf16_f32 v7, v14, v15
	v_and_b32_e32 v14, 0xffff0000, v88
	global_store_dwordx4 v[10:11], v[4:7], off offset:2048
	s_waitcnt lgkmcnt(0)
	v_lshlrev_b32_e32 v10, 16, v0
	v_and_b32_e32 v11, 0xffff0000, v0
	v_mul_f32_e32 v4, 0xbfb8aa3b, v13
	v_mul_f32_e32 v5, 0xbfb8aa3b, v14
	v_exp_f32_e32 v4, v4
	v_exp_f32_e32 v5, v5
	v_and_b32_e32 v19, 0xffff0000, v89
	v_or_b32_e32 v6, 4, v113
	v_mad_u64_u32 v[6:7], s[8:9], v6, s14, v[8:9]
	v_pk_add_f32 v[4:5], v[4:5], 1.0 op_sel_hi:[1,0]
	v_add_u32_e32 v7, s0, v7
	v_rcp_f32_e32 v16, v5
	s_nop 0
	v_rcp_f32_e32 v18, v4
	v_mul_f32_e32 v0, v14, v16
	v_mov_b32_e32 v5, v0
	v_lshlrev_b32_e32 v17, 16, v89
	v_mul_f32_e32 v14, 0xbfb8aa3b, v17
	v_mul_f32_e32 v15, 0xbfb8aa3b, v19
	v_exp_f32_e32 v14, v14
	v_exp_f32_e32 v15, v15
	v_mul_f32_e32 v0, v13, v18
	v_mov_b32_e32 v4, v0
	v_pk_mul_f32 v[4:5], v[4:5], v[10:11]
	v_pk_add_f32 v[10:11], v[14:15], 1.0 op_sel_hi:[1,0]
	v_cvt_pk_bf16_f32 v0, v4, v5
	v_rcp_f32_e32 v14, v11
	v_lshlrev_b32_e32 v4, 16, v1
	v_and_b32_e32 v5, 0xffff0000, v1
	v_rcp_f32_e32 v16, v10
	v_mul_f32_e32 v1, v19, v14
	v_mov_b32_e32 v11, v1
	v_and_b32_e32 v19, 0xffff0000, v90
	v_lshlrev_b32_e32 v13, 16, v90
	v_mul_f32_e32 v14, 0xbfb8aa3b, v13
	v_mul_f32_e32 v15, 0xbfb8aa3b, v19
	v_exp_f32_e32 v14, v14
	v_exp_f32_e32 v15, v15
	v_mul_f32_e32 v1, v17, v16
	v_mov_b32_e32 v10, v1
	v_pk_mul_f32 v[4:5], v[10:11], v[4:5]
	v_pk_add_f32 v[10:11], v[14:15], 1.0 op_sel_hi:[1,0]
	v_cvt_pk_bf16_f32 v1, v4, v5
	v_rcp_f32_e32 v15, v11
	v_lshlrev_b32_e32 v4, 16, v2
	v_and_b32_e32 v5, 0xffff0000, v2
	v_lshlrev_b32_e32 v18, 16, v91
	v_rcp_f32_e32 v17, v10
	v_mul_f32_e32 v2, v19, v15
	v_mov_b32_e32 v11, v2
	v_and_b32_e32 v19, 0xffff0000, v91
	v_mul_f32_e32 v14, 0xbfb8aa3b, v18
	v_mul_f32_e32 v15, 0xbfb8aa3b, v19
	v_exp_f32_e32 v14, v14
	v_exp_f32_e32 v15, v15
	v_mul_f32_e32 v2, v13, v17
	v_mov_b32_e32 v10, v2
	v_pk_mul_f32 v[4:5], v[10:11], v[4:5]
	v_pk_add_f32 v[10:11], v[14:15], 1.0 op_sel_hi:[1,0]
	v_cvt_pk_bf16_f32 v2, v4, v5
	v_rcp_f32_e32 v14, v11
	v_lshlrev_b32_e32 v4, 16, v3
	v_and_b32_e32 v5, 0xffff0000, v3
	v_rcp_f32_e32 v16, v10
	v_mul_f32_e32 v3, v19, v14
	v_mov_b32_e32 v11, v3
	v_mul_f32_e32 v3, v18, v16
	v_mov_b32_e32 v10, v3
	v_pk_mul_f32 v[4:5], v[10:11], v[4:5]
	v_lshlrev_b32_e32 v13, 16, v84
	v_cvt_pk_bf16_f32 v3, v4, v5
	v_and_b32_e32 v18, 0xffff0000, v84
	global_store_dwordx4 v[6:7], v[0:3], off offset:2048
	ds_read_b128 v[4:7], v12 offset:2176
	s_nop 0
	v_mul_f32_e32 v0, 0xbfb8aa3b, v13
	v_mul_f32_e32 v1, 0xbfb8aa3b, v18
	v_exp_f32_e32 v0, v0
	v_exp_f32_e32 v1, v1
	v_or_b32_e32 v2, 8, v113
	v_mad_u64_u32 v[10:11], s[8:9], v2, s14, v[8:9]
	v_pk_add_f32 v[14:15], v[0:1], 1.0 op_sel_hi:[1,0]
	ds_read_b128 v[0:3], v12 offset:3264
	v_rcp_f32_e32 v20, v15
	s_waitcnt lgkmcnt(1)
	v_lshlrev_b32_e32 v16, 16, v4
	v_and_b32_e32 v17, 0xffff0000, v4
	v_add_u32_e32 v11, s0, v11
	v_rcp_f32_e32 v22, v14
	v_mul_f32_e32 v4, v18, v20
	v_mov_b32_e32 v15, v4
	v_lshlrev_b32_e32 v21, 16, v85
	v_mul_f32_e32 v18, 0xbfb8aa3b, v21
	v_mul_f32_e32 v19, 0xbfb8aa3b, v23
	v_exp_f32_e32 v18, v18
	v_exp_f32_e32 v19, v19
	v_mul_f32_e32 v4, v13, v22
	v_mov_b32_e32 v14, v4
	v_pk_mul_f32 v[14:15], v[14:15], v[16:17]
	v_pk_add_f32 v[16:17], v[18:19], 1.0 op_sel_hi:[1,0]
	v_cvt_pk_bf16_f32 v4, v14, v15
	v_rcp_f32_e32 v18, v17
	v_lshlrev_b32_e32 v14, 16, v5
	v_and_b32_e32 v15, 0xffff0000, v5
	v_rcp_f32_e32 v20, v16
	v_mul_f32_e32 v5, v23, v18
	v_mov_b32_e32 v17, v5
	v_and_b32_e32 v23, 0xffff0000, v86
	v_lshlrev_b32_e32 v13, 16, v86
	v_mul_f32_e32 v18, 0xbfb8aa3b, v13
	v_mul_f32_e32 v19, 0xbfb8aa3b, v23
	v_exp_f32_e32 v18, v18
	v_exp_f32_e32 v19, v19
	v_mul_f32_e32 v5, v21, v20
	v_mov_b32_e32 v16, v5
	v_pk_mul_f32 v[14:15], v[16:17], v[14:15]
	v_pk_add_f32 v[16:17], v[18:19], 1.0 op_sel_hi:[1,0]
	v_cvt_pk_bf16_f32 v5, v14, v15
	v_rcp_f32_e32 v19, v17
	v_lshlrev_b32_e32 v14, 16, v6
	v_and_b32_e32 v15, 0xffff0000, v6
	v_lshlrev_b32_e32 v22, 16, v87
	v_rcp_f32_e32 v21, v16
	v_mul_f32_e32 v6, v23, v19
	v_mov_b32_e32 v17, v6
	v_and_b32_e32 v23, 0xffff0000, v87
	v_mul_f32_e32 v18, 0xbfb8aa3b, v22
	v_mul_f32_e32 v19, 0xbfb8aa3b, v23
	v_exp_f32_e32 v18, v18
	v_exp_f32_e32 v19, v19
	v_mul_f32_e32 v6, v13, v21
	v_mov_b32_e32 v16, v6
	v_pk_mul_f32 v[14:15], v[16:17], v[14:15]
	v_pk_add_f32 v[16:17], v[18:19], 1.0 op_sel_hi:[1,0]
	v_cvt_pk_bf16_f32 v6, v14, v15
	v_rcp_f32_e32 v18, v17
	v_lshlrev_b32_e32 v14, 16, v7
	v_and_b32_e32 v15, 0xffff0000, v7
	v_rcp_f32_e32 v20, v16
	v_mul_f32_e32 v7, v23, v18
	v_mov_b32_e32 v17, v7
	v_and_b32_e32 v23, 0xffff0000, v77
	v_mul_f32_e32 v7, v22, v20
	v_mov_b32_e32 v16, v7
	v_pk_mul_f32 v[14:15], v[16:17], v[14:15]
	v_lshlrev_b32_e32 v13, 16, v80
	v_cvt_pk_bf16_f32 v7, v14, v15
	v_and_b32_e32 v14, 0xffff0000, v80
	global_store_dwordx4 v[10:11], v[4:7], off offset:2048
	s_waitcnt lgkmcnt(0)
	v_lshlrev_b32_e32 v10, 16, v0
	v_and_b32_e32 v11, 0xffff0000, v0
	v_mul_f32_e32 v4, 0xbfb8aa3b, v13
	v_mul_f32_e32 v5, 0xbfb8aa3b, v14
	v_exp_f32_e32 v4, v4
	v_exp_f32_e32 v5, v5
	v_and_b32_e32 v19, 0xffff0000, v81
	v_or_b32_e32 v6, 12, v113
	v_mad_u64_u32 v[6:7], s[8:9], v6, s14, v[8:9]
	v_pk_add_f32 v[4:5], v[4:5], 1.0 op_sel_hi:[1,0]
	v_add_u32_e32 v7, s0, v7
	v_rcp_f32_e32 v16, v5
	s_nop 0
	v_rcp_f32_e32 v18, v4
	v_mul_f32_e32 v0, v14, v16
	v_mov_b32_e32 v5, v0
	v_lshlrev_b32_e32 v17, 16, v81
	v_mul_f32_e32 v14, 0xbfb8aa3b, v17
	v_mul_f32_e32 v15, 0xbfb8aa3b, v19
	v_exp_f32_e32 v14, v14
	v_exp_f32_e32 v15, v15
	v_mul_f32_e32 v0, v13, v18
	v_mov_b32_e32 v4, v0
	v_pk_mul_f32 v[4:5], v[4:5], v[10:11]
	v_pk_add_f32 v[10:11], v[14:15], 1.0 op_sel_hi:[1,0]
	v_cvt_pk_bf16_f32 v0, v4, v5
	v_rcp_f32_e32 v14, v11
	v_lshlrev_b32_e32 v4, 16, v1
	v_and_b32_e32 v5, 0xffff0000, v1
	v_rcp_f32_e32 v16, v10
	v_mul_f32_e32 v1, v19, v14
	v_mov_b32_e32 v11, v1
	v_and_b32_e32 v19, 0xffff0000, v82
	v_lshlrev_b32_e32 v13, 16, v82
	v_mul_f32_e32 v14, 0xbfb8aa3b, v13
	v_mul_f32_e32 v15, 0xbfb8aa3b, v19
	v_exp_f32_e32 v14, v14
	v_exp_f32_e32 v15, v15
	v_mul_f32_e32 v1, v17, v16
	v_mov_b32_e32 v10, v1
	v_pk_mul_f32 v[4:5], v[10:11], v[4:5]
	v_pk_add_f32 v[10:11], v[14:15], 1.0 op_sel_hi:[1,0]
	v_cvt_pk_bf16_f32 v1, v4, v5
	v_rcp_f32_e32 v15, v11
	v_lshlrev_b32_e32 v4, 16, v2
	v_and_b32_e32 v5, 0xffff0000, v2
	v_lshlrev_b32_e32 v18, 16, v83
	v_rcp_f32_e32 v17, v10
	v_mul_f32_e32 v2, v19, v15
	v_mov_b32_e32 v11, v2
	v_and_b32_e32 v19, 0xffff0000, v83
	v_mul_f32_e32 v14, 0xbfb8aa3b, v18
	v_mul_f32_e32 v15, 0xbfb8aa3b, v19
	v_exp_f32_e32 v14, v14
	v_exp_f32_e32 v15, v15
	v_mul_f32_e32 v2, v13, v17
	v_mov_b32_e32 v10, v2
	v_pk_mul_f32 v[4:5], v[10:11], v[4:5]
	v_pk_add_f32 v[10:11], v[14:15], 1.0 op_sel_hi:[1,0]
	v_cvt_pk_bf16_f32 v2, v4, v5
	v_rcp_f32_e32 v14, v11
	v_lshlrev_b32_e32 v4, 16, v3
	v_and_b32_e32 v5, 0xffff0000, v3
	v_rcp_f32_e32 v16, v10
	v_mul_f32_e32 v3, v19, v14
	v_mov_b32_e32 v11, v3
	v_mul_f32_e32 v3, v18, v16
	v_mov_b32_e32 v10, v3
	v_pk_mul_f32 v[4:5], v[10:11], v[4:5]
	v_lshlrev_b32_e32 v13, 16, v76
	v_cvt_pk_bf16_f32 v3, v4, v5
	v_and_b32_e32 v18, 0xffff0000, v76
	global_store_dwordx4 v[6:7], v[0:3], off offset:2048
	ds_read_b128 v[4:7], v12 offset:4352
	s_nop 0
	v_mul_f32_e32 v0, 0xbfb8aa3b, v13
	v_mul_f32_e32 v1, 0xbfb8aa3b, v18
	v_exp_f32_e32 v0, v0
	v_exp_f32_e32 v1, v1
	v_or_b32_e32 v2, 16, v113
	v_mad_u64_u32 v[10:11], s[8:9], v2, s14, v[8:9]
	v_pk_add_f32 v[14:15], v[0:1], 1.0 op_sel_hi:[1,0]
	ds_read_b128 v[0:3], v12 offset:5440
	v_rcp_f32_e32 v20, v15
	s_waitcnt lgkmcnt(1)
	v_lshlrev_b32_e32 v16, 16, v4
	v_and_b32_e32 v17, 0xffff0000, v4
	v_add_u32_e32 v11, s0, v11
	v_rcp_f32_e32 v22, v14
	v_mul_f32_e32 v4, v18, v20
	v_mov_b32_e32 v15, v4
	v_lshlrev_b32_e32 v21, 16, v77
	v_mul_f32_e32 v18, 0xbfb8aa3b, v21
	v_mul_f32_e32 v19, 0xbfb8aa3b, v23
	v_exp_f32_e32 v18, v18
	v_exp_f32_e32 v19, v19
	v_mul_f32_e32 v4, v13, v22
	v_mov_b32_e32 v14, v4
	v_pk_mul_f32 v[14:15], v[14:15], v[16:17]
	v_pk_add_f32 v[16:17], v[18:19], 1.0 op_sel_hi:[1,0]
	v_cvt_pk_bf16_f32 v4, v14, v15
	v_rcp_f32_e32 v18, v17
	v_lshlrev_b32_e32 v14, 16, v5
	v_and_b32_e32 v15, 0xffff0000, v5
	v_rcp_f32_e32 v20, v16
	v_mul_f32_e32 v5, v23, v18
	v_mov_b32_e32 v17, v5
	v_and_b32_e32 v23, 0xffff0000, v78
	v_lshlrev_b32_e32 v13, 16, v78
	v_mul_f32_e32 v18, 0xbfb8aa3b, v13
	v_mul_f32_e32 v19, 0xbfb8aa3b, v23
	v_exp_f32_e32 v18, v18
	v_exp_f32_e32 v19, v19
	v_mul_f32_e32 v5, v21, v20
	v_mov_b32_e32 v16, v5
	v_pk_mul_f32 v[14:15], v[16:17], v[14:15]
	v_pk_add_f32 v[16:17], v[18:19], 1.0 op_sel_hi:[1,0]
	v_cvt_pk_bf16_f32 v5, v14, v15
	v_rcp_f32_e32 v19, v17
	v_lshlrev_b32_e32 v14, 16, v6
	v_and_b32_e32 v15, 0xffff0000, v6
	v_lshlrev_b32_e32 v22, 16, v79
	v_rcp_f32_e32 v21, v16
	v_mul_f32_e32 v6, v23, v19
	v_mov_b32_e32 v17, v6
	v_and_b32_e32 v23, 0xffff0000, v79
	v_mul_f32_e32 v18, 0xbfb8aa3b, v22
	v_mul_f32_e32 v19, 0xbfb8aa3b, v23
	v_exp_f32_e32 v18, v18
	v_exp_f32_e32 v19, v19
	v_mul_f32_e32 v6, v13, v21
	v_mov_b32_e32 v16, v6
	v_pk_mul_f32 v[14:15], v[16:17], v[14:15]
	v_pk_add_f32 v[16:17], v[18:19], 1.0 op_sel_hi:[1,0]
	v_cvt_pk_bf16_f32 v6, v14, v15
	v_rcp_f32_e32 v18, v17
	v_lshlrev_b32_e32 v14, 16, v7
	v_and_b32_e32 v15, 0xffff0000, v7
	v_rcp_f32_e32 v20, v16
	v_mul_f32_e32 v7, v23, v18
	v_mov_b32_e32 v17, v7
	v_mul_f32_e32 v7, v22, v20
	v_mov_b32_e32 v16, v7
	v_pk_mul_f32 v[14:15], v[16:17], v[14:15]
	v_lshlrev_b32_e32 v13, 16, v72
	v_cvt_pk_bf16_f32 v7, v14, v15
	v_and_b32_e32 v14, 0xffff0000, v72
	global_store_dwordx4 v[10:11], v[4:7], off offset:2048
	s_waitcnt lgkmcnt(0)
	v_lshlrev_b32_e32 v10, 16, v0
	v_and_b32_e32 v11, 0xffff0000, v0
	v_mul_f32_e32 v4, 0xbfb8aa3b, v13
	v_mul_f32_e32 v5, 0xbfb8aa3b, v14
	v_exp_f32_e32 v4, v4
	v_exp_f32_e32 v5, v5
	v_and_b32_e32 v19, 0xffff0000, v73
	v_or_b32_e32 v6, 20, v113
	v_mad_u64_u32 v[6:7], s[8:9], v6, s14, v[8:9]
	v_pk_add_f32 v[4:5], v[4:5], 1.0 op_sel_hi:[1,0]
	v_add_u32_e32 v7, s0, v7
	v_rcp_f32_e32 v16, v5
	v_and_b32_e32 v22, 0xffff0000, v69
	v_rcp_f32_e32 v18, v4
	v_mul_f32_e32 v0, v14, v16
	v_mov_b32_e32 v5, v0
	v_lshlrev_b32_e32 v17, 16, v73
	v_mul_f32_e32 v14, 0xbfb8aa3b, v17
	v_mul_f32_e32 v15, 0xbfb8aa3b, v19
	v_exp_f32_e32 v14, v14
	v_exp_f32_e32 v15, v15
	v_mul_f32_e32 v0, v13, v18
	v_mov_b32_e32 v4, v0
	v_pk_mul_f32 v[4:5], v[4:5], v[10:11]
	v_pk_add_f32 v[10:11], v[14:15], 1.0 op_sel_hi:[1,0]
	v_cvt_pk_bf16_f32 v0, v4, v5
	v_rcp_f32_e32 v14, v11
	v_lshlrev_b32_e32 v4, 16, v1
	v_and_b32_e32 v5, 0xffff0000, v1
	v_rcp_f32_e32 v16, v10
	v_mul_f32_e32 v1, v19, v14
	v_mov_b32_e32 v11, v1
	v_and_b32_e32 v19, 0xffff0000, v74
	v_lshlrev_b32_e32 v13, 16, v74
	v_mul_f32_e32 v14, 0xbfb8aa3b, v13
	v_mul_f32_e32 v15, 0xbfb8aa3b, v19
	v_exp_f32_e32 v14, v14
	v_exp_f32_e32 v15, v15
	v_mul_f32_e32 v1, v17, v16
	v_mov_b32_e32 v10, v1
	v_pk_mul_f32 v[4:5], v[10:11], v[4:5]
	v_pk_add_f32 v[10:11], v[14:15], 1.0 op_sel_hi:[1,0]
	v_cvt_pk_bf16_f32 v1, v4, v5
	v_rcp_f32_e32 v15, v11
	v_lshlrev_b32_e32 v4, 16, v2
	v_and_b32_e32 v5, 0xffff0000, v2
	v_lshlrev_b32_e32 v18, 16, v75
	v_rcp_f32_e32 v17, v10
	v_mul_f32_e32 v2, v19, v15
	v_mov_b32_e32 v11, v2
	v_and_b32_e32 v19, 0xffff0000, v75
	v_mul_f32_e32 v14, 0xbfb8aa3b, v18
	v_mul_f32_e32 v15, 0xbfb8aa3b, v19
	v_exp_f32_e32 v14, v14
	v_exp_f32_e32 v15, v15
	v_mul_f32_e32 v2, v13, v17
	v_mov_b32_e32 v10, v2
	v_pk_mul_f32 v[4:5], v[10:11], v[4:5]
	v_pk_add_f32 v[10:11], v[14:15], 1.0 op_sel_hi:[1,0]
	v_cvt_pk_bf16_f32 v2, v4, v5
	v_rcp_f32_e32 v14, v11
	v_lshlrev_b32_e32 v4, 16, v3
	v_and_b32_e32 v5, 0xffff0000, v3
	v_rcp_f32_e32 v16, v10
	v_mul_f32_e32 v3, v19, v14
	v_mov_b32_e32 v11, v3
	v_mul_f32_e32 v3, v18, v16
	v_mov_b32_e32 v10, v3
	v_pk_mul_f32 v[4:5], v[10:11], v[4:5]
	v_lshlrev_b32_e32 v18, 16, v68
	v_cvt_pk_bf16_f32 v3, v4, v5
	v_and_b32_e32 v16, 0xffff0000, v68
	global_store_dwordx4 v[6:7], v[0:3], off offset:2048
	ds_read_b128 v[4:7], v12 offset:6528
	s_nop 0
	v_mul_f32_e32 v0, 0xbfb8aa3b, v18
	v_mul_f32_e32 v1, 0xbfb8aa3b, v16
	v_exp_f32_e32 v0, v0
	v_exp_f32_e32 v1, v1
	v_or_b32_e32 v2, 24, v113
	v_mad_u64_u32 v[10:11], s[8:9], v2, s14, v[8:9]
	v_pk_add_f32 v[14:15], v[0:1], 1.0 op_sel_hi:[1,0]
	ds_read_b128 v[0:3], v12 offset:7616
	v_rcp_f32_e32 v19, v15
	s_waitcnt lgkmcnt(1)
	v_lshlrev_b32_e32 v12, 16, v4
	v_and_b32_e32 v13, 0xffff0000, v4
	v_add_u32_e32 v11, s0, v11
	v_rcp_f32_e32 v21, v14
	v_mul_f32_e32 v4, v16, v19
	v_mov_b32_e32 v15, v4
	v_lshlrev_b32_e32 v20, 16, v69
	v_mul_f32_e32 v16, 0xbfb8aa3b, v20
	v_mul_f32_e32 v17, 0xbfb8aa3b, v22
	v_exp_f32_e32 v16, v16
	v_exp_f32_e32 v17, v17
	v_mul_f32_e32 v4, v18, v21
	v_mov_b32_e32 v14, v4
	v_pk_mul_f32 v[12:13], v[14:15], v[12:13]
	v_pk_add_f32 v[14:15], v[16:17], 1.0 op_sel_hi:[1,0]
	v_cvt_pk_bf16_f32 v4, v12, v13
	v_rcp_f32_e32 v17, v15
	v_lshlrev_b32_e32 v12, 16, v5
	v_and_b32_e32 v13, 0xffff0000, v5
	v_lshlrev_b32_e32 v21, 16, v70
	v_rcp_f32_e32 v19, v14
	v_mul_f32_e32 v5, v22, v17
	v_mov_b32_e32 v15, v5
	v_and_b32_e32 v22, 0xffff0000, v70
	v_mul_f32_e32 v16, 0xbfb8aa3b, v21
	v_mul_f32_e32 v17, 0xbfb8aa3b, v22
	v_exp_f32_e32 v16, v16
	v_exp_f32_e32 v17, v17
	v_mul_f32_e32 v5, v20, v19
	v_mov_b32_e32 v14, v5
	v_pk_mul_f32 v[12:13], v[14:15], v[12:13]
	v_pk_add_f32 v[14:15], v[16:17], 1.0 op_sel_hi:[1,0]
	v_cvt_pk_bf16_f32 v5, v12, v13
	v_rcp_f32_e32 v17, v15
	v_lshlrev_b32_e32 v12, 16, v6
	v_and_b32_e32 v13, 0xffff0000, v6
	v_lshlrev_b32_e32 v20, 16, v71
	v_rcp_f32_e32 v19, v14
	v_mul_f32_e32 v6, v22, v17
	v_mov_b32_e32 v15, v6
	v_and_b32_e32 v22, 0xffff0000, v71
	v_mul_f32_e32 v16, 0xbfb8aa3b, v20
	v_mul_f32_e32 v17, 0xbfb8aa3b, v22
	v_exp_f32_e32 v16, v16
	v_exp_f32_e32 v17, v17
	v_mul_f32_e32 v6, v21, v19
	v_mov_b32_e32 v14, v6
	v_pk_mul_f32 v[12:13], v[14:15], v[12:13]
	v_pk_add_f32 v[14:15], v[16:17], 1.0 op_sel_hi:[1,0]
	v_cvt_pk_bf16_f32 v6, v12, v13
	v_rcp_f32_e32 v17, v15
	v_lshlrev_b32_e32 v12, 16, v7
	v_and_b32_e32 v13, 0xffff0000, v7
	v_rcp_f32_e32 v19, v14
	v_mul_f32_e32 v7, v22, v17
	v_mov_b32_e32 v15, v7
	v_mul_f32_e32 v7, v20, v19
	v_mov_b32_e32 v14, v7
	v_pk_mul_f32 v[12:13], v[14:15], v[12:13]
	v_and_b32_e32 v16, 0xffff0000, v65
	v_cvt_pk_bf16_f32 v7, v12, v13
	global_store_dwordx4 v[10:11], v[4:7], off offset:2048
	v_lshlrev_b32_e32 v12, 16, v64
	v_and_b32_e32 v10, 0xffff0000, v64
	v_mul_f32_e32 v4, 0xbfb8aa3b, v12
	v_mul_f32_e32 v5, 0xbfb8aa3b, v10
	v_exp_f32_e32 v4, v4
	v_exp_f32_e32 v5, v5
	v_or_b32_e32 v6, 28, v113
	v_mad_u64_u32 v[6:7], s[8:9], v6, s14, v[8:9]
	v_pk_add_f32 v[4:5], v[4:5], 1.0 op_sel_hi:[1,0]
	s_waitcnt lgkmcnt(0)
	v_lshlrev_b32_e32 v8, 16, v0
	v_rcp_f32_e32 v13, v5
	v_and_b32_e32 v9, 0xffff0000, v0
	v_add_u32_e32 v7, s0, v7
	v_rcp_f32_e32 v15, v4
	v_mul_f32_e32 v0, v10, v13
	v_mov_b32_e32 v5, v0
	v_lshlrev_b32_e32 v14, 16, v65
	v_mul_f32_e32 v10, 0xbfb8aa3b, v14
	v_mul_f32_e32 v11, 0xbfb8aa3b, v16
	v_exp_f32_e32 v10, v10
	v_exp_f32_e32 v11, v11
	v_mul_f32_e32 v0, v12, v15
	v_mov_b32_e32 v4, v0
	v_pk_mul_f32 v[4:5], v[4:5], v[8:9]
	v_pk_add_f32 v[8:9], v[10:11], 1.0 op_sel_hi:[1,0]
	v_cvt_pk_bf16_f32 v0, v4, v5
	v_rcp_f32_e32 v11, v9
	v_lshlrev_b32_e32 v4, 16, v1
	v_and_b32_e32 v5, 0xffff0000, v1
	v_lshlrev_b32_e32 v15, 16, v66
	v_rcp_f32_e32 v13, v8
	v_mul_f32_e32 v1, v16, v11
	v_mov_b32_e32 v9, v1
	v_and_b32_e32 v16, 0xffff0000, v66
	v_mul_f32_e32 v10, 0xbfb8aa3b, v15
	v_mul_f32_e32 v11, 0xbfb8aa3b, v16
	v_exp_f32_e32 v10, v10
	v_exp_f32_e32 v11, v11
	v_mul_f32_e32 v1, v14, v13
	v_mov_b32_e32 v8, v1
	v_pk_mul_f32 v[4:5], v[8:9], v[4:5]
	v_pk_add_f32 v[8:9], v[10:11], 1.0 op_sel_hi:[1,0]
	v_cvt_pk_bf16_f32 v1, v4, v5
	v_rcp_f32_e32 v11, v9
	v_lshlrev_b32_e32 v4, 16, v2
	v_and_b32_e32 v5, 0xffff0000, v2
	v_lshlrev_b32_e32 v14, 16, v67
	v_rcp_f32_e32 v13, v8
	v_mul_f32_e32 v2, v16, v11
	v_mov_b32_e32 v9, v2
	v_and_b32_e32 v16, 0xffff0000, v67
	v_mul_f32_e32 v10, 0xbfb8aa3b, v14
	v_mul_f32_e32 v11, 0xbfb8aa3b, v16
	v_exp_f32_e32 v10, v10
	v_exp_f32_e32 v11, v11
	v_mul_f32_e32 v2, v15, v13
	v_mov_b32_e32 v8, v2
	v_pk_mul_f32 v[4:5], v[8:9], v[4:5]
	v_pk_add_f32 v[8:9], v[10:11], 1.0 op_sel_hi:[1,0]
	v_cvt_pk_bf16_f32 v2, v4, v5
	v_rcp_f32_e32 v11, v9
	v_lshlrev_b32_e32 v4, 16, v3
	v_and_b32_e32 v5, 0xffff0000, v3
	v_rcp_f32_e32 v13, v8
	v_mul_f32_e32 v3, v16, v11
	v_mov_b32_e32 v9, v3
	v_mul_f32_e32 v3, v14, v13
	v_mov_b32_e32 v8, v3
	v_pk_mul_f32 v[4:5], v[8:9], v[4:5]
	s_nop 0
	v_cvt_pk_bf16_f32 v3, v4, v5
	global_store_dwordx4 v[6:7], v[0:3], off offset:2048
	s_branch .LBB0_828

.LBB0_916:
	v_lshl_or_b32 v130, s7, 8, v152
	v_lshl_add_u32 v154, s8, 8, v150
	v_mov_b64_e32 v[144:145], s[82:83]
	v_ashrrev_i32_e32 v131, 31, v130
	v_mad_i64_i32 v[128:129], s[0:1], v154, s14, v[144:145]
	v_lshlrev_b64 v[146:147], 1, v[130:131]
	v_lshl_add_u64 v[148:149], v[128:129], 0, v[146:147]
	v_add_co_u32_e32 v128, vcc, 0x1000, v148
	v_lshl_add_u64 v[142:143], v[130:131], 2, s[72:73]
	s_nop 0
	v_addc_co_u32_e32 v129, vcc, 0, v149, vcc
	global_load_dwordx4 v[156:159], v[128:129], off
	global_load_dwordx4 v[160:163], v[148:149], off
	global_load_dwordx4 v[164:167], v[142:143], off offset:16
	global_load_dwordx4 v[168:171], v[142:143], off
	s_waitcnt vmcnt(0)
	v_pk_add_f32 v[130:131], v[122:123], v[166:167]
	v_pk_add_f32 v[124:125], v[124:125], v[168:169]
	v_pk_add_f32 v[122:123], v[120:121], v[164:165]
	v_mul_f32_e32 v120, 0xbfb8aa3b, v124
	v_mul_f32_e32 v121, 0xbfb8aa3b, v125
	v_exp_f32_e32 v120, v120
	v_exp_f32_e32 v121, v121
	v_lshlrev_b32_e32 v164, 16, v156
	v_and_b32_e32 v165, 0xffff0000, v156
	v_lshlrev_b32_e32 v155, 16, v160
	v_pk_add_f32 v[120:121], v[120:121], 1.0 op_sel_hi:[1,0]
	v_and_b32_e32 v160, 0xffff0000, v160
	v_rcp_f32_e32 v156, v121
	v_mul_f32_e32 v124, 0xbfb8aa3b, v155
	v_exp_f32_e32 v124, v124
	v_pk_add_f32 v[126:127], v[126:127], v[170:171]
	v_mul_f32_e32 v125, 1.0, v156
	v_mov_b32_e32 v121, v125
	v_rcp_f32_e32 v156, v120
	v_mul_f32_e32 v122, 0xbfb8aa3b, v122
	v_mul_f32_e32 v123, 0xbfb8aa3b, v123
	v_exp_f32_e32 v122, v122
	v_mul_f32_e32 v125, 1.0, v156
	v_mov_b32_e32 v120, v125
	v_mul_f32_e32 v125, 0xbfb8aa3b, v160
	v_exp_f32_e32 v125, v125
	v_pk_mul_f32 v[120:121], v[120:121], v[164:165]
	v_exp_f32_e32 v123, v123
	v_pk_add_f32 v[124:125], v[124:125], 1.0 op_sel_hi:[1,0]
	s_nop 0
	v_rcp_f32_e32 v164, v125
	v_pk_add_f32 v[122:123], v[122:123], 1.0 op_sel_hi:[1,0]
	v_mul_f32_e32 v156, v160, v164
	v_mov_b32_e32 v125, v156
	v_rcp_f32_e32 v160, v124
	s_nop 0
	v_mul_f32_e32 v156, v155, v160
	v_mov_b32_e32 v124, v156
	v_pk_mul_f32 v[120:121], v[124:125], v[120:121]
	v_and_b32_e32 v155, 0xffff0000, v161
	v_cvt_pk_bf16_f32 v120, v120, v121
	v_mul_f32_e32 v121, 0xbfb8aa3b, v126
	v_exp_f32_e32 v124, v121
	v_mul_f32_e32 v121, 0xbfb8aa3b, v127
	v_exp_f32_e32 v125, v121
	v_lshlrev_b32_e32 v121, 16, v161
	v_mul_f32_e32 v126, 0xbfb8aa3b, v121
	v_exp_f32_e32 v126, v126
	v_pk_add_f32 v[124:125], v[124:125], 1.0 op_sel_hi:[1,0]
	v_lshlrev_b32_e32 v156, 16, v157
	v_rcp_f32_e32 v160, v125
	v_and_b32_e32 v157, 0xffff0000, v157
	v_mul_f32_e32 v127, 1.0, v160
	v_mov_b32_e32 v125, v127
	v_rcp_f32_e32 v160, v124
	s_nop 0
	v_mul_f32_e32 v127, 1.0, v160
	v_mov_b32_e32 v124, v127
	v_mul_f32_e32 v127, 0xbfb8aa3b, v155
	v_exp_f32_e32 v127, v127
	v_pk_mul_f32 v[124:125], v[124:125], v[156:157]
	v_pk_add_f32 v[126:127], v[126:127], 1.0 op_sel_hi:[1,0]
	s_nop 0
	v_rcp_f32_e32 v157, v127
	s_nop 0
	v_mul_f32_e32 v156, v155, v157
	v_mov_b32_e32 v127, v156
	v_rcp_f32_e32 v156, v126
	s_nop 0
	v_mul_f32_e32 v155, v121, v156
	v_mov_b32_e32 v126, v155
	v_pk_mul_f32 v[124:125], v[126:127], v[124:125]
	v_lshlrev_b32_e32 v126, 16, v158
	v_cvt_pk_bf16_f32 v121, v124, v125
	v_rcp_f32_e32 v157, v123
	v_and_b32_e32 v127, 0xffff0000, v158
	v_lshlrev_b32_e32 v155, 16, v162
	v_and_b32_e32 v156, 0xffff0000, v162
	v_mul_f32_e32 v125, 1.0, v157
	v_mov_b32_e32 v123, v125
	v_rcp_f32_e32 v157, v122
	v_mul_f32_e32 v124, 0xbfb8aa3b, v155
	v_exp_f32_e32 v124, v124
	v_mul_f32_e32 v125, 1.0, v157
	v_mov_b32_e32 v122, v125
	v_mul_f32_e32 v125, 0xbfb8aa3b, v156
	v_exp_f32_e32 v125, v125
	v_pk_mul_f32 v[122:123], v[122:123], v[126:127]
	v_pk_add_f32 v[124:125], v[124:125], 1.0 op_sel_hi:[1,0]
	s_nop 0
	v_rcp_f32_e32 v127, v125
	s_nop 0
	v_mul_f32_e32 v126, v156, v127
	v_mov_b32_e32 v125, v126
	v_rcp_f32_e32 v127, v124
	s_nop 0
	v_mul_f32_e32 v126, v155, v127
	v_mov_b32_e32 v124, v126
	v_pk_mul_f32 v[122:123], v[124:125], v[122:123]
	v_and_b32_e32 v155, 0xffff0000, v163
	v_cvt_pk_bf16_f32 v122, v122, v123
	v_mul_f32_e32 v123, 0xbfb8aa3b, v130
	v_exp_f32_e32 v124, v123
	v_mul_f32_e32 v123, 0xbfb8aa3b, v131
	v_exp_f32_e32 v125, v123
	v_lshlrev_b32_e32 v130, 16, v159
	v_and_b32_e32 v131, 0xffff0000, v159
	v_lshlrev_b32_e32 v123, 16, v163
	v_pk_add_f32 v[124:125], v[124:125], 1.0 op_sel_hi:[1,0]
	v_mul_f32_e32 v126, 0xbfb8aa3b, v123
	v_rcp_f32_e32 v156, v125
	v_exp_f32_e32 v126, v126
	v_mul_f32_e32 v127, 1.0, v156
	v_mov_b32_e32 v125, v127
	v_rcp_f32_e32 v156, v124
	s_nop 0
	v_mul_f32_e32 v127, 1.0, v156
	v_mov_b32_e32 v124, v127
	v_mul_f32_e32 v127, 0xbfb8aa3b, v155
	v_exp_f32_e32 v127, v127
	v_pk_mul_f32 v[124:125], v[124:125], v[130:131]
	v_pk_add_f32 v[126:127], v[126:127], 1.0 op_sel_hi:[1,0]
	s_nop 0
	v_rcp_f32_e32 v131, v127
	s_nop 0
	v_mul_f32_e32 v130, v155, v131
	v_mov_b32_e32 v127, v130
	v_rcp_f32_e32 v131, v126
	s_nop 0
	v_mul_f32_e32 v130, v123, v131
	v_mov_b32_e32 v126, v130
	v_pk_mul_f32 v[124:125], v[126:127], v[124:125]
	s_nop 0
	v_cvt_pk_bf16_f32 v123, v124, v125
	global_store_dwordx4 v[148:149], v[120:123], off
	global_load_dwordx4 v[120:123], v[128:129], off offset:256
	s_nop 0
	global_load_dwordx4 v[124:127], v[148:149], off offset:256
	global_load_dwordx4 v[128:131], v[142:143], off offset:528
	global_load_dwordx4 v[156:159], v[142:143], off offset:512
	s_waitcnt vmcnt(2)
	v_lshlrev_b32_e32 v155, 16, v124
	v_and_b32_e32 v124, 0xffff0000, v124
	s_waitcnt vmcnt(0)
	v_pk_add_f32 v[156:157], v[116:117], v[156:157]
	v_pk_add_f32 v[116:117], v[114:115], v[130:131]
	v_pk_add_f32 v[114:115], v[112:113], v[128:129]
	v_mul_f32_e32 v112, 0xbfb8aa3b, v156
	v_mul_f32_e32 v113, 0xbfb8aa3b, v157
	v_exp_f32_e32 v112, v112
	v_exp_f32_e32 v113, v113
	v_lshlrev_b32_e32 v130, 16, v120
	v_and_b32_e32 v131, 0xffff0000, v120
	v_pk_add_f32 v[118:119], v[118:119], v[158:159]
	v_pk_add_f32 v[112:113], v[112:113], 1.0 op_sel_hi:[1,0]
	v_mul_f32_e32 v128, 0xbfb8aa3b, v155
	v_rcp_f32_e32 v129, v113
	v_exp_f32_e32 v128, v128
	v_mul_f32_e32 v114, 0xbfb8aa3b, v114
	v_mul_f32_e32 v115, 0xbfb8aa3b, v115
	v_mul_f32_e32 v120, 1.0, v129
	v_mov_b32_e32 v113, v120
	v_rcp_f32_e32 v129, v112
	v_exp_f32_e32 v114, v114
	v_exp_f32_e32 v115, v115
	v_mul_f32_e32 v120, 1.0, v129
	v_mov_b32_e32 v112, v120
	v_mul_f32_e32 v120, 0xbfb8aa3b, v124
	v_exp_f32_e32 v129, v120
	v_pk_mul_f32 v[112:113], v[112:113], v[130:131]
	v_pk_add_f32 v[114:115], v[114:115], 1.0 op_sel_hi:[1,0]
	v_pk_add_f32 v[128:129], v[128:129], 1.0 op_sel_hi:[1,0]
	s_nop 0
	v_rcp_f32_e32 v130, v129
	s_nop 0
	v_mul_f32_e32 v120, v124, v130
	v_mov_b32_e32 v129, v120
	v_rcp_f32_e32 v124, v128
	s_nop 0
	v_mul_f32_e32 v120, v155, v124
	v_mov_b32_e32 v128, v120
	v_pk_mul_f32 v[112:113], v[128:129], v[112:113]
	v_and_b32_e32 v128, 0xffff0000, v125
	v_cvt_pk_bf16_f32 v112, v112, v113
	v_mul_f32_e32 v113, 0xbfb8aa3b, v118
	v_exp_f32_e32 v118, v113
	v_mul_f32_e32 v113, 0xbfb8aa3b, v119
	v_exp_f32_e32 v119, v113
	v_lshlrev_b32_e32 v113, 16, v125
	v_lshlrev_b32_e32 v124, 16, v121
	v_and_b32_e32 v125, 0xffff0000, v121
	v_pk_add_f32 v[118:119], v[118:119], 1.0 op_sel_hi:[1,0]
	v_mul_f32_e32 v120, 0xbfb8aa3b, v113
	v_rcp_f32_e32 v129, v119
	v_exp_f32_e32 v120, v120
	v_mul_f32_e32 v121, 1.0, v129
	v_mov_b32_e32 v119, v121
	v_rcp_f32_e32 v129, v118
	s_nop 0
	v_mul_f32_e32 v121, 1.0, v129
	v_mov_b32_e32 v118, v121
	v_mul_f32_e32 v121, 0xbfb8aa3b, v128
	v_exp_f32_e32 v121, v121
	v_pk_mul_f32 v[118:119], v[118:119], v[124:125]
	v_pk_add_f32 v[120:121], v[120:121], 1.0 op_sel_hi:[1,0]
	s_nop 0
	v_rcp_f32_e32 v125, v121
	s_nop 0
	v_mul_f32_e32 v124, v128, v125
	v_mov_b32_e32 v121, v124
	v_rcp_f32_e32 v125, v120
	s_nop 0
	v_mul_f32_e32 v124, v113, v125
	v_mov_b32_e32 v120, v124
	v_pk_mul_f32 v[118:119], v[120:121], v[118:119]
	v_lshlrev_b32_e32 v120, 16, v122
	v_cvt_pk_bf16_f32 v113, v118, v119
	v_and_b32_e32 v121, 0xffff0000, v122
	v_rcp_f32_e32 v122, v115
	v_lshlrev_b32_e32 v124, 16, v126
	v_and_b32_e32 v125, 0xffff0000, v126
	v_mul_f32_e32 v118, 0xbfb8aa3b, v124
	v_mul_f32_e32 v119, 1.0, v122
	v_mov_b32_e32 v115, v119
	v_rcp_f32_e32 v122, v114
	v_exp_f32_e32 v118, v118
	v_mul_f32_e32 v119, 1.0, v122
	v_mov_b32_e32 v114, v119
	v_mul_f32_e32 v119, 0xbfb8aa3b, v125
	v_exp_f32_e32 v119, v119
	v_pk_mul_f32 v[114:115], v[114:115], v[120:121]
	v_pk_add_f32 v[118:119], v[118:119], 1.0 op_sel_hi:[1,0]
	s_nop 0
	v_rcp_f32_e32 v121, v119
	s_nop 0
	v_mul_f32_e32 v120, v125, v121
	v_mov_b32_e32 v119, v120
	v_rcp_f32_e32 v121, v118
	s_nop 0
	v_mul_f32_e32 v120, v124, v121
	v_mov_b32_e32 v118, v120
	v_pk_mul_f32 v[114:115], v[118:119], v[114:115]
	v_lshlrev_b32_e32 v120, 16, v123
	v_cvt_pk_bf16_f32 v114, v114, v115
	v_mul_f32_e32 v115, 0xbfb8aa3b, v116
	v_exp_f32_e32 v116, v115
	v_mul_f32_e32 v115, 0xbfb8aa3b, v117
	v_exp_f32_e32 v117, v115
	v_and_b32_e32 v121, 0xffff0000, v123
	v_lshlrev_b32_e32 v115, 16, v127
	v_and_b32_e32 v122, 0xffff0000, v127
	v_pk_add_f32 v[116:117], v[116:117], 1.0 op_sel_hi:[1,0]
	v_mul_f32_e32 v118, 0xbfb8aa3b, v115
	v_rcp_f32_e32 v123, v117
	v_exp_f32_e32 v118, v118
	v_mul_f32_e32 v119, 1.0, v123
	v_mov_b32_e32 v117, v119
	v_rcp_f32_e32 v123, v116
	s_nop 0
	v_mul_f32_e32 v119, 1.0, v123
	v_mov_b32_e32 v116, v119
	v_mul_f32_e32 v119, 0xbfb8aa3b, v122
	v_exp_f32_e32 v119, v119
	v_pk_mul_f32 v[116:117], v[116:117], v[120:121]
	v_pk_add_f32 v[118:119], v[118:119], 1.0 op_sel_hi:[1,0]
	s_nop 0
	v_rcp_f32_e32 v121, v119
	s_nop 0
	v_mul_f32_e32 v120, v122, v121
	v_mov_b32_e32 v119, v120
	v_rcp_f32_e32 v121, v118
	s_nop 0
	v_mul_f32_e32 v120, v115, v121
	v_mov_b32_e32 v118, v120
	v_pk_mul_f32 v[116:117], v[118:119], v[116:117]
	s_nop 0
	v_cvt_pk_bf16_f32 v115, v116, v117
	global_store_dwordx4 v[148:149], v[112:115], off offset:256
	s_nop 1
	v_or_b32_e32 v112, 16, v154
	v_mad_i64_i32 v[112:113], s[0:1], v112, s14, v[144:145]
	v_lshl_add_u64 v[120:121], v[112:113], 0, v[146:147]
	v_add_co_u32_e32 v122, vcc, s15, v120
	s_nop 1
	v_addc_co_u32_e32 v123, vcc, 0, v121, vcc
	global_load_dwordx4 v[112:115], v[122:123], off
	global_load_dwordx4 v[116:119], v[120:121], off
	global_load_dwordx4 v[124:127], v[142:143], off offset:16
	global_load_dwordx4 v[128:131], v[142:143], off
	s_waitcnt vmcnt(1)
	v_pk_add_f32 v[126:127], v[106:107], v[126:127]
	s_waitcnt vmcnt(0)
	v_pk_add_f32 v[108:109], v[108:109], v[128:129]
	v_pk_add_f32 v[106:107], v[104:105], v[124:125]
	v_mul_f32_e32 v104, 0xbfb8aa3b, v108
	v_mul_f32_e32 v105, 0xbfb8aa3b, v109
	v_exp_f32_e32 v104, v104
	v_exp_f32_e32 v105, v105
	v_lshlrev_b32_e32 v124, 16, v112
	v_and_b32_e32 v125, 0xffff0000, v112
	v_pk_add_f32 v[110:111], v[110:111], v[130:131]
	v_pk_add_f32 v[104:105], v[104:105], 1.0 op_sel_hi:[1,0]
	v_lshlrev_b32_e32 v128, 16, v116
	v_rcp_f32_e32 v112, v105
	v_and_b32_e32 v116, 0xffff0000, v116
	v_mul_f32_e32 v108, 0xbfb8aa3b, v128
	v_exp_f32_e32 v108, v108
	v_mul_f32_e32 v109, 1.0, v112
	v_mov_b32_e32 v105, v109
	v_rcp_f32_e32 v112, v104
	v_mul_f32_e32 v106, 0xbfb8aa3b, v106
	v_mul_f32_e32 v107, 0xbfb8aa3b, v107
	v_exp_f32_e32 v106, v106
	v_mul_f32_e32 v109, 1.0, v112
	v_mov_b32_e32 v104, v109
	v_mul_f32_e32 v109, 0xbfb8aa3b, v116
	v_exp_f32_e32 v109, v109
	v_pk_mul_f32 v[104:105], v[104:105], v[124:125]
	v_exp_f32_e32 v107, v107
	v_pk_add_f32 v[108:109], v[108:109], 1.0 op_sel_hi:[1,0]
	s_nop 0
	v_rcp_f32_e32 v124, v109
	v_pk_add_f32 v[106:107], v[106:107], 1.0 op_sel_hi:[1,0]
	v_mul_f32_e32 v112, v116, v124
	v_mov_b32_e32 v109, v112
	v_rcp_f32_e32 v116, v108
	s_nop 0
	v_mul_f32_e32 v112, v128, v116
	v_mov_b32_e32 v108, v112
	v_pk_mul_f32 v[104:105], v[108:109], v[104:105]
	v_and_b32_e32 v116, 0xffff0000, v117
	v_cvt_pk_bf16_f32 v104, v104, v105
	v_mul_f32_e32 v105, 0xbfb8aa3b, v110
	v_exp_f32_e32 v108, v105
	v_mul_f32_e32 v105, 0xbfb8aa3b, v111
	v_exp_f32_e32 v109, v105
	v_lshlrev_b32_e32 v105, 16, v117
	v_mul_f32_e32 v110, 0xbfb8aa3b, v105
	v_exp_f32_e32 v110, v110
	v_pk_add_f32 v[108:109], v[108:109], 1.0 op_sel_hi:[1,0]
	v_lshlrev_b32_e32 v112, 16, v113
	v_rcp_f32_e32 v117, v109
	v_and_b32_e32 v113, 0xffff0000, v113
	v_mul_f32_e32 v111, 1.0, v117
	v_mov_b32_e32 v109, v111
	v_rcp_f32_e32 v117, v108
	s_nop 0
	v_mul_f32_e32 v111, 1.0, v117
	v_mov_b32_e32 v108, v111
	v_mul_f32_e32 v111, 0xbfb8aa3b, v116
	v_exp_f32_e32 v111, v111
	v_pk_mul_f32 v[108:109], v[108:109], v[112:113]
	v_pk_add_f32 v[110:111], v[110:111], 1.0 op_sel_hi:[1,0]
	s_nop 0
	v_rcp_f32_e32 v113, v111
	s_nop 0
	v_mul_f32_e32 v112, v116, v113
	v_mov_b32_e32 v111, v112
	v_rcp_f32_e32 v113, v110
	s_nop 0
	v_mul_f32_e32 v112, v105, v113
	v_mov_b32_e32 v110, v112
	v_pk_mul_f32 v[108:109], v[110:111], v[108:109]
	v_lshlrev_b32_e32 v110, 16, v114
	v_cvt_pk_bf16_f32 v105, v108, v109
	v_and_b32_e32 v111, 0xffff0000, v114
	v_rcp_f32_e32 v114, v107
	v_lshlrev_b32_e32 v112, 16, v118
	v_and_b32_e32 v113, 0xffff0000, v118
	v_mul_f32_e32 v108, 0xbfb8aa3b, v112
	v_mul_f32_e32 v109, 1.0, v114
	v_mov_b32_e32 v107, v109
	v_rcp_f32_e32 v114, v106
	v_exp_f32_e32 v108, v108
	v_mul_f32_e32 v109, 1.0, v114
	v_mov_b32_e32 v106, v109
	v_mul_f32_e32 v109, 0xbfb8aa3b, v113
	v_exp_f32_e32 v109, v109
	v_pk_mul_f32 v[106:107], v[106:107], v[110:111]
	v_pk_add_f32 v[108:109], v[108:109], 1.0 op_sel_hi:[1,0]
	s_nop 0
	v_rcp_f32_e32 v111, v109
	s_nop 0
	v_mul_f32_e32 v110, v113, v111
	v_mov_b32_e32 v109, v110
	v_rcp_f32_e32 v111, v108
	s_nop 0
	v_mul_f32_e32 v110, v112, v111
	v_mov_b32_e32 v108, v110
	v_pk_mul_f32 v[106:107], v[108:109], v[106:107]
	v_lshlrev_b32_e32 v112, 16, v115
	v_cvt_pk_bf16_f32 v106, v106, v107
	v_mul_f32_e32 v107, 0xbfb8aa3b, v126
	v_exp_f32_e32 v108, v107
	v_mul_f32_e32 v107, 0xbfb8aa3b, v127
	v_exp_f32_e32 v109, v107
	v_and_b32_e32 v113, 0xffff0000, v115
	v_lshlrev_b32_e32 v107, 16, v119
	v_and_b32_e32 v114, 0xffff0000, v119
	v_pk_add_f32 v[108:109], v[108:109], 1.0 op_sel_hi:[1,0]
	v_mul_f32_e32 v110, 0xbfb8aa3b, v107
	v_rcp_f32_e32 v115, v109
	v_exp_f32_e32 v110, v110
	v_mul_f32_e32 v111, 1.0, v115
	v_mov_b32_e32 v109, v111
	v_rcp_f32_e32 v115, v108
	s_nop 0
	v_mul_f32_e32 v111, 1.0, v115
	v_mov_b32_e32 v108, v111
	v_mul_f32_e32 v111, 0xbfb8aa3b, v114
	v_exp_f32_e32 v111, v111
	v_pk_mul_f32 v[108:109], v[108:109], v[112:113]
	v_pk_add_f32 v[110:111], v[110:111], 1.0 op_sel_hi:[1,0]
	s_nop 0
	v_rcp_f32_e32 v113, v111
	s_nop 0
	v_mul_f32_e32 v112, v114, v113
	v_mov_b32_e32 v111, v112
	v_rcp_f32_e32 v113, v110
	s_nop 0
	v_mul_f32_e32 v112, v107, v113
	v_mov_b32_e32 v110, v112
	v_pk_mul_f32 v[108:109], v[110:111], v[108:109]
	s_nop 0
	v_cvt_pk_bf16_f32 v107, v108, v109
	global_store_dwordx4 v[120:121], v[104:107], off
	global_load_dwordx4 v[104:107], v[122:123], off offset:256
	s_nop 0
	global_load_dwordx4 v[108:111], v[120:121], off offset:256
	global_load_dwordx4 v[112:115], v[142:143], off offset:528
	global_load_dwordx4 v[116:119], v[142:143], off offset:512
	s_waitcnt vmcnt(0)
	v_pk_add_f32 v[116:117], v[100:101], v[116:117]
	v_pk_add_f32 v[100:101], v[98:99], v[114:115]
	v_pk_add_f32 v[98:99], v[96:97], v[112:113]
	v_mul_f32_e32 v96, 0xbfb8aa3b, v116
	v_mul_f32_e32 v97, 0xbfb8aa3b, v117
	v_exp_f32_e32 v96, v96
	v_exp_f32_e32 v97, v97
	v_lshlrev_b32_e32 v114, 16, v104
	v_and_b32_e32 v115, 0xffff0000, v104
	v_pk_add_f32 v[102:103], v[102:103], v[118:119]
	v_pk_add_f32 v[96:97], v[96:97], 1.0 op_sel_hi:[1,0]
	v_lshlrev_b32_e32 v116, 16, v108
	v_rcp_f32_e32 v113, v97
	v_and_b32_e32 v108, 0xffff0000, v108
	v_mul_f32_e32 v112, 0xbfb8aa3b, v116
	v_exp_f32_e32 v112, v112
	v_mul_f32_e32 v104, 1.0, v113
	v_mov_b32_e32 v97, v104
	v_rcp_f32_e32 v113, v96
	v_mul_f32_e32 v98, 0xbfb8aa3b, v98
	v_mul_f32_e32 v99, 0xbfb8aa3b, v99
	v_exp_f32_e32 v98, v98
	v_mul_f32_e32 v104, 1.0, v113
	v_mov_b32_e32 v96, v104
	v_mul_f32_e32 v104, 0xbfb8aa3b, v108
	v_exp_f32_e32 v113, v104
	v_pk_mul_f32 v[96:97], v[96:97], v[114:115]
	v_exp_f32_e32 v99, v99
	v_pk_add_f32 v[112:113], v[112:113], 1.0 op_sel_hi:[1,0]
	s_nop 0
	v_rcp_f32_e32 v114, v113
	v_pk_add_f32 v[98:99], v[98:99], 1.0 op_sel_hi:[1,0]
	v_mul_f32_e32 v104, v108, v114
	v_mov_b32_e32 v113, v104
	v_rcp_f32_e32 v108, v112
	s_nop 0
	v_mul_f32_e32 v104, v116, v108
	v_mov_b32_e32 v112, v104
	v_pk_mul_f32 v[96:97], v[112:113], v[96:97]
	v_and_b32_e32 v112, 0xffff0000, v109
	v_cvt_pk_bf16_f32 v96, v96, v97
	v_mul_f32_e32 v97, 0xbfb8aa3b, v102
	v_exp_f32_e32 v102, v97
	v_mul_f32_e32 v97, 0xbfb8aa3b, v103
	v_exp_f32_e32 v103, v97
	v_lshlrev_b32_e32 v97, 16, v109
	v_lshlrev_b32_e32 v108, 16, v105
	v_and_b32_e32 v109, 0xffff0000, v105
	v_pk_add_f32 v[102:103], v[102:103], 1.0 op_sel_hi:[1,0]
	v_mul_f32_e32 v104, 0xbfb8aa3b, v97
	v_rcp_f32_e32 v113, v103
	v_exp_f32_e32 v104, v104
	v_mul_f32_e32 v105, 1.0, v113
	v_mov_b32_e32 v103, v105
	v_rcp_f32_e32 v113, v102
	s_nop 0
	v_mul_f32_e32 v105, 1.0, v113
	v_mov_b32_e32 v102, v105
	v_mul_f32_e32 v105, 0xbfb8aa3b, v112
	v_exp_f32_e32 v105, v105
	v_pk_mul_f32 v[102:103], v[102:103], v[108:109]
	v_pk_add_f32 v[104:105], v[104:105], 1.0 op_sel_hi:[1,0]
	s_nop 0
	v_rcp_f32_e32 v109, v105
	s_nop 0
	v_mul_f32_e32 v108, v112, v109
	v_mov_b32_e32 v105, v108
	v_rcp_f32_e32 v109, v104
	s_nop 0
	v_mul_f32_e32 v108, v97, v109
	v_mov_b32_e32 v104, v108
	v_pk_mul_f32 v[102:103], v[104:105], v[102:103]
	v_lshlrev_b32_e32 v104, 16, v106
	v_cvt_pk_bf16_f32 v97, v102, v103
	v_and_b32_e32 v105, 0xffff0000, v106
	v_rcp_f32_e32 v106, v99
	v_lshlrev_b32_e32 v108, 16, v110
	v_and_b32_e32 v109, 0xffff0000, v110
	v_mul_f32_e32 v102, 0xbfb8aa3b, v108
	v_mul_f32_e32 v103, 1.0, v106
	v_mov_b32_e32 v99, v103
	v_rcp_f32_e32 v106, v98
	v_exp_f32_e32 v102, v102
	v_mul_f32_e32 v103, 1.0, v106
	v_mov_b32_e32 v98, v103
	v_mul_f32_e32 v103, 0xbfb8aa3b, v109
	v_exp_f32_e32 v103, v103
	v_pk_mul_f32 v[98:99], v[98:99], v[104:105]
	v_pk_add_f32 v[102:103], v[102:103], 1.0 op_sel_hi:[1,0]
	s_nop 0
	v_rcp_f32_e32 v105, v103
	s_nop 0
	v_mul_f32_e32 v104, v109, v105
	v_mov_b32_e32 v103, v104
	v_rcp_f32_e32 v105, v102
	s_nop 0
	v_mul_f32_e32 v104, v108, v105
	v_mov_b32_e32 v102, v104
	v_pk_mul_f32 v[98:99], v[102:103], v[98:99]
	v_lshlrev_b32_e32 v104, 16, v107
	v_cvt_pk_bf16_f32 v98, v98, v99
	v_mul_f32_e32 v99, 0xbfb8aa3b, v100
	v_exp_f32_e32 v100, v99
	v_mul_f32_e32 v99, 0xbfb8aa3b, v101
	v_exp_f32_e32 v101, v99
	v_and_b32_e32 v105, 0xffff0000, v107
	v_lshlrev_b32_e32 v99, 16, v111
	v_and_b32_e32 v106, 0xffff0000, v111
	v_pk_add_f32 v[100:101], v[100:101], 1.0 op_sel_hi:[1,0]
	v_mul_f32_e32 v102, 0xbfb8aa3b, v99
	v_rcp_f32_e32 v107, v101
	v_exp_f32_e32 v102, v102
	v_mul_f32_e32 v103, 1.0, v107
	v_mov_b32_e32 v101, v103
	v_rcp_f32_e32 v107, v100
	s_nop 0
	v_mul_f32_e32 v103, 1.0, v107
	v_mov_b32_e32 v100, v103
	v_mul_f32_e32 v103, 0xbfb8aa3b, v106
	v_exp_f32_e32 v103, v103
	v_pk_mul_f32 v[100:101], v[100:101], v[104:105]
	v_pk_add_f32 v[102:103], v[102:103], 1.0 op_sel_hi:[1,0]
	s_nop 0
	v_rcp_f32_e32 v105, v103
	s_nop 0
	v_mul_f32_e32 v104, v106, v105
	v_mov_b32_e32 v103, v104
	v_rcp_f32_e32 v105, v102
	s_nop 0
	v_mul_f32_e32 v104, v99, v105
	v_mov_b32_e32 v102, v104
	v_pk_mul_f32 v[100:101], v[102:103], v[100:101]
	s_nop 0
	v_cvt_pk_bf16_f32 v99, v100, v101
	global_store_dwordx4 v[120:121], v[96:99], off offset:256
	s_nop 1
	v_or_b32_e32 v96, 32, v154
	v_mad_i64_i32 v[96:97], s[0:1], v96, s14, v[144:145]
	v_lshl_add_u64 v[104:105], v[96:97], 0, v[146:147]
	v_add_co_u32_e32 v106, vcc, s15, v104
	s_nop 1
	v_addc_co_u32_e32 v107, vcc, 0, v105, vcc
	global_load_dwordx4 v[96:99], v[106:107], off
	global_load_dwordx4 v[100:103], v[104:105], off
	global_load_dwordx4 v[108:111], v[142:143], off offset:16
	global_load_dwordx4 v[112:115], v[142:143], off
	s_waitcnt vmcnt(1)
	v_pk_add_f32 v[110:111], v[90:91], v[110:111]
	s_waitcnt vmcnt(0)
	v_pk_add_f32 v[92:93], v[92:93], v[112:113]
	v_pk_add_f32 v[90:91], v[88:89], v[108:109]
	v_mul_f32_e32 v88, 0xbfb8aa3b, v92
	v_mul_f32_e32 v89, 0xbfb8aa3b, v93
	v_exp_f32_e32 v88, v88
	v_exp_f32_e32 v89, v89
	v_lshlrev_b32_e32 v108, 16, v96
	v_and_b32_e32 v109, 0xffff0000, v96
	v_pk_add_f32 v[94:95], v[94:95], v[114:115]
	v_pk_add_f32 v[88:89], v[88:89], 1.0 op_sel_hi:[1,0]
	v_lshlrev_b32_e32 v112, 16, v100
	v_rcp_f32_e32 v96, v89
	v_and_b32_e32 v100, 0xffff0000, v100
	v_mul_f32_e32 v92, 0xbfb8aa3b, v112
	v_exp_f32_e32 v92, v92
	v_mul_f32_e32 v93, 1.0, v96
	v_mov_b32_e32 v89, v93
	v_rcp_f32_e32 v96, v88
	v_mul_f32_e32 v90, 0xbfb8aa3b, v90
	v_mul_f32_e32 v91, 0xbfb8aa3b, v91
	v_exp_f32_e32 v90, v90
	v_mul_f32_e32 v93, 1.0, v96
	v_mov_b32_e32 v88, v93
	v_mul_f32_e32 v93, 0xbfb8aa3b, v100
	v_exp_f32_e32 v93, v93
	v_pk_mul_f32 v[88:89], v[88:89], v[108:109]
	v_exp_f32_e32 v91, v91
	v_pk_add_f32 v[92:93], v[92:93], 1.0 op_sel_hi:[1,0]
	s_nop 0
	v_rcp_f32_e32 v108, v93
	v_pk_add_f32 v[90:91], v[90:91], 1.0 op_sel_hi:[1,0]
	v_mul_f32_e32 v96, v100, v108
	v_mov_b32_e32 v93, v96
	v_rcp_f32_e32 v100, v92
	s_nop 0
	v_mul_f32_e32 v96, v112, v100
	v_mov_b32_e32 v92, v96
	v_pk_mul_f32 v[88:89], v[92:93], v[88:89]
	v_and_b32_e32 v100, 0xffff0000, v101
	v_cvt_pk_bf16_f32 v88, v88, v89
	v_mul_f32_e32 v89, 0xbfb8aa3b, v94
	v_exp_f32_e32 v92, v89
	v_mul_f32_e32 v89, 0xbfb8aa3b, v95
	v_exp_f32_e32 v93, v89
	v_lshlrev_b32_e32 v89, 16, v101
	v_mul_f32_e32 v94, 0xbfb8aa3b, v89
	v_exp_f32_e32 v94, v94
	v_pk_add_f32 v[92:93], v[92:93], 1.0 op_sel_hi:[1,0]
	v_lshlrev_b32_e32 v96, 16, v97
	v_rcp_f32_e32 v101, v93
	v_and_b32_e32 v97, 0xffff0000, v97
	v_mul_f32_e32 v95, 1.0, v101
	v_mov_b32_e32 v93, v95
	v_rcp_f32_e32 v101, v92
	s_nop 0
	v_mul_f32_e32 v95, 1.0, v101
	v_mov_b32_e32 v92, v95
	v_mul_f32_e32 v95, 0xbfb8aa3b, v100
	v_exp_f32_e32 v95, v95
	v_pk_mul_f32 v[92:93], v[92:93], v[96:97]
	v_pk_add_f32 v[94:95], v[94:95], 1.0 op_sel_hi:[1,0]
	s_nop 0
	v_rcp_f32_e32 v97, v95
	s_nop 0
	v_mul_f32_e32 v96, v100, v97
	v_mov_b32_e32 v95, v96
	v_rcp_f32_e32 v97, v94
	s_nop 0
	v_mul_f32_e32 v96, v89, v97
	v_mov_b32_e32 v94, v96
	v_pk_mul_f32 v[92:93], v[94:95], v[92:93]
	v_lshlrev_b32_e32 v94, 16, v98
	v_cvt_pk_bf16_f32 v89, v92, v93
	v_and_b32_e32 v95, 0xffff0000, v98
	v_rcp_f32_e32 v98, v91
	v_lshlrev_b32_e32 v96, 16, v102
	v_and_b32_e32 v97, 0xffff0000, v102
	v_mul_f32_e32 v92, 0xbfb8aa3b, v96
	v_mul_f32_e32 v93, 1.0, v98
	v_mov_b32_e32 v91, v93
	v_rcp_f32_e32 v98, v90
	v_exp_f32_e32 v92, v92
	v_mul_f32_e32 v93, 1.0, v98
	v_mov_b32_e32 v90, v93
	v_mul_f32_e32 v93, 0xbfb8aa3b, v97
	v_exp_f32_e32 v93, v93
	v_pk_mul_f32 v[90:91], v[90:91], v[94:95]
	v_pk_add_f32 v[92:93], v[92:93], 1.0 op_sel_hi:[1,0]
	s_nop 0
	v_rcp_f32_e32 v95, v93
	s_nop 0
	v_mul_f32_e32 v94, v97, v95
	v_mov_b32_e32 v93, v94
	v_rcp_f32_e32 v95, v92
	s_nop 0
	v_mul_f32_e32 v94, v96, v95
	v_mov_b32_e32 v92, v94
	v_pk_mul_f32 v[90:91], v[92:93], v[90:91]
	v_lshlrev_b32_e32 v96, 16, v99
	v_cvt_pk_bf16_f32 v90, v90, v91
	v_mul_f32_e32 v91, 0xbfb8aa3b, v110
	v_exp_f32_e32 v92, v91
	v_mul_f32_e32 v91, 0xbfb8aa3b, v111
	v_exp_f32_e32 v93, v91
	v_and_b32_e32 v97, 0xffff0000, v99
	v_lshlrev_b32_e32 v91, 16, v103
	v_and_b32_e32 v98, 0xffff0000, v103
	v_pk_add_f32 v[92:93], v[92:93], 1.0 op_sel_hi:[1,0]
	v_mul_f32_e32 v94, 0xbfb8aa3b, v91
	v_rcp_f32_e32 v99, v93
	v_exp_f32_e32 v94, v94
	v_mul_f32_e32 v95, 1.0, v99
	v_mov_b32_e32 v93, v95
	v_rcp_f32_e32 v99, v92
	s_nop 0
	v_mul_f32_e32 v95, 1.0, v99
	v_mov_b32_e32 v92, v95
	v_mul_f32_e32 v95, 0xbfb8aa3b, v98
	v_exp_f32_e32 v95, v95
	v_pk_mul_f32 v[92:93], v[92:93], v[96:97]
	v_pk_add_f32 v[94:95], v[94:95], 1.0 op_sel_hi:[1,0]
	s_nop 0
	v_rcp_f32_e32 v97, v95
	s_nop 0
	v_mul_f32_e32 v96, v98, v97
	v_mov_b32_e32 v95, v96
	v_rcp_f32_e32 v97, v94
	s_nop 0
	v_mul_f32_e32 v96, v91, v97
	v_mov_b32_e32 v94, v96
	v_pk_mul_f32 v[92:93], v[94:95], v[92:93]
	s_nop 0
	v_cvt_pk_bf16_f32 v91, v92, v93
	global_store_dwordx4 v[104:105], v[88:91], off
	global_load_dwordx4 v[88:91], v[106:107], off offset:256
	s_nop 0
	global_load_dwordx4 v[92:95], v[104:105], off offset:256
	global_load_dwordx4 v[96:99], v[142:143], off offset:528
	global_load_dwordx4 v[100:103], v[142:143], off offset:512
	s_waitcnt vmcnt(0)
	v_pk_add_f32 v[100:101], v[84:85], v[100:101]
	v_pk_add_f32 v[84:85], v[82:83], v[98:99]
	v_pk_add_f32 v[82:83], v[80:81], v[96:97]
	v_mul_f32_e32 v80, 0xbfb8aa3b, v100
	v_mul_f32_e32 v81, 0xbfb8aa3b, v101
	v_exp_f32_e32 v80, v80
	v_exp_f32_e32 v81, v81
	v_lshlrev_b32_e32 v98, 16, v88
	v_and_b32_e32 v99, 0xffff0000, v88
	v_pk_add_f32 v[86:87], v[86:87], v[102:103]
	v_pk_add_f32 v[80:81], v[80:81], 1.0 op_sel_hi:[1,0]
	v_lshlrev_b32_e32 v100, 16, v92
	v_rcp_f32_e32 v97, v81
	v_and_b32_e32 v92, 0xffff0000, v92
	v_mul_f32_e32 v96, 0xbfb8aa3b, v100
	v_exp_f32_e32 v96, v96
	v_mul_f32_e32 v88, 1.0, v97
	v_mov_b32_e32 v81, v88
	v_rcp_f32_e32 v97, v80
	v_mul_f32_e32 v82, 0xbfb8aa3b, v82
	v_mul_f32_e32 v83, 0xbfb8aa3b, v83
	v_exp_f32_e32 v82, v82
	v_mul_f32_e32 v88, 1.0, v97
	v_mov_b32_e32 v80, v88
	v_mul_f32_e32 v88, 0xbfb8aa3b, v92
	v_exp_f32_e32 v97, v88
	v_pk_mul_f32 v[80:81], v[80:81], v[98:99]
	v_exp_f32_e32 v83, v83
	v_pk_add_f32 v[96:97], v[96:97], 1.0 op_sel_hi:[1,0]
	s_nop 0
	v_rcp_f32_e32 v98, v97
	v_pk_add_f32 v[82:83], v[82:83], 1.0 op_sel_hi:[1,0]
	v_mul_f32_e32 v88, v92, v98
	v_mov_b32_e32 v97, v88
	v_rcp_f32_e32 v92, v96
	s_nop 0
	v_mul_f32_e32 v88, v100, v92
	v_mov_b32_e32 v96, v88
	v_pk_mul_f32 v[80:81], v[96:97], v[80:81]
	v_and_b32_e32 v96, 0xffff0000, v93
	v_cvt_pk_bf16_f32 v80, v80, v81
	v_mul_f32_e32 v81, 0xbfb8aa3b, v86
	v_exp_f32_e32 v86, v81
	v_mul_f32_e32 v81, 0xbfb8aa3b, v87
	v_exp_f32_e32 v87, v81
	v_lshlrev_b32_e32 v81, 16, v93
	v_lshlrev_b32_e32 v92, 16, v89
	v_and_b32_e32 v93, 0xffff0000, v89
	v_pk_add_f32 v[86:87], v[86:87], 1.0 op_sel_hi:[1,0]
	v_mul_f32_e32 v88, 0xbfb8aa3b, v81
	v_rcp_f32_e32 v97, v87
	v_exp_f32_e32 v88, v88
	v_mul_f32_e32 v89, 1.0, v97
	v_mov_b32_e32 v87, v89
	v_rcp_f32_e32 v97, v86
	s_nop 0
	v_mul_f32_e32 v89, 1.0, v97
	v_mov_b32_e32 v86, v89
	v_mul_f32_e32 v89, 0xbfb8aa3b, v96
	v_exp_f32_e32 v89, v89
	v_pk_mul_f32 v[86:87], v[86:87], v[92:93]
	v_pk_add_f32 v[88:89], v[88:89], 1.0 op_sel_hi:[1,0]
	s_nop 0
	v_rcp_f32_e32 v93, v89
	s_nop 0
	v_mul_f32_e32 v92, v96, v93
	v_mov_b32_e32 v89, v92
	v_rcp_f32_e32 v93, v88
	s_nop 0
	v_mul_f32_e32 v92, v81, v93
	v_mov_b32_e32 v88, v92
	v_pk_mul_f32 v[86:87], v[88:89], v[86:87]
	v_lshlrev_b32_e32 v88, 16, v90
	v_cvt_pk_bf16_f32 v81, v86, v87
	v_and_b32_e32 v89, 0xffff0000, v90
	v_rcp_f32_e32 v90, v83
	v_lshlrev_b32_e32 v92, 16, v94
	v_and_b32_e32 v93, 0xffff0000, v94
	v_mul_f32_e32 v86, 0xbfb8aa3b, v92
	v_mul_f32_e32 v87, 1.0, v90
	v_mov_b32_e32 v83, v87
	v_rcp_f32_e32 v90, v82
	v_exp_f32_e32 v86, v86
	v_mul_f32_e32 v87, 1.0, v90
	v_mov_b32_e32 v82, v87
	v_mul_f32_e32 v87, 0xbfb8aa3b, v93
	v_exp_f32_e32 v87, v87
	v_pk_mul_f32 v[82:83], v[82:83], v[88:89]
	v_pk_add_f32 v[86:87], v[86:87], 1.0 op_sel_hi:[1,0]
	s_nop 0
	v_rcp_f32_e32 v89, v87
	s_nop 0
	v_mul_f32_e32 v88, v93, v89
	v_mov_b32_e32 v87, v88
	v_rcp_f32_e32 v89, v86
	s_nop 0
	v_mul_f32_e32 v88, v92, v89
	v_mov_b32_e32 v86, v88
	v_pk_mul_f32 v[82:83], v[86:87], v[82:83]
	v_lshlrev_b32_e32 v88, 16, v91
	v_cvt_pk_bf16_f32 v82, v82, v83
	v_mul_f32_e32 v83, 0xbfb8aa3b, v84
	v_exp_f32_e32 v84, v83
	v_mul_f32_e32 v83, 0xbfb8aa3b, v85
	v_exp_f32_e32 v85, v83
	v_and_b32_e32 v89, 0xffff0000, v91
	v_lshlrev_b32_e32 v83, 16, v95
	v_and_b32_e32 v90, 0xffff0000, v95
	v_pk_add_f32 v[84:85], v[84:85], 1.0 op_sel_hi:[1,0]
	v_mul_f32_e32 v86, 0xbfb8aa3b, v83
	v_rcp_f32_e32 v91, v85
	v_exp_f32_e32 v86, v86
	v_mul_f32_e32 v87, 1.0, v91
	v_mov_b32_e32 v85, v87
	v_rcp_f32_e32 v91, v84
	s_nop 0
	v_mul_f32_e32 v87, 1.0, v91
	v_mov_b32_e32 v84, v87
	v_mul_f32_e32 v87, 0xbfb8aa3b, v90
	v_exp_f32_e32 v87, v87
	v_pk_mul_f32 v[84:85], v[84:85], v[88:89]
	v_pk_add_f32 v[86:87], v[86:87], 1.0 op_sel_hi:[1,0]
	s_nop 0
	v_rcp_f32_e32 v89, v87
	s_nop 0
	v_mul_f32_e32 v88, v90, v89
	v_mov_b32_e32 v87, v88
	v_rcp_f32_e32 v89, v86
	s_nop 0
	v_mul_f32_e32 v88, v83, v89
	v_mov_b32_e32 v86, v88
	v_pk_mul_f32 v[84:85], v[86:87], v[84:85]
	s_nop 0
	v_cvt_pk_bf16_f32 v83, v84, v85
	global_store_dwordx4 v[104:105], v[80:83], off offset:256
	s_nop 1
	v_or_b32_e32 v80, 48, v154
	v_mad_i64_i32 v[80:81], s[0:1], v80, s14, v[144:145]
	v_lshl_add_u64 v[88:89], v[80:81], 0, v[146:147]
	v_add_co_u32_e32 v90, vcc, s15, v88
	s_nop 1
	v_addc_co_u32_e32 v91, vcc, 0, v89, vcc
	global_load_dwordx4 v[80:83], v[90:91], off
	global_load_dwordx4 v[84:87], v[88:89], off
	global_load_dwordx4 v[92:95], v[142:143], off offset:16
	global_load_dwordx4 v[96:99], v[142:143], off
	s_waitcnt vmcnt(1)
	v_pk_add_f32 v[94:95], v[74:75], v[94:95]
	s_waitcnt vmcnt(0)
	v_pk_add_f32 v[76:77], v[76:77], v[96:97]
	v_pk_add_f32 v[74:75], v[72:73], v[92:93]
	v_mul_f32_e32 v72, 0xbfb8aa3b, v76
	v_mul_f32_e32 v73, 0xbfb8aa3b, v77
	v_exp_f32_e32 v72, v72
	v_exp_f32_e32 v73, v73
	v_lshlrev_b32_e32 v92, 16, v80
	v_and_b32_e32 v93, 0xffff0000, v80
	v_pk_add_f32 v[78:79], v[78:79], v[98:99]
	v_pk_add_f32 v[72:73], v[72:73], 1.0 op_sel_hi:[1,0]
	v_lshlrev_b32_e32 v96, 16, v84
	v_rcp_f32_e32 v80, v73
	v_and_b32_e32 v84, 0xffff0000, v84
	v_mul_f32_e32 v76, 0xbfb8aa3b, v96
	v_exp_f32_e32 v76, v76
	v_mul_f32_e32 v77, 1.0, v80
	v_mov_b32_e32 v73, v77
	v_rcp_f32_e32 v80, v72
	v_mul_f32_e32 v74, 0xbfb8aa3b, v74
	v_mul_f32_e32 v75, 0xbfb8aa3b, v75
	v_exp_f32_e32 v74, v74
	v_mul_f32_e32 v77, 1.0, v80
	v_mov_b32_e32 v72, v77
	v_mul_f32_e32 v77, 0xbfb8aa3b, v84
	v_exp_f32_e32 v77, v77
	v_pk_mul_f32 v[72:73], v[72:73], v[92:93]
	v_exp_f32_e32 v75, v75
	v_pk_add_f32 v[76:77], v[76:77], 1.0 op_sel_hi:[1,0]
	s_nop 0
	v_rcp_f32_e32 v92, v77
	v_pk_add_f32 v[74:75], v[74:75], 1.0 op_sel_hi:[1,0]
	v_mul_f32_e32 v80, v84, v92
	v_mov_b32_e32 v77, v80
	v_rcp_f32_e32 v84, v76
	s_nop 0
	v_mul_f32_e32 v80, v96, v84
	v_mov_b32_e32 v76, v80
	v_pk_mul_f32 v[72:73], v[76:77], v[72:73]
	v_and_b32_e32 v84, 0xffff0000, v85
	v_cvt_pk_bf16_f32 v72, v72, v73
	v_mul_f32_e32 v73, 0xbfb8aa3b, v78
	v_exp_f32_e32 v76, v73
	v_mul_f32_e32 v73, 0xbfb8aa3b, v79
	v_exp_f32_e32 v77, v73
	v_lshlrev_b32_e32 v73, 16, v85
	v_mul_f32_e32 v78, 0xbfb8aa3b, v73
	v_exp_f32_e32 v78, v78
	v_pk_add_f32 v[76:77], v[76:77], 1.0 op_sel_hi:[1,0]
	v_lshlrev_b32_e32 v80, 16, v81
	v_rcp_f32_e32 v85, v77
	v_and_b32_e32 v81, 0xffff0000, v81
	v_mul_f32_e32 v79, 1.0, v85
	v_mov_b32_e32 v77, v79
	v_rcp_f32_e32 v85, v76
	s_nop 0
	v_mul_f32_e32 v79, 1.0, v85
	v_mov_b32_e32 v76, v79
	v_mul_f32_e32 v79, 0xbfb8aa3b, v84
	v_exp_f32_e32 v79, v79
	v_pk_mul_f32 v[76:77], v[76:77], v[80:81]
	v_pk_add_f32 v[78:79], v[78:79], 1.0 op_sel_hi:[1,0]
	s_nop 0
	v_rcp_f32_e32 v81, v79
	s_nop 0
	v_mul_f32_e32 v80, v84, v81
	v_mov_b32_e32 v79, v80
	v_rcp_f32_e32 v81, v78
	s_nop 0
	v_mul_f32_e32 v80, v73, v81
	v_mov_b32_e32 v78, v80
	v_pk_mul_f32 v[76:77], v[78:79], v[76:77]
	v_lshlrev_b32_e32 v78, 16, v82
	v_cvt_pk_bf16_f32 v73, v76, v77
	v_and_b32_e32 v79, 0xffff0000, v82
	v_rcp_f32_e32 v82, v75
	v_lshlrev_b32_e32 v80, 16, v86
	v_and_b32_e32 v81, 0xffff0000, v86
	v_mul_f32_e32 v76, 0xbfb8aa3b, v80
	v_mul_f32_e32 v77, 1.0, v82
	v_mov_b32_e32 v75, v77
	v_rcp_f32_e32 v82, v74
	v_exp_f32_e32 v76, v76
	v_mul_f32_e32 v77, 1.0, v82
	v_mov_b32_e32 v74, v77
	v_mul_f32_e32 v77, 0xbfb8aa3b, v81
	v_exp_f32_e32 v77, v77
	v_pk_mul_f32 v[74:75], v[74:75], v[78:79]
	v_pk_add_f32 v[76:77], v[76:77], 1.0 op_sel_hi:[1,0]
	s_nop 0
	v_rcp_f32_e32 v79, v77
	s_nop 0
	v_mul_f32_e32 v78, v81, v79
	v_mov_b32_e32 v77, v78
	v_rcp_f32_e32 v79, v76
	s_nop 0
	v_mul_f32_e32 v78, v80, v79
	v_mov_b32_e32 v76, v78
	v_pk_mul_f32 v[74:75], v[76:77], v[74:75]
	v_lshlrev_b32_e32 v80, 16, v83
	v_cvt_pk_bf16_f32 v74, v74, v75
	v_mul_f32_e32 v75, 0xbfb8aa3b, v94
	v_exp_f32_e32 v76, v75
	v_mul_f32_e32 v75, 0xbfb8aa3b, v95
	v_exp_f32_e32 v77, v75
	v_and_b32_e32 v81, 0xffff0000, v83
	v_lshlrev_b32_e32 v75, 16, v87
	v_and_b32_e32 v82, 0xffff0000, v87
	v_pk_add_f32 v[76:77], v[76:77], 1.0 op_sel_hi:[1,0]
	v_mul_f32_e32 v78, 0xbfb8aa3b, v75
	v_rcp_f32_e32 v83, v77
	v_exp_f32_e32 v78, v78
	v_mul_f32_e32 v79, 1.0, v83
	v_mov_b32_e32 v77, v79
	v_rcp_f32_e32 v83, v76
	s_nop 0
	v_mul_f32_e32 v79, 1.0, v83
	v_mov_b32_e32 v76, v79
	v_mul_f32_e32 v79, 0xbfb8aa3b, v82
	v_exp_f32_e32 v79, v79
	v_pk_mul_f32 v[76:77], v[76:77], v[80:81]
	v_pk_add_f32 v[78:79], v[78:79], 1.0 op_sel_hi:[1,0]
	s_nop 0
	v_rcp_f32_e32 v81, v79
	s_nop 0
	v_mul_f32_e32 v80, v82, v81
	v_mov_b32_e32 v79, v80
	v_rcp_f32_e32 v81, v78
	s_nop 0
	v_mul_f32_e32 v80, v75, v81
	v_mov_b32_e32 v78, v80
	v_pk_mul_f32 v[76:77], v[78:79], v[76:77]
	s_nop 0
	v_cvt_pk_bf16_f32 v75, v76, v77
	global_store_dwordx4 v[88:89], v[72:75], off
	global_load_dwordx4 v[72:75], v[90:91], off offset:256
	s_nop 0
	global_load_dwordx4 v[76:79], v[88:89], off offset:256
	global_load_dwordx4 v[80:83], v[142:143], off offset:528
	global_load_dwordx4 v[84:87], v[142:143], off offset:512
	s_waitcnt vmcnt(0)
	v_pk_add_f32 v[84:85], v[68:69], v[84:85]
	v_pk_add_f32 v[68:69], v[66:67], v[82:83]
	v_pk_add_f32 v[66:67], v[64:65], v[80:81]
	v_mul_f32_e32 v64, 0xbfb8aa3b, v84
	v_mul_f32_e32 v65, 0xbfb8aa3b, v85
	v_exp_f32_e32 v64, v64
	v_exp_f32_e32 v65, v65
	v_lshlrev_b32_e32 v82, 16, v72
	v_and_b32_e32 v83, 0xffff0000, v72
	v_pk_add_f32 v[70:71], v[70:71], v[86:87]
	v_pk_add_f32 v[64:65], v[64:65], 1.0 op_sel_hi:[1,0]
	v_lshlrev_b32_e32 v84, 16, v76
	v_rcp_f32_e32 v81, v65
	v_and_b32_e32 v76, 0xffff0000, v76
	v_mul_f32_e32 v80, 0xbfb8aa3b, v84
	v_exp_f32_e32 v80, v80
	v_mul_f32_e32 v72, 1.0, v81
	v_mov_b32_e32 v65, v72
	v_rcp_f32_e32 v81, v64
	v_mul_f32_e32 v66, 0xbfb8aa3b, v66
	v_mul_f32_e32 v67, 0xbfb8aa3b, v67
	v_exp_f32_e32 v66, v66
	v_mul_f32_e32 v72, 1.0, v81
	v_mov_b32_e32 v64, v72
	v_mul_f32_e32 v72, 0xbfb8aa3b, v76
	v_exp_f32_e32 v81, v72
	v_pk_mul_f32 v[64:65], v[64:65], v[82:83]
	v_exp_f32_e32 v67, v67
	v_pk_add_f32 v[80:81], v[80:81], 1.0 op_sel_hi:[1,0]
	s_nop 0
	v_rcp_f32_e32 v82, v81
	v_pk_add_f32 v[66:67], v[66:67], 1.0 op_sel_hi:[1,0]
	v_mul_f32_e32 v72, v76, v82
	v_mov_b32_e32 v81, v72
	v_rcp_f32_e32 v76, v80
	s_nop 0
	v_mul_f32_e32 v72, v84, v76
	v_mov_b32_e32 v80, v72
	v_pk_mul_f32 v[64:65], v[80:81], v[64:65]
	v_and_b32_e32 v80, 0xffff0000, v77
	v_cvt_pk_bf16_f32 v64, v64, v65
	v_mul_f32_e32 v65, 0xbfb8aa3b, v70
	v_exp_f32_e32 v70, v65
	v_mul_f32_e32 v65, 0xbfb8aa3b, v71
	v_exp_f32_e32 v71, v65
	v_lshlrev_b32_e32 v65, 16, v77
	v_lshlrev_b32_e32 v76, 16, v73
	v_and_b32_e32 v77, 0xffff0000, v73
	v_pk_add_f32 v[70:71], v[70:71], 1.0 op_sel_hi:[1,0]
	v_mul_f32_e32 v72, 0xbfb8aa3b, v65
	v_rcp_f32_e32 v81, v71
	v_exp_f32_e32 v72, v72
	v_mul_f32_e32 v73, 1.0, v81
	v_mov_b32_e32 v71, v73
	v_rcp_f32_e32 v81, v70
	s_nop 0
	v_mul_f32_e32 v73, 1.0, v81
	v_mov_b32_e32 v70, v73
	v_mul_f32_e32 v73, 0xbfb8aa3b, v80
	v_exp_f32_e32 v73, v73
	v_pk_mul_f32 v[70:71], v[70:71], v[76:77]
	v_pk_add_f32 v[72:73], v[72:73], 1.0 op_sel_hi:[1,0]
	s_nop 0
	v_rcp_f32_e32 v77, v73
	s_nop 0
	v_mul_f32_e32 v76, v80, v77
	v_mov_b32_e32 v73, v76
	v_rcp_f32_e32 v77, v72
	s_nop 0
	v_mul_f32_e32 v76, v65, v77
	v_mov_b32_e32 v72, v76
	v_pk_mul_f32 v[70:71], v[72:73], v[70:71]
	v_lshlrev_b32_e32 v72, 16, v74
	v_cvt_pk_bf16_f32 v65, v70, v71
	v_and_b32_e32 v73, 0xffff0000, v74
	v_rcp_f32_e32 v74, v67
	v_lshlrev_b32_e32 v76, 16, v78
	v_and_b32_e32 v77, 0xffff0000, v78
	v_mul_f32_e32 v70, 0xbfb8aa3b, v76
	v_mul_f32_e32 v71, 1.0, v74
	v_mov_b32_e32 v67, v71
	v_rcp_f32_e32 v74, v66
	v_exp_f32_e32 v70, v70
	v_mul_f32_e32 v71, 1.0, v74
	v_mov_b32_e32 v66, v71
	v_mul_f32_e32 v71, 0xbfb8aa3b, v77
	v_exp_f32_e32 v71, v71
	v_pk_mul_f32 v[66:67], v[66:67], v[72:73]
	v_pk_add_f32 v[70:71], v[70:71], 1.0 op_sel_hi:[1,0]
	s_nop 0
	v_rcp_f32_e32 v73, v71
	s_nop 0
	v_mul_f32_e32 v72, v77, v73
	v_mov_b32_e32 v71, v72
	v_rcp_f32_e32 v73, v70
	s_nop 0
	v_mul_f32_e32 v72, v76, v73
	v_mov_b32_e32 v70, v72
	v_pk_mul_f32 v[66:67], v[70:71], v[66:67]
	v_lshlrev_b32_e32 v72, 16, v75
	v_cvt_pk_bf16_f32 v66, v66, v67
	v_mul_f32_e32 v67, 0xbfb8aa3b, v68
	v_exp_f32_e32 v68, v67
	v_mul_f32_e32 v67, 0xbfb8aa3b, v69
	v_exp_f32_e32 v69, v67
	v_and_b32_e32 v73, 0xffff0000, v75
	v_lshlrev_b32_e32 v67, 16, v79
	v_and_b32_e32 v74, 0xffff0000, v79
	v_pk_add_f32 v[68:69], v[68:69], 1.0 op_sel_hi:[1,0]
	v_mul_f32_e32 v70, 0xbfb8aa3b, v67
	v_rcp_f32_e32 v75, v69
	v_exp_f32_e32 v70, v70
	v_mul_f32_e32 v71, 1.0, v75
	v_mov_b32_e32 v69, v71
	v_rcp_f32_e32 v75, v68
	s_nop 0
	v_mul_f32_e32 v71, 1.0, v75
	v_mov_b32_e32 v68, v71
	v_mul_f32_e32 v71, 0xbfb8aa3b, v74
	v_exp_f32_e32 v71, v71
	v_pk_mul_f32 v[68:69], v[68:69], v[72:73]
	v_pk_add_f32 v[70:71], v[70:71], 1.0 op_sel_hi:[1,0]
	s_nop 0
	v_rcp_f32_e32 v73, v71
	s_nop 0
	v_mul_f32_e32 v72, v74, v73
	v_mov_b32_e32 v71, v72
	v_rcp_f32_e32 v73, v70
	s_nop 0
	v_mul_f32_e32 v72, v67, v73
	v_mov_b32_e32 v70, v72
	v_pk_mul_f32 v[68:69], v[70:71], v[68:69]
	s_nop 0
	v_cvt_pk_bf16_f32 v67, v68, v69
	global_store_dwordx4 v[88:89], v[64:67], off offset:256
	s_nop 1
	v_add_u32_e32 v64, 0x80, v154
	v_mad_i64_i32 v[64:65], s[0:1], v64, s14, v[144:145]
	v_lshl_add_u64 v[72:73], v[64:65], 0, v[146:147]
	v_add_co_u32_e32 v74, vcc, s15, v72
	s_nop 1
	v_addc_co_u32_e32 v75, vcc, 0, v73, vcc
	global_load_dwordx4 v[64:67], v[74:75], off
	global_load_dwordx4 v[68:71], v[72:73], off
	global_load_dwordx4 v[76:79], v[142:143], off offset:16
	global_load_dwordx4 v[80:83], v[142:143], off
	s_waitcnt vmcnt(1)
	v_pk_add_f32 v[78:79], v[58:59], v[78:79]
	s_waitcnt vmcnt(0)
	v_pk_add_f32 v[60:61], v[60:61], v[80:81]
	v_pk_add_f32 v[58:59], v[56:57], v[76:77]
	v_mul_f32_e32 v56, 0xbfb8aa3b, v60
	v_mul_f32_e32 v57, 0xbfb8aa3b, v61
	v_exp_f32_e32 v56, v56
	v_exp_f32_e32 v57, v57
	v_lshlrev_b32_e32 v76, 16, v64
	v_and_b32_e32 v77, 0xffff0000, v64
	v_pk_add_f32 v[62:63], v[62:63], v[82:83]
	v_pk_add_f32 v[56:57], v[56:57], 1.0 op_sel_hi:[1,0]
	v_lshlrev_b32_e32 v80, 16, v68
	v_rcp_f32_e32 v64, v57
	v_and_b32_e32 v68, 0xffff0000, v68
	v_mul_f32_e32 v60, 0xbfb8aa3b, v80
	v_exp_f32_e32 v60, v60
	v_mul_f32_e32 v61, 1.0, v64
	v_mov_b32_e32 v57, v61
	v_rcp_f32_e32 v64, v56
	v_mul_f32_e32 v58, 0xbfb8aa3b, v58
	v_mul_f32_e32 v59, 0xbfb8aa3b, v59
	v_exp_f32_e32 v58, v58
	v_mul_f32_e32 v61, 1.0, v64
	v_mov_b32_e32 v56, v61
	v_mul_f32_e32 v61, 0xbfb8aa3b, v68
	v_exp_f32_e32 v61, v61
	v_pk_mul_f32 v[56:57], v[56:57], v[76:77]
	v_exp_f32_e32 v59, v59
	v_pk_add_f32 v[60:61], v[60:61], 1.0 op_sel_hi:[1,0]
	s_nop 0
	v_rcp_f32_e32 v76, v61
	v_pk_add_f32 v[58:59], v[58:59], 1.0 op_sel_hi:[1,0]
	v_mul_f32_e32 v64, v68, v76
	v_mov_b32_e32 v61, v64
	v_rcp_f32_e32 v68, v60
	s_nop 0
	v_mul_f32_e32 v64, v80, v68
	v_mov_b32_e32 v60, v64
	v_pk_mul_f32 v[56:57], v[60:61], v[56:57]
	v_and_b32_e32 v68, 0xffff0000, v69
	v_cvt_pk_bf16_f32 v56, v56, v57
	v_mul_f32_e32 v57, 0xbfb8aa3b, v62
	v_exp_f32_e32 v60, v57
	v_mul_f32_e32 v57, 0xbfb8aa3b, v63
	v_exp_f32_e32 v61, v57
	v_lshlrev_b32_e32 v57, 16, v69
	v_mul_f32_e32 v62, 0xbfb8aa3b, v57
	v_exp_f32_e32 v62, v62
	v_pk_add_f32 v[60:61], v[60:61], 1.0 op_sel_hi:[1,0]
	v_lshlrev_b32_e32 v64, 16, v65
	v_rcp_f32_e32 v69, v61
	v_and_b32_e32 v65, 0xffff0000, v65
	v_mul_f32_e32 v63, 1.0, v69
	v_mov_b32_e32 v61, v63
	v_rcp_f32_e32 v69, v60
	s_nop 0
	v_mul_f32_e32 v63, 1.0, v69
	v_mov_b32_e32 v60, v63
	v_mul_f32_e32 v63, 0xbfb8aa3b, v68
	v_exp_f32_e32 v63, v63
	v_pk_mul_f32 v[60:61], v[60:61], v[64:65]
	v_pk_add_f32 v[62:63], v[62:63], 1.0 op_sel_hi:[1,0]
	s_nop 0
	v_rcp_f32_e32 v65, v63
	s_nop 0
	v_mul_f32_e32 v64, v68, v65
	v_mov_b32_e32 v63, v64
	v_rcp_f32_e32 v65, v62
	s_nop 0
	v_mul_f32_e32 v64, v57, v65
	v_mov_b32_e32 v62, v64
	v_pk_mul_f32 v[60:61], v[62:63], v[60:61]
	v_lshlrev_b32_e32 v62, 16, v66
	v_cvt_pk_bf16_f32 v57, v60, v61
	v_and_b32_e32 v63, 0xffff0000, v66
	v_rcp_f32_e32 v66, v59
	v_lshlrev_b32_e32 v64, 16, v70
	v_and_b32_e32 v65, 0xffff0000, v70
	v_mul_f32_e32 v60, 0xbfb8aa3b, v64
	v_mul_f32_e32 v61, 1.0, v66
	v_mov_b32_e32 v59, v61
	v_rcp_f32_e32 v66, v58
	v_exp_f32_e32 v60, v60
	v_mul_f32_e32 v61, 1.0, v66
	v_mov_b32_e32 v58, v61
	v_mul_f32_e32 v61, 0xbfb8aa3b, v65
	v_exp_f32_e32 v61, v61
	v_pk_mul_f32 v[58:59], v[58:59], v[62:63]
	v_pk_add_f32 v[60:61], v[60:61], 1.0 op_sel_hi:[1,0]
	s_nop 0
	v_rcp_f32_e32 v63, v61
	s_nop 0
	v_mul_f32_e32 v62, v65, v63
	v_mov_b32_e32 v61, v62
	v_rcp_f32_e32 v63, v60
	s_nop 0
	v_mul_f32_e32 v62, v64, v63
	v_mov_b32_e32 v60, v62
	v_pk_mul_f32 v[58:59], v[60:61], v[58:59]
	v_lshlrev_b32_e32 v64, 16, v67
	v_cvt_pk_bf16_f32 v58, v58, v59
	v_mul_f32_e32 v59, 0xbfb8aa3b, v78
	v_exp_f32_e32 v60, v59
	v_mul_f32_e32 v59, 0xbfb8aa3b, v79
	v_exp_f32_e32 v61, v59
	v_and_b32_e32 v65, 0xffff0000, v67
	v_lshlrev_b32_e32 v59, 16, v71
	v_and_b32_e32 v66, 0xffff0000, v71
	v_pk_add_f32 v[60:61], v[60:61], 1.0 op_sel_hi:[1,0]
	v_mul_f32_e32 v62, 0xbfb8aa3b, v59
	v_rcp_f32_e32 v67, v61
	v_exp_f32_e32 v62, v62
	v_mul_f32_e32 v63, 1.0, v67
	v_mov_b32_e32 v61, v63
	v_rcp_f32_e32 v67, v60
	s_nop 0
	v_mul_f32_e32 v63, 1.0, v67
	v_mov_b32_e32 v60, v63
	v_mul_f32_e32 v63, 0xbfb8aa3b, v66
	v_exp_f32_e32 v63, v63
	v_pk_mul_f32 v[60:61], v[60:61], v[64:65]
	v_pk_add_f32 v[62:63], v[62:63], 1.0 op_sel_hi:[1,0]
	s_nop 0
	v_rcp_f32_e32 v65, v63
	s_nop 0
	v_mul_f32_e32 v64, v66, v65
	v_mov_b32_e32 v63, v64
	v_rcp_f32_e32 v65, v62
	s_nop 0
	v_mul_f32_e32 v64, v59, v65
	v_mov_b32_e32 v62, v64
	v_pk_mul_f32 v[60:61], v[62:63], v[60:61]
	s_nop 0
	v_cvt_pk_bf16_f32 v59, v60, v61
	global_store_dwordx4 v[72:73], v[56:59], off
	global_load_dwordx4 v[56:59], v[74:75], off offset:256
	s_nop 0
	global_load_dwordx4 v[60:63], v[72:73], off offset:256
	global_load_dwordx4 v[64:67], v[142:143], off offset:528
	global_load_dwordx4 v[68:71], v[142:143], off offset:512
	s_waitcnt vmcnt(0)
	v_pk_add_f32 v[68:69], v[52:53], v[68:69]
	v_pk_add_f32 v[52:53], v[50:51], v[66:67]
	v_pk_add_f32 v[50:51], v[48:49], v[64:65]
	v_mul_f32_e32 v48, 0xbfb8aa3b, v68
	v_mul_f32_e32 v49, 0xbfb8aa3b, v69
	v_exp_f32_e32 v48, v48
	v_exp_f32_e32 v49, v49
	v_lshlrev_b32_e32 v66, 16, v56
	v_and_b32_e32 v67, 0xffff0000, v56
	v_pk_add_f32 v[54:55], v[54:55], v[70:71]
	v_pk_add_f32 v[48:49], v[48:49], 1.0 op_sel_hi:[1,0]
	v_lshlrev_b32_e32 v68, 16, v60
	v_rcp_f32_e32 v65, v49
	v_and_b32_e32 v60, 0xffff0000, v60
	v_mul_f32_e32 v64, 0xbfb8aa3b, v68
	v_exp_f32_e32 v64, v64
	v_mul_f32_e32 v56, 1.0, v65
	v_mov_b32_e32 v49, v56
	v_rcp_f32_e32 v65, v48
	v_mul_f32_e32 v50, 0xbfb8aa3b, v50
	v_mul_f32_e32 v51, 0xbfb8aa3b, v51
	v_exp_f32_e32 v50, v50
	v_mul_f32_e32 v56, 1.0, v65
	v_mov_b32_e32 v48, v56
	v_mul_f32_e32 v56, 0xbfb8aa3b, v60
	v_exp_f32_e32 v65, v56
	v_pk_mul_f32 v[48:49], v[48:49], v[66:67]
	v_exp_f32_e32 v51, v51
	v_pk_add_f32 v[64:65], v[64:65], 1.0 op_sel_hi:[1,0]
	s_nop 0
	v_rcp_f32_e32 v66, v65
	v_pk_add_f32 v[50:51], v[50:51], 1.0 op_sel_hi:[1,0]
	v_mul_f32_e32 v56, v60, v66
	v_mov_b32_e32 v65, v56
	v_rcp_f32_e32 v60, v64
	s_nop 0
	v_mul_f32_e32 v56, v68, v60
	v_mov_b32_e32 v64, v56
	v_pk_mul_f32 v[48:49], v[64:65], v[48:49]
	v_and_b32_e32 v64, 0xffff0000, v61
	v_cvt_pk_bf16_f32 v48, v48, v49
	v_mul_f32_e32 v49, 0xbfb8aa3b, v54
	v_exp_f32_e32 v54, v49
	v_mul_f32_e32 v49, 0xbfb8aa3b, v55
	v_exp_f32_e32 v55, v49
	v_lshlrev_b32_e32 v49, 16, v61
	v_lshlrev_b32_e32 v60, 16, v57
	v_and_b32_e32 v61, 0xffff0000, v57
	v_pk_add_f32 v[54:55], v[54:55], 1.0 op_sel_hi:[1,0]
	v_mul_f32_e32 v56, 0xbfb8aa3b, v49
	v_rcp_f32_e32 v65, v55
	v_exp_f32_e32 v56, v56
	v_mul_f32_e32 v57, 1.0, v65
	v_mov_b32_e32 v55, v57
	v_rcp_f32_e32 v65, v54
	s_nop 0
	v_mul_f32_e32 v57, 1.0, v65
	v_mov_b32_e32 v54, v57
	v_mul_f32_e32 v57, 0xbfb8aa3b, v64
	v_exp_f32_e32 v57, v57
	v_pk_mul_f32 v[54:55], v[54:55], v[60:61]
	v_pk_add_f32 v[56:57], v[56:57], 1.0 op_sel_hi:[1,0]
	s_nop 0
	v_rcp_f32_e32 v61, v57
	s_nop 0
	v_mul_f32_e32 v60, v64, v61
	v_mov_b32_e32 v57, v60
	v_rcp_f32_e32 v61, v56
	s_nop 0
	v_mul_f32_e32 v60, v49, v61
	v_mov_b32_e32 v56, v60
	v_pk_mul_f32 v[54:55], v[56:57], v[54:55]
	v_lshlrev_b32_e32 v56, 16, v58
	v_cvt_pk_bf16_f32 v49, v54, v55
	v_and_b32_e32 v57, 0xffff0000, v58
	v_rcp_f32_e32 v58, v51
	v_lshlrev_b32_e32 v60, 16, v62
	v_and_b32_e32 v61, 0xffff0000, v62
	v_mul_f32_e32 v54, 0xbfb8aa3b, v60
	v_mul_f32_e32 v55, 1.0, v58
	v_mov_b32_e32 v51, v55
	v_rcp_f32_e32 v58, v50
	v_exp_f32_e32 v54, v54
	v_mul_f32_e32 v55, 1.0, v58
	v_mov_b32_e32 v50, v55
	v_mul_f32_e32 v55, 0xbfb8aa3b, v61
	v_exp_f32_e32 v55, v55
	v_pk_mul_f32 v[50:51], v[50:51], v[56:57]
	v_pk_add_f32 v[54:55], v[54:55], 1.0 op_sel_hi:[1,0]
	s_nop 0
	v_rcp_f32_e32 v57, v55
	s_nop 0
	v_mul_f32_e32 v56, v61, v57
	v_mov_b32_e32 v55, v56
	v_rcp_f32_e32 v57, v54
	s_nop 0
	v_mul_f32_e32 v56, v60, v57
	v_mov_b32_e32 v54, v56
	v_pk_mul_f32 v[50:51], v[54:55], v[50:51]
	v_lshlrev_b32_e32 v56, 16, v59
	v_cvt_pk_bf16_f32 v50, v50, v51
	v_mul_f32_e32 v51, 0xbfb8aa3b, v52
	v_exp_f32_e32 v52, v51
	v_mul_f32_e32 v51, 0xbfb8aa3b, v53
	v_exp_f32_e32 v53, v51
	v_and_b32_e32 v57, 0xffff0000, v59
	v_lshlrev_b32_e32 v51, 16, v63
	v_and_b32_e32 v58, 0xffff0000, v63
	v_pk_add_f32 v[52:53], v[52:53], 1.0 op_sel_hi:[1,0]
	v_mul_f32_e32 v54, 0xbfb8aa3b, v51
	v_rcp_f32_e32 v59, v53
	v_exp_f32_e32 v54, v54
	v_mul_f32_e32 v55, 1.0, v59
	v_mov_b32_e32 v53, v55
	v_rcp_f32_e32 v59, v52
	s_nop 0
	v_mul_f32_e32 v55, 1.0, v59
	v_mov_b32_e32 v52, v55
	v_mul_f32_e32 v55, 0xbfb8aa3b, v58
	v_exp_f32_e32 v55, v55
	v_pk_mul_f32 v[52:53], v[52:53], v[56:57]
	v_pk_add_f32 v[54:55], v[54:55], 1.0 op_sel_hi:[1,0]
	s_nop 0
	v_rcp_f32_e32 v57, v55
	s_nop 0
	v_mul_f32_e32 v56, v58, v57
	v_mov_b32_e32 v55, v56
	v_rcp_f32_e32 v57, v54
	s_nop 0
	v_mul_f32_e32 v56, v51, v57
	v_mov_b32_e32 v54, v56
	v_pk_mul_f32 v[52:53], v[54:55], v[52:53]
	s_nop 0
	v_cvt_pk_bf16_f32 v51, v52, v53
	global_store_dwordx4 v[72:73], v[48:51], off offset:256
	s_nop 1
	v_add_u32_e32 v48, 0x90, v154
	v_mad_i64_i32 v[48:49], s[0:1], v48, s14, v[144:145]
	v_lshl_add_u64 v[56:57], v[48:49], 0, v[146:147]
	v_add_co_u32_e32 v58, vcc, s15, v56
	s_nop 1
	v_addc_co_u32_e32 v59, vcc, 0, v57, vcc
	global_load_dwordx4 v[48:51], v[58:59], off
	global_load_dwordx4 v[52:55], v[56:57], off
	global_load_dwordx4 v[60:63], v[142:143], off offset:16
	global_load_dwordx4 v[64:67], v[142:143], off
	s_waitcnt vmcnt(1)
	v_pk_add_f32 v[62:63], v[42:43], v[62:63]
	s_waitcnt vmcnt(0)
	v_pk_add_f32 v[44:45], v[44:45], v[64:65]
	v_pk_add_f32 v[42:43], v[40:41], v[60:61]
	v_mul_f32_e32 v40, 0xbfb8aa3b, v44
	v_mul_f32_e32 v41, 0xbfb8aa3b, v45
	v_exp_f32_e32 v40, v40
	v_exp_f32_e32 v41, v41
	v_lshlrev_b32_e32 v60, 16, v48
	v_and_b32_e32 v61, 0xffff0000, v48
	v_pk_add_f32 v[46:47], v[46:47], v[66:67]
	v_pk_add_f32 v[40:41], v[40:41], 1.0 op_sel_hi:[1,0]
	v_lshlrev_b32_e32 v64, 16, v52
	v_rcp_f32_e32 v48, v41
	v_and_b32_e32 v52, 0xffff0000, v52
	v_mul_f32_e32 v44, 0xbfb8aa3b, v64
	v_exp_f32_e32 v44, v44
	v_mul_f32_e32 v45, 1.0, v48
	v_mov_b32_e32 v41, v45
	v_rcp_f32_e32 v48, v40
	v_mul_f32_e32 v42, 0xbfb8aa3b, v42
	v_mul_f32_e32 v43, 0xbfb8aa3b, v43
	v_exp_f32_e32 v42, v42
	v_mul_f32_e32 v45, 1.0, v48
	v_mov_b32_e32 v40, v45
	v_mul_f32_e32 v45, 0xbfb8aa3b, v52
	v_exp_f32_e32 v45, v45
	v_pk_mul_f32 v[40:41], v[40:41], v[60:61]
	v_exp_f32_e32 v43, v43
	v_pk_add_f32 v[44:45], v[44:45], 1.0 op_sel_hi:[1,0]
	s_nop 0
	v_rcp_f32_e32 v60, v45
	v_pk_add_f32 v[42:43], v[42:43], 1.0 op_sel_hi:[1,0]
	v_mul_f32_e32 v48, v52, v60
	v_mov_b32_e32 v45, v48
	v_rcp_f32_e32 v52, v44
	s_nop 0
	v_mul_f32_e32 v48, v64, v52
	v_mov_b32_e32 v44, v48
	v_pk_mul_f32 v[40:41], v[44:45], v[40:41]
	v_and_b32_e32 v52, 0xffff0000, v53
	v_cvt_pk_bf16_f32 v40, v40, v41
	v_mul_f32_e32 v41, 0xbfb8aa3b, v46
	v_exp_f32_e32 v44, v41
	v_mul_f32_e32 v41, 0xbfb8aa3b, v47
	v_exp_f32_e32 v45, v41
	v_lshlrev_b32_e32 v41, 16, v53
	v_mul_f32_e32 v46, 0xbfb8aa3b, v41
	v_exp_f32_e32 v46, v46
	v_pk_add_f32 v[44:45], v[44:45], 1.0 op_sel_hi:[1,0]
	v_lshlrev_b32_e32 v48, 16, v49
	v_rcp_f32_e32 v53, v45
	v_and_b32_e32 v49, 0xffff0000, v49
	v_mul_f32_e32 v47, 1.0, v53
	v_mov_b32_e32 v45, v47
	v_rcp_f32_e32 v53, v44
	s_nop 0
	v_mul_f32_e32 v47, 1.0, v53
	v_mov_b32_e32 v44, v47
	v_mul_f32_e32 v47, 0xbfb8aa3b, v52
	v_exp_f32_e32 v47, v47
	v_pk_mul_f32 v[44:45], v[44:45], v[48:49]
	v_pk_add_f32 v[46:47], v[46:47], 1.0 op_sel_hi:[1,0]
	s_nop 0
	v_rcp_f32_e32 v49, v47
	s_nop 0
	v_mul_f32_e32 v48, v52, v49
	v_mov_b32_e32 v47, v48
	v_rcp_f32_e32 v49, v46
	s_nop 0
	v_mul_f32_e32 v48, v41, v49
	v_mov_b32_e32 v46, v48
	v_pk_mul_f32 v[44:45], v[46:47], v[44:45]
	v_lshlrev_b32_e32 v46, 16, v50
	v_cvt_pk_bf16_f32 v41, v44, v45
	v_and_b32_e32 v47, 0xffff0000, v50
	v_rcp_f32_e32 v50, v43
	v_lshlrev_b32_e32 v48, 16, v54
	v_and_b32_e32 v49, 0xffff0000, v54
	v_mul_f32_e32 v44, 0xbfb8aa3b, v48
	v_mul_f32_e32 v45, 1.0, v50
	v_mov_b32_e32 v43, v45
	v_rcp_f32_e32 v50, v42
	v_exp_f32_e32 v44, v44
	v_mul_f32_e32 v45, 1.0, v50
	v_mov_b32_e32 v42, v45
	v_mul_f32_e32 v45, 0xbfb8aa3b, v49
	v_exp_f32_e32 v45, v45
	v_pk_mul_f32 v[42:43], v[42:43], v[46:47]
	v_pk_add_f32 v[44:45], v[44:45], 1.0 op_sel_hi:[1,0]
	s_nop 0
	v_rcp_f32_e32 v47, v45
	s_nop 0
	v_mul_f32_e32 v46, v49, v47
	v_mov_b32_e32 v45, v46
	v_rcp_f32_e32 v47, v44
	s_nop 0
	v_mul_f32_e32 v46, v48, v47
	v_mov_b32_e32 v44, v46
	v_pk_mul_f32 v[42:43], v[44:45], v[42:43]
	v_lshlrev_b32_e32 v48, 16, v51
	v_cvt_pk_bf16_f32 v42, v42, v43
	v_mul_f32_e32 v43, 0xbfb8aa3b, v62
	v_exp_f32_e32 v44, v43
	v_mul_f32_e32 v43, 0xbfb8aa3b, v63
	v_exp_f32_e32 v45, v43
	v_and_b32_e32 v49, 0xffff0000, v51
	v_lshlrev_b32_e32 v43, 16, v55
	v_and_b32_e32 v50, 0xffff0000, v55
	v_pk_add_f32 v[44:45], v[44:45], 1.0 op_sel_hi:[1,0]
	v_mul_f32_e32 v46, 0xbfb8aa3b, v43
	v_rcp_f32_e32 v51, v45
	v_exp_f32_e32 v46, v46
	v_mul_f32_e32 v47, 1.0, v51
	v_mov_b32_e32 v45, v47
	v_rcp_f32_e32 v51, v44
	s_nop 0
	v_mul_f32_e32 v47, 1.0, v51
	v_mov_b32_e32 v44, v47
	v_mul_f32_e32 v47, 0xbfb8aa3b, v50
	v_exp_f32_e32 v47, v47
	v_pk_mul_f32 v[44:45], v[44:45], v[48:49]
	v_pk_add_f32 v[46:47], v[46:47], 1.0 op_sel_hi:[1,0]
	s_nop 0
	v_rcp_f32_e32 v49, v47
	s_nop 0
	v_mul_f32_e32 v48, v50, v49
	v_mov_b32_e32 v47, v48
	v_rcp_f32_e32 v49, v46
	s_nop 0
	v_mul_f32_e32 v48, v43, v49
	v_mov_b32_e32 v46, v48
	v_pk_mul_f32 v[44:45], v[46:47], v[44:45]
	s_nop 0
	v_cvt_pk_bf16_f32 v43, v44, v45
	global_store_dwordx4 v[56:57], v[40:43], off
	global_load_dwordx4 v[40:43], v[58:59], off offset:256
	s_nop 0
	global_load_dwordx4 v[44:47], v[56:57], off offset:256
	global_load_dwordx4 v[48:51], v[142:143], off offset:528
	global_load_dwordx4 v[52:55], v[142:143], off offset:512
	s_waitcnt vmcnt(0)
	v_pk_add_f32 v[52:53], v[36:37], v[52:53]
	v_pk_add_f32 v[36:37], v[34:35], v[50:51]
	v_pk_add_f32 v[34:35], v[32:33], v[48:49]
	v_mul_f32_e32 v32, 0xbfb8aa3b, v52
	v_mul_f32_e32 v33, 0xbfb8aa3b, v53
	v_exp_f32_e32 v32, v32
	v_exp_f32_e32 v33, v33
	v_lshlrev_b32_e32 v50, 16, v40
	v_and_b32_e32 v51, 0xffff0000, v40
	v_pk_add_f32 v[38:39], v[38:39], v[54:55]
	v_pk_add_f32 v[32:33], v[32:33], 1.0 op_sel_hi:[1,0]
	v_lshlrev_b32_e32 v52, 16, v44
	v_rcp_f32_e32 v49, v33
	v_and_b32_e32 v44, 0xffff0000, v44
	v_mul_f32_e32 v48, 0xbfb8aa3b, v52
	v_exp_f32_e32 v48, v48
	v_mul_f32_e32 v40, 1.0, v49
	v_mov_b32_e32 v33, v40
	v_rcp_f32_e32 v49, v32
	v_mul_f32_e32 v34, 0xbfb8aa3b, v34
	v_mul_f32_e32 v35, 0xbfb8aa3b, v35
	v_exp_f32_e32 v34, v34
	v_mul_f32_e32 v40, 1.0, v49
	v_mov_b32_e32 v32, v40
	v_mul_f32_e32 v40, 0xbfb8aa3b, v44
	v_exp_f32_e32 v49, v40
	v_pk_mul_f32 v[32:33], v[32:33], v[50:51]
	v_exp_f32_e32 v35, v35
	v_pk_add_f32 v[48:49], v[48:49], 1.0 op_sel_hi:[1,0]
	s_nop 0
	v_rcp_f32_e32 v50, v49
	v_pk_add_f32 v[34:35], v[34:35], 1.0 op_sel_hi:[1,0]
	v_mul_f32_e32 v40, v44, v50
	v_mov_b32_e32 v49, v40
	v_rcp_f32_e32 v44, v48
	s_nop 0
	v_mul_f32_e32 v40, v52, v44
	v_mov_b32_e32 v48, v40
	v_pk_mul_f32 v[32:33], v[48:49], v[32:33]
	v_and_b32_e32 v48, 0xffff0000, v45
	v_cvt_pk_bf16_f32 v32, v32, v33
	v_mul_f32_e32 v33, 0xbfb8aa3b, v38
	v_exp_f32_e32 v38, v33
	v_mul_f32_e32 v33, 0xbfb8aa3b, v39
	v_exp_f32_e32 v39, v33
	v_lshlrev_b32_e32 v33, 16, v45
	v_lshlrev_b32_e32 v44, 16, v41
	v_and_b32_e32 v45, 0xffff0000, v41
	v_pk_add_f32 v[38:39], v[38:39], 1.0 op_sel_hi:[1,0]
	v_mul_f32_e32 v40, 0xbfb8aa3b, v33
	v_rcp_f32_e32 v49, v39
	v_exp_f32_e32 v40, v40
	v_mul_f32_e32 v41, 1.0, v49
	v_mov_b32_e32 v39, v41
	v_rcp_f32_e32 v49, v38
	s_nop 0
	v_mul_f32_e32 v41, 1.0, v49
	v_mov_b32_e32 v38, v41
	v_mul_f32_e32 v41, 0xbfb8aa3b, v48
	v_exp_f32_e32 v41, v41
	v_pk_mul_f32 v[38:39], v[38:39], v[44:45]
	v_pk_add_f32 v[40:41], v[40:41], 1.0 op_sel_hi:[1,0]
	s_nop 0
	v_rcp_f32_e32 v45, v41
	s_nop 0
	v_mul_f32_e32 v44, v48, v45
	v_mov_b32_e32 v41, v44
	v_rcp_f32_e32 v45, v40
	s_nop 0
	v_mul_f32_e32 v44, v33, v45
	v_mov_b32_e32 v40, v44
	v_pk_mul_f32 v[38:39], v[40:41], v[38:39]
	v_lshlrev_b32_e32 v40, 16, v42
	v_cvt_pk_bf16_f32 v33, v38, v39
	v_and_b32_e32 v41, 0xffff0000, v42
	v_rcp_f32_e32 v42, v35
	v_lshlrev_b32_e32 v44, 16, v46
	v_and_b32_e32 v45, 0xffff0000, v46
	v_mul_f32_e32 v38, 0xbfb8aa3b, v44
	v_mul_f32_e32 v39, 1.0, v42
	v_mov_b32_e32 v35, v39
	v_rcp_f32_e32 v42, v34
	v_exp_f32_e32 v38, v38
	v_mul_f32_e32 v39, 1.0, v42
	v_mov_b32_e32 v34, v39
	v_mul_f32_e32 v39, 0xbfb8aa3b, v45
	v_exp_f32_e32 v39, v39
	v_pk_mul_f32 v[34:35], v[34:35], v[40:41]
	v_pk_add_f32 v[38:39], v[38:39], 1.0 op_sel_hi:[1,0]
	s_nop 0
	v_rcp_f32_e32 v41, v39
	s_nop 0
	v_mul_f32_e32 v40, v45, v41
	v_mov_b32_e32 v39, v40
	v_rcp_f32_e32 v41, v38
	s_nop 0
	v_mul_f32_e32 v40, v44, v41
	v_mov_b32_e32 v38, v40
	v_pk_mul_f32 v[34:35], v[38:39], v[34:35]
	v_lshlrev_b32_e32 v40, 16, v43
	v_cvt_pk_bf16_f32 v34, v34, v35
	v_mul_f32_e32 v35, 0xbfb8aa3b, v36
	v_exp_f32_e32 v36, v35
	v_mul_f32_e32 v35, 0xbfb8aa3b, v37
	v_exp_f32_e32 v37, v35
	v_and_b32_e32 v41, 0xffff0000, v43
	v_lshlrev_b32_e32 v35, 16, v47
	v_and_b32_e32 v42, 0xffff0000, v47
	v_pk_add_f32 v[36:37], v[36:37], 1.0 op_sel_hi:[1,0]
	v_mul_f32_e32 v38, 0xbfb8aa3b, v35
	v_rcp_f32_e32 v43, v37
	v_exp_f32_e32 v38, v38
	v_mul_f32_e32 v39, 1.0, v43
	v_mov_b32_e32 v37, v39
	v_rcp_f32_e32 v43, v36
	s_nop 0
	v_mul_f32_e32 v39, 1.0, v43
	v_mov_b32_e32 v36, v39
	v_mul_f32_e32 v39, 0xbfb8aa3b, v42
	v_exp_f32_e32 v39, v39
	v_pk_mul_f32 v[36:37], v[36:37], v[40:41]
	v_pk_add_f32 v[38:39], v[38:39], 1.0 op_sel_hi:[1,0]
	s_nop 0
	v_rcp_f32_e32 v41, v39
	s_nop 0
	v_mul_f32_e32 v40, v42, v41
	v_mov_b32_e32 v39, v40
	v_rcp_f32_e32 v41, v38
	s_nop 0
	v_mul_f32_e32 v40, v35, v41
	v_mov_b32_e32 v38, v40
	v_pk_mul_f32 v[36:37], v[38:39], v[36:37]
	s_nop 0
	v_cvt_pk_bf16_f32 v35, v36, v37
	global_store_dwordx4 v[56:57], v[32:35], off offset:256
	s_nop 1
	v_add_u32_e32 v32, 0xa0, v154
	v_mad_i64_i32 v[32:33], s[0:1], v32, s14, v[144:145]
	v_lshl_add_u64 v[40:41], v[32:33], 0, v[146:147]
	v_add_co_u32_e32 v42, vcc, s15, v40
	s_nop 1
	v_addc_co_u32_e32 v43, vcc, 0, v41, vcc
	global_load_dwordx4 v[32:35], v[42:43], off
	global_load_dwordx4 v[36:39], v[40:41], off
	global_load_dwordx4 v[44:47], v[142:143], off offset:16
	global_load_dwordx4 v[48:51], v[142:143], off
	s_waitcnt vmcnt(1)
	v_pk_add_f32 v[46:47], v[26:27], v[46:47]
	s_waitcnt vmcnt(0)
	v_pk_add_f32 v[28:29], v[28:29], v[48:49]
	v_pk_add_f32 v[26:27], v[24:25], v[44:45]
	v_mul_f32_e32 v24, 0xbfb8aa3b, v28
	v_mul_f32_e32 v25, 0xbfb8aa3b, v29
	v_exp_f32_e32 v24, v24
	v_exp_f32_e32 v25, v25
	v_lshlrev_b32_e32 v44, 16, v32
	v_and_b32_e32 v45, 0xffff0000, v32
	v_pk_add_f32 v[30:31], v[30:31], v[50:51]
	v_pk_add_f32 v[24:25], v[24:25], 1.0 op_sel_hi:[1,0]
	v_lshlrev_b32_e32 v48, 16, v36
	v_rcp_f32_e32 v32, v25
	v_and_b32_e32 v36, 0xffff0000, v36
	v_mul_f32_e32 v28, 0xbfb8aa3b, v48
	v_exp_f32_e32 v28, v28
	v_mul_f32_e32 v29, 1.0, v32
	v_mov_b32_e32 v25, v29
	v_rcp_f32_e32 v32, v24
	v_mul_f32_e32 v26, 0xbfb8aa3b, v26
	v_mul_f32_e32 v27, 0xbfb8aa3b, v27
	v_exp_f32_e32 v26, v26
	v_mul_f32_e32 v29, 1.0, v32
	v_mov_b32_e32 v24, v29
	v_mul_f32_e32 v29, 0xbfb8aa3b, v36
	v_exp_f32_e32 v29, v29
	v_pk_mul_f32 v[24:25], v[24:25], v[44:45]
	v_exp_f32_e32 v27, v27
	v_pk_add_f32 v[28:29], v[28:29], 1.0 op_sel_hi:[1,0]
	s_nop 0
	v_rcp_f32_e32 v44, v29
	v_pk_add_f32 v[26:27], v[26:27], 1.0 op_sel_hi:[1,0]
	v_mul_f32_e32 v32, v36, v44
	v_mov_b32_e32 v29, v32
	v_rcp_f32_e32 v36, v28
	s_nop 0
	v_mul_f32_e32 v32, v48, v36
	v_mov_b32_e32 v28, v32
	v_pk_mul_f32 v[24:25], v[28:29], v[24:25]
	v_and_b32_e32 v36, 0xffff0000, v37
	v_cvt_pk_bf16_f32 v24, v24, v25
	v_mul_f32_e32 v25, 0xbfb8aa3b, v30
	v_exp_f32_e32 v28, v25
	v_mul_f32_e32 v25, 0xbfb8aa3b, v31
	v_exp_f32_e32 v29, v25
	v_lshlrev_b32_e32 v25, 16, v37
	v_mul_f32_e32 v30, 0xbfb8aa3b, v25
	v_exp_f32_e32 v30, v30
	v_pk_add_f32 v[28:29], v[28:29], 1.0 op_sel_hi:[1,0]
	v_lshlrev_b32_e32 v32, 16, v33
	v_rcp_f32_e32 v37, v29
	v_and_b32_e32 v33, 0xffff0000, v33
	v_mul_f32_e32 v31, 1.0, v37
	v_mov_b32_e32 v29, v31
	v_rcp_f32_e32 v37, v28
	s_nop 0
	v_mul_f32_e32 v31, 1.0, v37
	v_mov_b32_e32 v28, v31
	v_mul_f32_e32 v31, 0xbfb8aa3b, v36
	v_exp_f32_e32 v31, v31
	v_pk_mul_f32 v[28:29], v[28:29], v[32:33]
	v_pk_add_f32 v[30:31], v[30:31], 1.0 op_sel_hi:[1,0]
	s_nop 0
	v_rcp_f32_e32 v33, v31
	s_nop 0
	v_mul_f32_e32 v32, v36, v33
	v_mov_b32_e32 v31, v32
	v_rcp_f32_e32 v33, v30
	s_nop 0
	v_mul_f32_e32 v32, v25, v33
	v_mov_b32_e32 v30, v32
	v_pk_mul_f32 v[28:29], v[30:31], v[28:29]
	v_lshlrev_b32_e32 v30, 16, v34
	v_cvt_pk_bf16_f32 v25, v28, v29
	v_and_b32_e32 v31, 0xffff0000, v34
	v_rcp_f32_e32 v34, v27
	v_lshlrev_b32_e32 v32, 16, v38
	v_and_b32_e32 v33, 0xffff0000, v38
	v_mul_f32_e32 v28, 0xbfb8aa3b, v32
	v_mul_f32_e32 v29, 1.0, v34
	v_mov_b32_e32 v27, v29
	v_rcp_f32_e32 v34, v26
	v_exp_f32_e32 v28, v28
	v_mul_f32_e32 v29, 1.0, v34
	v_mov_b32_e32 v26, v29
	v_mul_f32_e32 v29, 0xbfb8aa3b, v33
	v_exp_f32_e32 v29, v29
	v_pk_mul_f32 v[26:27], v[26:27], v[30:31]
	v_pk_add_f32 v[28:29], v[28:29], 1.0 op_sel_hi:[1,0]
	s_nop 0
	v_rcp_f32_e32 v31, v29
	s_nop 0
	v_mul_f32_e32 v30, v33, v31
	v_mov_b32_e32 v29, v30
	v_rcp_f32_e32 v31, v28
	s_nop 0
	v_mul_f32_e32 v30, v32, v31
	v_mov_b32_e32 v28, v30
	v_pk_mul_f32 v[26:27], v[28:29], v[26:27]
	v_lshlrev_b32_e32 v32, 16, v35
	v_cvt_pk_bf16_f32 v26, v26, v27
	v_mul_f32_e32 v27, 0xbfb8aa3b, v46
	v_exp_f32_e32 v28, v27
	v_mul_f32_e32 v27, 0xbfb8aa3b, v47
	v_exp_f32_e32 v29, v27
	v_and_b32_e32 v33, 0xffff0000, v35
	v_lshlrev_b32_e32 v27, 16, v39
	v_and_b32_e32 v34, 0xffff0000, v39
	v_pk_add_f32 v[28:29], v[28:29], 1.0 op_sel_hi:[1,0]
	v_mul_f32_e32 v30, 0xbfb8aa3b, v27
	v_rcp_f32_e32 v35, v29
	v_exp_f32_e32 v30, v30
	v_mul_f32_e32 v31, 1.0, v35
	v_mov_b32_e32 v29, v31
	v_rcp_f32_e32 v35, v28
	s_nop 0
	v_mul_f32_e32 v31, 1.0, v35
	v_mov_b32_e32 v28, v31
	v_mul_f32_e32 v31, 0xbfb8aa3b, v34
	v_exp_f32_e32 v31, v31
	v_pk_mul_f32 v[28:29], v[28:29], v[32:33]
	v_pk_add_f32 v[30:31], v[30:31], 1.0 op_sel_hi:[1,0]
	s_nop 0
	v_rcp_f32_e32 v33, v31
	s_nop 0
	v_mul_f32_e32 v32, v34, v33
	v_mov_b32_e32 v31, v32
	v_rcp_f32_e32 v33, v30
	s_nop 0
	v_mul_f32_e32 v32, v27, v33
	v_mov_b32_e32 v30, v32
	v_pk_mul_f32 v[28:29], v[30:31], v[28:29]
	s_nop 0
	v_cvt_pk_bf16_f32 v27, v28, v29
	global_store_dwordx4 v[40:41], v[24:27], off
	global_load_dwordx4 v[24:27], v[42:43], off offset:256
	s_nop 0
	global_load_dwordx4 v[28:31], v[40:41], off offset:256
	global_load_dwordx4 v[32:35], v[142:143], off offset:528
	global_load_dwordx4 v[36:39], v[142:143], off offset:512
	s_waitcnt vmcnt(0)
	v_pk_add_f32 v[36:37], v[20:21], v[36:37]
	v_pk_add_f32 v[20:21], v[18:19], v[34:35]
	v_pk_add_f32 v[18:19], v[16:17], v[32:33]
	v_mul_f32_e32 v16, 0xbfb8aa3b, v36
	v_mul_f32_e32 v17, 0xbfb8aa3b, v37
	v_exp_f32_e32 v16, v16
	v_exp_f32_e32 v17, v17
	v_lshlrev_b32_e32 v34, 16, v24
	v_and_b32_e32 v35, 0xffff0000, v24
	v_pk_add_f32 v[22:23], v[22:23], v[38:39]
	v_pk_add_f32 v[16:17], v[16:17], 1.0 op_sel_hi:[1,0]
	v_lshlrev_b32_e32 v36, 16, v28
	v_rcp_f32_e32 v33, v17
	v_and_b32_e32 v28, 0xffff0000, v28
	v_mul_f32_e32 v32, 0xbfb8aa3b, v36
	v_exp_f32_e32 v32, v32
	v_mul_f32_e32 v24, 1.0, v33
	v_mov_b32_e32 v17, v24
	v_rcp_f32_e32 v33, v16
	v_mul_f32_e32 v18, 0xbfb8aa3b, v18
	v_mul_f32_e32 v19, 0xbfb8aa3b, v19
	v_exp_f32_e32 v18, v18
	v_mul_f32_e32 v24, 1.0, v33
	v_mov_b32_e32 v16, v24
	v_mul_f32_e32 v24, 0xbfb8aa3b, v28
	v_exp_f32_e32 v33, v24
	v_pk_mul_f32 v[16:17], v[16:17], v[34:35]
	v_exp_f32_e32 v19, v19
	v_pk_add_f32 v[32:33], v[32:33], 1.0 op_sel_hi:[1,0]
	s_nop 0
	v_rcp_f32_e32 v34, v33
	v_pk_add_f32 v[18:19], v[18:19], 1.0 op_sel_hi:[1,0]
	v_mul_f32_e32 v24, v28, v34
	v_mov_b32_e32 v33, v24
	v_rcp_f32_e32 v28, v32
	s_nop 0
	v_mul_f32_e32 v24, v36, v28
	v_mov_b32_e32 v32, v24
	v_pk_mul_f32 v[16:17], v[32:33], v[16:17]
	v_and_b32_e32 v32, 0xffff0000, v29
	v_cvt_pk_bf16_f32 v16, v16, v17
	v_mul_f32_e32 v17, 0xbfb8aa3b, v22
	v_exp_f32_e32 v22, v17
	v_mul_f32_e32 v17, 0xbfb8aa3b, v23
	v_exp_f32_e32 v23, v17
	v_lshlrev_b32_e32 v17, 16, v29
	v_lshlrev_b32_e32 v28, 16, v25
	v_and_b32_e32 v29, 0xffff0000, v25
	v_pk_add_f32 v[22:23], v[22:23], 1.0 op_sel_hi:[1,0]
	v_mul_f32_e32 v24, 0xbfb8aa3b, v17
	v_rcp_f32_e32 v33, v23
	v_exp_f32_e32 v24, v24
	v_mul_f32_e32 v25, 1.0, v33
	v_mov_b32_e32 v23, v25
	v_rcp_f32_e32 v33, v22
	s_nop 0
	v_mul_f32_e32 v25, 1.0, v33
	v_mov_b32_e32 v22, v25
	v_mul_f32_e32 v25, 0xbfb8aa3b, v32
	v_exp_f32_e32 v25, v25
	v_pk_mul_f32 v[22:23], v[22:23], v[28:29]
	v_pk_add_f32 v[24:25], v[24:25], 1.0 op_sel_hi:[1,0]
	s_nop 0
	v_rcp_f32_e32 v29, v25
	s_nop 0
	v_mul_f32_e32 v28, v32, v29
	v_mov_b32_e32 v25, v28
	v_rcp_f32_e32 v29, v24
	s_nop 0
	v_mul_f32_e32 v28, v17, v29
	v_mov_b32_e32 v24, v28
	v_pk_mul_f32 v[22:23], v[24:25], v[22:23]
	v_lshlrev_b32_e32 v24, 16, v26
	v_cvt_pk_bf16_f32 v17, v22, v23
	v_and_b32_e32 v25, 0xffff0000, v26
	v_rcp_f32_e32 v26, v19
	v_lshlrev_b32_e32 v28, 16, v30
	v_and_b32_e32 v29, 0xffff0000, v30
	v_mul_f32_e32 v22, 0xbfb8aa3b, v28
	v_mul_f32_e32 v23, 1.0, v26
	v_mov_b32_e32 v19, v23
	v_rcp_f32_e32 v26, v18
	v_exp_f32_e32 v22, v22
	v_mul_f32_e32 v23, 1.0, v26
	v_mov_b32_e32 v18, v23
	v_mul_f32_e32 v23, 0xbfb8aa3b, v29
	v_exp_f32_e32 v23, v23
	v_pk_mul_f32 v[18:19], v[18:19], v[24:25]
	v_pk_add_f32 v[22:23], v[22:23], 1.0 op_sel_hi:[1,0]
	s_nop 0
	v_rcp_f32_e32 v25, v23
	s_nop 0
	v_mul_f32_e32 v24, v29, v25
	v_mov_b32_e32 v23, v24
	v_rcp_f32_e32 v25, v22
	s_nop 0
	v_mul_f32_e32 v24, v28, v25
	v_mov_b32_e32 v22, v24
	v_pk_mul_f32 v[18:19], v[22:23], v[18:19]
	v_lshlrev_b32_e32 v24, 16, v27
	v_cvt_pk_bf16_f32 v18, v18, v19
	v_mul_f32_e32 v19, 0xbfb8aa3b, v20
	v_exp_f32_e32 v20, v19
	v_mul_f32_e32 v19, 0xbfb8aa3b, v21
	v_exp_f32_e32 v21, v19
	v_and_b32_e32 v25, 0xffff0000, v27
	v_lshlrev_b32_e32 v19, 16, v31
	v_and_b32_e32 v26, 0xffff0000, v31
	v_pk_add_f32 v[20:21], v[20:21], 1.0 op_sel_hi:[1,0]
	v_mul_f32_e32 v22, 0xbfb8aa3b, v19
	v_rcp_f32_e32 v27, v21
	v_exp_f32_e32 v22, v22
	v_mul_f32_e32 v23, 1.0, v27
	v_mov_b32_e32 v21, v23
	v_rcp_f32_e32 v27, v20
	s_nop 0
	v_mul_f32_e32 v23, 1.0, v27
	v_mov_b32_e32 v20, v23
	v_mul_f32_e32 v23, 0xbfb8aa3b, v26
	v_exp_f32_e32 v23, v23
	v_pk_mul_f32 v[20:21], v[20:21], v[24:25]
	v_pk_add_f32 v[22:23], v[22:23], 1.0 op_sel_hi:[1,0]
	s_nop 0
	v_rcp_f32_e32 v25, v23
	s_nop 0
	v_mul_f32_e32 v24, v26, v25
	v_mov_b32_e32 v23, v24
	v_rcp_f32_e32 v25, v22
	s_nop 0
	v_mul_f32_e32 v24, v19, v25
	v_mov_b32_e32 v22, v24
	v_pk_mul_f32 v[20:21], v[22:23], v[20:21]
	s_nop 0
	v_cvt_pk_bf16_f32 v19, v20, v21
	global_store_dwordx4 v[40:41], v[16:19], off offset:256
	s_nop 1
	v_add_u32_e32 v16, 0xb0, v154
	v_mad_i64_i32 v[16:17], s[0:1], v16, s14, v[144:145]
	v_lshl_add_u64 v[24:25], v[16:17], 0, v[146:147]
	v_add_co_u32_e32 v26, vcc, s15, v24
	s_nop 1
	v_addc_co_u32_e32 v27, vcc, 0, v25, vcc
	global_load_dwordx4 v[16:19], v[26:27], off
	global_load_dwordx4 v[20:23], v[24:25], off
	global_load_dwordx4 v[28:31], v[142:143], off offset:16
	global_load_dwordx4 v[32:35], v[142:143], off
	s_waitcnt vmcnt(1)
	v_pk_add_f32 v[30:31], v[10:11], v[30:31]
	s_waitcnt vmcnt(0)
	v_pk_add_f32 v[12:13], v[12:13], v[32:33]
	v_pk_add_f32 v[10:11], v[8:9], v[28:29]
	v_mul_f32_e32 v8, 0xbfb8aa3b, v12
	v_mul_f32_e32 v9, 0xbfb8aa3b, v13
	v_exp_f32_e32 v8, v8
	v_exp_f32_e32 v9, v9
	v_lshlrev_b32_e32 v28, 16, v16
	v_and_b32_e32 v29, 0xffff0000, v16
	v_pk_add_f32 v[14:15], v[14:15], v[34:35]
	v_pk_add_f32 v[8:9], v[8:9], 1.0 op_sel_hi:[1,0]
	v_lshlrev_b32_e32 v32, 16, v20
	v_rcp_f32_e32 v16, v9
	v_and_b32_e32 v20, 0xffff0000, v20
	v_mul_f32_e32 v12, 0xbfb8aa3b, v32
	v_exp_f32_e32 v12, v12
	v_mul_f32_e32 v13, 1.0, v16
	v_mov_b32_e32 v9, v13
	v_rcp_f32_e32 v16, v8
	v_mul_f32_e32 v10, 0xbfb8aa3b, v10
	v_mul_f32_e32 v11, 0xbfb8aa3b, v11
	v_exp_f32_e32 v10, v10
	v_mul_f32_e32 v13, 1.0, v16
	v_mov_b32_e32 v8, v13
	v_mul_f32_e32 v13, 0xbfb8aa3b, v20
	v_exp_f32_e32 v13, v13
	v_pk_mul_f32 v[8:9], v[8:9], v[28:29]
	v_exp_f32_e32 v11, v11
	v_pk_add_f32 v[12:13], v[12:13], 1.0 op_sel_hi:[1,0]
	s_nop 0
	v_rcp_f32_e32 v28, v13
	v_pk_add_f32 v[10:11], v[10:11], 1.0 op_sel_hi:[1,0]
	v_mul_f32_e32 v16, v20, v28
	v_mov_b32_e32 v13, v16
	v_rcp_f32_e32 v20, v12
	s_nop 0
	v_mul_f32_e32 v16, v32, v20
	v_mov_b32_e32 v12, v16
	v_pk_mul_f32 v[8:9], v[12:13], v[8:9]
	v_and_b32_e32 v20, 0xffff0000, v21
	v_cvt_pk_bf16_f32 v8, v8, v9
	v_mul_f32_e32 v9, 0xbfb8aa3b, v14
	v_exp_f32_e32 v12, v9
	v_mul_f32_e32 v9, 0xbfb8aa3b, v15
	v_exp_f32_e32 v13, v9
	v_lshlrev_b32_e32 v9, 16, v21
	v_mul_f32_e32 v14, 0xbfb8aa3b, v9
	v_exp_f32_e32 v14, v14
	v_pk_add_f32 v[12:13], v[12:13], 1.0 op_sel_hi:[1,0]
	v_lshlrev_b32_e32 v16, 16, v17
	v_rcp_f32_e32 v21, v13
	v_and_b32_e32 v17, 0xffff0000, v17
	v_mul_f32_e32 v15, 1.0, v21
	v_mov_b32_e32 v13, v15
	v_rcp_f32_e32 v21, v12
	s_nop 0
	v_mul_f32_e32 v15, 1.0, v21
	v_mov_b32_e32 v12, v15
	v_mul_f32_e32 v15, 0xbfb8aa3b, v20
	v_exp_f32_e32 v15, v15
	v_pk_mul_f32 v[12:13], v[12:13], v[16:17]
	v_pk_add_f32 v[14:15], v[14:15], 1.0 op_sel_hi:[1,0]
	s_nop 0
	v_rcp_f32_e32 v17, v15
	s_nop 0
	v_mul_f32_e32 v16, v20, v17
	v_mov_b32_e32 v15, v16
	v_rcp_f32_e32 v17, v14
	s_nop 0
	v_mul_f32_e32 v16, v9, v17
	v_mov_b32_e32 v14, v16
	v_pk_mul_f32 v[12:13], v[14:15], v[12:13]
	v_lshlrev_b32_e32 v14, 16, v18
	v_cvt_pk_bf16_f32 v9, v12, v13
	v_and_b32_e32 v15, 0xffff0000, v18
	v_rcp_f32_e32 v18, v11
	v_lshlrev_b32_e32 v16, 16, v22
	v_and_b32_e32 v17, 0xffff0000, v22
	v_mul_f32_e32 v12, 0xbfb8aa3b, v16
	v_mul_f32_e32 v13, 1.0, v18
	v_mov_b32_e32 v11, v13
	v_rcp_f32_e32 v18, v10
	v_exp_f32_e32 v12, v12
	v_mul_f32_e32 v13, 1.0, v18
	v_mov_b32_e32 v10, v13
	v_mul_f32_e32 v13, 0xbfb8aa3b, v17
	v_exp_f32_e32 v13, v13
	v_pk_mul_f32 v[10:11], v[10:11], v[14:15]
	v_pk_add_f32 v[12:13], v[12:13], 1.0 op_sel_hi:[1,0]
	s_nop 0
	v_rcp_f32_e32 v15, v13
	s_nop 0
	v_mul_f32_e32 v14, v17, v15
	v_mov_b32_e32 v13, v14
	v_rcp_f32_e32 v15, v12
	s_nop 0
	v_mul_f32_e32 v14, v16, v15
	v_mov_b32_e32 v12, v14
	v_pk_mul_f32 v[10:11], v[12:13], v[10:11]
	v_lshlrev_b32_e32 v16, 16, v19
	v_cvt_pk_bf16_f32 v10, v10, v11
	v_mul_f32_e32 v11, 0xbfb8aa3b, v30
	v_exp_f32_e32 v12, v11
	v_mul_f32_e32 v11, 0xbfb8aa3b, v31
	v_exp_f32_e32 v13, v11
	v_and_b32_e32 v17, 0xffff0000, v19
	v_lshlrev_b32_e32 v11, 16, v23
	v_and_b32_e32 v18, 0xffff0000, v23
	v_pk_add_f32 v[12:13], v[12:13], 1.0 op_sel_hi:[1,0]
	v_mul_f32_e32 v14, 0xbfb8aa3b, v11
	v_rcp_f32_e32 v19, v13
	v_exp_f32_e32 v14, v14
	v_mul_f32_e32 v15, 1.0, v19
	v_mov_b32_e32 v13, v15
	v_rcp_f32_e32 v19, v12
	s_nop 0
	v_mul_f32_e32 v15, 1.0, v19
	v_mov_b32_e32 v12, v15
	v_mul_f32_e32 v15, 0xbfb8aa3b, v18
	v_exp_f32_e32 v15, v15
	v_pk_mul_f32 v[12:13], v[12:13], v[16:17]
	v_pk_add_f32 v[14:15], v[14:15], 1.0 op_sel_hi:[1,0]
	s_nop 0
	v_rcp_f32_e32 v17, v15
	s_nop 0
	v_mul_f32_e32 v16, v18, v17
	v_mov_b32_e32 v15, v16
	v_rcp_f32_e32 v17, v14
	s_nop 0
	v_mul_f32_e32 v16, v11, v17
	v_mov_b32_e32 v14, v16
	v_pk_mul_f32 v[12:13], v[14:15], v[12:13]
	s_nop 0
	v_cvt_pk_bf16_f32 v11, v12, v13
	global_store_dwordx4 v[24:25], v[8:11], off
	global_load_dwordx4 v[8:11], v[26:27], off offset:256
	s_nop 0
	global_load_dwordx4 v[12:15], v[24:25], off offset:256
	global_load_dwordx4 v[16:19], v[142:143], off offset:528
	global_load_dwordx4 v[20:23], v[142:143], off offset:512
	s_waitcnt vmcnt(0)
	v_pk_add_f32 v[20:21], v[4:5], v[20:21]
	v_pk_add_f32 v[4:5], v[2:3], v[18:19]
	v_pk_add_f32 v[2:3], v[0:1], v[16:17]
	v_mul_f32_e32 v0, 0xbfb8aa3b, v20
	v_mul_f32_e32 v1, 0xbfb8aa3b, v21
	v_exp_f32_e32 v0, v0
	v_exp_f32_e32 v1, v1
	v_lshlrev_b32_e32 v18, 16, v8
	v_and_b32_e32 v19, 0xffff0000, v8
	v_pk_add_f32 v[6:7], v[6:7], v[22:23]
	v_pk_add_f32 v[0:1], v[0:1], 1.0 op_sel_hi:[1,0]
	v_lshlrev_b32_e32 v20, 16, v12
	v_rcp_f32_e32 v17, v1
	v_and_b32_e32 v12, 0xffff0000, v12
	v_mul_f32_e32 v16, 0xbfb8aa3b, v20
	v_exp_f32_e32 v16, v16
	v_mul_f32_e32 v8, 1.0, v17
	v_mov_b32_e32 v1, v8
	v_rcp_f32_e32 v17, v0
	v_mul_f32_e32 v2, 0xbfb8aa3b, v2
	v_mul_f32_e32 v3, 0xbfb8aa3b, v3
	v_exp_f32_e32 v2, v2
	v_mul_f32_e32 v8, 1.0, v17
	v_mov_b32_e32 v0, v8
	v_mul_f32_e32 v8, 0xbfb8aa3b, v12
	v_exp_f32_e32 v17, v8
	v_pk_mul_f32 v[0:1], v[0:1], v[18:19]
	v_exp_f32_e32 v3, v3
	v_pk_add_f32 v[16:17], v[16:17], 1.0 op_sel_hi:[1,0]
	s_nop 0
	v_rcp_f32_e32 v18, v17
	v_pk_add_f32 v[2:3], v[2:3], 1.0 op_sel_hi:[1,0]
	v_mul_f32_e32 v8, v12, v18
	v_mov_b32_e32 v17, v8
	v_rcp_f32_e32 v12, v16
	s_nop 0
	v_mul_f32_e32 v8, v20, v12
	v_mov_b32_e32 v16, v8
	v_pk_mul_f32 v[0:1], v[16:17], v[0:1]
	v_and_b32_e32 v16, 0xffff0000, v13
	v_cvt_pk_bf16_f32 v0, v0, v1
	v_mul_f32_e32 v1, 0xbfb8aa3b, v6
	v_exp_f32_e32 v6, v1
	v_mul_f32_e32 v1, 0xbfb8aa3b, v7
	v_exp_f32_e32 v7, v1
	v_lshlrev_b32_e32 v1, 16, v13
	v_lshlrev_b32_e32 v12, 16, v9
	v_and_b32_e32 v13, 0xffff0000, v9
	v_pk_add_f32 v[6:7], v[6:7], 1.0 op_sel_hi:[1,0]
	v_mul_f32_e32 v8, 0xbfb8aa3b, v1
	v_rcp_f32_e32 v17, v7
	v_exp_f32_e32 v8, v8
	v_mul_f32_e32 v9, 1.0, v17
	v_mov_b32_e32 v7, v9
	v_rcp_f32_e32 v17, v6
	s_nop 0
	v_mul_f32_e32 v9, 1.0, v17
	v_mov_b32_e32 v6, v9
	v_mul_f32_e32 v9, 0xbfb8aa3b, v16
	v_exp_f32_e32 v9, v9
	v_pk_mul_f32 v[6:7], v[6:7], v[12:13]
	v_pk_add_f32 v[8:9], v[8:9], 1.0 op_sel_hi:[1,0]
	s_nop 0
	v_rcp_f32_e32 v13, v9
	s_nop 0
	v_mul_f32_e32 v12, v16, v13
	v_mov_b32_e32 v9, v12
	v_rcp_f32_e32 v13, v8
	s_nop 0
	v_mul_f32_e32 v12, v1, v13
	v_mov_b32_e32 v8, v12
	v_pk_mul_f32 v[6:7], v[8:9], v[6:7]
	v_lshlrev_b32_e32 v8, 16, v10
	v_cvt_pk_bf16_f32 v1, v6, v7
	v_and_b32_e32 v9, 0xffff0000, v10
	v_rcp_f32_e32 v10, v3
	v_lshlrev_b32_e32 v12, 16, v14
	v_and_b32_e32 v13, 0xffff0000, v14
	v_mul_f32_e32 v6, 0xbfb8aa3b, v12
	v_mul_f32_e32 v7, 1.0, v10
	v_mov_b32_e32 v3, v7
	v_rcp_f32_e32 v10, v2
	v_exp_f32_e32 v6, v6
	v_mul_f32_e32 v7, 1.0, v10
	v_mov_b32_e32 v2, v7
	v_mul_f32_e32 v7, 0xbfb8aa3b, v13
	v_exp_f32_e32 v7, v7
	v_pk_mul_f32 v[2:3], v[2:3], v[8:9]
	v_pk_add_f32 v[6:7], v[6:7], 1.0 op_sel_hi:[1,0]
	s_nop 0
	v_rcp_f32_e32 v9, v7
	s_nop 0
	v_mul_f32_e32 v8, v13, v9
	v_mov_b32_e32 v7, v8
	v_rcp_f32_e32 v9, v6
	s_nop 0
	v_mul_f32_e32 v8, v12, v9
	v_mov_b32_e32 v6, v8
	v_pk_mul_f32 v[2:3], v[6:7], v[2:3]
	v_lshlrev_b32_e32 v8, 16, v11
	v_cvt_pk_bf16_f32 v2, v2, v3
	v_mul_f32_e32 v3, 0xbfb8aa3b, v4
	v_exp_f32_e32 v4, v3
	v_mul_f32_e32 v3, 0xbfb8aa3b, v5
	v_exp_f32_e32 v5, v3
	v_and_b32_e32 v9, 0xffff0000, v11
	v_lshlrev_b32_e32 v3, 16, v15
	v_and_b32_e32 v10, 0xffff0000, v15
	v_pk_add_f32 v[4:5], v[4:5], 1.0 op_sel_hi:[1,0]
	v_mul_f32_e32 v6, 0xbfb8aa3b, v3
	v_rcp_f32_e32 v11, v5
	v_exp_f32_e32 v6, v6
	v_mul_f32_e32 v7, 1.0, v11
	v_mov_b32_e32 v5, v7
	v_rcp_f32_e32 v11, v4
	s_nop 0
	v_mul_f32_e32 v7, 1.0, v11
	v_mov_b32_e32 v4, v7
	v_mul_f32_e32 v7, 0xbfb8aa3b, v10
	v_exp_f32_e32 v7, v7
	v_pk_mul_f32 v[4:5], v[4:5], v[8:9]
	v_pk_add_f32 v[6:7], v[6:7], 1.0 op_sel_hi:[1,0]
	s_nop 0
	v_rcp_f32_e32 v9, v7
	s_nop 0
	v_mul_f32_e32 v8, v10, v9
	v_mov_b32_e32 v7, v8
	v_rcp_f32_e32 v9, v6
	s_mov_b64 s[0:1], -1
	v_mul_f32_e32 v8, v3, v9
	v_mov_b32_e32 v6, v8
	v_pk_mul_f32 v[4:5], v[6:7], v[4:5]
	s_and_b64 vcc, exec, s[38:39]
	v_cvt_pk_bf16_f32 v3, v4, v5
	global_store_dwordx4 v[24:25], v[0:3], off offset:256
	s_cbranch_vccnz .LBB0_903
	s_andn2_b64 vcc, exec, s[84:85]
	s_cbranch_vccnz .LBB0_902
	s_barrier
	s_branch .LBB0_902
